# saddr + 32-MFMA merged blocks (half the barriers) + prologue vmcnt(2) fix for first-tile race
# speedup vs baseline: 1.0123x; 1.0123x over previous
; #define PG8_STAGE(bufoff, gbase, voff) do { _Pragma("unroll") for (int _i = 0; _i < 2; ++_i) \
;     __builtin_amdgcn_global_load_lds((const unsigned*)((const char*)(gbase) + (voff)[_i]), (LAS unsigned*)(lds + (bufoff) + ldsw + _i * 8192), 16, 0, 0); } while (0)
; #define PG8_WAIT_V(n) asm volatile("s_waitcnt vmcnt(" #n ")" ::: "memory")
; #define PG8_BAR __builtin_amdgcn_s_barrier()
; template <class Epi, class Sched = StaticOrder>
; DI void gemm_phase(LAS unsigned char* lds, const Gemm g, const Sched& S, const Epi& E) {
;     ...
;   const char* cA = (const char*)g.A + (size_t)cur.pm * tstep; const char* cB = (const char*)g.Bt + (size_t)cur.pn * tstep;
;   PG8_STAGE(PG8_SB(0, 0), cB, voffB); PG8_STAGE(PG8_SA(0, 0), cA, voffA); PG8_STAGE(PG8_SB(0, 1), cB + hstep, voffB); PG8_STAGE(PG8_SA(0, 1), cA + hstep, voffA);
;   if (wr == 1) PG8_BAR;
;   PG8_WAIT_V(4); PG8_BAR;
;   PG8_STAGE(PG8_SB(1, 0), cB + kstep, voffB); PG8_STAGE(PG8_SA(1, 0), cA + kstep, voffA); PG8_STAGE(PG8_SB(1, 1), cB + hstep + kstep, voffB);
;   PG8_WAIT_V(6); PG8_BAR;
;   for (;;) {
.LBB0_342:
	s_add_u32 s2, s84, 0x10903600
	s_addc_u32 s3, s85, 0
	s_lshl_b32 s5, s10, 5
	s_mov_b64 s[22:23], 0x80
	s_and_b32 s26, s5, 0x60
	s_add_i32 m0, s48, 0x18000
	v_lshl_add_u64 v[6:7], v[6:7], 0, s[22:23]
	s_lshl_b32 s24, s1, 13
	s_lshl_b32 s28, s26, 7
	s_waitcnt vmcnt(2)
	s_barrier
	global_load_lds_dwordx4 v[6:7], off
	v_lshl_add_u64 v[4:5], v[4:5], 0, s[22:23]
	s_add_i32 m0, s48, 0x1a000
	s_add_i32 s56, s48, 0x8000
	s_add_i32 s57, s48, 0xa000
	global_load_lds_dwordx4 v[4:5], off
	v_lshl_add_u64 v[2:3], v[2:3], 0, s[22:23]
	s_mov_b32 m0, s56
	s_add_u32 s10, s8, 0x80080
	global_load_lds_dwordx4 v[2:3], off
	v_lshl_add_u64 v[0:1], v[0:1], 0, s[22:23]
	s_mov_b32 m0, s57
	s_addc_u32 s11, s9, 0
	global_load_lds_dwordx4 v[0:1], off
	s_add_i32 m0, s48, 0x1c000
	v_lshl_add_u64 v[0:1], s[10:11], 0, v[140:141]
	global_load_lds_dwordx4 v[0:1], off
	v_lshl_add_u64 v[0:1], s[10:11], 0, v[136:137]
	s_add_i32 m0, s48, 0x1e000
	v_lshlrev_b32_e32 v2, 2, v210
	global_load_lds_dwordx4 v[0:1], off
	v_and_b32_e32 v0, 15, v210
	v_lshlrev_b32_e32 v1, 1, v11
	v_lshl_or_b32 v170, s1, 6, v0
	v_lshl_or_b32 v0, v0, 6, v1
	v_and_b32_e32 v2, 32, v2
	s_sext_i32_i16 s5, s0
	v_bitop3_b32 v3, v0, s24, v2 bitop3:0xde
	v_lshlrev_b32_e32 v0, 6, v210
	s_movk_i32 s0, 0x3c0
	v_and_or_b32 v0, v0, s0, v1
	v_bitop3_b32 v171, s28, v0, v2 bitop3:0xf6
	v_lshlrev_b32_e32 v0, 2, v11
	v_mov_b32_e32 v1, v141
	v_lshl_add_u64 v[0:1], s[84:85], 0, v[0:1]
	s_mov_b64 s[0:1], 0x10103600
	v_lshl_add_u64 v[144:145], v[0:1], 0, s[0:1]
	v_lshlrev_b32_e32 v0, 9, v210
	v_and_b32_e32 v0, 0x70000, v0
	v_lshlrev_b32_e32 v1, 12, v12
	v_or3_b32 v0, v9, v0, v1
	v_add_u32_e32 v146, v0, v10
	v_lshlrev_b32_e32 v0, 5, v8
	v_and_b32_e32 v0, 0xf0000, v0
	s_waitcnt vmcnt(6)
	v_or3_b32 v0, v9, v0, v1
	v_add_u32_e32 v148, v0, v10
	s_add_i32 s65, 0, 0x10000
	s_add_i32 s72, 0, 0x14000
	v_mbcnt_lo_u32_b32 v0, -1, 0
	s_mov_b32 s62, 0
	s_ashr_i32 s63, s96, 31
	s_mov_b32 s64, s96
	v_or_b32_e32 v172, s26, v11
	v_mov_b32_e32 v147, v141
	v_mov_b32_e32 v149, v141
	v_mov_b64_e32 v[150:151], 0x4c0
	v_mov_b64_e32 v[152:153], 0x4bf
	v_add_u32_e32 v173, s65, v171
	v_add_u32_e32 v174, 0, v3
	v_add_u32_e32 v175, s72, v171
	v_mbcnt_hi_u32_b32 v176, -1, v0
	s_mov_b32 s24, 0x3a000000
	s_mov_b32 s26, 0x358637bd
	s_mov_b32 s73, 0x800000
	s_movk_i32 s76, 0x2600
	s_barrier

; #define PG8_STAGE(bufoff, gbase, voff) do { _Pragma("unroll") for (int _i = 0; _i < 2; ++_i) \
;     __builtin_amdgcn_global_load_lds((const unsigned*)((const char*)(gbase) + (voff)[_i]), (LAS unsigned*)(lds + (bufoff) + ldsw + _i * 8192), 16, 0, 0); } while (0)
; #define PG8_LDA(dst, b, h) do { _Pragma("unroll") for (int m = 0; m < 4; ++m) _Pragma("unroll") for (int k = 0; k < 2; ++k) dst[m][k] = *(const LAS bf16x8*)(lds + PG8_SA(b, h) + aoff + m * 2048 + k * 1024); } while (0)
; #define PG8_LDB(dst, b, h) do { _Pragma("unroll") for (int n = 0; n < 2; ++n) _Pragma("unroll") for (int k = 0; k < 2; ++k) dst[n][k] = *(const LAS bf16x8*)(lds + PG8_SB(b, h) + boff + n * 2048 + k * 1024); } while (0)
; #define PG8_MMA(ai, bj, At, Bt) do { __builtin_amdgcn_s_setprio(1); _Pragma("unroll") for (int m = 0; m < 4; ++m) _Pragma("unroll") for (int n = 0; n < 2; ++n) _Pragma("unroll") for (int k = 0; k < 2; ++k) \
;     acc[ai][bj][m][n] = __builtin_amdgcn_mfma_f32_16x16x32_bf16(Bt[n][k], At[m][k], acc[ai][bj][m][n], 0, 0, 0); __builtin_amdgcn_s_setprio(0); } while (0)
; #define PG8_WAIT_V(n) asm volatile("s_waitcnt vmcnt(" #n ")" ::: "memory")
; #define PG8_WAIT_L(n) asm volatile("s_waitcnt lgkmcnt(" #n ")" ::: "memory")
; #define PG8_BAR __builtin_amdgcn_s_barrier()
; #define PG8_SCHED __builtin_amdgcn_sched_barrier(0)
; template <class Epi, class Sched = StaticOrder>
; DI void gemm_phase(LAS unsigned char* lds, const Gemm g, const Sched& S, const Epi& E) {
;     ...
;     for (int t = 0; t < nt; t += 2) {
;       const bool last = (t == nt - 2);
;       const char* a1 = cA + (size_t)(t + 1) * kstep;
;       const char* a2 = last ? nA : cA + (size_t)(t + 2) * kstep; const char* b2 = last ? nB : cB + (size_t)(t + 2) * kstep;
;       const char* a3 = a2 + kstep; const char* b3 = b2 + kstep;
;       PG8_LDB(B0, 0, 0); PG8_SCHED; PG8_LDA(At, 0, 0); PG8_STAGE(PG8_SA(1, 1), a1 + hstep, voffA);
;       PG8_WAIT_L(8); PG8_BAR; PG8_WAIT_L(0); PG8_MMA(0, 0, At, B0); PG8_BAR; PG8_SCHED;
;       PG8_LDB(B1, 0, 1); PG8_STAGE(PG8_SB(0, 0), b2, voffB);
;       PG8_BAR; PG8_WAIT_L(0); PG8_MMA(0, 1, At, B1); PG8_BAR;
;       PG8_LDA(At, 0, 1); PG8_STAGE(PG8_SA(0, 0), a2, voffA);
;       PG8_BAR; PG8_WAIT_L(0); PG8_MMA(1, 0, At, B0); PG8_BAR; PG8_SCHED;
;       PG8_STAGE(PG8_SB(0, 1), b2 + hstep, voffB);
;       PG8_WAIT_V(6); PG8_BAR; PG8_MMA(1, 1, At, B1); PG8_BAR;
.LBB0_346:
	ds_read_b128 v[128:131], v173
	ds_read_b128 v[132:135], v173 offset:1024
	ds_read_b128 v[154:157], v173 offset:2048
	ds_read_b128 v[158:161], v173 offset:3072
	s_add_u32 s8, s6, 0xfff80080
	s_addc_u32 s9, s7, -1
	s_cmp_eq_u32 s52, 28
	s_cselect_b32 s11, s31, s9
	s_cselect_b32 s10, s42, s8
	s_cselect_b32 s9, s29, s45
	s_cselect_b32 s8, s43, s44
	s_add_i32 m0, s48, 0xc000
	ds_read_b128 v[162:165], v174
	ds_read_b128 v[166:169], v174 offset:1024
	ds_read_b128 v[178:181], v174 offset:2048
	ds_read_b128 v[182:185], v174 offset:3072
	ds_read_b128 v[186:189], v174 offset:4096
	ds_read_b128 v[190:193], v174 offset:5120
	ds_read_b128 v[194:197], v174 offset:6144
	ds_read_b128 v[198:201], v174 offset:7168
	global_load_lds_dwordx4 v146, s[6:7]
	s_add_i32 m0, s48, 0xe000
	s_nop 0
	global_load_lds_dwordx4 v148, s[6:7]
	ds_read_b128 v[202:205], v175
	ds_read_b128 v[206:209], v175 offset:1024
	ds_read_b128 v[212:215], v175 offset:2048
	ds_read_b128 v[216:219], v175 offset:3072
	s_waitcnt vmcnt(8)
	s_waitcnt lgkmcnt(0)
	s_setprio 1
	s_barrier
	v_mfma_f32_16x16x32_bf16 v[124:127], v[128:131], v[162:165], v[124:127]
	v_mfma_f32_16x16x32_bf16 v[120:123], v[154:157], v[162:165], v[120:123]
	v_mfma_f32_16x16x32_bf16 v[108:111], v[128:131], v[178:181], v[108:111]
	v_mfma_f32_16x16x32_bf16 v[104:107], v[154:157], v[178:181], v[104:107]
	v_mfma_f32_16x16x32_bf16 v[100:103], v[128:131], v[186:189], v[100:103]
	v_mfma_f32_16x16x32_bf16 v[92:95], v[154:157], v[186:189], v[92:95]
	v_mfma_f32_16x16x32_bf16 v[84:87], v[128:131], v[194:197], v[84:87]
	v_mfma_f32_16x16x32_bf16 v[76:79], v[154:157], v[194:197], v[76:79]
	v_mfma_f32_16x16x32_bf16 v[124:127], v[132:135], v[166:169], v[124:127]
	v_mfma_f32_16x16x32_bf16 v[120:123], v[158:161], v[166:169], v[120:123]
	v_mfma_f32_16x16x32_bf16 v[108:111], v[132:135], v[182:185], v[108:111]
	v_mfma_f32_16x16x32_bf16 v[104:107], v[158:161], v[182:185], v[104:107]
	v_mfma_f32_16x16x32_bf16 v[100:103], v[132:135], v[190:193], v[100:103]
	v_mfma_f32_16x16x32_bf16 v[92:95], v[158:161], v[190:193], v[92:95]
	v_mfma_f32_16x16x32_bf16 v[84:87], v[132:135], v[198:201], v[84:87]
	v_mfma_f32_16x16x32_bf16 v[76:79], v[158:161], v[198:201], v[76:79]
	v_mfma_f32_16x16x32_bf16 v[116:119], v[202:205], v[162:165], v[116:119]
	v_mfma_f32_16x16x32_bf16 v[112:115], v[212:215], v[162:165], v[112:115]
	v_mfma_f32_16x16x32_bf16 v[96:99], v[202:205], v[178:181], v[96:99]
	v_mfma_f32_16x16x32_bf16 v[88:91], v[212:215], v[178:181], v[88:91]
	v_mfma_f32_16x16x32_bf16 v[80:83], v[202:205], v[186:189], v[80:83]
	v_mfma_f32_16x16x32_bf16 v[72:75], v[212:215], v[186:189], v[72:75]
	v_mfma_f32_16x16x32_bf16 v[68:71], v[202:205], v[194:197], v[68:71]
	v_mfma_f32_16x16x32_bf16 v[64:67], v[212:215], v[194:197], v[64:67]
	v_mfma_f32_16x16x32_bf16 v[116:119], v[206:209], v[166:169], v[116:119]
	v_mfma_f32_16x16x32_bf16 v[112:115], v[216:219], v[166:169], v[112:115]
	v_mfma_f32_16x16x32_bf16 v[96:99], v[206:209], v[182:185], v[96:99]
	v_mfma_f32_16x16x32_bf16 v[88:91], v[216:219], v[182:185], v[88:91]
	v_mfma_f32_16x16x32_bf16 v[80:83], v[206:209], v[190:193], v[80:83]
	v_mfma_f32_16x16x32_bf16 v[72:75], v[216:219], v[190:193], v[72:75]
	v_mfma_f32_16x16x32_bf16 v[68:71], v[206:209], v[198:201], v[68:71]
	v_mfma_f32_16x16x32_bf16 v[64:67], v[216:219], v[198:201], v[64:67]
	s_barrier
	s_setprio 0
	s_add_i32 s53, s65, s41
	s_add_u32 s98, s8, 0x80
	s_addc_u32 s99, s9, 0
	s_add_u32 s100, s10, 0x80
	s_addc_u32 s101, s11, 0
	s_mov_b32 m0, s53
	s_nop 0
	global_load_lds_dwordx4 v140, s[8:9]
	s_add_i32 m0, s53, 0x2000
	s_nop 0
	global_load_lds_dwordx4 v136, s[8:9]
	s_mov_b32 m0, s48
	ds_read_b128 v[162:165], v174 offset:16384
	ds_read_b128 v[166:169], v174 offset:17408
	ds_read_b128 v[178:181], v174 offset:18432
	ds_read_b128 v[182:185], v174 offset:19456
	ds_read_b128 v[186:189], v174 offset:20480
	ds_read_b128 v[190:193], v174 offset:21504
	ds_read_b128 v[194:197], v174 offset:22528
	ds_read_b128 v[198:201], v174 offset:23552
	global_load_lds_dwordx4 v142, s[10:11]
	s_mov_b32 m0, s49
	s_nop 0
	global_load_lds_dwordx4 v138, s[10:11]
	s_add_u32 s54, s8, 0x80000
	s_addc_u32 s55, s9, 0
	s_add_i32 s53, s72, s41
	s_mov_b32 m0, s53
	s_nop 0
	global_load_lds_dwordx4 v140, s[54:55]
	s_add_i32 m0, s53, 0x2000
	s_nop 0
	global_load_lds_dwordx4 v136, s[54:55]
	s_waitcnt vmcnt(8)
	s_waitcnt lgkmcnt(0)
	s_setprio 1
	s_barrier
	v_mfma_f32_16x16x32_bf16 v[60:63], v[128:131], v[162:165], v[60:63]
	v_mfma_f32_16x16x32_bf16 v[56:59], v[154:157], v[162:165], v[56:59]
	v_mfma_f32_16x16x32_bf16 v[52:55], v[128:131], v[178:181], v[52:55]
	v_mfma_f32_16x16x32_bf16 v[44:47], v[154:157], v[178:181], v[44:47]
	v_mfma_f32_16x16x32_bf16 v[36:39], v[128:131], v[186:189], v[36:39]
	v_mfma_f32_16x16x32_bf16 v[28:31], v[154:157], v[186:189], v[28:31]
	v_mfma_f32_16x16x32_bf16 v[20:23], v[128:131], v[194:197], v[20:23]
	v_mfma_f32_16x16x32_bf16 v[12:15], v[154:157], v[194:197], v[12:15]
	v_mfma_f32_16x16x32_bf16 v[60:63], v[132:135], v[166:169], v[60:63]
	v_mfma_f32_16x16x32_bf16 v[56:59], v[158:161], v[166:169], v[56:59]
	v_mfma_f32_16x16x32_bf16 v[52:55], v[132:135], v[182:185], v[52:55]
	v_mfma_f32_16x16x32_bf16 v[44:47], v[158:161], v[182:185], v[44:47]
	v_mfma_f32_16x16x32_bf16 v[36:39], v[132:135], v[190:193], v[36:39]
	v_mfma_f32_16x16x32_bf16 v[28:31], v[158:161], v[190:193], v[28:31]
	v_mfma_f32_16x16x32_bf16 v[20:23], v[132:135], v[198:201], v[20:23]
	v_mfma_f32_16x16x32_bf16 v[12:15], v[158:161], v[198:201], v[12:15]
	v_mfma_f32_16x16x32_bf16 v[48:51], v[202:205], v[162:165], v[48:51]
	v_mfma_f32_16x16x32_bf16 v[40:43], v[212:215], v[162:165], v[40:43]
	v_mfma_f32_16x16x32_bf16 v[32:35], v[202:205], v[178:181], v[32:35]
	v_mfma_f32_16x16x32_bf16 v[24:27], v[212:215], v[178:181], v[24:27]
	v_mfma_f32_16x16x32_bf16 v[16:19], v[202:205], v[186:189], v[16:19]
	v_mfma_f32_16x16x32_bf16 v[8:11], v[212:215], v[186:189], v[8:11]
	v_mfma_f32_16x16x32_bf16 v[4:7], v[202:205], v[194:197], v[4:7]
	v_mfma_f32_16x16x32_bf16 v[0:3], v[212:215], v[194:197], v[0:3]
	v_mfma_f32_16x16x32_bf16 v[48:51], v[206:209], v[166:169], v[48:51]
	v_mfma_f32_16x16x32_bf16 v[40:43], v[216:219], v[166:169], v[40:43]
	v_mfma_f32_16x16x32_bf16 v[32:35], v[206:209], v[182:185], v[32:35]
	v_mfma_f32_16x16x32_bf16 v[24:27], v[216:219], v[182:185], v[24:27]
	v_mfma_f32_16x16x32_bf16 v[16:19], v[206:209], v[190:193], v[16:19]
	v_mfma_f32_16x16x32_bf16 v[8:11], v[216:219], v[190:193], v[8:11]
	v_mfma_f32_16x16x32_bf16 v[4:7], v[206:209], v[198:201], v[4:7]
	v_mfma_f32_16x16x32_bf16 v[0:3], v[216:219], v[198:201], v[0:3]
	s_barrier
; #define PG8_STAGE(bufoff, gbase, voff) do { _Pragma("unroll") for (int _i = 0; _i < 2; ++_i) \
;     __builtin_amdgcn_global_load_lds((const unsigned*)((const char*)(gbase) + (voff)[_i]), (LAS unsigned*)(lds + (bufoff) + ldsw + _i * 8192), 16, 0, 0); } while (0)
; #define PG8_LDA(dst, b, h) do { _Pragma("unroll") for (int m = 0; m < 4; ++m) _Pragma("unroll") for (int k = 0; k < 2; ++k) dst[m][k] = *(const LAS bf16x8*)(lds + PG8_SA(b, h) + aoff + m * 2048 + k * 1024); } while (0)
; #define PG8_LDB(dst, b, h) do { _Pragma("unroll") for (int n = 0; n < 2; ++n) _Pragma("unroll") for (int k = 0; k < 2; ++k) dst[n][k] = *(const LAS bf16x8*)(lds + PG8_SB(b, h) + boff + n * 2048 + k * 1024); } while (0)
; #define PG8_MMA(ai, bj, At, Bt) do { __builtin_amdgcn_s_setprio(1); _Pragma("unroll") for (int m = 0; m < 4; ++m) _Pragma("unroll") for (int n = 0; n < 2; ++n) _Pragma("unroll") for (int k = 0; k < 2; ++k) \
;     acc[ai][bj][m][n] = __builtin_amdgcn_mfma_f32_16x16x32_bf16(Bt[n][k], At[m][k], acc[ai][bj][m][n], 0, 0, 0); __builtin_amdgcn_s_setprio(0); } while (0)
; #define PG8_WAIT_V(n) asm volatile("s_waitcnt vmcnt(" #n ")" ::: "memory")
; #define PG8_WAIT_L(n) asm volatile("s_waitcnt lgkmcnt(" #n ")" ::: "memory")
; #define PG8_BAR __builtin_amdgcn_s_barrier()
; #define PG8_SCHED __builtin_amdgcn_sched_barrier(0)
; template <class Epi, class Sched = StaticOrder>
; DI void gemm_phase(LAS unsigned char* lds, const Gemm g, const Sched& S, const Epi& E) {
;     ...
;       PG8_LDB(B0, 1, 0); PG8_SCHED; PG8_LDA(At, 1, 0); PG8_STAGE(PG8_SA(0, 1), a2 + hstep, voffA);
;       PG8_WAIT_L(8); PG8_BAR; PG8_WAIT_L(0); PG8_MMA(0, 0, At, B0); PG8_BAR; PG8_SCHED;
;       PG8_LDB(B1, 1, 1); PG8_STAGE(PG8_SB(1, 0), b3, voffB);
;       PG8_BAR; PG8_WAIT_L(0); PG8_MMA(0, 1, At, B1); PG8_BAR;
;       PG8_LDA(At, 1, 1); PG8_STAGE(PG8_SA(1, 0), a3, voffA);
;       PG8_BAR; PG8_WAIT_L(0); PG8_MMA(1, 0, At, B0); PG8_BAR; PG8_SCHED;
;       PG8_STAGE(PG8_SB(1, 1), b3 + hstep, voffB);
;       PG8_WAIT_V(6); PG8_BAR; PG8_MMA(1, 1, At, B1); PG8_BAR;
	s_setprio 0
	s_add_i32 s53, 0, 0x18000
	v_add_u32_e32 v158, s53, v171
	ds_read_b128 v[128:131], v158
	ds_read_b128 v[132:135], v158 offset:1024
	ds_read_b128 v[154:157], v158 offset:2048
	ds_read_b128 v[158:161], v158 offset:3072
	s_add_u32 s10, s10, 0x80000
	s_addc_u32 s11, s11, 0
	s_mov_b32 m0, s50
	ds_read_b128 v[162:165], v174 offset:32768
	ds_read_b128 v[166:169], v174 offset:33792
	ds_read_b128 v[178:181], v174 offset:34816
	ds_read_b128 v[182:185], v174 offset:35840
	ds_read_b128 v[186:189], v174 offset:36864
	ds_read_b128 v[190:193], v174 offset:37888
	ds_read_b128 v[194:197], v174 offset:38912
	ds_read_b128 v[198:201], v174 offset:39936
	global_load_lds_dwordx4 v142, s[10:11]
	s_mov_b32 m0, s51
	s_nop 0
	global_load_lds_dwordx4 v138, s[10:11]
	s_add_i32 s10, 0, 0x1c000
	v_add_u32_e32 v177, s10, v171
	ds_read_b128 v[202:205], v177
	ds_read_b128 v[206:209], v177 offset:1024
	ds_read_b128 v[212:215], v177 offset:2048
	ds_read_b128 v[216:219], v177 offset:3072
	s_waitcnt vmcnt(8)
	s_waitcnt lgkmcnt(0)
	s_setprio 1
	s_barrier
	v_mfma_f32_16x16x32_bf16 v[124:127], v[128:131], v[162:165], v[124:127]
	v_mfma_f32_16x16x32_bf16 v[120:123], v[154:157], v[162:165], v[120:123]
	v_mfma_f32_16x16x32_bf16 v[108:111], v[128:131], v[178:181], v[108:111]
	v_mfma_f32_16x16x32_bf16 v[104:107], v[154:157], v[178:181], v[104:107]
	v_mfma_f32_16x16x32_bf16 v[100:103], v[128:131], v[186:189], v[100:103]
	v_mfma_f32_16x16x32_bf16 v[92:95], v[154:157], v[186:189], v[92:95]
	v_mfma_f32_16x16x32_bf16 v[84:87], v[128:131], v[194:197], v[84:87]
	v_mfma_f32_16x16x32_bf16 v[76:79], v[154:157], v[194:197], v[76:79]
	v_mfma_f32_16x16x32_bf16 v[124:127], v[132:135], v[166:169], v[124:127]
	v_mfma_f32_16x16x32_bf16 v[120:123], v[158:161], v[166:169], v[120:123]
	v_mfma_f32_16x16x32_bf16 v[108:111], v[132:135], v[182:185], v[108:111]
	v_mfma_f32_16x16x32_bf16 v[104:107], v[158:161], v[182:185], v[104:107]
	v_mfma_f32_16x16x32_bf16 v[100:103], v[132:135], v[190:193], v[100:103]
	v_mfma_f32_16x16x32_bf16 v[92:95], v[158:161], v[190:193], v[92:95]
	v_mfma_f32_16x16x32_bf16 v[84:87], v[132:135], v[198:201], v[84:87]
	v_mfma_f32_16x16x32_bf16 v[76:79], v[158:161], v[198:201], v[76:79]
	v_mfma_f32_16x16x32_bf16 v[116:119], v[202:205], v[162:165], v[116:119]
	v_mfma_f32_16x16x32_bf16 v[112:115], v[212:215], v[162:165], v[112:115]
	v_mfma_f32_16x16x32_bf16 v[96:99], v[202:205], v[178:181], v[96:99]
	v_mfma_f32_16x16x32_bf16 v[88:91], v[212:215], v[178:181], v[88:91]
	v_mfma_f32_16x16x32_bf16 v[80:83], v[202:205], v[186:189], v[80:83]
	v_mfma_f32_16x16x32_bf16 v[72:75], v[212:215], v[186:189], v[72:75]
	v_mfma_f32_16x16x32_bf16 v[68:71], v[202:205], v[194:197], v[68:71]
	v_mfma_f32_16x16x32_bf16 v[64:67], v[212:215], v[194:197], v[64:67]
	v_mfma_f32_16x16x32_bf16 v[116:119], v[206:209], v[166:169], v[116:119]
	v_mfma_f32_16x16x32_bf16 v[112:115], v[216:219], v[166:169], v[112:115]
	v_mfma_f32_16x16x32_bf16 v[96:99], v[206:209], v[182:185], v[96:99]
	v_mfma_f32_16x16x32_bf16 v[88:91], v[216:219], v[182:185], v[88:91]
	v_mfma_f32_16x16x32_bf16 v[80:83], v[206:209], v[190:193], v[80:83]
	v_mfma_f32_16x16x32_bf16 v[72:75], v[216:219], v[190:193], v[72:75]
	v_mfma_f32_16x16x32_bf16 v[68:71], v[206:209], v[198:201], v[68:71]
	v_mfma_f32_16x16x32_bf16 v[64:67], v[216:219], v[198:201], v[64:67]
	s_barrier
	s_setprio 0
	s_add_i32 s11, s53, s41
	s_mov_b32 m0, s11
	s_nop 0
	global_load_lds_dwordx4 v140, s[98:99]
	s_add_i32 m0, s11, 0x2000
	s_nop 0
	global_load_lds_dwordx4 v136, s[98:99]
	s_mov_b32 m0, s56
	ds_read_b128 v[162:165], v174 offset:49152
	ds_read_b128 v[166:169], v174 offset:50176
	ds_read_b128 v[178:181], v174 offset:51200
	ds_read_b128 v[182:185], v174 offset:52224
	ds_read_b128 v[186:189], v174 offset:53248
	ds_read_b128 v[190:193], v174 offset:54272
	ds_read_b128 v[194:197], v174 offset:55296
	ds_read_b128 v[198:201], v174 offset:56320
	global_load_lds_dwordx4 v142, s[100:101]
	s_mov_b32 m0, s57
	s_nop 0
	global_load_lds_dwordx4 v138, s[100:101]
	s_add_u32 s8, s8, 0x80080
	s_addc_u32 s9, s9, 0
	s_add_i32 s10, s10, s41
	s_mov_b32 m0, s10
	s_nop 0
	global_load_lds_dwordx4 v140, s[8:9]
	s_add_i32 m0, s10, 0x2000
	s_nop 0
	global_load_lds_dwordx4 v136, s[8:9]
	s_add_i32 s52, s52, 2
	s_add_u32 s6, s6, 0x100
	s_addc_u32 s7, s7, 0
	s_add_u32 s44, s44, 0x100
	s_addc_u32 s45, s45, 0
	s_cmp_gt_u32 s52, 29
	s_waitcnt vmcnt(8)
	s_waitcnt lgkmcnt(0)
	s_setprio 1
	s_barrier
	v_mfma_f32_16x16x32_bf16 v[60:63], v[128:131], v[162:165], v[60:63]
	v_mfma_f32_16x16x32_bf16 v[56:59], v[154:157], v[162:165], v[56:59]
	v_mfma_f32_16x16x32_bf16 v[52:55], v[128:131], v[178:181], v[52:55]
	v_mfma_f32_16x16x32_bf16 v[44:47], v[154:157], v[178:181], v[44:47]
	v_mfma_f32_16x16x32_bf16 v[36:39], v[128:131], v[186:189], v[36:39]
	v_mfma_f32_16x16x32_bf16 v[28:31], v[154:157], v[186:189], v[28:31]
	v_mfma_f32_16x16x32_bf16 v[20:23], v[128:131], v[194:197], v[20:23]
	v_mfma_f32_16x16x32_bf16 v[12:15], v[154:157], v[194:197], v[12:15]
	v_mfma_f32_16x16x32_bf16 v[60:63], v[132:135], v[166:169], v[60:63]
	v_mfma_f32_16x16x32_bf16 v[56:59], v[158:161], v[166:169], v[56:59]
	v_mfma_f32_16x16x32_bf16 v[52:55], v[132:135], v[182:185], v[52:55]
	v_mfma_f32_16x16x32_bf16 v[44:47], v[158:161], v[182:185], v[44:47]
	v_mfma_f32_16x16x32_bf16 v[36:39], v[132:135], v[190:193], v[36:39]
	v_mfma_f32_16x16x32_bf16 v[28:31], v[158:161], v[190:193], v[28:31]
	v_mfma_f32_16x16x32_bf16 v[20:23], v[132:135], v[198:201], v[20:23]
	v_mfma_f32_16x16x32_bf16 v[12:15], v[158:161], v[198:201], v[12:15]
	v_mfma_f32_16x16x32_bf16 v[48:51], v[202:205], v[162:165], v[48:51]
	v_mfma_f32_16x16x32_bf16 v[40:43], v[212:215], v[162:165], v[40:43]
	v_mfma_f32_16x16x32_bf16 v[32:35], v[202:205], v[178:181], v[32:35]
	v_mfma_f32_16x16x32_bf16 v[24:27], v[212:215], v[178:181], v[24:27]
	v_mfma_f32_16x16x32_bf16 v[16:19], v[202:205], v[186:189], v[16:19]
	v_mfma_f32_16x16x32_bf16 v[8:11], v[212:215], v[186:189], v[8:11]
	v_mfma_f32_16x16x32_bf16 v[4:7], v[202:205], v[194:197], v[4:7]
	v_mfma_f32_16x16x32_bf16 v[0:3], v[212:215], v[194:197], v[0:3]
	v_mfma_f32_16x16x32_bf16 v[48:51], v[206:209], v[166:169], v[48:51]
	v_mfma_f32_16x16x32_bf16 v[40:43], v[216:219], v[166:169], v[40:43]
	v_mfma_f32_16x16x32_bf16 v[32:35], v[206:209], v[182:185], v[32:35]
	v_mfma_f32_16x16x32_bf16 v[24:27], v[216:219], v[182:185], v[24:27]
	v_mfma_f32_16x16x32_bf16 v[16:19], v[206:209], v[190:193], v[16:19]
	v_mfma_f32_16x16x32_bf16 v[8:11], v[216:219], v[190:193], v[8:11]
	v_mfma_f32_16x16x32_bf16 v[4:7], v[206:209], v[198:201], v[4:7]
	v_mfma_f32_16x16x32_bf16 v[0:3], v[216:219], v[198:201], v[0:3]
	s_barrier
; DI unsigned pack2(float lo, float hi) { f32x2 v = {lo, hi}; bf16v2 r = __builtin_convertvector(v, bf16v2); return __builtin_bit_cast(unsigned, r); }
; DI float row_rstd(const float* ssq, int row, int fq) {
;   const f32x4 a = *(const f32x4*)(ssq + (size_t)row * 32 + fq * 8), b = *(const f32x4*)(ssq + (size_t)row * 32 + fq * 8 + 4);
;   float sm = ((a[0] + a[1]) + (a[2] + a[3])) + ((b[0] + b[1]) + (b[2] + b[3]));
;   sm += __shfl_xor(sm, 16); sm += __shfl_xor(sm, 32);
;   return rsqrtf(sm * (1.0f / 2048.f) + 1e-6f);
; }
;   DI void operator()(const f32x4 (&acc)[2][2][4][2], const Unit& u, int wr, int wc, int fr, int fq) const {
;     const int row0 = u.pm * BM + wr * 64 + fr, col0 = u.pn * BM + wc * 32 + 8 * fq;
;     float rsv[2][4];
; #pragma unroll
;     for (int ai = 0; ai < 2; ++ai)
; #pragma unroll
;       for (int m = 0; m < 4; ++m) rsv[ai][m] = row_rstd(ssq, row0 + ai * HALF + m * 16, fq);
; #pragma unroll
;     for (int ai = 0; ai < 2; ++ai)
; #pragma unroll
;       for (int m = 0; m < 4; ++m) {
;         const int row = row0 + ai * HALF + m * 16;
;         const float rs = rsv[ai][m];
;         bf16_t* rowp = O + (size_t)row * ldc + col0;
; #pragma unroll
;         for (int bj = 0; bj < 2; ++bj) {
;           const f32x4 v0 = acc[ai][bj][m][0] * rs, v1 = acc[ai][bj][m][1] * rs;
;           u32x4 w; w.x = pack2(v0[0], v0[1]); w.y = pack2(v0[2], v0[3]); w.z = pack2(v1[0], v1[1]); w.w = pack2(v1[2], v1[3]);
;           *(u32x4*)(rowp + bj * HALF) = w;
	s_setprio 0
	s_cbranch_scc0 .LBB0_346
	v_lshl_add_u32 v168, s4, 8, v170
	v_ashrrev_i32_e32 v169, 31, v168
	v_or_b32_e32 v154, 16, v168
	v_lshlrev_b64 v[128:129], 7, v[168:169]
	v_ashrrev_i32_e32 v155, 31, v154
	v_lshl_add_u64 v[128:129], v[144:145], 0, v[128:129]
	v_lshlrev_b64 v[156:157], 7, v[154:155]
	global_load_dwordx4 v[132:135], v[128:129], off
	s_nop 0
	global_load_dwordx4 v[128:131], v[128:129], off offset:16
	v_lshl_add_u64 v[156:157], v[144:145], 0, v[156:157]
	global_load_dwordx4 v[178:181], v[156:157], off
	global_load_dwordx4 v[182:185], v[156:157], off offset:16
	v_or_b32_e32 v160, 32, v168
	v_ashrrev_i32_e32 v161, 31, v160
	v_lshlrev_b64 v[156:157], 7, v[160:161]
	v_lshl_add_u64 v[156:157], v[144:145], 0, v[156:157]
	global_load_dwordx4 v[186:189], v[156:157], off
	global_load_dwordx4 v[190:193], v[156:157], off offset:16
	v_or_b32_e32 v156, 48, v168
	v_ashrrev_i32_e32 v157, 31, v156
	v_lshlrev_b64 v[158:159], 7, v[156:157]
	v_lshl_add_u64 v[158:159], v[144:145], 0, v[158:159]
	global_load_dwordx4 v[194:197], v[158:159], off
	global_load_dwordx4 v[198:201], v[158:159], off offset:16
	v_add_u32_e32 v164, 0x80, v168
	v_ashrrev_i32_e32 v165, 31, v164
	v_lshlrev_b64 v[158:159], 7, v[164:165]
	v_lshl_add_u64 v[158:159], v[144:145], 0, v[158:159]
	global_load_dwordx4 v[202:205], v[158:159], off
	global_load_dwordx4 v[206:209], v[158:159], off offset:16
	v_add_u32_e32 v158, 0x90, v168
	v_ashrrev_i32_e32 v159, 31, v158
	v_lshlrev_b64 v[162:163], 7, v[158:159]
	v_lshl_add_u64 v[162:163], v[144:145], 0, v[162:163]
	global_load_dwordx4 v[212:215], v[162:163], off
	global_load_dwordx4 v[216:219], v[162:163], off offset:16
	v_add_u32_e32 v166, 0xa0, v168
	v_ashrrev_i32_e32 v167, 31, v166
	v_lshlrev_b64 v[162:163], 7, v[166:167]
	v_lshl_add_u64 v[162:163], v[144:145], 0, v[162:163]
	global_load_dwordx4 v[220:223], v[162:163], off
	global_load_dwordx4 v[224:227], v[162:163], off offset:16
	v_add_u32_e32 v162, 0xb0, v168
	v_ashrrev_i32_e32 v163, 31, v162
	v_lshlrev_b64 v[228:229], 7, v[162:163]
	v_lshl_add_u64 v[232:233], v[144:145], 0, v[228:229]
	global_load_dwordx4 v[228:231], v[232:233], off
	s_nop 0
	global_load_dwordx4 v[232:235], v[232:233], off offset:16
	s_waitcnt vmcnt(0)
	v_mov_b32_e32 v236, v132
	v_mov_b32_e32 v237, v128
	v_mov_b32_e32 v128, v133
	v_mov_b32_e32 v132, v134
	v_mov_b32_e32 v133, v130
	v_mov_b32_e32 v130, v135
	v_pk_add_f32 v[130:131], v[132:133], v[130:131]
	v_mov_b32_e32 v132, v178
	v_mov_b32_e32 v133, v182
	v_mov_b32_e32 v182, v179
	v_mov_b32_e32 v134, v180
	v_mov_b32_e32 v135, v184
	v_mov_b32_e32 v184, v181
	v_pk_add_f32 v[128:129], v[236:237], v[128:129]
	v_pk_add_f32 v[132:133], v[132:133], v[182:183]
	v_pk_add_f32 v[134:135], v[134:135], v[184:185]
	v_pk_add_f32 v[128:129], v[128:129], v[130:131]
	v_pk_add_f32 v[130:131], v[132:133], v[134:135]
	v_mov_b32_e32 v133, v128
	v_mov_b32_e32 v132, v130
	v_and_b32_e32 v130, 64, v176
	v_add_u32_e32 v155, 64, v130
	v_xor_b32_e32 v130, 16, v176
	v_cmp_lt_i32_e32 vcc, v130, v155
	v_mov_b32_e32 v128, v131
	v_pk_add_f32 v[128:129], v[132:133], v[128:129]
	v_cndmask_b32_e32 v130, v176, v130, vcc
	v_lshlrev_b32_e32 v157, 2, v130
	ds_bpermute_b32 v131, v157, v129
	ds_bpermute_b32 v130, v157, v128
	v_mov_b32_e32 v178, v186
	v_mov_b32_e32 v179, v190
	v_mov_b32_e32 v190, v187
	v_mov_b32_e32 v186, v194
	s_waitcnt lgkmcnt(0)
	v_pk_add_f32 v[128:129], v[128:129], v[130:131]
	v_xor_b32_e32 v130, 32, v176
	v_cmp_lt_i32_e32 vcc, v130, v155
	v_mov_b32_e32 v187, v198
	v_mov_b32_e32 v198, v195
	v_cndmask_b32_e32 v130, v176, v130, vcc
	v_lshlrev_b32_e32 v155, 2, v130
	ds_bpermute_b32 v131, v155, v129
	ds_bpermute_b32 v130, v155, v128
	v_pk_add_f32 v[182:183], v[186:187], v[198:199]
	v_mov_b32_e32 v180, v188
	v_mov_b32_e32 v181, v192
	v_mov_b32_e32 v192, v189
	s_waitcnt lgkmcnt(0)
	v_pk_add_f32 v[128:129], v[128:129], v[130:131]
	v_mov_b64_e32 v[130:131], s[26:27]
	v_pk_fma_f32 v[128:129], v[128:129], s[24:25], v[130:131] op_sel_hi:[1,0,0]
	v_mov_b32_e32 v188, v196
	v_mul_f32_e32 v159, 0x4b800000, v129
	v_cmp_gt_f32_e32 vcc, s73, v129
	v_mov_b32_e32 v189, v200
	v_mov_b32_e32 v200, v197
	v_cndmask_b32_e32 v129, v129, v159, vcc
	v_rsq_f32_e32 v129, v129
	v_pk_add_f32 v[178:179], v[178:179], v[190:191]
	v_pk_add_f32 v[180:181], v[180:181], v[192:193]
	v_pk_add_f32 v[184:185], v[188:189], v[200:201]
	v_mul_f32_e32 v159, 0x45800000, v129
	v_cndmask_b32_e32 v198, v129, v159, vcc
	v_pk_mul_f32 v[126:127], v[126:127], v[198:199] op_sel_hi:[1,0]
	v_pk_mul_f32 v[124:125], v[124:125], v[198:199] op_sel_hi:[1,0]
	v_pk_mul_f32 v[122:123], v[122:123], v[198:199] op_sel_hi:[1,0]
	v_pk_mul_f32 v[120:121], v[120:121], v[198:199] op_sel_hi:[1,0]
	v_cvt_pk_bf16_f32 v124, v124, v125
	v_cvt_pk_bf16_f32 v125, v126, v127
	v_cvt_pk_bf16_f32 v127, v122, v123
	v_lshl_or_b32 v122, s5, 8, v172
	v_cvt_pk_bf16_f32 v126, v120, v121
	v_ashrrev_i32_e32 v123, 31, v122
	v_mov_b64_e32 v[120:121], s[2:3]
	v_mad_i64_i32 v[168:169], s[4:5], v168, s76, v[120:121]
	v_lshlrev_b64 v[122:123], 1, v[122:123]
	v_lshl_add_u64 v[168:169], v[168:169], 0, v[122:123]
	global_store_dwordx4 v[168:169], v[124:127], off
	v_mov_b32_e32 v194, v202
	v_mov_b32_e32 v195, v206
	v_pk_add_f32 v[124:125], v[178:179], v[180:181]
	v_pk_add_f32 v[126:127], v[182:183], v[184:185]
	v_mov_b32_e32 v179, v124
	v_mov_b32_e32 v178, v126
	v_mov_b32_e32 v124, v127
	v_pk_add_f32 v[124:125], v[178:179], v[124:125]
	ds_bpermute_b32 v127, v157, v125
	ds_bpermute_b32 v126, v157, v124
	v_mov_b32_e32 v206, v203
	v_mov_b32_e32 v196, v204
	v_mov_b32_e32 v197, v208
	v_mov_b32_e32 v208, v205
	v_mov_b32_e32 v202, v212
	v_mov_b32_e32 v203, v216
	v_mov_b32_e32 v216, v213
	v_mov_b32_e32 v204, v214
	v_mov_b32_e32 v205, v218
	v_mov_b32_e32 v218, v215
	v_pk_add_f32 v[186:187], v[194:195], v[206:207]
	v_pk_add_f32 v[188:189], v[196:197], v[208:209]
	v_pk_add_f32 v[190:191], v[202:203], v[216:217]
	v_pk_add_f32 v[192:193], v[204:205], v[218:219]
	v_pk_mul_f32 v[178:179], v[114:115], v[198:199] op_sel_hi:[1,0]
	s_waitcnt lgkmcnt(0)
; DI unsigned pack2(float lo, float hi) { f32x2 v = {lo, hi}; bf16v2 r = __builtin_convertvector(v, bf16v2); return __builtin_bit_cast(unsigned, r); }
; DI float row_rstd(const float* ssq, int row, int fq) {
;   const f32x4 a = *(const f32x4*)(ssq + (size_t)row * 32 + fq * 8), b = *(const f32x4*)(ssq + (size_t)row * 32 + fq * 8 + 4);
;   float sm = ((a[0] + a[1]) + (a[2] + a[3])) + ((b[0] + b[1]) + (b[2] + b[3]));
;   sm += __shfl_xor(sm, 16); sm += __shfl_xor(sm, 32);
;   return rsqrtf(sm * (1.0f / 2048.f) + 1e-6f);
; }
;   DI void operator()(const f32x4 (&acc)[2][2][4][2], const Unit& u, int wr, int wc, int fr, int fq) const {
;     ...
;       for (int m = 0; m < 4; ++m) rsv[ai][m] = row_rstd(ssq, row0 + ai * HALF + m * 16, fq);
; #pragma unroll
;     for (int ai = 0; ai < 2; ++ai)
; #pragma unroll
;       for (int m = 0; m < 4; ++m) {
;         const int row = row0 + ai * HALF + m * 16;
;         const float rs = rsv[ai][m];
;         bf16_t* rowp = O + (size_t)row * ldc + col0;
; #pragma unroll
;         for (int bj = 0; bj < 2; ++bj) {
;           const f32x4 v0 = acc[ai][bj][m][0] * rs, v1 = acc[ai][bj][m][1] * rs;
;           u32x4 w; w.x = pack2(v0[0], v0[1]); w.y = pack2(v0[2], v0[3]); w.z = pack2(v1[0], v1[1]); w.w = pack2(v1[2], v1[3]);
;           *(u32x4*)(rowp + bj * HALF) = w;
	v_pk_add_f32 v[114:115], v[124:125], v[126:127]
	v_pk_add_f32 v[126:127], v[186:187], v[188:189]
	v_pk_add_f32 v[180:181], v[190:191], v[192:193]
	v_mov_b32_e32 v183, v126
	v_mov_b32_e32 v182, v180
	v_mov_b32_e32 v126, v181
	v_pk_add_f32 v[126:127], v[182:183], v[126:127]
	ds_bpermute_b32 v125, v155, v115
	ds_bpermute_b32 v124, v155, v114
	ds_bpermute_b32 v181, v157, v127
	ds_bpermute_b32 v180, v157, v126
	v_mul_f32_e32 v129, 0x4b800000, v128
	v_cmp_gt_f32_e32 vcc, s73, v128
	s_waitcnt lgkmcnt(2)
	v_pk_add_f32 v[114:115], v[114:115], v[124:125]
	v_mov_b32_e32 v194, v220
	s_waitcnt lgkmcnt(0)
	v_pk_add_f32 v[124:125], v[126:127], v[180:181]
	ds_bpermute_b32 v127, v155, v125
	ds_bpermute_b32 v126, v155, v124
	v_pk_fma_f32 v[114:115], v[114:115], s[24:25], v[130:131] op_sel_hi:[1,0,0]
	v_cndmask_b32_e32 v159, v128, v129, vcc
	v_mul_f32_e32 v128, 0x4b800000, v115
	v_cmp_gt_f32_e64 s[4:5], s73, v115
	v_cmp_gt_f32_e64 s[6:7], s73, v114
	v_mov_b32_e32 v195, v224
	v_cndmask_b32_e64 v161, v115, v128, s[4:5]
	v_mul_f32_e32 v115, 0x4b800000, v114
	v_mov_b32_e32 v224, v221
	v_mov_b32_e32 v196, v222
	v_mov_b32_e32 v197, v226
	v_mov_b32_e32 v226, v223
	v_cndmask_b32_e64 v163, v114, v115, s[6:7]
	s_waitcnt lgkmcnt(0)
	v_pk_add_f32 v[114:115], v[124:125], v[126:127]
	v_pk_add_f32 v[132:133], v[194:195], v[224:225]
	v_pk_add_f32 v[134:135], v[196:197], v[226:227]
	v_mov_b32_e32 v194, v228
	v_mov_b32_e32 v195, v232
	v_mov_b32_e32 v232, v229
	v_mov_b32_e32 v196, v230
	v_mov_b32_e32 v197, v234
	v_mov_b32_e32 v234, v231
	v_pk_fma_f32 v[114:115], v[114:115], s[24:25], v[130:131] op_sel_hi:[1,0,0]
	v_pk_add_f32 v[194:195], v[194:195], v[232:233]
	v_pk_add_f32 v[196:197], v[196:197], v[234:235]
	v_mul_f32_e32 v124, 0x4b800000, v115
	v_cmp_gt_f32_e64 s[8:9], s73, v115
	v_pk_add_f32 v[126:127], v[194:195], v[196:197]
	v_cmp_gt_f32_e64 s[10:11], s73, v114
	v_cndmask_b32_e64 v165, v115, v124, s[8:9]
	v_pk_add_f32 v[124:125], v[132:133], v[134:135]
	v_mov_b32_e32 v128, v126
	v_mov_b32_e32 v129, v124
	v_mov_b32_e32 v124, v127
	v_pk_add_f32 v[124:125], v[128:129], v[124:125]
	ds_bpermute_b32 v127, v157, v125
	ds_bpermute_b32 v126, v157, v124
	v_rsq_f32_e32 v128, v159
	v_mul_f32_e32 v115, 0x4b800000, v114
	v_cndmask_b32_e64 v129, v114, v115, s[10:11]
	v_pk_mul_f32 v[116:117], v[116:117], v[198:199] op_sel_hi:[1,0]
	s_waitcnt lgkmcnt(0)
	v_pk_add_f32 v[114:115], v[124:125], v[126:127]
	ds_bpermute_b32 v125, v155, v115
	ds_bpermute_b32 v124, v155, v114
	v_mul_f32_e32 v126, 0x45800000, v128
	v_rsq_f32_e32 v127, v161
	v_cndmask_b32_e32 v126, v128, v126, vcc
	v_rsq_f32_e32 v128, v163
	s_waitcnt lgkmcnt(0)
	v_pk_add_f32 v[114:115], v[114:115], v[124:125]
	v_mul_f32_e32 v124, 0x45800000, v127
	v_cndmask_b32_e64 v124, v127, v124, s[4:5]
	v_mul_f32_e32 v127, 0x45800000, v128
	v_pk_fma_f32 v[114:115], v[114:115], s[24:25], v[130:131] op_sel_hi:[1,0,0]
	v_rsq_f32_e32 v125, v165
	v_cndmask_b32_e64 v128, v128, v127, s[6:7]
	v_rsq_f32_e32 v127, v129
	v_mul_f32_e32 v129, 0x4b800000, v115
	v_cmp_gt_f32_e32 vcc, s73, v115
	v_cmp_gt_f32_e64 s[4:5], s73, v114
	v_pk_mul_f32 v[118:119], v[118:119], v[198:199] op_sel_hi:[1,0]
	v_cndmask_b32_e32 v129, v115, v129, vcc
	v_mul_f32_e32 v115, 0x4b800000, v114
	v_cndmask_b32_e64 v131, v114, v115, s[4:5]
	v_cvt_pk_bf16_f32 v114, v116, v117
	v_rsq_f32_e32 v117, v129
	v_cvt_pk_bf16_f32 v115, v118, v119
	v_rsq_f32_e32 v119, v131
	v_mul_f32_e32 v116, 0x45800000, v125
	v_pk_mul_f32 v[112:113], v[112:113], v[198:199] op_sel_hi:[1,0]
	v_cndmask_b32_e64 v118, v125, v116, s[8:9]
	v_mul_f32_e32 v116, 0x45800000, v127
	v_cndmask_b32_e64 v130, v127, v116, s[10:11]
	v_cvt_pk_bf16_f32 v116, v112, v113
	v_mul_f32_e32 v112, 0x45800000, v117
	v_cndmask_b32_e32 v132, v117, v112, vcc
	v_mul_f32_e32 v112, 0x45800000, v119
	v_cvt_pk_bf16_f32 v117, v178, v179
	v_cndmask_b32_e64 v112, v119, v112, s[4:5]
	global_store_dwordx4 v[168:169], v[114:117], off offset:256
	v_pk_mul_f32 v[110:111], v[110:111], v[126:127] op_sel_hi:[1,0]
	v_pk_mul_f32 v[108:109], v[108:109], v[126:127] op_sel_hi:[1,0]
	v_mad_i64_i32 v[114:115], s[4:5], v154, s76, v[120:121]
	v_pk_mul_f32 v[116:117], v[106:107], v[126:127] op_sel_hi:[1,0]
	v_pk_mul_f32 v[106:107], v[104:105], v[126:127] op_sel_hi:[1,0]
	v_lshl_add_u64 v[114:115], v[114:115], 0, v[122:123]
	v_cvt_pk_bf16_f32 v104, v108, v109
	v_cvt_pk_bf16_f32 v105, v110, v111
	v_cvt_pk_bf16_f32 v106, v106, v107
	v_cvt_pk_bf16_f32 v107, v116, v117
	global_store_dwordx4 v[114:115], v[104:107], off
	v_pk_mul_f32 v[98:99], v[98:99], v[126:127] op_sel_hi:[1,0]
	v_pk_mul_f32 v[96:97], v[96:97], v[126:127] op_sel_hi:[1,0]
	v_pk_mul_f32 v[104:105], v[90:91], v[126:127] op_sel_hi:[1,0]
	v_pk_mul_f32 v[90:91], v[88:89], v[126:127] op_sel_hi:[1,0]
	v_cvt_pk_bf16_f32 v88, v96, v97
	v_cvt_pk_bf16_f32 v89, v98, v99
	v_cvt_pk_bf16_f32 v90, v90, v91
	v_cvt_pk_bf16_f32 v91, v104, v105
	global_store_dwordx4 v[114:115], v[88:91], off offset:256
	v_pk_mul_f32 v[94:95], v[94:95], v[124:125] op_sel_hi:[1,0]
	v_pk_mul_f32 v[92:93], v[92:93], v[124:125] op_sel_hi:[1,0]
	v_mad_i64_i32 v[88:89], s[4:5], v160, s76, v[120:121]
	v_lshl_add_u64 v[96:97], v[88:89], 0, v[122:123]
	v_pk_mul_f32 v[90:91], v[102:103], v[124:125] op_sel_hi:[1,0]
	v_pk_mul_f32 v[88:89], v[100:101], v[124:125] op_sel_hi:[1,0]
	v_pk_mul_f32 v[82:83], v[82:83], v[124:125] op_sel_hi:[1,0]
	v_cvt_pk_bf16_f32 v88, v88, v89
	v_cvt_pk_bf16_f32 v89, v90, v91
	v_cvt_pk_bf16_f32 v90, v92, v93
; DI unsigned pack2(float lo, float hi) { f32x2 v = {lo, hi}; bf16v2 r = __builtin_convertvector(v, bf16v2); return __builtin_bit_cast(unsigned, r); }
; #define PG8_WAIT_V(n) asm volatile("s_waitcnt vmcnt(" #n ")" ::: "memory")
; #define PG8_BAR __builtin_amdgcn_s_barrier()
;   DI void operator()(const f32x4 (&acc)[2][2][4][2], const Unit& u, int wr, int wc, int fr, int fq) const {
;     ...
;     for (int ai = 0; ai < 2; ++ai)
; #pragma unroll
;       for (int m = 0; m < 4; ++m) {
;         const int row = row0 + ai * HALF + m * 16;
;         const float rs = rsv[ai][m];
;         bf16_t* rowp = O + (size_t)row * ldc + col0;
; #pragma unroll
;         for (int bj = 0; bj < 2; ++bj) {
;           const f32x4 v0 = acc[ai][bj][m][0] * rs, v1 = acc[ai][bj][m][1] * rs;
;           u32x4 w; w.x = pack2(v0[0], v0[1]); w.y = pack2(v0[2], v0[3]); w.z = pack2(v1[0], v1[1]); w.w = pack2(v1[2], v1[3]);
;           *(u32x4*)(rowp + bj * HALF) = w;
;         }
;       }
;   }
; template <class Epi, class Sched = StaticOrder>
; DI void gemm_phase(LAS unsigned char* lds, const Gemm g, const Sched& S, const Epi& E) {
;     ...
;     E(acc, cur, wr, wc, fr, fq);
;     if (!has_next) break;
; #pragma unroll
;     for (int a = 0; a < 2; ++a)
; #pragma unroll
;       for (int b = 0; b < 2; ++b)
; #pragma unroll
;         for (int m = 0; m < 4; ++m)
; #pragma unroll
;           for (int n = 0; n < 2; ++n) acc[a][b][m][n] = (f32x4){0.f, 0.f, 0.f, 0.f};
;     cur = nxt; cA = nA; cB = nB; ++ui;
;   }
;   PG8_WAIT_V(0);
;   if (wr == 0) PG8_BAR;
;   PG8_BAR;
	v_cvt_pk_bf16_f32 v91, v94, v95
	global_store_dwordx4 v[96:97], v[88:91], off
	v_pk_mul_f32 v[80:81], v[80:81], v[124:125] op_sel_hi:[1,0]
	v_pk_mul_f32 v[78:79], v[78:79], v[128:129] op_sel_hi:[1,0]
	v_pk_mul_f32 v[88:89], v[74:75], v[124:125] op_sel_hi:[1,0]
	v_pk_mul_f32 v[74:75], v[72:73], v[124:125] op_sel_hi:[1,0]
	v_cvt_pk_bf16_f32 v72, v80, v81
	v_cvt_pk_bf16_f32 v73, v82, v83
	v_cvt_pk_bf16_f32 v74, v74, v75
	v_cvt_pk_bf16_f32 v75, v88, v89
	global_store_dwordx4 v[96:97], v[72:75], off offset:256
	v_pk_mul_f32 v[76:77], v[76:77], v[128:129] op_sel_hi:[1,0]
	v_pk_mul_f32 v[70:71], v[70:71], v[128:129] op_sel_hi:[1,0]
	v_mad_i64_i32 v[72:73], s[4:5], v156, s76, v[120:121]
	v_lshl_add_u64 v[80:81], v[72:73], 0, v[122:123]
	v_pk_mul_f32 v[74:75], v[86:87], v[128:129] op_sel_hi:[1,0]
	v_pk_mul_f32 v[72:73], v[84:85], v[128:129] op_sel_hi:[1,0]
	v_pk_mul_f32 v[68:69], v[68:69], v[128:129] op_sel_hi:[1,0]
	v_cvt_pk_bf16_f32 v72, v72, v73
	v_cvt_pk_bf16_f32 v73, v74, v75
	v_cvt_pk_bf16_f32 v74, v76, v77
	v_cvt_pk_bf16_f32 v75, v78, v79
	global_store_dwordx4 v[80:81], v[72:75], off
	v_pk_mul_f32 v[62:63], v[62:63], v[118:119] op_sel_hi:[1,0]
	v_pk_mul_f32 v[60:61], v[60:61], v[118:119] op_sel_hi:[1,0]
	v_pk_mul_f32 v[72:73], v[66:67], v[128:129] op_sel_hi:[1,0]
	v_pk_mul_f32 v[66:67], v[64:65], v[128:129] op_sel_hi:[1,0]
	v_cvt_pk_bf16_f32 v64, v68, v69
	v_cvt_pk_bf16_f32 v65, v70, v71
	v_cvt_pk_bf16_f32 v66, v66, v67
	v_cvt_pk_bf16_f32 v67, v72, v73
	global_store_dwordx4 v[80:81], v[64:67], off offset:256
	v_pk_mul_f32 v[50:51], v[50:51], v[118:119] op_sel_hi:[1,0]
	v_pk_mul_f32 v[48:49], v[48:49], v[118:119] op_sel_hi:[1,0]
	v_mad_i64_i32 v[64:65], s[4:5], v164, s76, v[120:121]
	v_pk_mul_f32 v[66:67], v[58:59], v[118:119] op_sel_hi:[1,0]
	v_pk_mul_f32 v[58:59], v[56:57], v[118:119] op_sel_hi:[1,0]
	v_lshl_add_u64 v[64:65], v[64:65], 0, v[122:123]
	v_cvt_pk_bf16_f32 v56, v60, v61
	v_cvt_pk_bf16_f32 v57, v62, v63
	v_cvt_pk_bf16_f32 v58, v58, v59
	v_cvt_pk_bf16_f32 v59, v66, v67
	global_store_dwordx4 v[64:65], v[56:59], off
	v_pk_mul_f32 v[46:47], v[46:47], v[130:131] op_sel_hi:[1,0]
	v_pk_mul_f32 v[44:45], v[44:45], v[130:131] op_sel_hi:[1,0]
	v_pk_mul_f32 v[56:57], v[42:43], v[118:119] op_sel_hi:[1,0]
	v_pk_mul_f32 v[42:43], v[40:41], v[118:119] op_sel_hi:[1,0]
	v_cvt_pk_bf16_f32 v40, v48, v49
	v_cvt_pk_bf16_f32 v41, v50, v51
	v_cvt_pk_bf16_f32 v42, v42, v43
	v_cvt_pk_bf16_f32 v43, v56, v57
	global_store_dwordx4 v[64:65], v[40:43], off offset:256
	v_pk_mul_f32 v[34:35], v[34:35], v[130:131] op_sel_hi:[1,0]
	v_pk_mul_f32 v[32:33], v[32:33], v[130:131] op_sel_hi:[1,0]
	v_mad_i64_i32 v[40:41], s[4:5], v158, s76, v[120:121]
	v_lshl_add_u64 v[48:49], v[40:41], 0, v[122:123]
	v_pk_mul_f32 v[42:43], v[54:55], v[130:131] op_sel_hi:[1,0]
	v_pk_mul_f32 v[40:41], v[52:53], v[130:131] op_sel_hi:[1,0]
	v_pk_mul_f32 v[30:31], v[30:31], v[132:133] op_sel_hi:[1,0]
	v_cvt_pk_bf16_f32 v40, v40, v41
	v_cvt_pk_bf16_f32 v41, v42, v43
	v_cvt_pk_bf16_f32 v42, v44, v45
	v_cvt_pk_bf16_f32 v43, v46, v47
	global_store_dwordx4 v[48:49], v[40:43], off
	v_pk_mul_f32 v[28:29], v[28:29], v[132:133] op_sel_hi:[1,0]
	v_pk_mul_f32 v[18:19], v[18:19], v[132:133] op_sel_hi:[1,0]
	v_pk_mul_f32 v[40:41], v[26:27], v[130:131] op_sel_hi:[1,0]
	v_pk_mul_f32 v[26:27], v[24:25], v[130:131] op_sel_hi:[1,0]
	v_cvt_pk_bf16_f32 v24, v32, v33
	v_cvt_pk_bf16_f32 v25, v34, v35
	v_cvt_pk_bf16_f32 v26, v26, v27
	v_cvt_pk_bf16_f32 v27, v40, v41
	global_store_dwordx4 v[48:49], v[24:27], off offset:256
	v_pk_mul_f32 v[16:17], v[16:17], v[132:133] op_sel_hi:[1,0]
	v_pk_mul_f32 v[14:15], v[14:15], v[112:113] op_sel_hi:[1,0]
	v_mad_i64_i32 v[24:25], s[4:5], v166, s76, v[120:121]
	v_lshl_add_u64 v[32:33], v[24:25], 0, v[122:123]
	v_pk_mul_f32 v[26:27], v[38:39], v[132:133] op_sel_hi:[1,0]
	v_pk_mul_f32 v[24:25], v[36:37], v[132:133] op_sel_hi:[1,0]
	v_pk_mul_f32 v[12:13], v[12:13], v[112:113] op_sel_hi:[1,0]
	v_cvt_pk_bf16_f32 v24, v24, v25
	v_cvt_pk_bf16_f32 v25, v26, v27
	v_cvt_pk_bf16_f32 v26, v28, v29
	v_cvt_pk_bf16_f32 v27, v30, v31
	global_store_dwordx4 v[32:33], v[24:27], off
	v_pk_mul_f32 v[6:7], v[6:7], v[112:113] op_sel_hi:[1,0]
	v_pk_mul_f32 v[4:5], v[4:5], v[112:113] op_sel_hi:[1,0]
	v_pk_mul_f32 v[24:25], v[10:11], v[132:133] op_sel_hi:[1,0]
	v_pk_mul_f32 v[10:11], v[8:9], v[132:133] op_sel_hi:[1,0]
	v_cvt_pk_bf16_f32 v8, v16, v17
	v_cvt_pk_bf16_f32 v9, v18, v19
	v_cvt_pk_bf16_f32 v10, v10, v11
	v_cvt_pk_bf16_f32 v11, v24, v25
	global_store_dwordx4 v[32:33], v[8:11], off offset:256
	s_and_b64 vcc, exec, s[0:1]
	s_mov_b64 s[8:9], s[36:37]
	v_mad_i64_i32 v[8:9], s[4:5], v162, s76, v[120:121]
	v_lshl_add_u64 v[16:17], v[8:9], 0, v[122:123]
	v_pk_mul_f32 v[10:11], v[22:23], v[112:113] op_sel_hi:[1,0]
	v_pk_mul_f32 v[8:9], v[20:21], v[112:113] op_sel_hi:[1,0]
	s_mov_b32 s5, s28
	v_cvt_pk_bf16_f32 v8, v8, v9
	v_cvt_pk_bf16_f32 v9, v10, v11
	v_cvt_pk_bf16_f32 v10, v12, v13
	v_cvt_pk_bf16_f32 v11, v14, v15
	global_store_dwordx4 v[16:17], v[8:11], off
	s_mov_b32 s4, s30
	s_mov_b64 s[6:7], s[34:35]
	v_pk_mul_f32 v[8:9], v[2:3], v[112:113] op_sel_hi:[1,0]
	v_pk_mul_f32 v[2:3], v[0:1], v[112:113] op_sel_hi:[1,0]
	v_cvt_pk_bf16_f32 v0, v4, v5
	v_cvt_pk_bf16_f32 v1, v6, v7
	v_cvt_pk_bf16_f32 v2, v2, v3
	v_cvt_pk_bf16_f32 v3, v8, v9
	global_store_dwordx4 v[16:17], v[0:3], off offset:256
	s_cbranch_vccz .LBB0_343
	s_waitcnt vmcnt(0)
	s_cmpk_gt_u32 s27, 0xff
	s_cbranch_scc1 .LBB0_350
	s_barrier

; #define PG8_STAGE(bufoff, gbase, voff) do { _Pragma("unroll") for (int _i = 0; _i < 2; ++_i) \
;     __builtin_amdgcn_global_load_lds((const unsigned*)((const char*)(gbase) + (voff)[_i]), (LAS unsigned*)(lds + (bufoff) + ldsw + _i * 8192), 16, 0, 0); } while (0)
; #define PG8_WAIT_V(n) asm volatile("s_waitcnt vmcnt(" #n ")" ::: "memory")
; #define PG8_BAR __builtin_amdgcn_s_barrier()
; template <class Epi, class Sched = StaticOrder>
; DI void gemm_phase(LAS unsigned char* lds, const Gemm g, const Sched& S, const Epi& E) {
;     ...
;   for (int i = 0; i < 2; ++i) { int R, C; stage_rc(tid * 16 + i * 8192, R, C); const int Rb = Epi::PERM ? ((R & ~31) + perm32(R & 31)) : R;
;     voffA[i] = (unsigned)(R * K + C) * 2u; voffB[i] = (unsigned)(Rb * K + C) * 2u; }
;   const size_t kstep = (size_t)(BK * 2);
;   const size_t hstep = (size_t)HALF * K * 2;
;   const size_t tstep = 2 * hstep;
;   const unsigned ldsw = (unsigned)wid * 1024u;
;   const int aoff = lds_byte(wr * 64 + fr, fq * 8), boff = lds_byte(wc * 32 + fr, fq * 8);
;     ...
;   Unit cur, nxt; int ui = 0;
;   if (!S.next(0, cur)) return;
;   f32x4 acc[2][2][4][2];
; #pragma unroll
;   for (int a = 0; a < 2; ++a)
; #pragma unroll
;     for (int b = 0; b < 2; ++b)
; #pragma unroll
;       for (int m = 0; m < 4; ++m)
; #pragma unroll
;         for (int n = 0; n < 2; ++n) acc[a][b][m][n] = (f32x4){0.f, 0.f, 0.f, 0.f};
;   bf16x8 At[4][2], B0[2][2], B1[2][2];
;   const char* cA = (const char*)g.A + (size_t)cur.pm * tstep; const char* cB = (const char*)g.Bt + (size_t)cur.pn * tstep;
;   PG8_STAGE(PG8_SB(0, 0), cB, voffB); PG8_STAGE(PG8_SA(0, 0), cA, voffA); PG8_STAGE(PG8_SB(0, 1), cB + hstep, voffB); PG8_STAGE(PG8_SA(0, 1), cA + hstep, voffA);
;   if (wr == 1) PG8_BAR;
;   PG8_WAIT_V(4); PG8_BAR;
;   PG8_STAGE(PG8_SB(1, 0), cB + kstep, voffB); PG8_STAGE(PG8_SA(1, 0), cA + kstep, voffA); PG8_STAGE(PG8_SB(1, 1), cB + hstep + kstep, voffB);
;   PG8_WAIT_V(6); PG8_BAR;
.LBB0_723:
	s_add_u32 s2, s84, 0xc103600
	s_addc_u32 s3, s85, 0
	s_add_u32 s8, s84, 0x10303600
	s_mov_b64 s[10:11], 0x80
	s_addc_u32 s9, s85, 0
	s_and_b32 s41, s4, 3
	s_add_i32 m0, s37, 0x18000
	v_lshl_add_u64 v[6:7], v[6:7], 0, s[10:11]
	s_lshl_b32 s13, s1, 13
	s_lshl_b32 s14, s41, 12
	s_waitcnt vmcnt(2)
	s_barrier
	global_load_lds_dwordx4 v[6:7], off
	v_lshl_add_u64 v[4:5], v[4:5], 0, s[10:11]
	s_add_i32 m0, s37, 0x1a000
	s_add_i32 s46, s37, 0x8000
	s_add_i32 s47, s37, 0xa000
	global_load_lds_dwordx4 v[4:5], off
	v_lshl_add_u64 v[2:3], v[2:3], 0, s[10:11]
	s_mov_b32 m0, s46
	s_add_u32 s4, s24, 0x80080
	global_load_lds_dwordx4 v[2:3], off
	v_lshl_add_u64 v[0:1], v[0:1], 0, s[10:11]
	s_mov_b32 m0, s47
	s_addc_u32 s5, s25, 0
	global_load_lds_dwordx4 v[0:1], off
	s_add_i32 m0, s37, 0x1c000
	v_lshl_add_u64 v[0:1], s[4:5], 0, v[180:181]
	global_load_lds_dwordx4 v[0:1], off
	v_lshl_add_u64 v[0:1], s[4:5], 0, v[176:177]
	s_add_i32 m0, s37, 0x1e000
	s_sext_i32_i8 s42, s0
	global_load_lds_dwordx4 v[0:1], off
	v_bfe_u32 v0, v210, 4, 2
	v_and_b32_e32 v1, 15, v210
	v_lshlrev_b32_e32 v3, 4, v0
	v_lshlrev_b32_e32 v5, 6, v210
	s_movk_i32 s0, 0x3c0
	v_lshl_or_b32 v204, s1, 6, v1
	v_lshlrev_b32_e32 v2, 3, v0
	v_lshl_or_b32 v1, v1, 6, v3
	v_and_or_b32 v3, v5, s0, v3
	v_cmp_eq_u32_e64 s[0:1], 0, v0
	v_lshlrev_b32_e32 v0, 9, v210
	v_lshl_or_b32 v206, s41, 5, v2
	v_and_b32_e32 v0, 0x70000, v0
	v_lshlrev_b32_e32 v2, 12, v11
	v_or3_b32 v0, v9, v0, v2
	v_add_u32_e32 v184, v0, v10
	v_lshlrev_b32_e32 v0, 5, v8
	v_lshlrev_b32_e32 v4, 2, v210
	v_and_b32_e32 v0, 0xf0000, v0
	v_and_b32_e32 v4, 32, v4
	s_waitcnt vmcnt(6)
	v_or3_b32 v0, v9, v0, v2
	v_bitop3_b32 v1, v1, s13, v4 bitop3:0xde
	v_bitop3_b32 v205, s14, v3, v4 bitop3:0xf6
	v_add_u32_e32 v186, v0, v10
	s_add_i32 s50, 0, 0x10000
	s_add_i32 s51, 0, 0x14000
	v_mbcnt_lo_u32_b32 v0, -1, 0
	s_mov_b32 s13, 0
	s_ashr_i32 s48, s96, 31
	s_mov_b32 s49, s96
	v_mov_b32_e32 v185, v181
	v_mov_b32_e32 v187, v181
	v_mov_b64_e32 v[188:189], 0x200
	v_mov_b64_e32 v[190:191], 0x1ff
	v_add_u32_e32 v207, s50, v205
	v_add_u32_e32 v208, 0, v1
	v_add_u32_e32 v209, s51, v205
	v_mbcnt_hi_u32_b32 v211, -1, v0
	s_mov_b32 s56, 0
	s_barrier
	s_branch .LBB0_725

; #define PG8_STAGE(bufoff, gbase, voff) do { _Pragma("unroll") for (int _i = 0; _i < 2; ++_i) \
;     __builtin_amdgcn_global_load_lds((const unsigned*)((const char*)(gbase) + (voff)[_i]), (LAS unsigned*)(lds + (bufoff) + ldsw + _i * 8192), 16, 0, 0); } while (0)
; #define PG8_LDA(dst, b, h) do { _Pragma("unroll") for (int m = 0; m < 4; ++m) _Pragma("unroll") for (int k = 0; k < 2; ++k) dst[m][k] = *(const LAS bf16x8*)(lds + PG8_SA(b, h) + aoff + m * 2048 + k * 1024); } while (0)
; #define PG8_LDB(dst, b, h) do { _Pragma("unroll") for (int n = 0; n < 2; ++n) _Pragma("unroll") for (int k = 0; k < 2; ++k) dst[n][k] = *(const LAS bf16x8*)(lds + PG8_SB(b, h) + boff + n * 2048 + k * 1024); } while (0)
; #define PG8_MMA(ai, bj, At, Bt) do { __builtin_amdgcn_s_setprio(1); _Pragma("unroll") for (int m = 0; m < 4; ++m) _Pragma("unroll") for (int n = 0; n < 2; ++n) _Pragma("unroll") for (int k = 0; k < 2; ++k) \
;     acc[ai][bj][m][n] = __builtin_amdgcn_mfma_f32_16x16x32_bf16(Bt[n][k], At[m][k], acc[ai][bj][m][n], 0, 0, 0); __builtin_amdgcn_s_setprio(0); } while (0)
; #define PG8_WAIT_V(n) asm volatile("s_waitcnt vmcnt(" #n ")" ::: "memory")
; #define PG8_WAIT_L(n) asm volatile("s_waitcnt lgkmcnt(" #n ")" ::: "memory")
; #define PG8_BAR __builtin_amdgcn_s_barrier()
; #define PG8_SCHED __builtin_amdgcn_sched_barrier(0)
; template <class Epi, class Sched = StaticOrder>
; DI void gemm_phase(LAS unsigned char* lds, const Gemm g, const Sched& S, const Epi& E) {
;     ...
;     for (int t = 0; t < nt; t += 2) {
;       const bool last = (t == nt - 2);
;       const char* a1 = cA + (size_t)(t + 1) * kstep;
;       const char* a2 = last ? nA : cA + (size_t)(t + 2) * kstep; const char* b2 = last ? nB : cB + (size_t)(t + 2) * kstep;
;       const char* a3 = a2 + kstep; const char* b3 = b2 + kstep;
;       PG8_LDB(B0, 0, 0); PG8_SCHED; PG8_LDA(At, 0, 0); PG8_STAGE(PG8_SA(1, 1), a1 + hstep, voffA);
;       PG8_WAIT_L(8); PG8_BAR; PG8_WAIT_L(0); PG8_MMA(0, 0, At, B0); PG8_BAR; PG8_SCHED;
;       PG8_LDB(B1, 0, 1); PG8_STAGE(PG8_SB(0, 0), b2, voffB);
;       PG8_BAR; PG8_WAIT_L(0); PG8_MMA(0, 1, At, B1); PG8_BAR;
;       PG8_LDA(At, 0, 1); PG8_STAGE(PG8_SA(0, 0), a2, voffA);
;       PG8_BAR; PG8_WAIT_L(0); PG8_MMA(1, 0, At, B0); PG8_BAR; PG8_SCHED;
;       PG8_STAGE(PG8_SB(0, 1), b2 + hstep, voffB);
;       PG8_WAIT_V(6); PG8_BAR; PG8_MMA(1, 1, At, B1); PG8_BAR;
.LBB0_728:
	ds_read_b128 v[128:131], v207
	ds_read_b128 v[132:135], v207 offset:1024
	ds_read_b128 v[136:139], v207 offset:2048
	ds_read_b128 v[140:143], v207 offset:3072
	s_add_u32 s24, s22, 0xfff80080
	s_addc_u32 s25, s23, -1
	s_cmp_eq_u32 s53, 28
	s_cselect_b32 s27, s17, s25
	s_cselect_b32 s26, s43, s24
	s_cselect_b32 s25, s15, s52
	s_cselect_b32 s24, s44, s45
	s_add_i32 m0, s37, 0xc000
	ds_read_b128 v[144:147], v208
	ds_read_b128 v[148:151], v208 offset:1024
	ds_read_b128 v[152:155], v208 offset:2048
	ds_read_b128 v[156:159], v208 offset:3072
	ds_read_b128 v[160:163], v208 offset:4096
	ds_read_b128 v[164:167], v208 offset:5120
	ds_read_b128 v[168:171], v208 offset:6144
	ds_read_b128 v[172:175], v208 offset:7168
	global_load_lds_dwordx4 v184, s[22:23]
	s_add_i32 m0, s37, 0xe000
	s_nop 0
	global_load_lds_dwordx4 v186, s[22:23]
	ds_read_b128 v[192:195], v209
	ds_read_b128 v[196:199], v209 offset:1024
	ds_read_b128 v[200:203], v209 offset:2048
	ds_read_b128 v[212:215], v209 offset:3072
	s_waitcnt vmcnt(8)
	s_waitcnt lgkmcnt(0)
	s_setprio 1
	s_barrier
	v_mfma_f32_16x16x32_bf16 v[124:127], v[128:131], v[144:147], v[124:127]
	v_mfma_f32_16x16x32_bf16 v[120:123], v[136:139], v[144:147], v[120:123]
	v_mfma_f32_16x16x32_bf16 v[108:111], v[128:131], v[152:155], v[108:111]
	v_mfma_f32_16x16x32_bf16 v[104:107], v[136:139], v[152:155], v[104:107]
	v_mfma_f32_16x16x32_bf16 v[92:95], v[128:131], v[160:163], v[92:95]
	v_mfma_f32_16x16x32_bf16 v[88:91], v[136:139], v[160:163], v[88:91]
	v_mfma_f32_16x16x32_bf16 v[76:79], v[128:131], v[168:171], v[76:79]
	v_mfma_f32_16x16x32_bf16 v[72:75], v[136:139], v[168:171], v[72:75]
	v_mfma_f32_16x16x32_bf16 v[124:127], v[132:135], v[148:151], v[124:127]
	v_mfma_f32_16x16x32_bf16 v[120:123], v[140:143], v[148:151], v[120:123]
	v_mfma_f32_16x16x32_bf16 v[108:111], v[132:135], v[156:159], v[108:111]
	v_mfma_f32_16x16x32_bf16 v[104:107], v[140:143], v[156:159], v[104:107]
	v_mfma_f32_16x16x32_bf16 v[92:95], v[132:135], v[164:167], v[92:95]
	v_mfma_f32_16x16x32_bf16 v[88:91], v[140:143], v[164:167], v[88:91]
	v_mfma_f32_16x16x32_bf16 v[76:79], v[132:135], v[172:175], v[76:79]
	v_mfma_f32_16x16x32_bf16 v[72:75], v[140:143], v[172:175], v[72:75]
	v_mfma_f32_16x16x32_bf16 v[116:119], v[192:195], v[144:147], v[116:119]
	v_mfma_f32_16x16x32_bf16 v[112:115], v[200:203], v[144:147], v[112:115]
	v_mfma_f32_16x16x32_bf16 v[100:103], v[192:195], v[152:155], v[100:103]
	v_mfma_f32_16x16x32_bf16 v[96:99], v[200:203], v[152:155], v[96:99]
	v_mfma_f32_16x16x32_bf16 v[84:87], v[192:195], v[160:163], v[84:87]
	v_mfma_f32_16x16x32_bf16 v[80:83], v[200:203], v[160:163], v[80:83]
	v_mfma_f32_16x16x32_bf16 v[68:71], v[192:195], v[168:171], v[68:71]
	v_mfma_f32_16x16x32_bf16 v[64:67], v[200:203], v[168:171], v[64:67]
	v_mfma_f32_16x16x32_bf16 v[116:119], v[196:199], v[148:151], v[116:119]
	v_mfma_f32_16x16x32_bf16 v[112:115], v[212:215], v[148:151], v[112:115]
	v_mfma_f32_16x16x32_bf16 v[100:103], v[196:199], v[156:159], v[100:103]
	v_mfma_f32_16x16x32_bf16 v[96:99], v[212:215], v[156:159], v[96:99]
	v_mfma_f32_16x16x32_bf16 v[84:87], v[196:199], v[164:167], v[84:87]
	v_mfma_f32_16x16x32_bf16 v[80:83], v[212:215], v[164:167], v[80:83]
	v_mfma_f32_16x16x32_bf16 v[68:71], v[196:199], v[172:175], v[68:71]
	v_mfma_f32_16x16x32_bf16 v[64:67], v[212:215], v[172:175], v[64:67]
	s_barrier
	s_setprio 0
	s_add_i32 s54, s50, s35
	s_add_u32 s98, s24, 0x80
	s_addc_u32 s99, s25, 0
	s_add_u32 s100, s26, 0x80
	s_addc_u32 s101, s27, 0
	s_mov_b32 m0, s54
	s_nop 0
	global_load_lds_dwordx4 v180, s[24:25]
	s_add_i32 m0, s54, 0x2000
	s_nop 0
	global_load_lds_dwordx4 v176, s[24:25]
	s_mov_b32 m0, s37
	ds_read_b128 v[144:147], v208 offset:16384
	ds_read_b128 v[148:151], v208 offset:17408
	ds_read_b128 v[152:155], v208 offset:18432
	ds_read_b128 v[156:159], v208 offset:19456
	ds_read_b128 v[160:163], v208 offset:20480
	ds_read_b128 v[164:167], v208 offset:21504
	ds_read_b128 v[168:171], v208 offset:22528
	ds_read_b128 v[172:175], v208 offset:23552
	global_load_lds_dwordx4 v182, s[26:27]
	s_mov_b32 m0, s38
	s_nop 0
	global_load_lds_dwordx4 v178, s[26:27]
	s_add_u32 s54, s24, 0x80000
	s_addc_u32 s55, s25, 0
	s_add_i32 s57, s51, s35
	s_mov_b32 m0, s57
	s_nop 0
	global_load_lds_dwordx4 v180, s[54:55]
	s_add_i32 m0, s57, 0x2000
	s_nop 0
	global_load_lds_dwordx4 v176, s[54:55]
	s_waitcnt vmcnt(8)
	s_waitcnt lgkmcnt(0)
	s_setprio 1
	s_barrier
	v_mfma_f32_16x16x32_bf16 v[60:63], v[128:131], v[144:147], v[60:63]
	v_mfma_f32_16x16x32_bf16 v[56:59], v[136:139], v[144:147], v[56:59]
	v_mfma_f32_16x16x32_bf16 v[44:47], v[128:131], v[152:155], v[44:47]
	v_mfma_f32_16x16x32_bf16 v[40:43], v[136:139], v[152:155], v[40:43]
	v_mfma_f32_16x16x32_bf16 v[28:31], v[128:131], v[160:163], v[28:31]
	v_mfma_f32_16x16x32_bf16 v[24:27], v[136:139], v[160:163], v[24:27]
	v_mfma_f32_16x16x32_bf16 v[12:15], v[128:131], v[168:171], v[12:15]
	v_mfma_f32_16x16x32_bf16 v[8:11], v[136:139], v[168:171], v[8:11]
	v_mfma_f32_16x16x32_bf16 v[60:63], v[132:135], v[148:151], v[60:63]
	v_mfma_f32_16x16x32_bf16 v[56:59], v[140:143], v[148:151], v[56:59]
	v_mfma_f32_16x16x32_bf16 v[44:47], v[132:135], v[156:159], v[44:47]
	v_mfma_f32_16x16x32_bf16 v[40:43], v[140:143], v[156:159], v[40:43]
	v_mfma_f32_16x16x32_bf16 v[28:31], v[132:135], v[164:167], v[28:31]
	v_mfma_f32_16x16x32_bf16 v[24:27], v[140:143], v[164:167], v[24:27]
	v_mfma_f32_16x16x32_bf16 v[12:15], v[132:135], v[172:175], v[12:15]
	v_mfma_f32_16x16x32_bf16 v[8:11], v[140:143], v[172:175], v[8:11]
	v_mfma_f32_16x16x32_bf16 v[52:55], v[192:195], v[144:147], v[52:55]
	v_mfma_f32_16x16x32_bf16 v[48:51], v[200:203], v[144:147], v[48:51]
	v_mfma_f32_16x16x32_bf16 v[36:39], v[192:195], v[152:155], v[36:39]
	v_mfma_f32_16x16x32_bf16 v[32:35], v[200:203], v[152:155], v[32:35]
	v_mfma_f32_16x16x32_bf16 v[20:23], v[192:195], v[160:163], v[20:23]
	v_mfma_f32_16x16x32_bf16 v[16:19], v[200:203], v[160:163], v[16:19]
	v_mfma_f32_16x16x32_bf16 v[4:7], v[192:195], v[168:171], v[4:7]
	v_mfma_f32_16x16x32_bf16 v[0:3], v[200:203], v[168:171], v[0:3]
	v_mfma_f32_16x16x32_bf16 v[52:55], v[196:199], v[148:151], v[52:55]
	v_mfma_f32_16x16x32_bf16 v[48:51], v[212:215], v[148:151], v[48:51]
	v_mfma_f32_16x16x32_bf16 v[36:39], v[196:199], v[156:159], v[36:39]
	v_mfma_f32_16x16x32_bf16 v[32:35], v[212:215], v[156:159], v[32:35]
	v_mfma_f32_16x16x32_bf16 v[20:23], v[196:199], v[164:167], v[20:23]
	v_mfma_f32_16x16x32_bf16 v[16:19], v[212:215], v[164:167], v[16:19]
	v_mfma_f32_16x16x32_bf16 v[4:7], v[196:199], v[172:175], v[4:7]
	v_mfma_f32_16x16x32_bf16 v[0:3], v[212:215], v[172:175], v[0:3]
	s_barrier
; #define PG8_STAGE(bufoff, gbase, voff) do { _Pragma("unroll") for (int _i = 0; _i < 2; ++_i) \
;     __builtin_amdgcn_global_load_lds((const unsigned*)((const char*)(gbase) + (voff)[_i]), (LAS unsigned*)(lds + (bufoff) + ldsw + _i * 8192), 16, 0, 0); } while (0)
; #define PG8_LDA(dst, b, h) do { _Pragma("unroll") for (int m = 0; m < 4; ++m) _Pragma("unroll") for (int k = 0; k < 2; ++k) dst[m][k] = *(const LAS bf16x8*)(lds + PG8_SA(b, h) + aoff + m * 2048 + k * 1024); } while (0)
; #define PG8_LDB(dst, b, h) do { _Pragma("unroll") for (int n = 0; n < 2; ++n) _Pragma("unroll") for (int k = 0; k < 2; ++k) dst[n][k] = *(const LAS bf16x8*)(lds + PG8_SB(b, h) + boff + n * 2048 + k * 1024); } while (0)
; #define PG8_MMA(ai, bj, At, Bt) do { __builtin_amdgcn_s_setprio(1); _Pragma("unroll") for (int m = 0; m < 4; ++m) _Pragma("unroll") for (int n = 0; n < 2; ++n) _Pragma("unroll") for (int k = 0; k < 2; ++k) \
;     acc[ai][bj][m][n] = __builtin_amdgcn_mfma_f32_16x16x32_bf16(Bt[n][k], At[m][k], acc[ai][bj][m][n], 0, 0, 0); __builtin_amdgcn_s_setprio(0); } while (0)
; #define PG8_WAIT_V(n) asm volatile("s_waitcnt vmcnt(" #n ")" ::: "memory")
; #define PG8_WAIT_L(n) asm volatile("s_waitcnt lgkmcnt(" #n ")" ::: "memory")
; #define PG8_BAR __builtin_amdgcn_s_barrier()
; #define PG8_SCHED __builtin_amdgcn_sched_barrier(0)
; template <class Epi, class Sched = StaticOrder>
; DI void gemm_phase(LAS unsigned char* lds, const Gemm g, const Sched& S, const Epi& E) {
;     ...
;       PG8_LDB(B0, 1, 0); PG8_SCHED; PG8_LDA(At, 1, 0); PG8_STAGE(PG8_SA(0, 1), a2 + hstep, voffA);
;       PG8_WAIT_L(8); PG8_BAR; PG8_WAIT_L(0); PG8_MMA(0, 0, At, B0); PG8_BAR; PG8_SCHED;
;       PG8_LDB(B1, 1, 1); PG8_STAGE(PG8_SB(1, 0), b3, voffB);
;       PG8_BAR; PG8_WAIT_L(0); PG8_MMA(0, 1, At, B1); PG8_BAR;
;       PG8_LDA(At, 1, 1); PG8_STAGE(PG8_SA(1, 0), a3, voffA);
;       PG8_BAR; PG8_WAIT_L(0); PG8_MMA(1, 0, At, B0); PG8_BAR; PG8_SCHED;
;       PG8_STAGE(PG8_SB(1, 1), b3 + hstep, voffB);
;       PG8_WAIT_V(6); PG8_BAR; PG8_MMA(1, 1, At, B1); PG8_BAR;
	s_setprio 0
	s_add_i32 s54, 0, 0x18000
	v_add_u32_e32 v140, s54, v205
	ds_read_b128 v[128:131], v140
	ds_read_b128 v[132:135], v140 offset:1024
	ds_read_b128 v[136:139], v140 offset:2048
	ds_read_b128 v[140:143], v140 offset:3072
	s_add_u32 s26, s26, 0x80000
	s_addc_u32 s27, s27, 0
	s_mov_b32 m0, s39
	ds_read_b128 v[144:147], v208 offset:32768
	ds_read_b128 v[148:151], v208 offset:33792
	ds_read_b128 v[152:155], v208 offset:34816
	ds_read_b128 v[156:159], v208 offset:35840
	ds_read_b128 v[160:163], v208 offset:36864
	ds_read_b128 v[164:167], v208 offset:37888
	ds_read_b128 v[168:171], v208 offset:38912
	ds_read_b128 v[172:175], v208 offset:39936
	global_load_lds_dwordx4 v182, s[26:27]
	s_mov_b32 m0, s40
	s_nop 0
	global_load_lds_dwordx4 v178, s[26:27]
	s_add_i32 s26, 0, 0x1c000
	v_add_u32_e32 v212, s26, v205
	ds_read_b128 v[192:195], v212
	ds_read_b128 v[196:199], v212 offset:1024
	ds_read_b128 v[200:203], v212 offset:2048
	ds_read_b128 v[212:215], v212 offset:3072
	s_waitcnt vmcnt(8)
	s_waitcnt lgkmcnt(0)
	s_setprio 1
	s_barrier
	v_mfma_f32_16x16x32_bf16 v[124:127], v[128:131], v[144:147], v[124:127]
	v_mfma_f32_16x16x32_bf16 v[120:123], v[136:139], v[144:147], v[120:123]
	v_mfma_f32_16x16x32_bf16 v[108:111], v[128:131], v[152:155], v[108:111]
	v_mfma_f32_16x16x32_bf16 v[104:107], v[136:139], v[152:155], v[104:107]
	v_mfma_f32_16x16x32_bf16 v[92:95], v[128:131], v[160:163], v[92:95]
	v_mfma_f32_16x16x32_bf16 v[88:91], v[136:139], v[160:163], v[88:91]
	v_mfma_f32_16x16x32_bf16 v[76:79], v[128:131], v[168:171], v[76:79]
	v_mfma_f32_16x16x32_bf16 v[72:75], v[136:139], v[168:171], v[72:75]
	v_mfma_f32_16x16x32_bf16 v[124:127], v[132:135], v[148:151], v[124:127]
	v_mfma_f32_16x16x32_bf16 v[120:123], v[140:143], v[148:151], v[120:123]
	v_mfma_f32_16x16x32_bf16 v[108:111], v[132:135], v[156:159], v[108:111]
	v_mfma_f32_16x16x32_bf16 v[104:107], v[140:143], v[156:159], v[104:107]
	v_mfma_f32_16x16x32_bf16 v[92:95], v[132:135], v[164:167], v[92:95]
	v_mfma_f32_16x16x32_bf16 v[88:91], v[140:143], v[164:167], v[88:91]
	v_mfma_f32_16x16x32_bf16 v[76:79], v[132:135], v[172:175], v[76:79]
	v_mfma_f32_16x16x32_bf16 v[72:75], v[140:143], v[172:175], v[72:75]
	v_mfma_f32_16x16x32_bf16 v[116:119], v[192:195], v[144:147], v[116:119]
	v_mfma_f32_16x16x32_bf16 v[112:115], v[200:203], v[144:147], v[112:115]
	v_mfma_f32_16x16x32_bf16 v[100:103], v[192:195], v[152:155], v[100:103]
	v_mfma_f32_16x16x32_bf16 v[96:99], v[200:203], v[152:155], v[96:99]
	v_mfma_f32_16x16x32_bf16 v[84:87], v[192:195], v[160:163], v[84:87]
	v_mfma_f32_16x16x32_bf16 v[80:83], v[200:203], v[160:163], v[80:83]
	v_mfma_f32_16x16x32_bf16 v[68:71], v[192:195], v[168:171], v[68:71]
	v_mfma_f32_16x16x32_bf16 v[64:67], v[200:203], v[168:171], v[64:67]
	v_mfma_f32_16x16x32_bf16 v[116:119], v[196:199], v[148:151], v[116:119]
	v_mfma_f32_16x16x32_bf16 v[112:115], v[212:215], v[148:151], v[112:115]
	v_mfma_f32_16x16x32_bf16 v[100:103], v[196:199], v[156:159], v[100:103]
	v_mfma_f32_16x16x32_bf16 v[96:99], v[212:215], v[156:159], v[96:99]
	v_mfma_f32_16x16x32_bf16 v[84:87], v[196:199], v[164:167], v[84:87]
	v_mfma_f32_16x16x32_bf16 v[80:83], v[212:215], v[164:167], v[80:83]
	v_mfma_f32_16x16x32_bf16 v[68:71], v[196:199], v[172:175], v[68:71]
	v_mfma_f32_16x16x32_bf16 v[64:67], v[212:215], v[172:175], v[64:67]
	s_barrier
	s_setprio 0
	s_add_i32 s27, s54, s35
	s_mov_b32 m0, s27
	s_nop 0
	global_load_lds_dwordx4 v180, s[98:99]
	s_add_i32 m0, s27, 0x2000
	s_nop 0
	global_load_lds_dwordx4 v176, s[98:99]
	s_mov_b32 m0, s46
	ds_read_b128 v[144:147], v208 offset:49152
	ds_read_b128 v[148:151], v208 offset:50176
	ds_read_b128 v[152:155], v208 offset:51200
	ds_read_b128 v[156:159], v208 offset:52224
	ds_read_b128 v[160:163], v208 offset:53248
	ds_read_b128 v[164:167], v208 offset:54272
	ds_read_b128 v[168:171], v208 offset:55296
	ds_read_b128 v[172:175], v208 offset:56320
	global_load_lds_dwordx4 v182, s[100:101]
	s_mov_b32 m0, s47
	s_nop 0
	global_load_lds_dwordx4 v178, s[100:101]
	s_add_u32 s24, s24, 0x80080
	s_addc_u32 s25, s25, 0
	s_add_i32 s26, s26, s35
	s_mov_b32 m0, s26
	s_nop 0
	global_load_lds_dwordx4 v180, s[24:25]
	s_add_i32 m0, s26, 0x2000
	s_nop 0
	global_load_lds_dwordx4 v176, s[24:25]
	s_add_i32 s53, s53, 2
	s_add_u32 s22, s22, 0x100
	s_addc_u32 s23, s23, 0
	s_add_u32 s45, s45, 0x100
	s_addc_u32 s52, s52, 0
	s_cmp_gt_u32 s53, 29
	s_waitcnt vmcnt(8)
	s_waitcnt lgkmcnt(0)
	s_setprio 1
	s_barrier
	v_mfma_f32_16x16x32_bf16 v[60:63], v[128:131], v[144:147], v[60:63]
	v_mfma_f32_16x16x32_bf16 v[56:59], v[136:139], v[144:147], v[56:59]
	v_mfma_f32_16x16x32_bf16 v[44:47], v[128:131], v[152:155], v[44:47]
	v_mfma_f32_16x16x32_bf16 v[40:43], v[136:139], v[152:155], v[40:43]
	v_mfma_f32_16x16x32_bf16 v[28:31], v[128:131], v[160:163], v[28:31]
	v_mfma_f32_16x16x32_bf16 v[24:27], v[136:139], v[160:163], v[24:27]
	v_mfma_f32_16x16x32_bf16 v[12:15], v[128:131], v[168:171], v[12:15]
	v_mfma_f32_16x16x32_bf16 v[8:11], v[136:139], v[168:171], v[8:11]
	v_mfma_f32_16x16x32_bf16 v[60:63], v[132:135], v[148:151], v[60:63]
	v_mfma_f32_16x16x32_bf16 v[56:59], v[140:143], v[148:151], v[56:59]
	v_mfma_f32_16x16x32_bf16 v[44:47], v[132:135], v[156:159], v[44:47]
	v_mfma_f32_16x16x32_bf16 v[40:43], v[140:143], v[156:159], v[40:43]
	v_mfma_f32_16x16x32_bf16 v[28:31], v[132:135], v[164:167], v[28:31]
	v_mfma_f32_16x16x32_bf16 v[24:27], v[140:143], v[164:167], v[24:27]
	v_mfma_f32_16x16x32_bf16 v[12:15], v[132:135], v[172:175], v[12:15]
	v_mfma_f32_16x16x32_bf16 v[8:11], v[140:143], v[172:175], v[8:11]
	v_mfma_f32_16x16x32_bf16 v[52:55], v[192:195], v[144:147], v[52:55]
	v_mfma_f32_16x16x32_bf16 v[48:51], v[200:203], v[144:147], v[48:51]
	v_mfma_f32_16x16x32_bf16 v[36:39], v[192:195], v[152:155], v[36:39]
	v_mfma_f32_16x16x32_bf16 v[32:35], v[200:203], v[152:155], v[32:35]
	v_mfma_f32_16x16x32_bf16 v[20:23], v[192:195], v[160:163], v[20:23]
	v_mfma_f32_16x16x32_bf16 v[16:19], v[200:203], v[160:163], v[16:19]
	v_mfma_f32_16x16x32_bf16 v[4:7], v[192:195], v[168:171], v[4:7]
	v_mfma_f32_16x16x32_bf16 v[0:3], v[200:203], v[168:171], v[0:3]
	v_mfma_f32_16x16x32_bf16 v[52:55], v[196:199], v[148:151], v[52:55]
	v_mfma_f32_16x16x32_bf16 v[48:51], v[212:215], v[148:151], v[48:51]
	v_mfma_f32_16x16x32_bf16 v[36:39], v[196:199], v[156:159], v[36:39]
	v_mfma_f32_16x16x32_bf16 v[32:35], v[212:215], v[156:159], v[32:35]
	v_mfma_f32_16x16x32_bf16 v[20:23], v[196:199], v[164:167], v[20:23]
	v_mfma_f32_16x16x32_bf16 v[16:19], v[212:215], v[164:167], v[16:19]
	v_mfma_f32_16x16x32_bf16 v[4:7], v[196:199], v[172:175], v[4:7]
	v_mfma_f32_16x16x32_bf16 v[0:3], v[212:215], v[172:175], v[0:3]
	s_barrier
; DI unsigned pack2(float lo, float hi) { f32x2 v = {lo, hi}; bf16v2 r = __builtin_convertvector(v, bf16v2); return __builtin_bit_cast(unsigned, r); }
;   DI void operator()(const f32x4 (&acc)[2][2][4][2], const Unit& u, int wr, int wc, int fr, int fq) const {
;     const int row0 = u.pm * BM + wr * 64 + fr, col0 = u.pn * BM + wc * 32 + 8 * fq;
; #pragma unroll
;     for (int ai = 0; ai < 2; ++ai) {
;       f32x4 bv[4][2][2];
; #pragma unroll
;       for (int m = 0; m < 4; ++m)
; #pragma unroll
;         for (int bj = 0; bj < 2; ++bj) {
;           const float* bp = base + (size_t)(row0 + ai * HALF + m * 16) * 2048 + col0 + bj * HALF;
;           bv[m][bj][0] = *(const f32x4*)bp; bv[m][bj][1] = *(const f32x4*)(bp + 4);
;         }
; #pragma unroll
;       for (int m = 0; m < 4; ++m) {
;         const int row = row0 + ai * HALF + m * 16;
;         const size_t off = (size_t)row * 2048 + col0;
;         float ss = 0.f;
; #pragma unroll
;         for (int bj = 0; bj < 2; ++bj) {
;           const f32x4 v0 = acc[ai][bj][m][0] + bv[m][bj][0], v1 = acc[ai][bj][m][1] + bv[m][bj][1];
;           *(f32x4*)(C + off + bj * HALF) = v0; *(f32x4*)(C + off + bj * HALF + 4) = v1;
;           if (xb) {
;             u32x4 w; w.x = pack2(v0[0], v0[1]); w.y = pack2(v0[2], v0[3]); w.z = pack2(v1[0], v1[1]); w.w = pack2(v1[2], v1[3]);
;             *(u32x4*)(xb + off + bj * HALF) = w;
;             ss += v0[0] * v0[0] + v0[1] * v0[1] + v0[2] * v0[2] + v0[3] * v0[3] + v1[0] * v1[0] + v1[1] * v1[1] + v1[2] * v1[2] + v1[3] * v1[3];
;           }
;         }
;         if (xb) {
;           ss += __shfl_xor(ss, 16); ss += __shfl_xor(ss, 32);
;           if (fq == 0) ssq[(size_t)row * 32 + u.pn * 4 + wc] = ss;
;         }
;       }
; template <class Epi, class Sched = StaticOrder>
; DI void gemm_phase(LAS unsigned char* lds, const Gemm g, const Sched& S, const Epi& E) {
;     ...
;     E(acc, cur, wr, wc, fr, fq);
	s_setprio 0
	s_cbranch_scc0 .LBB0_728
	v_lshl_add_u32 v196, s12, 8, v204
	v_lshl_or_b32 v192, s42, 8, v206
	v_ashrrev_i32_e32 v193, 31, v192
	v_ashrrev_i32_e32 v197, 31, v196
	v_lshl_add_u64 v[194:195], v[192:193], 2, s[60:61]
	v_lshlrev_b64 v[128:129], 13, v[196:197]
	v_lshl_add_u64 v[128:129], v[194:195], 0, v[128:129]
	global_load_dwordx4 v[214:217], v[128:129], off
	global_load_dwordx4 v[218:221], v[128:129], off offset:16
	global_load_dwordx4 v[222:225], v[128:129], off offset:512
	global_load_dwordx4 v[226:229], v[128:129], off offset:528
	v_or_b32_e32 v202, 16, v196
	v_or_b32_e32 v200, 32, v196
	v_or_b32_e32 v198, 48, v196
	v_ashrrev_i32_e32 v203, 31, v202
	v_ashrrev_i32_e32 v201, 31, v200
	v_ashrrev_i32_e32 v199, 31, v198
	v_lshlrev_b64 v[128:129], 13, v[202:203]
	v_lshlrev_b64 v[130:131], 13, v[200:201]
	v_lshlrev_b64 v[132:133], 13, v[198:199]
	v_lshl_add_u64 v[128:129], v[194:195], 0, v[128:129]
	v_lshl_add_u64 v[130:131], v[194:195], 0, v[130:131]
	v_lshl_add_u64 v[132:133], v[194:195], 0, v[132:133]
	global_load_dwordx4 v[168:171], v[128:129], off offset:16
	global_load_dwordx4 v[172:175], v[128:129], off
	global_load_dwordx4 v[160:163], v[128:129], off offset:528
	global_load_dwordx4 v[164:167], v[128:129], off offset:512
	global_load_dwordx4 v[152:155], v[130:131], off offset:16
	global_load_dwordx4 v[156:159], v[130:131], off
	global_load_dwordx4 v[144:147], v[130:131], off offset:528
	global_load_dwordx4 v[148:151], v[130:131], off offset:512
	global_load_dwordx4 v[136:139], v[132:133], off offset:16
	global_load_dwordx4 v[140:143], v[132:133], off
	s_nop 0
	global_load_dwordx4 v[128:131], v[132:133], off offset:528
	s_nop 0
	global_load_dwordx4 v[132:135], v[132:133], off offset:512
	v_and_b32_e32 v212, 64, v211
	v_xor_b32_e32 v230, 16, v211
	v_add_u32_e32 v232, 64, v212
	v_xor_b32_e32 v231, 32, v211
	v_cmp_lt_i32_e32 vcc, v230, v232
	v_lshlrev_b64 v[212:213], 11, v[196:197]
	v_readlane_b32 s64, v243, 3
	v_cndmask_b32_e32 v233, v211, v230, vcc
	v_cmp_lt_i32_e32 vcc, v231, v232
	v_readlane_b32 s78, v243, 17
	v_readlane_b32 s79, v243, 18
	v_cndmask_b32_e32 v234, v211, v231, vcc
	v_lshl_add_u64 v[230:231], v[212:213], 0, v[192:193]
	v_lshlrev_b32_e32 v212, 2, v233
	v_lshl_add_u64 v[232:233], v[230:231], 2, s[78:79]
	v_lshl_add_u64 v[230:231], v[230:231], 1, s[2:3]
	s_lshl_b32 s22, s42, 2
	s_ashr_i32 s23, s22, 31
	v_readlane_b32 s65, v243, 4
	v_readlane_b32 s66, v243, 5
	v_readlane_b32 s67, v243, 6
	v_readlane_b32 s68, v243, 7
	v_readlane_b32 s69, v243, 8
	v_readlane_b32 s70, v243, 9
	v_readlane_b32 s71, v243, 10
	v_readlane_b32 s72, v243, 11
	v_readlane_b32 s73, v243, 12
	v_readlane_b32 s74, v243, 13
	v_readlane_b32 s75, v243, 14
	v_readlane_b32 s76, v243, 15
	v_readlane_b32 s77, v243, 16
	s_waitcnt vmcnt(0)
	v_pk_add_f32 v[126:127], v[126:127], v[216:217]
	v_pk_add_f32 v[124:125], v[124:125], v[214:215]
	v_pk_add_f32 v[116:117], v[116:117], v[222:223]
	v_pk_add_f32 v[122:123], v[122:123], v[220:221]
	v_pk_add_f32 v[120:121], v[120:121], v[218:219]
	v_pk_add_f32 v[214:215], v[112:113], v[226:227]
	global_store_dwordx4 v[232:233], v[124:127], off
	global_store_dwordx4 v[232:233], v[120:123], off offset:16
	v_cvt_pk_bf16_f32 v112, v124, v125
	v_mul_f32_e32 v125, v125, v125
	v_mul_f32_e32 v213, v117, v117
	v_pk_add_f32 v[118:119], v[118:119], v[224:225]
	v_fmac_f32_e32 v125, v124, v124
	v_fmac_f32_e32 v213, v116, v116
	v_fmac_f32_e32 v125, v126, v126
	v_fmac_f32_e32 v213, v118, v118
	v_fmac_f32_e32 v125, v127, v127
	v_fmac_f32_e32 v213, v119, v119
	v_fmac_f32_e32 v125, v120, v120
	v_fmac_f32_e32 v213, v214, v214
	v_pk_add_f32 v[216:217], v[114:115], v[228:229]
	v_fmac_f32_e32 v125, v121, v121
	v_fmac_f32_e32 v213, v215, v215
	v_fmac_f32_e32 v125, v122, v122
	v_fmac_f32_e32 v213, v216, v216
	v_fmac_f32_e32 v125, v123, v123
	v_fmac_f32_e32 v213, v217, v217
	v_cvt_pk_bf16_f32 v114, v120, v121
	v_add_f32_e32 v120, v125, v213
	ds_bpermute_b32 v121, v212, v120
	v_cvt_pk_bf16_f32 v113, v126, v127
	v_cvt_pk_bf16_f32 v115, v122, v123
	global_store_dwordx4 v[230:231], v[112:115], off
	global_store_dwordx4 v[232:233], v[116:119], off offset:512
	global_store_dwordx4 v[232:233], v[214:217], off offset:528
	v_cvt_pk_bf16_f32 v122, v116, v117
	s_waitcnt lgkmcnt(0)
	v_add_f32_e32 v112, v120, v121
	v_lshlrev_b32_e32 v120, 2, v234
	ds_bpermute_b32 v113, v120, v112
	v_cvt_pk_bf16_f32 v123, v118, v119
	v_cvt_pk_bf16_f32 v124, v214, v215
	v_cvt_pk_bf16_f32 v125, v216, v217
	global_store_dwordx4 v[230:231], v[122:125], off offset:256
	s_and_saveexec_b64 s[24:25], s[0:1]
	s_cbranch_execz .LBB0_731
	s_waitcnt lgkmcnt(0)
	v_add_f32_e32 v114, v112, v113
	v_lshlrev_b64 v[112:113], 7, v[196:197]
	v_lshl_add_u64 v[112:113], s[8:9], 0, v[112:113]
	v_lshl_add_u64 v[112:113], s[22:23], 2, v[112:113]
	s_lshl_b32 s12, s41, 2
	v_lshl_add_u64 v[112:113], v[112:113], 0, s[12:13]
	global_store_dword v[112:113], v114, off

; #define PG8_STAGE(bufoff, gbase, voff) do { _Pragma("unroll") for (int _i = 0; _i < 2; ++_i) \
;     __builtin_amdgcn_global_load_lds((const unsigned*)((const char*)(gbase) + (voff)[_i]), (LAS unsigned*)(lds + (bufoff) + ldsw + _i * 8192), 16, 0, 0); } while (0)
; #define PG8_WAIT_V(n) asm volatile("s_waitcnt vmcnt(" #n ")" ::: "memory")
; #define PG8_BAR __builtin_amdgcn_s_barrier()
; template <class Epi, class Sched = StaticOrder>
; DI void gemm_phase(LAS unsigned char* lds, const Gemm g, const Sched& S, const Epi& E) {
;     ...
;   for (int i = 0; i < 2; ++i) { int R, C; stage_rc(tid * 16 + i * 8192, R, C); const int Rb = Epi::PERM ? ((R & ~31) + perm32(R & 31)) : R;
;     voffA[i] = (unsigned)(R * K + C) * 2u; voffB[i] = (unsigned)(Rb * K + C) * 2u; }
;   const size_t kstep = (size_t)(BK * 2);
;   const size_t hstep = (size_t)HALF * K * 2;
;   const size_t tstep = 2 * hstep;
;   const unsigned ldsw = (unsigned)wid * 1024u;
;   const int aoff = lds_byte(wr * 64 + fr, fq * 8), boff = lds_byte(wc * 32 + fr, fq * 8);
;     ...
;   Unit cur, nxt; int ui = 0;
;   if (!S.next(0, cur)) return;
;   f32x4 acc[2][2][4][2];
; #pragma unroll
;   for (int a = 0; a < 2; ++a)
; #pragma unroll
;     for (int b = 0; b < 2; ++b)
; #pragma unroll
;       for (int m = 0; m < 4; ++m)
; #pragma unroll
;         for (int n = 0; n < 2; ++n) acc[a][b][m][n] = (f32x4){0.f, 0.f, 0.f, 0.f};
;   bf16x8 At[4][2], B0[2][2], B1[2][2];
;   const char* cA = (const char*)g.A + (size_t)cur.pm * tstep; const char* cB = (const char*)g.Bt + (size_t)cur.pn * tstep;
;   PG8_STAGE(PG8_SB(0, 0), cB, voffB); PG8_STAGE(PG8_SA(0, 0), cA, voffA); PG8_STAGE(PG8_SB(0, 1), cB + hstep, voffB); PG8_STAGE(PG8_SA(0, 1), cA + hstep, voffA);
;   if (wr == 1) PG8_BAR;
;   PG8_WAIT_V(4); PG8_BAR;
;   PG8_STAGE(PG8_SB(1, 0), cB + kstep, voffB); PG8_STAGE(PG8_SA(1, 0), cA + kstep, voffA); PG8_STAGE(PG8_SB(1, 1), cB + hstep + kstep, voffB);
;   PG8_WAIT_V(6); PG8_BAR;
.LBB0_806:
	s_add_u32 s16, s84, 0x10903600
	s_addc_u32 s17, s85, 0
	s_add_u32 s18, s84, 0x1b903600
	s_addc_u32 s19, s85, 0
	s_add_u32 s20, s84, 0x1c403600
	s_addc_u32 s21, s85, 0
	s_add_u32 s22, s84, 0x1cf03600
	s_addc_u32 s23, s85, 0
	s_lshl_b32 s1, s1, 5
	s_mov_b64 s[24:25], 0x80
	s_and_b32 s26, s1, 0x60
	s_add_i32 m0, s62, 0x18000
	v_lshl_add_u64 v[6:7], v[6:7], 0, s[24:25]
	s_lshl_b32 s66, s4, 6
	s_lshl_b32 s6, s4, 13
	s_lshl_b32 s1, s26, 7
	s_waitcnt vmcnt(2)
	s_barrier
	global_load_lds_dwordx4 v[6:7], off
	v_lshl_add_u64 v[4:5], v[4:5], 0, s[24:25]
	s_add_i32 m0, s62, 0x1a000
	s_add_i32 s67, s62, 0x8000
	s_add_i32 s68, s62, 0xa000
	global_load_lds_dwordx4 v[4:5], off
	v_lshl_add_u64 v[2:3], v[2:3], 0, s[24:25]
	s_mov_b32 m0, s67
	s_add_u32 s4, s46, 0x80080
	global_load_lds_dwordx4 v[2:3], off
	v_lshl_add_u64 v[0:1], v[0:1], 0, s[24:25]
	s_mov_b32 m0, s68
	s_addc_u32 s5, s47, 0
	global_load_lds_dwordx4 v[0:1], off
	s_add_i32 m0, s62, 0x1c000
	v_lshl_add_u64 v[0:1], s[4:5], 0, v[164:165]
	global_load_lds_dwordx4 v[0:1], off
	v_lshl_add_u64 v[0:1], s[4:5], 0, v[160:161]
	s_add_i32 m0, s62, 0x1e000
	v_and_b32_e32 v179, 15, v210
	global_load_lds_dwordx4 v[0:1], off
	v_lshlrev_b32_e32 v0, 1, v11
	v_lshlrev_b32_e32 v2, 2, v210
	v_lshl_or_b32 v1, v179, 6, v0
	v_and_b32_e32 v2, 32, v2
	s_sext_i32_i16 s13, s0
	v_bitop3_b32 v3, v1, s6, v2 bitop3:0xde
	v_lshlrev_b32_e32 v1, 6, v210
	s_movk_i32 s0, 0x3c0
	v_and_or_b32 v0, v1, s0, v0
	v_bitop3_b32 v198, s1, v0, v2 bitop3:0xf6
	v_lshlrev_b32_e32 v0, 2, v11
	v_mov_b32_e32 v1, v165
	v_lshl_add_u64 v[0:1], s[84:85], 0, v[0:1]
	s_mov_b64 s[8:9], 0x10303600
	v_lshl_add_u64 v[168:169], v[0:1], 0, s[8:9]
	v_lshlrev_b32_e32 v0, 9, v210
	v_and_b32_e32 v0, 0x70000, v0
	v_lshlrev_b32_e32 v1, 12, v12
	v_or3_b32 v0, v9, v0, v1
	v_add_u32_e32 v170, v0, v10
	v_lshlrev_b32_e32 v0, 5, v8
	v_and_b32_e32 v0, 0xf0000, v0
	s_waitcnt vmcnt(6)
	v_or3_b32 v0, v9, v0, v1
	v_add_u32_e32 v172, v0, v10
	s_add_i32 s72, 0, 0x10000
	s_add_i32 s73, 0, 0x14000
	v_mbcnt_lo_u32_b32 v0, -1, 0
	s_mov_b32 s69, 0
	v_cmp_eq_u32_e64 s[0:1], 0, v179
	v_cmp_lt_u32_e64 s[10:11], 1, v179
	v_cmp_gt_u32_e64 s[4:5], 2, v179
	v_cmp_lt_u32_e64 s[6:7], 13, v179
	v_add_u32_e32 v199, -14, v179
	s_ashr_i32 s70, s96, 31
	s_mov_b32 s71, s96
	v_or_b32_e32 v200, s26, v11
	v_mov_b32_e32 v171, v165
	v_mov_b32_e32 v173, v165
	v_mov_b64_e32 v[174:175], 0xb00
	v_mov_b64_e32 v[176:177], 0xaff
	v_add_u32_e32 v201, s72, v198
	v_add_u32_e32 v202, 0, v3
	v_add_u32_e32 v203, s73, v198
	s_mov_b64 s[26:27], 0x5800
	s_mov_b64 s[28:29], 0xb000
	s_mov_b32 s30, 0x3a000000
	s_mov_b32 s74, 0x800000
	s_movk_i32 s75, 0x2c00
	s_movk_i32 s76, 0x5800
	v_mbcnt_hi_u32_b32 v204, -1, v0
	v_mov_b32_e32 v178, 0x358637bd
	s_barrier
	s_branch .LBB0_808

; #define PG8_STAGE(bufoff, gbase, voff) do { _Pragma("unroll") for (int _i = 0; _i < 2; ++_i) \
;     __builtin_amdgcn_global_load_lds((const unsigned*)((const char*)(gbase) + (voff)[_i]), (LAS unsigned*)(lds + (bufoff) + ldsw + _i * 8192), 16, 0, 0); } while (0)
; #define PG8_LDA(dst, b, h) do { _Pragma("unroll") for (int m = 0; m < 4; ++m) _Pragma("unroll") for (int k = 0; k < 2; ++k) dst[m][k] = *(const LAS bf16x8*)(lds + PG8_SA(b, h) + aoff + m * 2048 + k * 1024); } while (0)
; #define PG8_LDB(dst, b, h) do { _Pragma("unroll") for (int n = 0; n < 2; ++n) _Pragma("unroll") for (int k = 0; k < 2; ++k) dst[n][k] = *(const LAS bf16x8*)(lds + PG8_SB(b, h) + boff + n * 2048 + k * 1024); } while (0)
; #define PG8_MMA(ai, bj, At, Bt) do { __builtin_amdgcn_s_setprio(1); _Pragma("unroll") for (int m = 0; m < 4; ++m) _Pragma("unroll") for (int n = 0; n < 2; ++n) _Pragma("unroll") for (int k = 0; k < 2; ++k) \
;     acc[ai][bj][m][n] = __builtin_amdgcn_mfma_f32_16x16x32_bf16(Bt[n][k], At[m][k], acc[ai][bj][m][n], 0, 0, 0); __builtin_amdgcn_s_setprio(0); } while (0)
; #define PG8_WAIT_V(n) asm volatile("s_waitcnt vmcnt(" #n ")" ::: "memory")
; #define PG8_WAIT_L(n) asm volatile("s_waitcnt lgkmcnt(" #n ")" ::: "memory")
; #define PG8_BAR __builtin_amdgcn_s_barrier()
; #define PG8_SCHED __builtin_amdgcn_sched_barrier(0)
; template <class Epi, class Sched = StaticOrder>
; DI void gemm_phase(LAS unsigned char* lds, const Gemm g, const Sched& S, const Epi& E) {
;     ...
;     for (int t = 0; t < nt; t += 2) {
;       const bool last = (t == nt - 2);
;       const char* a1 = cA + (size_t)(t + 1) * kstep;
;       const char* a2 = last ? nA : cA + (size_t)(t + 2) * kstep; const char* b2 = last ? nB : cB + (size_t)(t + 2) * kstep;
;       const char* a3 = a2 + kstep; const char* b3 = b2 + kstep;
;       PG8_LDB(B0, 0, 0); PG8_SCHED; PG8_LDA(At, 0, 0); PG8_STAGE(PG8_SA(1, 1), a1 + hstep, voffA);
;       PG8_WAIT_L(8); PG8_BAR; PG8_WAIT_L(0); PG8_MMA(0, 0, At, B0); PG8_BAR; PG8_SCHED;
;       PG8_LDB(B1, 0, 1); PG8_STAGE(PG8_SB(0, 0), b2, voffB);
;       PG8_BAR; PG8_WAIT_L(0); PG8_MMA(0, 1, At, B1); PG8_BAR;
;       PG8_LDA(At, 0, 1); PG8_STAGE(PG8_SA(0, 0), a2, voffA);
;       PG8_BAR; PG8_WAIT_L(0); PG8_MMA(1, 0, At, B0); PG8_BAR; PG8_SCHED;
;       PG8_STAGE(PG8_SB(0, 1), b2 + hstep, voffB);
;       PG8_WAIT_V(6); PG8_BAR; PG8_MMA(1, 1, At, B1); PG8_BAR;
.LBB0_811:
	ds_read_b128 v[64:67], v201
	ds_read_b128 v[68:71], v201 offset:1024
	ds_read_b128 v[72:75], v201 offset:2048
	ds_read_b128 v[76:79], v201 offset:3072
	s_add_u32 s46, s14, 0xfff80080
	s_addc_u32 s47, s15, -1
	s_cmp_eq_u32 s52, 28
	s_cselect_b32 s49, s37, s47
	s_cselect_b32 s48, s42, s46
	s_cselect_b32 s47, s35, s45
	s_cselect_b32 s46, s43, s44
	s_add_i32 m0, s62, 0xc000
	ds_read_b128 v[80:83], v202
	ds_read_b128 v[84:87], v202 offset:1024
	ds_read_b128 v[92:95], v202 offset:2048
	ds_read_b128 v[96:99], v202 offset:3072
	ds_read_b128 v[180:183], v202 offset:4096
	ds_read_b128 v[184:187], v202 offset:5120
	ds_read_b128 v[188:191], v202 offset:6144
	ds_read_b128 v[192:195], v202 offset:7168
	global_load_lds_dwordx4 v170, s[14:15]
	s_add_i32 m0, s62, 0xe000
	s_nop 0
	global_load_lds_dwordx4 v172, s[14:15]
	ds_read_b128 v[206:209], v203
	ds_read_b128 v[212:215], v203 offset:1024
	ds_read_b128 v[216:219], v203 offset:2048
	ds_read_b128 v[220:223], v203 offset:3072
	s_waitcnt vmcnt(8)
	s_waitcnt lgkmcnt(0)
	s_setprio 1
	s_barrier
	v_mfma_f32_16x16x32_bf16 v[156:159], v[64:67], v[80:83], v[156:159]
	v_mfma_f32_16x16x32_bf16 v[144:147], v[72:75], v[80:83], v[144:147]
	v_mfma_f32_16x16x32_bf16 v[140:143], v[64:67], v[92:95], v[140:143]
	v_mfma_f32_16x16x32_bf16 v[132:135], v[72:75], v[92:95], v[132:135]
	v_mfma_f32_16x16x32_bf16 v[124:127], v[64:67], v[180:183], v[124:127]
	v_mfma_f32_16x16x32_bf16 v[116:119], v[72:75], v[180:183], v[116:119]
	v_mfma_f32_16x16x32_bf16 v[112:115], v[64:67], v[188:191], v[112:115]
	v_mfma_f32_16x16x32_bf16 v[108:111], v[72:75], v[188:191], v[108:111]
	v_mfma_f32_16x16x32_bf16 v[156:159], v[68:71], v[84:87], v[156:159]
	v_mfma_f32_16x16x32_bf16 v[144:147], v[76:79], v[84:87], v[144:147]
	v_mfma_f32_16x16x32_bf16 v[140:143], v[68:71], v[96:99], v[140:143]
	v_mfma_f32_16x16x32_bf16 v[132:135], v[76:79], v[96:99], v[132:135]
	v_mfma_f32_16x16x32_bf16 v[124:127], v[68:71], v[184:187], v[124:127]
	v_mfma_f32_16x16x32_bf16 v[116:119], v[76:79], v[184:187], v[116:119]
	v_mfma_f32_16x16x32_bf16 v[112:115], v[68:71], v[192:195], v[112:115]
	v_mfma_f32_16x16x32_bf16 v[108:111], v[76:79], v[192:195], v[108:111]
	v_mfma_f32_16x16x32_bf16 v[152:155], v[206:209], v[80:83], v[152:155]
	v_mfma_f32_16x16x32_bf16 v[80:83], v[216:219], v[80:83], v[148:151]
	v_mfma_f32_16x16x32_bf16 v[152:155], v[212:215], v[84:87], v[152:155]
	v_mfma_f32_16x16x32_bf16 v[80:83], v[220:223], v[84:87], v[80:83]
	v_mfma_f32_16x16x32_bf16 v[84:87], v[206:209], v[92:95], v[136:139]
	v_mfma_f32_16x16x32_bf16 v[92:95], v[216:219], v[92:95], v[128:131]
	v_mfma_f32_16x16x32_bf16 v[104:107], v[216:219], v[180:183], v[104:107]
	v_mfma_f32_16x16x32_bf16 v[100:103], v[206:209], v[188:191], v[100:103]
	v_mfma_f32_16x16x32_bf16 v[88:91], v[216:219], v[188:191], v[88:91]
	v_mfma_f32_16x16x32_bf16 v[84:87], v[212:215], v[96:99], v[84:87]
	v_mfma_f32_16x16x32_bf16 v[92:95], v[220:223], v[96:99], v[92:95]
	v_mfma_f32_16x16x32_bf16 v[96:99], v[206:209], v[180:183], v[120:123]
	v_mfma_f32_16x16x32_bf16 v[104:107], v[220:223], v[184:187], v[104:107]
	v_mfma_f32_16x16x32_bf16 v[100:103], v[212:215], v[192:195], v[100:103]
	v_mfma_f32_16x16x32_bf16 v[88:91], v[220:223], v[192:195], v[88:91]
	v_mfma_f32_16x16x32_bf16 v[96:99], v[212:215], v[184:187], v[96:99]
	s_barrier
	s_setprio 0
	s_add_i32 s53, s72, s60
	s_add_u32 s98, s46, 0x80
	s_addc_u32 s99, s47, 0
	s_add_u32 s100, s48, 0x80
	s_addc_u32 s101, s49, 0
	s_mov_b32 m0, s53
	s_nop 0
	global_load_lds_dwordx4 v164, s[46:47]
	s_add_i32 m0, s53, 0x2000
	s_nop 0
	global_load_lds_dwordx4 v160, s[46:47]
	s_mov_b32 m0, s62
	ds_read_b128 v[120:123], v202 offset:16384
	ds_read_b128 v[128:131], v202 offset:17408
	ds_read_b128 v[136:139], v202 offset:18432
	ds_read_b128 v[148:151], v202 offset:19456
	ds_read_b128 v[180:183], v202 offset:20480
	ds_read_b128 v[184:187], v202 offset:21504
	ds_read_b128 v[188:191], v202 offset:22528
	ds_read_b128 v[192:195], v202 offset:23552
	global_load_lds_dwordx4 v166, s[48:49]
	s_mov_b32 m0, s63
	s_nop 0
	global_load_lds_dwordx4 v162, s[48:49]
	s_add_u32 s54, s46, 0x80000
	s_addc_u32 s55, s47, 0
	s_add_i32 s53, s73, s60
	s_mov_b32 m0, s53
	s_nop 0
	global_load_lds_dwordx4 v164, s[54:55]
	s_add_i32 m0, s53, 0x2000
	s_nop 0
	global_load_lds_dwordx4 v160, s[54:55]
	s_waitcnt vmcnt(8)
	s_waitcnt lgkmcnt(0)
	s_setprio 1
	s_barrier
	v_mfma_f32_16x16x32_bf16 v[60:63], v[64:67], v[120:123], v[60:63]
	v_mfma_f32_16x16x32_bf16 v[48:51], v[72:75], v[120:123], v[48:51]
	v_mfma_f32_16x16x32_bf16 v[44:47], v[64:67], v[136:139], v[44:47]
	v_mfma_f32_16x16x32_bf16 v[36:39], v[72:75], v[136:139], v[36:39]
	v_mfma_f32_16x16x32_bf16 v[28:31], v[64:67], v[180:183], v[28:31]
	v_mfma_f32_16x16x32_bf16 v[20:23], v[72:75], v[180:183], v[20:23]
	v_mfma_f32_16x16x32_bf16 v[16:19], v[64:67], v[188:191], v[16:19]
	v_mfma_f32_16x16x32_bf16 v[12:15], v[72:75], v[188:191], v[12:15]
	v_mfma_f32_16x16x32_bf16 v[60:63], v[68:71], v[128:131], v[60:63]
	v_mfma_f32_16x16x32_bf16 v[48:51], v[76:79], v[128:131], v[48:51]
	v_mfma_f32_16x16x32_bf16 v[44:47], v[68:71], v[148:151], v[44:47]
	v_mfma_f32_16x16x32_bf16 v[36:39], v[76:79], v[148:151], v[36:39]
	v_mfma_f32_16x16x32_bf16 v[28:31], v[68:71], v[184:187], v[28:31]
	v_mfma_f32_16x16x32_bf16 v[20:23], v[76:79], v[184:187], v[20:23]
	v_mfma_f32_16x16x32_bf16 v[16:19], v[68:71], v[192:195], v[16:19]
	v_mfma_f32_16x16x32_bf16 v[12:15], v[76:79], v[192:195], v[12:15]
	v_mfma_f32_16x16x32_bf16 v[56:59], v[206:209], v[120:123], v[56:59]
	v_mfma_f32_16x16x32_bf16 v[52:55], v[216:219], v[120:123], v[52:55]
	v_mfma_f32_16x16x32_bf16 v[40:43], v[206:209], v[136:139], v[40:43]
	v_mfma_f32_16x16x32_bf16 v[32:35], v[216:219], v[136:139], v[32:35]
	v_mfma_f32_16x16x32_bf16 v[24:27], v[206:209], v[180:183], v[24:27]
	v_mfma_f32_16x16x32_bf16 v[8:11], v[216:219], v[180:183], v[8:11]
	v_mfma_f32_16x16x32_bf16 v[4:7], v[206:209], v[188:191], v[4:7]
	v_mfma_f32_16x16x32_bf16 v[0:3], v[216:219], v[188:191], v[0:3]
	v_mfma_f32_16x16x32_bf16 v[56:59], v[212:215], v[128:131], v[56:59]
	v_mfma_f32_16x16x32_bf16 v[52:55], v[220:223], v[128:131], v[52:55]
	v_mfma_f32_16x16x32_bf16 v[40:43], v[212:215], v[148:151], v[40:43]
	v_mfma_f32_16x16x32_bf16 v[32:35], v[220:223], v[148:151], v[32:35]
	v_mfma_f32_16x16x32_bf16 v[24:27], v[212:215], v[184:187], v[24:27]
	v_mfma_f32_16x16x32_bf16 v[8:11], v[220:223], v[184:187], v[8:11]
	v_mfma_f32_16x16x32_bf16 v[4:7], v[212:215], v[192:195], v[4:7]
	v_mfma_f32_16x16x32_bf16 v[0:3], v[220:223], v[192:195], v[0:3]
	s_barrier
; #define PG8_STAGE(bufoff, gbase, voff) do { _Pragma("unroll") for (int _i = 0; _i < 2; ++_i) \
;     __builtin_amdgcn_global_load_lds((const unsigned*)((const char*)(gbase) + (voff)[_i]), (LAS unsigned*)(lds + (bufoff) + ldsw + _i * 8192), 16, 0, 0); } while (0)
; #define PG8_LDA(dst, b, h) do { _Pragma("unroll") for (int m = 0; m < 4; ++m) _Pragma("unroll") for (int k = 0; k < 2; ++k) dst[m][k] = *(const LAS bf16x8*)(lds + PG8_SA(b, h) + aoff + m * 2048 + k * 1024); } while (0)
; #define PG8_LDB(dst, b, h) do { _Pragma("unroll") for (int n = 0; n < 2; ++n) _Pragma("unroll") for (int k = 0; k < 2; ++k) dst[n][k] = *(const LAS bf16x8*)(lds + PG8_SB(b, h) + boff + n * 2048 + k * 1024); } while (0)
; #define PG8_MMA(ai, bj, At, Bt) do { __builtin_amdgcn_s_setprio(1); _Pragma("unroll") for (int m = 0; m < 4; ++m) _Pragma("unroll") for (int n = 0; n < 2; ++n) _Pragma("unroll") for (int k = 0; k < 2; ++k) \
;     acc[ai][bj][m][n] = __builtin_amdgcn_mfma_f32_16x16x32_bf16(Bt[n][k], At[m][k], acc[ai][bj][m][n], 0, 0, 0); __builtin_amdgcn_s_setprio(0); } while (0)
; #define PG8_WAIT_V(n) asm volatile("s_waitcnt vmcnt(" #n ")" ::: "memory")
; #define PG8_WAIT_L(n) asm volatile("s_waitcnt lgkmcnt(" #n ")" ::: "memory")
; #define PG8_BAR __builtin_amdgcn_s_barrier()
; #define PG8_SCHED __builtin_amdgcn_sched_barrier(0)
; template <class Epi, class Sched = StaticOrder>
; DI void gemm_phase(LAS unsigned char* lds, const Gemm g, const Sched& S, const Epi& E) {
;     ...
;       PG8_LDB(B0, 1, 0); PG8_SCHED; PG8_LDA(At, 1, 0); PG8_STAGE(PG8_SA(0, 1), a2 + hstep, voffA);
;       PG8_WAIT_L(8); PG8_BAR; PG8_WAIT_L(0); PG8_MMA(0, 0, At, B0); PG8_BAR; PG8_SCHED;
;       PG8_LDB(B1, 1, 1); PG8_STAGE(PG8_SB(1, 0), b3, voffB);
;       PG8_BAR; PG8_WAIT_L(0); PG8_MMA(0, 1, At, B1); PG8_BAR;
;       PG8_LDA(At, 1, 1); PG8_STAGE(PG8_SA(1, 0), a3, voffA);
;       PG8_BAR; PG8_WAIT_L(0); PG8_MMA(1, 0, At, B0); PG8_BAR; PG8_SCHED;
;       PG8_STAGE(PG8_SB(1, 1), b3 + hstep, voffB);
;       PG8_WAIT_V(6); PG8_BAR; PG8_MMA(1, 1, At, B1); PG8_BAR;
	s_setprio 0
	s_add_i32 s53, 0, 0x18000
	v_add_u32_e32 v76, s53, v198
	ds_read_b128 v[64:67], v76
	ds_read_b128 v[68:71], v76 offset:1024
	ds_read_b128 v[72:75], v76 offset:2048
	ds_read_b128 v[76:79], v76 offset:3072
	s_add_u32 s48, s48, 0x80000
	s_addc_u32 s49, s49, 0
	s_mov_b32 m0, s64
	ds_read_b128 v[120:123], v202 offset:32768
	ds_read_b128 v[128:131], v202 offset:33792
	ds_read_b128 v[180:183], v202 offset:34816
	ds_read_b128 v[184:187], v202 offset:35840
	ds_read_b128 v[188:191], v202 offset:36864
	ds_read_b128 v[192:195], v202 offset:37888
	ds_read_b128 v[206:209], v202 offset:38912
	ds_read_b128 v[212:215], v202 offset:39936
	global_load_lds_dwordx4 v166, s[48:49]
	s_mov_b32 m0, s65
	s_nop 0
	global_load_lds_dwordx4 v162, s[48:49]
	s_add_i32 s48, 0, 0x1c000
	v_add_u32_e32 v244, s48, v198
	ds_read_b128 v[216:219], v244
	ds_read_b128 v[220:223], v244 offset:1024
	ds_read_b128 v[224:227], v244 offset:2048
	ds_read_b128 v[228:231], v244 offset:3072
	s_waitcnt vmcnt(8)
	s_waitcnt lgkmcnt(0)
	s_setprio 1
	s_barrier
	v_mfma_f32_16x16x32_bf16 v[136:139], v[64:67], v[120:123], v[156:159]
	v_mfma_f32_16x16x32_bf16 v[156:159], v[68:71], v[128:131], v[136:139]
	v_mfma_f32_16x16x32_bf16 v[136:139], v[72:75], v[120:123], v[144:147]
	v_mfma_f32_16x16x32_bf16 v[144:147], v[76:79], v[128:131], v[136:139]
	v_mfma_f32_16x16x32_bf16 v[136:139], v[64:67], v[180:183], v[140:143]
	v_mfma_f32_16x16x32_bf16 v[132:135], v[72:75], v[180:183], v[132:135]
	v_mfma_f32_16x16x32_bf16 v[124:127], v[64:67], v[188:191], v[124:127]
	v_mfma_f32_16x16x32_bf16 v[116:119], v[72:75], v[188:191], v[116:119]
	v_mfma_f32_16x16x32_bf16 v[112:115], v[64:67], v[206:209], v[112:115]
	v_mfma_f32_16x16x32_bf16 v[108:111], v[72:75], v[206:209], v[108:111]
	v_mfma_f32_16x16x32_bf16 v[140:143], v[68:71], v[184:187], v[136:139]
	v_mfma_f32_16x16x32_bf16 v[132:135], v[76:79], v[184:187], v[132:135]
	v_mfma_f32_16x16x32_bf16 v[124:127], v[68:71], v[192:195], v[124:127]
	v_mfma_f32_16x16x32_bf16 v[116:119], v[76:79], v[192:195], v[116:119]
	v_mfma_f32_16x16x32_bf16 v[112:115], v[68:71], v[212:215], v[112:115]
	v_mfma_f32_16x16x32_bf16 v[108:111], v[76:79], v[212:215], v[108:111]
	v_mfma_f32_16x16x32_bf16 v[80:83], v[224:227], v[120:123], v[80:83]
	v_mfma_f32_16x16x32_bf16 v[136:139], v[216:219], v[120:123], v[152:155]
	v_mfma_f32_16x16x32_bf16 v[148:151], v[228:231], v[128:131], v[80:83]
	v_mfma_f32_16x16x32_bf16 v[80:83], v[216:219], v[180:183], v[84:87]
	v_mfma_f32_16x16x32_bf16 v[152:155], v[220:223], v[128:131], v[136:139]
	v_mfma_f32_16x16x32_bf16 v[136:139], v[220:223], v[184:187], v[80:83]
	v_mfma_f32_16x16x32_bf16 v[80:83], v[224:227], v[180:183], v[92:95]
	v_mfma_f32_16x16x32_bf16 v[128:131], v[228:231], v[184:187], v[80:83]
	v_mfma_f32_16x16x32_bf16 v[80:83], v[216:219], v[188:191], v[96:99]
	v_mfma_f32_16x16x32_bf16 v[120:123], v[220:223], v[192:195], v[80:83]
	v_mfma_f32_16x16x32_bf16 v[80:83], v[224:227], v[188:191], v[104:107]
	v_mfma_f32_16x16x32_bf16 v[104:107], v[228:231], v[192:195], v[80:83]
	v_mfma_f32_16x16x32_bf16 v[80:83], v[216:219], v[206:209], v[100:103]
	v_mfma_f32_16x16x32_bf16 v[100:103], v[220:223], v[212:215], v[80:83]
	v_mfma_f32_16x16x32_bf16 v[80:83], v[224:227], v[206:209], v[88:91]
	v_mfma_f32_16x16x32_bf16 v[88:91], v[228:231], v[212:215], v[80:83]
	s_barrier
	s_setprio 0
	s_add_i32 s49, s53, s60
	s_mov_b32 m0, s49
	s_nop 0
	global_load_lds_dwordx4 v164, s[98:99]
	s_add_i32 m0, s49, 0x2000
	s_nop 0
	global_load_lds_dwordx4 v160, s[98:99]
	s_mov_b32 m0, s67
	s_nop 2
	ds_read_b128 v[80:83], v202 offset:49152
	ds_read_b128 v[84:87], v202 offset:50176
	ds_read_b128 v[92:95], v202 offset:51200
	ds_read_b128 v[96:99], v202 offset:52224
	ds_read_b128 v[180:183], v202 offset:53248
	ds_read_b128 v[184:187], v202 offset:54272
	ds_read_b128 v[188:191], v202 offset:55296
	ds_read_b128 v[192:195], v202 offset:56320
	global_load_lds_dwordx4 v166, s[100:101]
	s_mov_b32 m0, s68
	s_nop 0
	global_load_lds_dwordx4 v162, s[100:101]
	s_add_u32 s46, s46, 0x80080
	s_addc_u32 s47, s47, 0
	s_add_i32 s48, s48, s60
	s_mov_b32 m0, s48
	s_nop 0
	global_load_lds_dwordx4 v164, s[46:47]
	s_add_i32 m0, s48, 0x2000
	s_nop 0
	global_load_lds_dwordx4 v160, s[46:47]
	s_add_i32 s52, s52, 2
	s_add_u32 s14, s14, 0x100
	s_addc_u32 s15, s15, 0
	s_add_u32 s44, s44, 0x100
	s_addc_u32 s45, s45, 0
	s_cmp_gt_u32 s52, 29
	s_waitcnt vmcnt(8)
	s_waitcnt lgkmcnt(0)
	s_setprio 1
	s_barrier
	v_mfma_f32_16x16x32_bf16 v[60:63], v[64:67], v[80:83], v[60:63]
	v_mfma_f32_16x16x32_bf16 v[48:51], v[72:75], v[80:83], v[48:51]
	v_mfma_f32_16x16x32_bf16 v[44:47], v[64:67], v[92:95], v[44:47]
	v_mfma_f32_16x16x32_bf16 v[36:39], v[72:75], v[92:95], v[36:39]
	v_mfma_f32_16x16x32_bf16 v[28:31], v[64:67], v[180:183], v[28:31]
	v_mfma_f32_16x16x32_bf16 v[20:23], v[72:75], v[180:183], v[20:23]
	v_mfma_f32_16x16x32_bf16 v[16:19], v[64:67], v[188:191], v[16:19]
	v_mfma_f32_16x16x32_bf16 v[12:15], v[72:75], v[188:191], v[12:15]
	v_mfma_f32_16x16x32_bf16 v[60:63], v[68:71], v[84:87], v[60:63]
	v_mfma_f32_16x16x32_bf16 v[48:51], v[76:79], v[84:87], v[48:51]
	v_mfma_f32_16x16x32_bf16 v[44:47], v[68:71], v[96:99], v[44:47]
	v_mfma_f32_16x16x32_bf16 v[36:39], v[76:79], v[96:99], v[36:39]
	v_mfma_f32_16x16x32_bf16 v[28:31], v[68:71], v[184:187], v[28:31]
	v_mfma_f32_16x16x32_bf16 v[20:23], v[76:79], v[184:187], v[20:23]
	v_mfma_f32_16x16x32_bf16 v[16:19], v[68:71], v[192:195], v[16:19]
	v_mfma_f32_16x16x32_bf16 v[12:15], v[76:79], v[192:195], v[12:15]
	v_mfma_f32_16x16x32_bf16 v[56:59], v[216:219], v[80:83], v[56:59]
	v_mfma_f32_16x16x32_bf16 v[52:55], v[224:227], v[80:83], v[52:55]
	v_mfma_f32_16x16x32_bf16 v[40:43], v[216:219], v[92:95], v[40:43]
	v_mfma_f32_16x16x32_bf16 v[32:35], v[224:227], v[92:95], v[32:35]
	v_mfma_f32_16x16x32_bf16 v[24:27], v[216:219], v[180:183], v[24:27]
	v_mfma_f32_16x16x32_bf16 v[8:11], v[224:227], v[180:183], v[8:11]
	v_mfma_f32_16x16x32_bf16 v[4:7], v[216:219], v[188:191], v[4:7]
	v_mfma_f32_16x16x32_bf16 v[0:3], v[224:227], v[188:191], v[0:3]
	v_mfma_f32_16x16x32_bf16 v[56:59], v[220:223], v[84:87], v[56:59]
	v_mfma_f32_16x16x32_bf16 v[52:55], v[228:231], v[84:87], v[52:55]
	v_mfma_f32_16x16x32_bf16 v[40:43], v[220:223], v[96:99], v[40:43]
	v_mfma_f32_16x16x32_bf16 v[32:35], v[228:231], v[96:99], v[32:35]
	v_mfma_f32_16x16x32_bf16 v[24:27], v[220:223], v[184:187], v[24:27]
	v_mfma_f32_16x16x32_bf16 v[8:11], v[228:231], v[184:187], v[8:11]
	v_mfma_f32_16x16x32_bf16 v[4:7], v[220:223], v[192:195], v[4:7]
	v_mfma_f32_16x16x32_bf16 v[0:3], v[228:231], v[192:195], v[0:3]
	s_barrier
; DI float row_rstd(const float* ssq, int row, int fq) {
;   const f32x4 a = *(const f32x4*)(ssq + (size_t)row * 32 + fq * 8), b = *(const f32x4*)(ssq + (size_t)row * 32 + fq * 8 + 4);
;   float sm = ((a[0] + a[1]) + (a[2] + a[3])) + ((b[0] + b[1]) + (b[2] + b[3]));
;   sm += __shfl_xor(sm, 16); sm += __shfl_xor(sm, 32);
;   return rsqrtf(sm * (1.0f / 2048.f) + 1e-6f);
; }
;   DI void operator()(const f32x4 (&acc)[2][2][4][2], const Unit& u, int wr, int wc, int fr, int fq) const {
;     const int col = u.pn * 128 + wc * 32 + 8 * fq;
;     float w0[8], w1[8], w2[8], bb[8];
; #pragma unroll
;     for (int e = 0; e < 8; ++e) { w0[e] = cw[col + e]; w1[e] = cw[5632 + col + e]; w2[e] = cw[2 * 5632 + col + e]; bb[e] = cb[col + e]; }
; #pragma unroll
;     for (int ai = 0; ai < 2; ++ai) {
;       const int row0 = u.pm * BM + ai * HALF + wr * 64, span = row0 >> 6;
;       float rsv[4];
; #pragma unroll
;       for (int m = 0; m < 4; ++m) rsv[m] = row_rstd(ssq, row0 + 16 * m + fr, fq);
	s_setprio 0
	s_cbranch_scc0 .LBB0_811
	s_lshl_b32 s35, s12, 8
	s_add_i32 s35, s35, s66
	v_or_b32_e32 v190, s35, v179
	v_ashrrev_i32_e32 v191, 31, v190
	v_lshlrev_b64 v[64:65], 7, v[190:191]
	v_or_b32_e32 v188, 16, v190
	v_lshl_add_u64 v[64:65], v[168:169], 0, v[64:65]
	v_ashrrev_i32_e32 v189, 31, v188
	global_load_dwordx4 v[192:195], v[64:65], off
	global_load_dwordx4 v[206:209], v[64:65], off offset:16
	v_lshlrev_b64 v[64:65], 7, v[188:189]
	v_lshl_add_u64 v[64:65], v[168:169], 0, v[64:65]
	global_load_dwordx4 v[212:215], v[64:65], off
	global_load_dwordx4 v[216:219], v[64:65], off offset:16
	v_or_b32_e32 v186, 32, v190
	v_ashrrev_i32_e32 v187, 31, v186
	v_lshlrev_b64 v[64:65], 7, v[186:187]
	v_or_b32_e32 v184, 48, v190
	v_lshl_add_u64 v[64:65], v[168:169], 0, v[64:65]
	v_ashrrev_i32_e32 v185, 31, v184
	global_load_dwordx4 v[220:223], v[64:65], off
	global_load_dwordx4 v[224:227], v[64:65], off offset:16
	v_lshlrev_b64 v[64:65], 7, v[184:185]
	v_lshl_add_u64 v[64:65], v[168:169], 0, v[64:65]
	global_load_dwordx4 v[228:231], v[64:65], off
	global_load_dwordx4 v[232:235], v[64:65], off offset:16
	v_lshl_or_b32 v180, s13, 7, v200
	v_and_b32_e32 v65, 64, v204
	v_xor_b32_e32 v64, 16, v204
	v_ashrrev_i32_e32 v181, 31, v180
	v_add_u32_e32 v65, 64, v65
	v_readlane_b32 s44, v243, 3
	v_xor_b32_e32 v66, 32, v204
	v_lshlrev_b64 v[182:183], 2, v[180:181]
	v_cmp_lt_i32_e32 vcc, v64, v65
	v_readlane_b32 s52, v243, 11
	v_readlane_b32 s53, v243, 12
	v_cndmask_b32_e32 v64, v204, v64, vcc
	v_cmp_lt_i32_e32 vcc, v66, v65
	v_lshl_add_u64 v[92:93], s[52:53], 0, v[182:183]
	v_readlane_b32 s54, v243, 13
	v_cndmask_b32_e32 v65, v204, v66, vcc
	v_add_co_u32_e32 v94, vcc, 0x5000, v92
	v_readlane_b32 s55, v243, 14
	s_nop 0
	v_addc_co_u32_e32 v95, vcc, 0, v93, vcc
	v_add_co_u32_e32 v96, vcc, 0xb000, v92
	v_lshl_add_u64 v[72:73], s[54:55], 0, v[182:183]
	v_lshl_add_u64 v[74:75], v[92:93], 0, s[26:27]
	v_lshl_add_u64 v[76:77], v[92:93], 0, s[28:29]
	v_addc_co_u32_e32 v97, vcc, 0, v93, vcc
	v_lshlrev_b32_e32 v187, 2, v64
	v_lshlrev_b32_e32 v185, 2, v65
	global_load_dwordx4 v[64:67], v[92:93], off offset:16
	global_load_dwordx4 v[80:83], v[92:93], off
	global_load_dwordx4 v[68:71], v[72:73], off offset:16
	global_load_dwordx4 v[84:87], v[72:73], off
	s_nop 0
	global_load_dwordx4 v[72:75], v[74:75], off offset:16
	s_nop 0
	global_load_dwordx4 v[76:79], v[76:77], off offset:16
	s_nop 0
	global_load_dwordx4 v[92:95], v[94:95], off offset:2048
	s_nop 0
	global_load_dwordx4 v[96:99], v[96:97], off
	v_mov_b32_e32 v211, 0
	v_mov_b32_e32 v205, 0
	v_readlane_b32 s45, v243, 4
	v_readlane_b32 s46, v243, 5
	v_readlane_b32 s47, v243, 6
	v_readlane_b32 s48, v243, 7
	v_readlane_b32 s49, v243, 8
	v_readlane_b32 s50, v243, 9
	v_readlane_b32 s51, v243, 10
	v_readlane_b32 s56, v243, 15
	v_readlane_b32 s57, v243, 16
	v_readlane_b32 s58, v243, 17
	v_readlane_b32 s59, v243, 18
	s_waitcnt vmcnt(0)
	v_mov_b32_e32 v196, v192
	v_mov_b32_e32 v197, v206
	v_mov_b32_e32 v206, v193
	v_mov_b32_e32 v192, v194
	v_mov_b32_e32 v193, v208
	v_mov_b32_e32 v208, v195
	v_pk_add_f32 v[194:195], v[196:197], v[206:207]
	v_pk_add_f32 v[192:193], v[192:193], v[208:209]
	v_mov_b32_e32 v196, v212
	v_mov_b32_e32 v197, v216
	v_mov_b32_e32 v216, v213
	v_mov_b32_e32 v206, v214
	v_mov_b32_e32 v207, v218
	v_mov_b32_e32 v218, v215
	v_pk_add_f32 v[192:193], v[194:195], v[192:193]
	v_pk_add_f32 v[194:195], v[196:197], v[216:217]
	v_pk_add_f32 v[196:197], v[206:207], v[218:219]
	v_mov_b32_e32 v208, v220
	v_pk_add_f32 v[194:195], v[194:195], v[196:197]
	v_mov_b32_e32 v197, v192
	v_mov_b32_e32 v196, v194
	v_mov_b32_e32 v192, v195
	v_pk_add_f32 v[192:193], v[196:197], v[192:193]
	ds_bpermute_b32 v195, v187, v193
	ds_bpermute_b32 v194, v187, v192
	v_mov_b32_e32 v209, v224
	v_mov_b32_e32 v224, v221
	v_mov_b32_e32 v212, v222
	v_mov_b32_e32 v213, v226
	s_waitcnt lgkmcnt(0)
	v_pk_add_f32 v[192:193], v[192:193], v[194:195]
	ds_bpermute_b32 v195, v185, v193
	ds_bpermute_b32 v194, v185, v192
	v_mov_b32_e32 v226, v223
	v_mov_b32_e32 v196, v228
	v_mov_b32_e32 v197, v232
	v_mov_b32_e32 v232, v229
	s_waitcnt lgkmcnt(0)
; DI unsigned pack2(float lo, float hi) { f32x2 v = {lo, hi}; bf16v2 r = __builtin_convertvector(v, bf16v2); return __builtin_bit_cast(unsigned, r); }
; DI float silu_f(float x) { return x * sigmoid_f(x); }
; DI float dpp_ror1(float v) { return __int_as_float(__builtin_amdgcn_update_dpp(0, __float_as_int(v), 0x121, 0xf, 0xf, false)); }
; DI float dpp_ror2(float v) { return __int_as_float(__builtin_amdgcn_update_dpp(0, __float_as_int(v), 0x122, 0xf, 0xf, false)); }
; DI float row_rstd(const float* ssq, int row, int fq) {
;   const f32x4 a = *(const f32x4*)(ssq + (size_t)row * 32 + fq * 8), b = *(const f32x4*)(ssq + (size_t)row * 32 + fq * 8 + 4);
;   float sm = ((a[0] + a[1]) + (a[2] + a[3])) + ((b[0] + b[1]) + (b[2] + b[3]));
;   sm += __shfl_xor(sm, 16); sm += __shfl_xor(sm, 32);
;   return rsqrtf(sm * (1.0f / 2048.f) + 1e-6f);
; }
;   DI void operator()(const f32x4 (&acc)[2][2][4][2], const Unit& u, int wr, int wc, int fr, int fq) const {
;     ...
;       for (int m = 0; m < 4; ++m) {
;         float g[8], uu[8], a[8];
;         const float rs = rsv[m];
; #pragma unroll
;         for (int e = 0; e < 4; ++e) { g[e] = acc[ai][0][m][0][e] * rs; g[4 + e] = acc[ai][0][m][1][e] * rs; uu[e] = acc[ai][1][m][0][e] * rs; uu[4 + e] = acc[ai][1][m][1][e] * rs; }
; #pragma unroll
;         for (int e = 0; e < 8; ++e) {
;           const float x1 = dpp_ror1(g[e]), x2 = dpp_ror2(g[e]);
;           const float pr1 = (fr == 0) ? p1[e] : x1, pr2 = (fr < 2) ? p2[e] : x2;
;           a[e] = w2[e] * g[e] + w1[e] * pr1 + w0[e] * pr2 + bb[e];
;           p1[e] = x1; p2[e] = x2;
;         }
;         if (m == 0 && fr < 2) {
;           float* ha = headA + (size_t)(span * 2 + fr) * 5632 + col; float* hu = headU + (size_t)(span * 2 + fr) * 5632 + col;
;           *(f32x4*)ha = (f32x4){a[0], a[1], a[2], a[3]}; *(f32x4*)(ha + 4) = (f32x4){a[4], a[5], a[6], a[7]};
;           *(f32x4*)hu = (f32x4){uu[0], uu[1], uu[2], uu[3]}; *(f32x4*)(hu + 4) = (f32x4){uu[4], uu[5], uu[6], uu[7]};
;         } else {
;           u32x4 w;
;           w.x = pack2(silu_f(a[0]) * uu[0], silu_f(a[1]) * uu[1]);
;           w.y = pack2(silu_f(a[2]) * uu[2], silu_f(a[3]) * uu[3]);
;           w.z = pack2(silu_f(a[4]) * uu[4], silu_f(a[5]) * uu[5]);
;           w.w = pack2(silu_f(a[6]) * uu[6], silu_f(a[7]) * uu[7]);
;           *(u32x4*)(H + (size_t)(row0 + 16 * m + fr) * 5632 + col) = w;
;         }
	v_pk_add_f32 v[192:193], v[192:193], v[194:195]
	v_mov_b32_e32 v206, v230
	v_pk_fma_f32 v[192:193], v[192:193], s[30:31], v[178:179] op_sel_hi:[1,0,0]
	v_mov_b32_e32 v207, v234
	v_mul_f32_e32 v189, 0x4b800000, v193
	v_cmp_gt_f32_e64 s[12:13], s74, v193
	v_mov_b32_e32 v234, v231
	v_pk_add_f32 v[208:209], v[208:209], v[224:225]
	v_cndmask_b32_e64 v189, v193, v189, s[12:13]
	v_rsq_f32_e32 v189, v189
	v_pk_add_f32 v[212:213], v[212:213], v[226:227]
	v_pk_add_f32 v[196:197], v[196:197], v[232:233]
	v_pk_add_f32 v[194:195], v[206:207], v[234:235]
	v_mul_f32_e32 v191, 0x45800000, v189
	v_cndmask_b32_e64 v220, v189, v191, s[12:13]
	v_pk_add_f32 v[208:209], v[208:209], v[212:213]
	v_pk_add_f32 v[194:195], v[196:197], v[194:195]
	v_pk_mul_f32 v[156:157], v[156:157], v[220:221] op_sel_hi:[1,0]
	v_mov_b32_e32 v216, 0
	v_mov_b32_e32 v218, 0
	v_mov_b32_e32 v196, v194
	v_mov_b32_e32 v197, v208
	v_mov_b32_e32 v208, v195
	v_mov_b32_dpp v216, v156 row_ror:1 row_mask:0xf bank_mask:0xf
	v_mov_b32_dpp v218, v157 row_ror:1 row_mask:0xf bank_mask:0xf
	v_pk_add_f32 v[194:195], v[196:197], v[208:209]
	v_cndmask_b32_e64 v207, v218, 0, s[0:1]
	v_cndmask_b32_e64 v206, v216, 0, s[0:1]
	v_pk_mul_f32 v[158:159], v[158:159], v[220:221] op_sel_hi:[1,0]
	v_mov_b32_e32 v212, 0
	v_mov_b32_e32 v214, 0
	ds_bpermute_b32 v197, v187, v195
	ds_bpermute_b32 v196, v187, v194
	v_mov_b32_e32 v215, 0
	v_mov_b32_e32 v217, 0
	v_pk_mul_f32 v[206:207], v[92:93], v[206:207]
	v_mov_b32_dpp v212, v158 row_ror:1 row_mask:0xf bank_mask:0xf
	v_mov_b32_dpp v214, v159 row_ror:1 row_mask:0xf bank_mask:0xf
	v_mov_b32_dpp v215, v156 row_ror:2 row_mask:0xf bank_mask:0xf
	v_mov_b32_dpp v217, v157 row_ror:2 row_mask:0xf bank_mask:0xf
	v_pk_fma_f32 v[156:157], v[96:97], v[156:157], v[206:207]
	v_mov_b32_e32 v213, 0
	v_cndmask_b32_e64 v207, v214, 0, s[0:1]
	v_cndmask_b32_e64 v206, v212, 0, s[0:1]
	v_cndmask_b32_e64 v209, v217, 0, s[4:5]
	v_cndmask_b32_e64 v208, v215, 0, s[4:5]
	v_mov_b32_dpp v211, v158 row_ror:2 row_mask:0xf bank_mask:0xf
	v_mov_b32_dpp v213, v159 row_ror:2 row_mask:0xf bank_mask:0xf
	v_pk_mul_f32 v[206:207], v[94:95], v[206:207]
	v_pk_fma_f32 v[156:157], v[80:81], v[208:209], v[156:157]
	v_cndmask_b32_e64 v209, v213, 0, s[4:5]
	v_cndmask_b32_e64 v208, v211, 0, s[4:5]
	v_pk_fma_f32 v[158:159], v[98:99], v[158:159], v[206:207]
	v_pk_mul_f32 v[144:145], v[144:145], v[220:221] op_sel_hi:[1,0]
	v_pk_fma_f32 v[158:159], v[82:83], v[208:209], v[158:159]
	v_mov_b32_e32 v207, 0
	v_mov_b32_e32 v209, 0
	v_pk_mul_f32 v[146:147], v[146:147], v[220:221] op_sel_hi:[1,0]
	v_mov_b32_e32 v191, 0
	s_waitcnt lgkmcnt(0)
	v_pk_add_f32 v[194:195], v[194:195], v[196:197]
	v_mov_b32_dpp v207, v144 row_ror:1 row_mask:0xf bank_mask:0xf
	v_mov_b32_dpp v209, v145 row_ror:1 row_mask:0xf bank_mask:0xf
	v_mov_b32_dpp v191, v146 row_ror:1 row_mask:0xf bank_mask:0xf
	v_mov_b32_dpp v205, v147 row_ror:1 row_mask:0xf bank_mask:0xf
	ds_bpermute_b32 v197, v185, v195
	ds_bpermute_b32 v196, v185, v194
	v_pk_mul_f32 v[152:153], v[152:153], v[220:221] op_sel_hi:[1,0]
	v_pk_mul_f32 v[148:149], v[148:149], v[220:221] op_sel_hi:[1,0]
	v_pk_mul_f32 v[154:155], v[154:155], v[220:221] op_sel_hi:[1,0]
	v_pk_mul_f32 v[150:151], v[150:151], v[220:221] op_sel_hi:[1,0]
	v_mov_b32_e32 v206, 0
	v_mov_b32_e32 v208, 0
	v_cndmask_b32_e64 v223, v209, 0, s[0:1]
	v_cndmask_b32_e64 v222, v207, 0, s[0:1]
	v_mov_b32_e32 v189, 0
	v_mov_b32_e32 v193, 0
	v_cndmask_b32_e64 v221, v205, 0, s[0:1]
	v_cndmask_b32_e64 v220, v191, 0, s[0:1]
	v_mov_b32_dpp v206, v144 row_ror:2 row_mask:0xf bank_mask:0xf
	v_mov_b32_dpp v208, v145 row_ror:2 row_mask:0xf bank_mask:0xf
	v_pk_mul_f32 v[222:223], v[72:73], v[222:223]
	v_mov_b32_dpp v189, v146 row_ror:2 row_mask:0xf bank_mask:0xf
	v_mov_b32_dpp v193, v147 row_ror:2 row_mask:0xf bank_mask:0xf
	v_pk_mul_f32 v[220:221], v[74:75], v[220:221]
	v_cndmask_b32_e64 v225, v208, 0, s[4:5]
	v_cndmask_b32_e64 v224, v206, 0, s[4:5]
	v_pk_fma_f32 v[144:145], v[76:77], v[144:145], v[222:223]
	v_cndmask_b32_e64 v223, v193, 0, s[4:5]
	v_cndmask_b32_e64 v222, v189, 0, s[4:5]
	v_pk_fma_f32 v[146:147], v[78:79], v[146:147], v[220:221]
	v_pk_fma_f32 v[144:145], v[64:65], v[224:225], v[144:145]
	v_pk_fma_f32 v[146:147], v[66:67], v[222:223], v[146:147]
	v_cmp_gt_f32_e32 vcc, s74, v192
	v_pk_add_f32 v[156:157], v[84:85], v[156:157]
	v_pk_add_f32 v[158:159], v[86:87], v[158:159]
	v_pk_add_f32 v[144:145], v[68:69], v[144:145]
	v_pk_add_f32 v[146:147], v[70:71], v[146:147]
	s_and_saveexec_b64 s[12:13], s[10:11]
	s_xor_b64 s[12:13], exec, s[12:13]
	s_cbranch_execz .LBB0_814
	v_mul_f32_e32 v219, 0xbfb8aa3b, v156
	v_exp_f32_e32 v219, v219
	v_mul_f32_e32 v220, 0xbfb8aa3b, v157
	v_exp_f32_e32 v220, v220
	v_mul_f32_e32 v222, 0xbfb8aa3b, v159
	v_add_f32_e32 v219, 1.0, v219
	v_exp_f32_e32 v223, v222
	v_add_f32_e32 v221, 1.0, v220
	v_rcp_f32_e32 v220, v219
	v_mul_f32_e32 v219, 0xbfb8aa3b, v158
	v_exp_f32_e32 v219, v219
	v_rcp_f32_e32 v221, v221
	v_add_f32_e32 v219, 1.0, v219
	v_rcp_f32_e32 v222, v219
	v_add_f32_e32 v219, 1.0, v223
	v_rcp_f32_e32 v223, v219
	v_pk_mul_f32 v[156:157], v[156:157], v[220:221]
	s_nop 0
	v_pk_mul_f32 v[152:153], v[152:153], v[156:157]
	v_pk_mul_f32 v[156:157], v[158:159], v[222:223]
	v_cvt_pk_bf16_f32 v152, v152, v153
	v_mul_f32_e32 v153, 0xbfb8aa3b, v144
	v_pk_mul_f32 v[154:155], v[154:155], v[156:157]
	v_exp_f32_e32 v156, v153
	v_mul_f32_e32 v153, 0xbfb8aa3b, v145
	v_exp_f32_e32 v157, v153
	v_cvt_pk_bf16_f32 v153, v154, v155
	v_add_f32_e32 v154, 1.0, v156
	v_mul_f32_e32 v156, 0xbfb8aa3b, v146
	v_add_f32_e32 v155, 1.0, v157
	v_mul_f32_e32 v157, 0xbfb8aa3b, v147
	v_exp_f32_e32 v156, v156
	v_exp_f32_e32 v157, v157
	v_rcp_f32_e32 v154, v154
	v_rcp_f32_e32 v155, v155
	v_add_f32_e32 v156, 1.0, v156
	v_add_f32_e32 v157, 1.0, v157
	v_rcp_f32_e32 v156, v156
	v_rcp_f32_e32 v157, v157
	v_pk_mul_f32 v[144:145], v[144:145], v[154:155]
	s_nop 0
	v_pk_mul_f32 v[144:145], v[148:149], v[144:145]
	s_nop 0
	v_cvt_pk_bf16_f32 v154, v144, v145
	v_pk_mul_f32 v[144:145], v[146:147], v[156:157]
	s_nop 0
	v_pk_mul_f32 v[144:145], v[150:151], v[144:145]
	s_nop 0
	v_cvt_pk_bf16_f32 v155, v144, v145
	v_mov_b64_e32 v[144:145], s[16:17]
	v_mad_i64_i32 v[144:145], s[14:15], v190, s75, v[144:145]
	v_lshl_add_u64 v[144:145], v[180:181], 1, v[144:145]
	global_store_dwordx4 v[144:145], v[152:155], off

; #define PG8_STAGE(bufoff, gbase, voff) do { _Pragma("unroll") for (int _i = 0; _i < 2; ++_i) \
;     __builtin_amdgcn_global_load_lds((const unsigned*)((const char*)(gbase) + (voff)[_i]), (LAS unsigned*)(lds + (bufoff) + ldsw + _i * 8192), 16, 0, 0); } while (0)
; #define PG8_WAIT_V(n) asm volatile("s_waitcnt vmcnt(" #n ")" ::: "memory")
; #define PG8_BAR __builtin_amdgcn_s_barrier()
; template <class Epi, class Sched = StaticOrder>
; DI void gemm_phase(LAS unsigned char* lds, const Gemm g, const Sched& S, const Epi& E) {
;     ...
;   for (int i = 0; i < 2; ++i) { int R, C; stage_rc(tid * 16 + i * 8192, R, C); const int Rb = Epi::PERM ? ((R & ~31) + perm32(R & 31)) : R;
;     voffA[i] = (unsigned)(R * K + C) * 2u; voffB[i] = (unsigned)(Rb * K + C) * 2u; }
;   const size_t kstep = (size_t)(BK * 2);
;   const size_t hstep = (size_t)HALF * K * 2;
;   const size_t tstep = 2 * hstep;
;   const unsigned ldsw = (unsigned)wid * 1024u;
;   const int aoff = lds_byte(wr * 64 + fr, fq * 8), boff = lds_byte(wc * 32 + fr, fq * 8);
;     ...
;   Unit cur, nxt; int ui = 0;
;   if (!S.next(0, cur)) return;
;   f32x4 acc[2][2][4][2];
; #pragma unroll
;   for (int a = 0; a < 2; ++a)
; #pragma unroll
;     for (int b = 0; b < 2; ++b)
; #pragma unroll
;       for (int m = 0; m < 4; ++m)
; #pragma unroll
;         for (int n = 0; n < 2; ++n) acc[a][b][m][n] = (f32x4){0.f, 0.f, 0.f, 0.f};
;   bf16x8 At[4][2], B0[2][2], B1[2][2];
;   const char* cA = (const char*)g.A + (size_t)cur.pm * tstep; const char* cB = (const char*)g.Bt + (size_t)cur.pn * tstep;
;   PG8_STAGE(PG8_SB(0, 0), cB, voffB); PG8_STAGE(PG8_SA(0, 0), cA, voffA); PG8_STAGE(PG8_SB(0, 1), cB + hstep, voffB); PG8_STAGE(PG8_SA(0, 1), cA + hstep, voffA);
;   if (wr == 1) PG8_BAR;
;   PG8_WAIT_V(4); PG8_BAR;
;   PG8_STAGE(PG8_SB(1, 0), cB + kstep, voffB); PG8_STAGE(PG8_SA(1, 0), cA + kstep, voffA); PG8_STAGE(PG8_SB(1, 1), cB + hstep + kstep, voffB);
;   PG8_WAIT_V(6); PG8_BAR;
.LBB0_952:
	s_add_u32 s12, s84, 0xc103600
	s_addc_u32 s13, s85, 0
	s_add_u32 s14, s84, 0x10503600
	s_mov_b64 s[16:17], 0x80
	s_addc_u32 s15, s85, 0
	s_and_b32 s36, s1, 3
	s_add_i32 m0, s31, 0x18000
	v_lshl_add_u64 v[6:7], v[6:7], 0, s[16:17]
	s_lshl_b32 s1, s0, 13
	s_lshl_b32 s6, s36, 12
	s_waitcnt vmcnt(2)
	s_barrier
	global_load_lds_dwordx4 v[6:7], off
	v_lshl_add_u64 v[4:5], v[4:5], 0, s[16:17]
	s_add_i32 m0, s31, 0x1a000
	s_add_i32 s37, s31, 0x8000
	s_add_i32 s38, s31, 0xa000
	global_load_lds_dwordx4 v[4:5], off
	v_lshl_add_u64 v[2:3], v[2:3], 0, s[16:17]
	s_mov_b32 m0, s37
	s_add_u32 s4, s20, 0x160080
	global_load_lds_dwordx4 v[2:3], off
	v_lshl_add_u64 v[0:1], v[0:1], 0, s[16:17]
	s_mov_b32 m0, s38
	s_addc_u32 s5, s21, 0
	global_load_lds_dwordx4 v[0:1], off
	s_add_i32 m0, s31, 0x1c000
	v_lshl_add_u64 v[0:1], s[4:5], 0, v[178:179]
	global_load_lds_dwordx4 v[0:1], off
	v_lshl_add_u64 v[0:1], s[4:5], 0, v[182:183]
	s_add_i32 m0, s31, 0x1e000
	v_lshlrev_b32_e32 v4, 2, v210
	global_load_lds_dwordx4 v[0:1], off
	v_bfe_u32 v0, v210, 4, 2
	v_and_b32_e32 v1, 15, v210
	v_lshlrev_b32_e32 v3, 4, v0
	v_lshl_or_b32 v211, s0, 6, v1
	v_lshl_or_b32 v1, v1, 6, v3
	v_and_b32_e32 v4, 32, v4
	v_lshlrev_b32_e32 v5, 6, v210
	s_movk_i32 s0, 0x3c0
	v_lshlrev_b32_e32 v2, 3, v0
	v_bitop3_b32 v1, v1, s1, v4 bitop3:0xde
	v_and_or_b32 v3, v5, s0, v3
	v_cmp_eq_u32_e64 s[0:1], 0, v0
	v_add_u16_e32 v0, v8, v9
	s_waitcnt vmcnt(6)
	v_lshrrev_b16_e32 v0, 1, v0
	v_bitop3_b32 v212, s6, v3, v4 bitop3:0xf6
	v_add_lshl_u32 v184, v10, v0, 1
	v_add_lshl_u32 v186, v11, v0, 1
	s_add_i32 s46, 0, 0x10000
	s_add_i32 s47, 0, 0x14000
	v_mbcnt_lo_u32_b32 v0, -1, 0
	v_lshl_or_b32 v213, s36, 5, v2
	s_ashr_i32 s39, s96, 31
	s_mov_b32 s40, s96
	s_ashr_i32 s41, s24, 31
	v_mov_b32_e32 v185, v179
	v_mov_b32_e32 v187, v179
	v_mov_b64_e32 v[188:189], 0x200
	v_mov_b64_e32 v[190:191], 0x1ff
	v_add_u32_e32 v214, s46, v212
	v_add_u32_e32 v215, 0, v1
	v_add_u32_e32 v216, s47, v212
	v_mbcnt_hi_u32_b32 v217, -1, v0
	s_mov_b32 s48, 0
	s_barrier
	s_branch .LBB0_954

; #define PG8_STAGE(bufoff, gbase, voff) do { _Pragma("unroll") for (int _i = 0; _i < 2; ++_i) \
;     __builtin_amdgcn_global_load_lds((const unsigned*)((const char*)(gbase) + (voff)[_i]), (LAS unsigned*)(lds + (bufoff) + ldsw + _i * 8192), 16, 0, 0); } while (0)
; #define PG8_LDA(dst, b, h) do { _Pragma("unroll") for (int m = 0; m < 4; ++m) _Pragma("unroll") for (int k = 0; k < 2; ++k) dst[m][k] = *(const LAS bf16x8*)(lds + PG8_SA(b, h) + aoff + m * 2048 + k * 1024); } while (0)
; #define PG8_LDB(dst, b, h) do { _Pragma("unroll") for (int n = 0; n < 2; ++n) _Pragma("unroll") for (int k = 0; k < 2; ++k) dst[n][k] = *(const LAS bf16x8*)(lds + PG8_SB(b, h) + boff + n * 2048 + k * 1024); } while (0)
; #define PG8_MMA(ai, bj, At, Bt) do { __builtin_amdgcn_s_setprio(1); _Pragma("unroll") for (int m = 0; m < 4; ++m) _Pragma("unroll") for (int n = 0; n < 2; ++n) _Pragma("unroll") for (int k = 0; k < 2; ++k) \
;     acc[ai][bj][m][n] = __builtin_amdgcn_mfma_f32_16x16x32_bf16(Bt[n][k], At[m][k], acc[ai][bj][m][n], 0, 0, 0); __builtin_amdgcn_s_setprio(0); } while (0)
; #define PG8_WAIT_V(n) asm volatile("s_waitcnt vmcnt(" #n ")" ::: "memory")
; #define PG8_WAIT_L(n) asm volatile("s_waitcnt lgkmcnt(" #n ")" ::: "memory")
; #define PG8_BAR __builtin_amdgcn_s_barrier()
; #define PG8_SCHED __builtin_amdgcn_sched_barrier(0)
; template <class Epi, class Sched = StaticOrder>
; DI void gemm_phase(LAS unsigned char* lds, const Gemm g, const Sched& S, const Epi& E) {
;     ...
;     for (int t = 0; t < nt; t += 2) {
;       const bool last = (t == nt - 2);
;       const char* a1 = cA + (size_t)(t + 1) * kstep;
;       const char* a2 = last ? nA : cA + (size_t)(t + 2) * kstep; const char* b2 = last ? nB : cB + (size_t)(t + 2) * kstep;
;       const char* a3 = a2 + kstep; const char* b3 = b2 + kstep;
;       PG8_LDB(B0, 0, 0); PG8_SCHED; PG8_LDA(At, 0, 0); PG8_STAGE(PG8_SA(1, 1), a1 + hstep, voffA);
;       PG8_WAIT_L(8); PG8_BAR; PG8_WAIT_L(0); PG8_MMA(0, 0, At, B0); PG8_BAR; PG8_SCHED;
;       PG8_LDB(B1, 0, 1); PG8_STAGE(PG8_SB(0, 0), b2, voffB);
;       PG8_BAR; PG8_WAIT_L(0); PG8_MMA(0, 1, At, B1); PG8_BAR;
;       PG8_LDA(At, 0, 1); PG8_STAGE(PG8_SA(0, 0), a2, voffA);
;       PG8_BAR; PG8_WAIT_L(0); PG8_MMA(1, 0, At, B0); PG8_BAR; PG8_SCHED;
;       PG8_STAGE(PG8_SB(0, 1), b2 + hstep, voffB);
;       PG8_WAIT_V(6); PG8_BAR; PG8_MMA(1, 1, At, B1); PG8_BAR;
.LBB0_961:
	ds_read_b128 v[128:131], v214
	ds_read_b128 v[132:135], v214 offset:1024
	ds_read_b128 v[136:139], v214 offset:2048
	ds_read_b128 v[140:143], v214 offset:3072
	s_add_u32 s20, s18, 0xffea0080
	s_addc_u32 s21, s19, -1
	s_cmpk_eq_i32 s44, 0x54
	s_cselect_b32 s23, s5, s21
	s_cselect_b32 s22, s4, s20
	s_cselect_b32 s21, s7, s43
	s_cselect_b32 s20, s6, s42
	s_add_i32 m0, s31, 0xc000
	ds_read_b128 v[144:147], v215
	ds_read_b128 v[148:151], v215 offset:1024
	ds_read_b128 v[152:155], v215 offset:2048
	ds_read_b128 v[156:159], v215 offset:3072
	ds_read_b128 v[160:163], v215 offset:4096
	ds_read_b128 v[164:167], v215 offset:5120
	ds_read_b128 v[168:171], v215 offset:6144
	ds_read_b128 v[172:175], v215 offset:7168
	global_load_lds_dwordx4 v184, s[18:19]
	s_add_i32 m0, s31, 0xe000
	s_nop 0
	global_load_lds_dwordx4 v186, s[18:19]
	ds_read_b128 v[192:195], v216
	ds_read_b128 v[196:199], v216 offset:1024
	ds_read_b128 v[200:203], v216 offset:2048
	ds_read_b128 v[204:207], v216 offset:3072
	s_waitcnt vmcnt(8)
	s_waitcnt lgkmcnt(0)
	s_setprio 1
	s_barrier
	v_mfma_f32_16x16x32_bf16 v[124:127], v[128:131], v[144:147], v[124:127]
	v_mfma_f32_16x16x32_bf16 v[120:123], v[136:139], v[144:147], v[120:123]
	v_mfma_f32_16x16x32_bf16 v[108:111], v[128:131], v[152:155], v[108:111]
	v_mfma_f32_16x16x32_bf16 v[104:107], v[136:139], v[152:155], v[104:107]
	v_mfma_f32_16x16x32_bf16 v[92:95], v[128:131], v[160:163], v[92:95]
	v_mfma_f32_16x16x32_bf16 v[88:91], v[136:139], v[160:163], v[88:91]
	v_mfma_f32_16x16x32_bf16 v[76:79], v[128:131], v[168:171], v[76:79]
	v_mfma_f32_16x16x32_bf16 v[72:75], v[136:139], v[168:171], v[72:75]
	v_mfma_f32_16x16x32_bf16 v[124:127], v[132:135], v[148:151], v[124:127]
	v_mfma_f32_16x16x32_bf16 v[120:123], v[140:143], v[148:151], v[120:123]
	v_mfma_f32_16x16x32_bf16 v[108:111], v[132:135], v[156:159], v[108:111]
	v_mfma_f32_16x16x32_bf16 v[104:107], v[140:143], v[156:159], v[104:107]
	v_mfma_f32_16x16x32_bf16 v[92:95], v[132:135], v[164:167], v[92:95]
	v_mfma_f32_16x16x32_bf16 v[88:91], v[140:143], v[164:167], v[88:91]
	v_mfma_f32_16x16x32_bf16 v[76:79], v[132:135], v[172:175], v[76:79]
	v_mfma_f32_16x16x32_bf16 v[72:75], v[140:143], v[172:175], v[72:75]
	v_mfma_f32_16x16x32_bf16 v[116:119], v[192:195], v[144:147], v[116:119]
	v_mfma_f32_16x16x32_bf16 v[112:115], v[200:203], v[144:147], v[112:115]
	v_mfma_f32_16x16x32_bf16 v[100:103], v[192:195], v[152:155], v[100:103]
	v_mfma_f32_16x16x32_bf16 v[96:99], v[200:203], v[152:155], v[96:99]
	v_mfma_f32_16x16x32_bf16 v[84:87], v[192:195], v[160:163], v[84:87]
	v_mfma_f32_16x16x32_bf16 v[80:83], v[200:203], v[160:163], v[80:83]
	v_mfma_f32_16x16x32_bf16 v[68:71], v[192:195], v[168:171], v[68:71]
	v_mfma_f32_16x16x32_bf16 v[64:67], v[200:203], v[168:171], v[64:67]
	v_mfma_f32_16x16x32_bf16 v[116:119], v[196:199], v[148:151], v[116:119]
	v_mfma_f32_16x16x32_bf16 v[112:115], v[204:207], v[148:151], v[112:115]
	v_mfma_f32_16x16x32_bf16 v[100:103], v[196:199], v[156:159], v[100:103]
	v_mfma_f32_16x16x32_bf16 v[96:99], v[204:207], v[156:159], v[96:99]
	v_mfma_f32_16x16x32_bf16 v[84:87], v[196:199], v[164:167], v[84:87]
	v_mfma_f32_16x16x32_bf16 v[80:83], v[204:207], v[164:167], v[80:83]
	v_mfma_f32_16x16x32_bf16 v[68:71], v[196:199], v[172:175], v[68:71]
	v_mfma_f32_16x16x32_bf16 v[64:67], v[204:207], v[172:175], v[64:67]
	s_barrier
	s_setprio 0
	s_add_i32 s45, s46, s30
	s_add_u32 s98, s20, 0x80
	s_addc_u32 s99, s21, 0
	s_add_u32 s100, s22, 0x80
	s_addc_u32 s101, s23, 0
	s_mov_b32 m0, s45
	s_nop 0
	global_load_lds_dwordx4 v178, s[20:21]
	s_add_i32 m0, s45, 0x2000
	s_nop 0
	global_load_lds_dwordx4 v182, s[20:21]
	s_mov_b32 m0, s31
	ds_read_b128 v[144:147], v215 offset:16384
	ds_read_b128 v[148:151], v215 offset:17408
	ds_read_b128 v[152:155], v215 offset:18432
	ds_read_b128 v[156:159], v215 offset:19456
	ds_read_b128 v[160:163], v215 offset:20480
	ds_read_b128 v[164:167], v215 offset:21504
	ds_read_b128 v[168:171], v215 offset:22528
	ds_read_b128 v[172:175], v215 offset:23552
	global_load_lds_dwordx4 v176, s[22:23]
	s_mov_b32 m0, s33
	s_nop 0
	global_load_lds_dwordx4 v180, s[22:23]
	s_add_u32 s52, s20, 0x160000
	s_addc_u32 s53, s21, 0
	s_add_i32 s45, s47, s30
	s_mov_b32 m0, s45
	s_nop 0
	global_load_lds_dwordx4 v178, s[52:53]
	s_add_i32 m0, s45, 0x2000
	s_nop 0
	global_load_lds_dwordx4 v182, s[52:53]
	s_waitcnt vmcnt(8)
	s_waitcnt lgkmcnt(0)
	s_setprio 1
	s_barrier
	v_mfma_f32_16x16x32_bf16 v[60:63], v[128:131], v[144:147], v[60:63]
	v_mfma_f32_16x16x32_bf16 v[56:59], v[136:139], v[144:147], v[56:59]
	v_mfma_f32_16x16x32_bf16 v[44:47], v[128:131], v[152:155], v[44:47]
	v_mfma_f32_16x16x32_bf16 v[40:43], v[136:139], v[152:155], v[40:43]
	v_mfma_f32_16x16x32_bf16 v[28:31], v[128:131], v[160:163], v[28:31]
	v_mfma_f32_16x16x32_bf16 v[24:27], v[136:139], v[160:163], v[24:27]
	v_mfma_f32_16x16x32_bf16 v[12:15], v[128:131], v[168:171], v[12:15]
	v_mfma_f32_16x16x32_bf16 v[8:11], v[136:139], v[168:171], v[8:11]
	v_mfma_f32_16x16x32_bf16 v[60:63], v[132:135], v[148:151], v[60:63]
	v_mfma_f32_16x16x32_bf16 v[56:59], v[140:143], v[148:151], v[56:59]
	v_mfma_f32_16x16x32_bf16 v[44:47], v[132:135], v[156:159], v[44:47]
	v_mfma_f32_16x16x32_bf16 v[40:43], v[140:143], v[156:159], v[40:43]
	v_mfma_f32_16x16x32_bf16 v[28:31], v[132:135], v[164:167], v[28:31]
	v_mfma_f32_16x16x32_bf16 v[24:27], v[140:143], v[164:167], v[24:27]
	v_mfma_f32_16x16x32_bf16 v[12:15], v[132:135], v[172:175], v[12:15]
	v_mfma_f32_16x16x32_bf16 v[8:11], v[140:143], v[172:175], v[8:11]
	v_mfma_f32_16x16x32_bf16 v[52:55], v[192:195], v[144:147], v[52:55]
	v_mfma_f32_16x16x32_bf16 v[48:51], v[200:203], v[144:147], v[48:51]
	v_mfma_f32_16x16x32_bf16 v[36:39], v[192:195], v[152:155], v[36:39]
	v_mfma_f32_16x16x32_bf16 v[32:35], v[200:203], v[152:155], v[32:35]
	v_mfma_f32_16x16x32_bf16 v[20:23], v[192:195], v[160:163], v[20:23]
	v_mfma_f32_16x16x32_bf16 v[16:19], v[200:203], v[160:163], v[16:19]
	v_mfma_f32_16x16x32_bf16 v[4:7], v[192:195], v[168:171], v[4:7]
	v_mfma_f32_16x16x32_bf16 v[0:3], v[200:203], v[168:171], v[0:3]
	v_mfma_f32_16x16x32_bf16 v[52:55], v[196:199], v[148:151], v[52:55]
	v_mfma_f32_16x16x32_bf16 v[48:51], v[204:207], v[148:151], v[48:51]
	v_mfma_f32_16x16x32_bf16 v[36:39], v[196:199], v[156:159], v[36:39]
	v_mfma_f32_16x16x32_bf16 v[32:35], v[204:207], v[156:159], v[32:35]
	v_mfma_f32_16x16x32_bf16 v[20:23], v[196:199], v[164:167], v[20:23]
	v_mfma_f32_16x16x32_bf16 v[16:19], v[204:207], v[164:167], v[16:19]
	v_mfma_f32_16x16x32_bf16 v[4:7], v[196:199], v[172:175], v[4:7]
	v_mfma_f32_16x16x32_bf16 v[0:3], v[204:207], v[172:175], v[0:3]
	s_barrier
; #define PG8_STAGE(bufoff, gbase, voff) do { _Pragma("unroll") for (int _i = 0; _i < 2; ++_i) \
;     __builtin_amdgcn_global_load_lds((const unsigned*)((const char*)(gbase) + (voff)[_i]), (LAS unsigned*)(lds + (bufoff) + ldsw + _i * 8192), 16, 0, 0); } while (0)
; #define PG8_LDA(dst, b, h) do { _Pragma("unroll") for (int m = 0; m < 4; ++m) _Pragma("unroll") for (int k = 0; k < 2; ++k) dst[m][k] = *(const LAS bf16x8*)(lds + PG8_SA(b, h) + aoff + m * 2048 + k * 1024); } while (0)
; #define PG8_LDB(dst, b, h) do { _Pragma("unroll") for (int n = 0; n < 2; ++n) _Pragma("unroll") for (int k = 0; k < 2; ++k) dst[n][k] = *(const LAS bf16x8*)(lds + PG8_SB(b, h) + boff + n * 2048 + k * 1024); } while (0)
; #define PG8_MMA(ai, bj, At, Bt) do { __builtin_amdgcn_s_setprio(1); _Pragma("unroll") for (int m = 0; m < 4; ++m) _Pragma("unroll") for (int n = 0; n < 2; ++n) _Pragma("unroll") for (int k = 0; k < 2; ++k) \
;     acc[ai][bj][m][n] = __builtin_amdgcn_mfma_f32_16x16x32_bf16(Bt[n][k], At[m][k], acc[ai][bj][m][n], 0, 0, 0); __builtin_amdgcn_s_setprio(0); } while (0)
; #define PG8_WAIT_V(n) asm volatile("s_waitcnt vmcnt(" #n ")" ::: "memory")
; #define PG8_WAIT_L(n) asm volatile("s_waitcnt lgkmcnt(" #n ")" ::: "memory")
; #define PG8_BAR __builtin_amdgcn_s_barrier()
; #define PG8_SCHED __builtin_amdgcn_sched_barrier(0)
; template <class Epi, class Sched = StaticOrder>
; DI void gemm_phase(LAS unsigned char* lds, const Gemm g, const Sched& S, const Epi& E) {
;     ...
;       PG8_LDB(B0, 1, 0); PG8_SCHED; PG8_LDA(At, 1, 0); PG8_STAGE(PG8_SA(0, 1), a2 + hstep, voffA);
;       PG8_WAIT_L(8); PG8_BAR; PG8_WAIT_L(0); PG8_MMA(0, 0, At, B0); PG8_BAR; PG8_SCHED;
;       PG8_LDB(B1, 1, 1); PG8_STAGE(PG8_SB(1, 0), b3, voffB);
;       PG8_BAR; PG8_WAIT_L(0); PG8_MMA(0, 1, At, B1); PG8_BAR;
;       PG8_LDA(At, 1, 1); PG8_STAGE(PG8_SA(1, 0), a3, voffA);
;       PG8_BAR; PG8_WAIT_L(0); PG8_MMA(1, 0, At, B0); PG8_BAR; PG8_SCHED;
;       PG8_STAGE(PG8_SB(1, 1), b3 + hstep, voffB);
;       PG8_WAIT_V(6); PG8_BAR; PG8_MMA(1, 1, At, B1); PG8_BAR;
	s_setprio 0
	s_add_i32 s45, 0, 0x18000
	v_add_u32_e32 v140, s45, v212
	ds_read_b128 v[128:131], v140
	ds_read_b128 v[132:135], v140 offset:1024
	ds_read_b128 v[136:139], v140 offset:2048
	ds_read_b128 v[140:143], v140 offset:3072
	s_add_u32 s22, s22, 0x160000
	s_addc_u32 s23, s23, 0
	s_mov_b32 m0, s34
	ds_read_b128 v[144:147], v215 offset:32768
	ds_read_b128 v[148:151], v215 offset:33792
	ds_read_b128 v[152:155], v215 offset:34816
	ds_read_b128 v[156:159], v215 offset:35840
	ds_read_b128 v[160:163], v215 offset:36864
	ds_read_b128 v[164:167], v215 offset:37888
	ds_read_b128 v[168:171], v215 offset:38912
	ds_read_b128 v[172:175], v215 offset:39936
	global_load_lds_dwordx4 v176, s[22:23]
	s_mov_b32 m0, s35
	s_nop 0
	global_load_lds_dwordx4 v180, s[22:23]
	s_add_i32 s22, 0, 0x1c000
	v_add_u32_e32 v204, s22, v212
	ds_read_b128 v[192:195], v204
	ds_read_b128 v[196:199], v204 offset:1024
	ds_read_b128 v[200:203], v204 offset:2048
	ds_read_b128 v[204:207], v204 offset:3072
	s_waitcnt vmcnt(8)
	s_waitcnt lgkmcnt(0)
	s_setprio 1
	s_barrier
	v_mfma_f32_16x16x32_bf16 v[124:127], v[128:131], v[144:147], v[124:127]
	v_mfma_f32_16x16x32_bf16 v[120:123], v[136:139], v[144:147], v[120:123]
	v_mfma_f32_16x16x32_bf16 v[108:111], v[128:131], v[152:155], v[108:111]
	v_mfma_f32_16x16x32_bf16 v[104:107], v[136:139], v[152:155], v[104:107]
	v_mfma_f32_16x16x32_bf16 v[92:95], v[128:131], v[160:163], v[92:95]
	v_mfma_f32_16x16x32_bf16 v[88:91], v[136:139], v[160:163], v[88:91]
	v_mfma_f32_16x16x32_bf16 v[76:79], v[128:131], v[168:171], v[76:79]
	v_mfma_f32_16x16x32_bf16 v[72:75], v[136:139], v[168:171], v[72:75]
	v_mfma_f32_16x16x32_bf16 v[124:127], v[132:135], v[148:151], v[124:127]
	v_mfma_f32_16x16x32_bf16 v[120:123], v[140:143], v[148:151], v[120:123]
	v_mfma_f32_16x16x32_bf16 v[108:111], v[132:135], v[156:159], v[108:111]
	v_mfma_f32_16x16x32_bf16 v[104:107], v[140:143], v[156:159], v[104:107]
	v_mfma_f32_16x16x32_bf16 v[92:95], v[132:135], v[164:167], v[92:95]
	v_mfma_f32_16x16x32_bf16 v[88:91], v[140:143], v[164:167], v[88:91]
	v_mfma_f32_16x16x32_bf16 v[76:79], v[132:135], v[172:175], v[76:79]
	v_mfma_f32_16x16x32_bf16 v[72:75], v[140:143], v[172:175], v[72:75]
	v_mfma_f32_16x16x32_bf16 v[116:119], v[192:195], v[144:147], v[116:119]
	v_mfma_f32_16x16x32_bf16 v[112:115], v[200:203], v[144:147], v[112:115]
	v_mfma_f32_16x16x32_bf16 v[100:103], v[192:195], v[152:155], v[100:103]
	v_mfma_f32_16x16x32_bf16 v[96:99], v[200:203], v[152:155], v[96:99]
	v_mfma_f32_16x16x32_bf16 v[84:87], v[192:195], v[160:163], v[84:87]
	v_mfma_f32_16x16x32_bf16 v[80:83], v[200:203], v[160:163], v[80:83]
	v_mfma_f32_16x16x32_bf16 v[68:71], v[192:195], v[168:171], v[68:71]
	v_mfma_f32_16x16x32_bf16 v[64:67], v[200:203], v[168:171], v[64:67]
	v_mfma_f32_16x16x32_bf16 v[116:119], v[196:199], v[148:151], v[116:119]
	v_mfma_f32_16x16x32_bf16 v[112:115], v[204:207], v[148:151], v[112:115]
	v_mfma_f32_16x16x32_bf16 v[100:103], v[196:199], v[156:159], v[100:103]
	v_mfma_f32_16x16x32_bf16 v[96:99], v[204:207], v[156:159], v[96:99]
	v_mfma_f32_16x16x32_bf16 v[84:87], v[196:199], v[164:167], v[84:87]
	v_mfma_f32_16x16x32_bf16 v[80:83], v[204:207], v[164:167], v[80:83]
	v_mfma_f32_16x16x32_bf16 v[68:71], v[196:199], v[172:175], v[68:71]
	v_mfma_f32_16x16x32_bf16 v[64:67], v[204:207], v[172:175], v[64:67]
	s_barrier
	s_setprio 0
	s_add_i32 s23, s45, s30
	s_mov_b32 m0, s23
	s_nop 0
	global_load_lds_dwordx4 v178, s[98:99]
	s_add_i32 m0, s23, 0x2000
	s_nop 0
	global_load_lds_dwordx4 v182, s[98:99]
	s_mov_b32 m0, s37
	ds_read_b128 v[144:147], v215 offset:49152
	ds_read_b128 v[148:151], v215 offset:50176
	ds_read_b128 v[152:155], v215 offset:51200
	ds_read_b128 v[156:159], v215 offset:52224
	ds_read_b128 v[160:163], v215 offset:53248
	ds_read_b128 v[164:167], v215 offset:54272
	ds_read_b128 v[168:171], v215 offset:55296
	ds_read_b128 v[172:175], v215 offset:56320
	global_load_lds_dwordx4 v176, s[100:101]
	s_mov_b32 m0, s38
	s_nop 0
	global_load_lds_dwordx4 v180, s[100:101]
	s_add_u32 s20, s20, 0x160080
	s_addc_u32 s21, s21, 0
	s_add_i32 s22, s22, s30
	s_mov_b32 m0, s22
	s_nop 0
	global_load_lds_dwordx4 v178, s[20:21]
	s_add_i32 m0, s22, 0x2000
	s_nop 0
	global_load_lds_dwordx4 v182, s[20:21]
	s_add_i32 s44, s44, 2
	s_add_u32 s18, s18, 0x100
	s_addc_u32 s19, s19, 0
	s_add_u32 s42, s42, 0x100
	s_addc_u32 s43, s43, 0
	s_cmpk_gt_u32 s44, 0x55
	s_waitcnt vmcnt(8)
	s_waitcnt lgkmcnt(0)
	s_setprio 1
	s_barrier
	v_mfma_f32_16x16x32_bf16 v[60:63], v[128:131], v[144:147], v[60:63]
	v_mfma_f32_16x16x32_bf16 v[56:59], v[136:139], v[144:147], v[56:59]
	v_mfma_f32_16x16x32_bf16 v[44:47], v[128:131], v[152:155], v[44:47]
	v_mfma_f32_16x16x32_bf16 v[40:43], v[136:139], v[152:155], v[40:43]
	v_mfma_f32_16x16x32_bf16 v[28:31], v[128:131], v[160:163], v[28:31]
	v_mfma_f32_16x16x32_bf16 v[24:27], v[136:139], v[160:163], v[24:27]
	v_mfma_f32_16x16x32_bf16 v[12:15], v[128:131], v[168:171], v[12:15]
	v_mfma_f32_16x16x32_bf16 v[8:11], v[136:139], v[168:171], v[8:11]
	v_mfma_f32_16x16x32_bf16 v[60:63], v[132:135], v[148:151], v[60:63]
	v_mfma_f32_16x16x32_bf16 v[56:59], v[140:143], v[148:151], v[56:59]
	v_mfma_f32_16x16x32_bf16 v[44:47], v[132:135], v[156:159], v[44:47]
	v_mfma_f32_16x16x32_bf16 v[40:43], v[140:143], v[156:159], v[40:43]
	v_mfma_f32_16x16x32_bf16 v[28:31], v[132:135], v[164:167], v[28:31]
	v_mfma_f32_16x16x32_bf16 v[24:27], v[140:143], v[164:167], v[24:27]
	v_mfma_f32_16x16x32_bf16 v[12:15], v[132:135], v[172:175], v[12:15]
	v_mfma_f32_16x16x32_bf16 v[8:11], v[140:143], v[172:175], v[8:11]
	v_mfma_f32_16x16x32_bf16 v[52:55], v[192:195], v[144:147], v[52:55]
	v_mfma_f32_16x16x32_bf16 v[48:51], v[200:203], v[144:147], v[48:51]
	v_mfma_f32_16x16x32_bf16 v[36:39], v[192:195], v[152:155], v[36:39]
	v_mfma_f32_16x16x32_bf16 v[32:35], v[200:203], v[152:155], v[32:35]
	v_mfma_f32_16x16x32_bf16 v[20:23], v[192:195], v[160:163], v[20:23]
	v_mfma_f32_16x16x32_bf16 v[16:19], v[200:203], v[160:163], v[16:19]
	v_mfma_f32_16x16x32_bf16 v[4:7], v[192:195], v[168:171], v[4:7]
	v_mfma_f32_16x16x32_bf16 v[0:3], v[200:203], v[168:171], v[0:3]
	v_mfma_f32_16x16x32_bf16 v[52:55], v[196:199], v[148:151], v[52:55]
	v_mfma_f32_16x16x32_bf16 v[48:51], v[204:207], v[148:151], v[48:51]
	v_mfma_f32_16x16x32_bf16 v[36:39], v[196:199], v[156:159], v[36:39]
	v_mfma_f32_16x16x32_bf16 v[32:35], v[204:207], v[156:159], v[32:35]
	v_mfma_f32_16x16x32_bf16 v[20:23], v[196:199], v[164:167], v[20:23]
	v_mfma_f32_16x16x32_bf16 v[16:19], v[204:207], v[164:167], v[16:19]
	v_mfma_f32_16x16x32_bf16 v[4:7], v[196:199], v[172:175], v[4:7]
	v_mfma_f32_16x16x32_bf16 v[0:3], v[204:207], v[172:175], v[0:3]
	s_barrier
; DI unsigned pack2(float lo, float hi) { f32x2 v = {lo, hi}; bf16v2 r = __builtin_convertvector(v, bf16v2); return __builtin_bit_cast(unsigned, r); }
;   DI void operator()(const f32x4 (&acc)[2][2][4][2], const Unit& u, int wr, int wc, int fr, int fq) const {
;     const int row0 = u.pm * BM + wr * 64 + fr, col0 = u.pn * BM + wc * 32 + 8 * fq;
; #pragma unroll
;     for (int ai = 0; ai < 2; ++ai) {
;       f32x4 bv[4][2][2];
; #pragma unroll
;       for (int m = 0; m < 4; ++m)
; #pragma unroll
;         for (int bj = 0; bj < 2; ++bj) {
;           const float* bp = base + (size_t)(row0 + ai * HALF + m * 16) * 2048 + col0 + bj * HALF;
;           bv[m][bj][0] = *(const f32x4*)bp; bv[m][bj][1] = *(const f32x4*)(bp + 4);
;         }
; #pragma unroll
;       for (int m = 0; m < 4; ++m) {
;         const int row = row0 + ai * HALF + m * 16;
;         const size_t off = (size_t)row * 2048 + col0;
;         float ss = 0.f;
; #pragma unroll
;         for (int bj = 0; bj < 2; ++bj) {
;           const f32x4 v0 = acc[ai][bj][m][0] + bv[m][bj][0], v1 = acc[ai][bj][m][1] + bv[m][bj][1];
;           *(f32x4*)(C + off + bj * HALF) = v0; *(f32x4*)(C + off + bj * HALF + 4) = v1;
;           if (xb) {
;             u32x4 w; w.x = pack2(v0[0], v0[1]); w.y = pack2(v0[2], v0[3]); w.z = pack2(v1[0], v1[1]); w.w = pack2(v1[2], v1[3]);
;             *(u32x4*)(xb + off + bj * HALF) = w;
;             ss += v0[0] * v0[0] + v0[1] * v0[1] + v0[2] * v0[2] + v0[3] * v0[3] + v1[0] * v1[0] + v1[1] * v1[1] + v1[2] * v1[2] + v1[3] * v1[3];
;           }
;         }
;         if (xb) {
;           ss += __shfl_xor(ss, 16); ss += __shfl_xor(ss, 32);
;           if (fq == 0) ssq[(size_t)row * 32 + u.pn * 4 + wc] = ss;
;         }
;       }
; template <class Epi, class Sched = StaticOrder>
; DI void gemm_phase(LAS unsigned char* lds, const Gemm g, const Sched& S, const Epi& E) {
;     ...
;     E(acc, cur, wr, wc, fr, fq);
	s_setprio 0
	s_cbranch_scc0 .LBB0_961
	v_lshl_add_u32 v194, s51, 8, v211
	v_lshl_or_b32 v192, s2, 8, v213
	v_readlane_b32 s52, v243, 3
	v_ashrrev_i32_e32 v193, 31, v192
	v_readlane_b32 s66, v243, 17
	v_readlane_b32 s67, v243, 18
	v_ashrrev_i32_e32 v195, 31, v194
	v_lshlrev_b64 v[128:129], 13, v[194:195]
	v_lshl_add_u64 v[196:197], v[192:193], 2, s[66:67]
	v_lshl_add_u64 v[236:237], v[196:197], 0, v[128:129]
	global_load_dwordx4 v[220:223], v[236:237], off
	global_load_dwordx4 v[224:227], v[236:237], off offset:16
	global_load_dwordx4 v[228:231], v[236:237], off offset:512
	global_load_dwordx4 v[232:235], v[236:237], off offset:528
	v_or_b32_e32 v206, 16, v194
	v_or_b32_e32 v202, 32, v194
	v_or_b32_e32 v198, 48, v194
	v_ashrrev_i32_e32 v207, 31, v206
	v_ashrrev_i32_e32 v203, 31, v202
	v_ashrrev_i32_e32 v199, 31, v198
	v_lshlrev_b64 v[128:129], 13, v[206:207]
	v_lshlrev_b64 v[130:131], 13, v[202:203]
	v_lshlrev_b64 v[132:133], 13, v[198:199]
	v_lshl_add_u64 v[208:209], v[196:197], 0, v[128:129]
	v_lshl_add_u64 v[204:205], v[196:197], 0, v[130:131]
	v_lshl_add_u64 v[200:201], v[196:197], 0, v[132:133]
	global_load_dwordx4 v[168:171], v[208:209], off offset:16
	global_load_dwordx4 v[172:175], v[208:209], off
	global_load_dwordx4 v[160:163], v[208:209], off offset:528
	global_load_dwordx4 v[164:167], v[208:209], off offset:512
	global_load_dwordx4 v[152:155], v[204:205], off offset:16
	global_load_dwordx4 v[156:159], v[204:205], off
	global_load_dwordx4 v[144:147], v[204:205], off offset:528
	global_load_dwordx4 v[148:151], v[204:205], off offset:512
	global_load_dwordx4 v[136:139], v[200:201], off offset:16
	global_load_dwordx4 v[140:143], v[200:201], off
	global_load_dwordx4 v[128:131], v[200:201], off offset:528
	global_load_dwordx4 v[132:135], v[200:201], off offset:512
	v_and_b32_e32 v218, 64, v217
	v_xor_b32_e32 v238, 16, v217
	v_add_u32_e32 v240, 64, v218
	v_xor_b32_e32 v239, 32, v217
	v_cmp_lt_i32_e32 vcc, v238, v240
	v_lshlrev_b64 v[218:219], 11, v[194:195]
	s_lshl_b32 s18, s2, 2
	v_cndmask_b32_e32 v241, v217, v238, vcc
	v_cmp_lt_i32_e32 vcc, v239, v240
	s_ashr_i32 s19, s18, 31
	v_readlane_b32 s53, v243, 4
	v_cndmask_b32_e32 v240, v217, v239, vcc
	v_lshl_add_u64 v[238:239], v[218:219], 0, v[192:193]
	v_lshlrev_b32_e32 v218, 2, v241
	v_lshl_add_u64 v[238:239], v[238:239], 1, s[12:13]
	v_readlane_b32 s54, v243, 5
	v_readlane_b32 s55, v243, 6
	v_readlane_b32 s56, v243, 7
	v_readlane_b32 s57, v243, 8
	v_readlane_b32 s58, v243, 9
	v_readlane_b32 s59, v243, 10
	v_readlane_b32 s60, v243, 11
	v_readlane_b32 s61, v243, 12
	v_readlane_b32 s62, v243, 13
	v_readlane_b32 s63, v243, 14
	v_readlane_b32 s64, v243, 15
	v_readlane_b32 s65, v243, 16
	s_waitcnt vmcnt(0)
	v_pk_add_f32 v[126:127], v[126:127], v[222:223]
	v_pk_add_f32 v[124:125], v[124:125], v[220:221]
	v_pk_add_f32 v[116:117], v[116:117], v[228:229]
	v_pk_add_f32 v[122:123], v[122:123], v[226:227]
	v_pk_add_f32 v[120:121], v[120:121], v[224:225]
	v_pk_add_f32 v[220:221], v[112:113], v[232:233]
	global_store_dwordx4 v[236:237], v[124:127], off
	global_store_dwordx4 v[236:237], v[120:123], off offset:16
	v_cvt_pk_bf16_f32 v112, v124, v125
	v_mul_f32_e32 v125, v125, v125
	v_mul_f32_e32 v219, v117, v117
	v_pk_add_f32 v[118:119], v[118:119], v[230:231]
	v_fmac_f32_e32 v125, v124, v124
	v_fmac_f32_e32 v219, v116, v116
	v_fmac_f32_e32 v125, v126, v126
	v_fmac_f32_e32 v219, v118, v118
	v_fmac_f32_e32 v125, v127, v127
	v_fmac_f32_e32 v219, v119, v119
	v_fmac_f32_e32 v125, v120, v120
	v_fmac_f32_e32 v219, v220, v220
	v_pk_add_f32 v[222:223], v[114:115], v[234:235]
	v_fmac_f32_e32 v125, v121, v121
	v_fmac_f32_e32 v219, v221, v221
	v_fmac_f32_e32 v125, v122, v122
	v_fmac_f32_e32 v219, v222, v222
	v_fmac_f32_e32 v125, v123, v123
	v_fmac_f32_e32 v219, v223, v223
	v_cvt_pk_bf16_f32 v114, v120, v121
	v_add_f32_e32 v121, v125, v219
	v_cvt_pk_bf16_f32 v115, v122, v123
	ds_bpermute_b32 v122, v218, v121
	v_cvt_pk_bf16_f32 v113, v126, v127
	global_store_dwordx4 v[238:239], v[112:115], off
	global_store_dwordx4 v[236:237], v[116:119], off offset:512
	global_store_dwordx4 v[236:237], v[220:223], off offset:528
	v_lshlrev_b32_e32 v126, 2, v240
	v_cvt_pk_bf16_f32 v120, v116, v117
	s_waitcnt lgkmcnt(0)
	v_add_f32_e32 v112, v121, v122
	ds_bpermute_b32 v113, v126, v112
	v_cvt_pk_bf16_f32 v121, v118, v119
	v_cvt_pk_bf16_f32 v122, v220, v221
	v_cvt_pk_bf16_f32 v123, v222, v223
	global_store_dwordx4 v[238:239], v[120:123], off offset:256
	s_and_saveexec_b64 s[20:21], s[0:1]
	s_cbranch_execz .LBB0_964
	s_waitcnt lgkmcnt(0)
	v_add_f32_e32 v114, v112, v113
	v_lshlrev_b64 v[112:113], 7, v[194:195]
	v_lshl_add_u64 v[112:113], s[14:15], 0, v[112:113]
	v_lshl_add_u64 v[112:113], s[18:19], 2, v[112:113]
	s_lshl_b32 s2, s36, 2
	v_lshl_add_u64 v[112:113], v[112:113], 0, s[2:3]
	global_store_dword v[112:113], v114, off

; #define PG8_STAGE(bufoff, gbase, voff) do { _Pragma("unroll") for (int _i = 0; _i < 2; ++_i) \
;     __builtin_amdgcn_global_load_lds((const unsigned*)((const char*)(gbase) + (voff)[_i]), (LAS unsigned*)(lds + (bufoff) + ldsw + _i * 8192), 16, 0, 0); } while (0)
; #define PG8_WAIT_V(n) asm volatile("s_waitcnt vmcnt(" #n ")" ::: "memory")
; #define PG8_BAR __builtin_amdgcn_s_barrier()
; template <class Epi, class Sched = StaticOrder>
; DI void gemm_phase(LAS unsigned char* lds, const Gemm g, const Sched& S, const Epi& E) {
;     ...
;   for (int i = 0; i < 2; ++i) { int R, C; stage_rc(tid * 16 + i * 8192, R, C); const int Rb = Epi::PERM ? ((R & ~31) + perm32(R & 31)) : R;
;     voffA[i] = (unsigned)(R * K + C) * 2u; voffB[i] = (unsigned)(Rb * K + C) * 2u; }
;   const size_t kstep = (size_t)(BK * 2);
;   const size_t hstep = (size_t)HALF * K * 2;
;   const size_t tstep = 2 * hstep;
;   const unsigned ldsw = (unsigned)wid * 1024u;
;   const int aoff = lds_byte(wr * 64 + fr, fq * 8), boff = lds_byte(wc * 32 + fr, fq * 8);
;     ...
;   Unit cur, nxt; int ui = 0;
;   if (!S.next(0, cur)) return;
;   f32x4 acc[2][2][4][2];
; #pragma unroll
;   for (int a = 0; a < 2; ++a)
; #pragma unroll
;     for (int b = 0; b < 2; ++b)
; #pragma unroll
;       for (int m = 0; m < 4; ++m)
; #pragma unroll
;         for (int n = 0; n < 2; ++n) acc[a][b][m][n] = (f32x4){0.f, 0.f, 0.f, 0.f};
;   bf16x8 At[4][2], B0[2][2], B1[2][2];
;   const char* cA = (const char*)g.A + (size_t)cur.pm * tstep; const char* cB = (const char*)g.Bt + (size_t)cur.pn * tstep;
;   PG8_STAGE(PG8_SB(0, 0), cB, voffB); PG8_STAGE(PG8_SA(0, 0), cA, voffA); PG8_STAGE(PG8_SB(0, 1), cB + hstep, voffB); PG8_STAGE(PG8_SA(0, 1), cA + hstep, voffA);
;   if (wr == 1) PG8_BAR;
;   PG8_WAIT_V(4); PG8_BAR;
;   PG8_STAGE(PG8_SB(1, 0), cB + kstep, voffB); PG8_STAGE(PG8_SA(1, 0), cA + kstep, voffA); PG8_STAGE(PG8_SB(1, 1), cB + hstep + kstep, voffB);
;   PG8_WAIT_V(6); PG8_BAR;
.LBB0_1043:
	s_add_u32 s16, s84, 0x18903600
	s_addc_u32 s17, s85, 0
	s_add_u32 s18, s84, 0x14903600
	s_addc_u32 s19, s85, 0
	s_add_u32 s20, s84, 0x1c903600
	s_addc_u32 s21, s85, 0
	s_add_u32 s22, s84, 0x1cd03600
	s_addc_u32 s23, s85, 0
	s_lshl_b32 s0, s0, 5
	s_mov_b64 s[24:25], 0x80
	s_and_b32 s5, s0, 0x60
	s_add_i32 m0, s61, 0x18000
	v_lshl_add_u64 v[6:7], v[6:7], 0, s[24:25]
	s_lshl_b32 s75, s1, 6
	s_lshl_b32 s4, s1, 13
	s_lshl_b32 s6, s5, 7
	s_waitcnt vmcnt(2)
	s_barrier
	global_load_lds_dwordx4 v[6:7], off
	v_lshl_add_u64 v[4:5], v[4:5], 0, s[24:25]
	s_add_i32 m0, s61, 0x1a000
	s_add_i32 s76, s61, 0x8000
	s_add_i32 s77, s61, 0xa000
	global_load_lds_dwordx4 v[4:5], off
	v_lshl_add_u64 v[2:3], v[2:3], 0, s[24:25]
	s_mov_b32 m0, s76
	s_add_u32 s0, s12, 0x80080
	global_load_lds_dwordx4 v[2:3], off
	v_lshl_add_u64 v[0:1], v[0:1], 0, s[24:25]
	s_mov_b32 m0, s77
	s_addc_u32 s1, s13, 0
	global_load_lds_dwordx4 v[0:1], off
	s_add_i32 m0, s61, 0x1c000
	v_lshl_add_u64 v[0:1], s[0:1], 0, v[162:163]
	global_load_lds_dwordx4 v[0:1], off
	v_lshl_add_u64 v[0:1], s[0:1], 0, v[166:167]
	s_add_i32 m0, s61, 0x1e000
	v_and_b32_e32 v177, 15, v210
	global_load_lds_dwordx4 v[0:1], off
	v_lshlrev_b32_e32 v0, 1, v12
	v_lshlrev_b32_e32 v2, 2, v210
	v_lshl_or_b32 v1, v177, 6, v0
	v_and_b32_e32 v2, 32, v2
	v_bitop3_b32 v3, v1, s4, v2 bitop3:0xde
	v_lshlrev_b32_e32 v1, 6, v210
	s_movk_i32 s0, 0x3c0
	v_and_or_b32 v0, v1, s0, v0
	v_lshlrev_b32_e32 v168, 2, v12
	v_bitop3_b32 v199, s6, v0, v2 bitop3:0xf6
	v_lshl_add_u64 v[0:1], s[84:85], 0, v[168:169]
	s_mov_b64 s[26:27], 0x10503600
	v_lshl_add_u64 v[170:171], v[0:1], 0, s[26:27]
	v_lshlrev_b32_e32 v0, 9, v210
	v_and_b32_e32 v0, 0x70000, v0
	v_lshlrev_b32_e32 v1, 12, v10
	v_or3_b32 v0, v8, v0, v1
	v_add_u32_e32 v172, v0, v9
	v_lshlrev_b32_e32 v0, 5, v11
	v_and_b32_e32 v0, 0xf0000, v0
	s_waitcnt vmcnt(6)
	s_ashr_i32 s78, s31, 3
	s_lshl_b32 s0, s31, 3
	v_or3_b32 v0, v8, v0, v1
	v_or_b32_e32 v200, s5, v12
	s_and_b32 s0, s0, 56
	s_and_b32 s1, s78, 7
	v_add_u32_e32 v174, v0, v9
	s_add_i32 s80, 0, 0x10000
	s_add_i32 s81, 0, 0x14000
	v_mbcnt_lo_u32_b32 v0, -1, 0
	v_or_b32_e32 v198, s75, v177
	v_or_b32_e32 v201, 0xfffff000, v200
	s_or_b32 s79, s0, s1
	v_cmp_eq_u32_e64 s[0:1], 0, v177
	v_cmp_gt_u32_e64 s[8:9], 2, v177
	v_cmp_lt_u32_e64 s[4:5], 1, v177
	v_cmp_lt_u32_e64 s[6:7], 13, v177
	v_add_u32_e32 v202, -14, v177
	s_mov_b64 s[94:95], s[84:85]
	v_mov_b32_e32 v173, v169
	v_mov_b32_e32 v175, v169
	v_add_u32_e32 v203, s80, v199
	v_add_u32_e32 v204, 0, v3
	v_add_u32_e32 v205, s81, v199
	s_mov_b64 s[26:27], 0x2000
	s_mov_b64 s[28:29], 0x4000
	s_mov_b32 s30, 0x3a000000
	s_mov_b32 s84, 0x800000
	s_mov_b64 s[34:35], 0x90000
	s_mov_b64 s[36:37], 0xa0000
	s_mov_b64 s[38:39], 0xb0000
	v_mbcnt_hi_u32_b32 v206, -1, v0
	v_mov_b32_e32 v176, 0x358637bd
	s_barrier
	s_branch .LBB0_1045

; #define PG8_STAGE(bufoff, gbase, voff) do { _Pragma("unroll") for (int _i = 0; _i < 2; ++_i) \
;     __builtin_amdgcn_global_load_lds((const unsigned*)((const char*)(gbase) + (voff)[_i]), (LAS unsigned*)(lds + (bufoff) + ldsw + _i * 8192), 16, 0, 0); } while (0)
; #define PG8_LDA(dst, b, h) do { _Pragma("unroll") for (int m = 0; m < 4; ++m) _Pragma("unroll") for (int k = 0; k < 2; ++k) dst[m][k] = *(const LAS bf16x8*)(lds + PG8_SA(b, h) + aoff + m * 2048 + k * 1024); } while (0)
; #define PG8_LDB(dst, b, h) do { _Pragma("unroll") for (int n = 0; n < 2; ++n) _Pragma("unroll") for (int k = 0; k < 2; ++k) dst[n][k] = *(const LAS bf16x8*)(lds + PG8_SB(b, h) + boff + n * 2048 + k * 1024); } while (0)
; #define PG8_MMA(ai, bj, At, Bt) do { __builtin_amdgcn_s_setprio(1); _Pragma("unroll") for (int m = 0; m < 4; ++m) _Pragma("unroll") for (int n = 0; n < 2; ++n) _Pragma("unroll") for (int k = 0; k < 2; ++k) \
;     acc[ai][bj][m][n] = __builtin_amdgcn_mfma_f32_16x16x32_bf16(Bt[n][k], At[m][k], acc[ai][bj][m][n], 0, 0, 0); __builtin_amdgcn_s_setprio(0); } while (0)
; #define PG8_WAIT_V(n) asm volatile("s_waitcnt vmcnt(" #n ")" ::: "memory")
; #define PG8_WAIT_L(n) asm volatile("s_waitcnt lgkmcnt(" #n ")" ::: "memory")
; #define PG8_BAR __builtin_amdgcn_s_barrier()
; #define PG8_SCHED __builtin_amdgcn_sched_barrier(0)
; template <class Epi, class Sched = StaticOrder>
; DI void gemm_phase(LAS unsigned char* lds, const Gemm g, const Sched& S, const Epi& E) {
;     ...
;     for (int t = 0; t < nt; t += 2) {
;       const bool last = (t == nt - 2);
;       const char* a1 = cA + (size_t)(t + 1) * kstep;
;       const char* a2 = last ? nA : cA + (size_t)(t + 2) * kstep; const char* b2 = last ? nB : cB + (size_t)(t + 2) * kstep;
;       const char* a3 = a2 + kstep; const char* b3 = b2 + kstep;
;       PG8_LDB(B0, 0, 0); PG8_SCHED; PG8_LDA(At, 0, 0); PG8_STAGE(PG8_SA(1, 1), a1 + hstep, voffA);
;       PG8_WAIT_L(8); PG8_BAR; PG8_WAIT_L(0); PG8_MMA(0, 0, At, B0); PG8_BAR; PG8_SCHED;
;       PG8_LDB(B1, 0, 1); PG8_STAGE(PG8_SB(0, 0), b2, voffB);
;       PG8_BAR; PG8_WAIT_L(0); PG8_MMA(0, 1, At, B1); PG8_BAR;
;       PG8_LDA(At, 0, 1); PG8_STAGE(PG8_SA(0, 0), a2, voffA);
;       PG8_BAR; PG8_WAIT_L(0); PG8_MMA(1, 0, At, B0); PG8_BAR; PG8_SCHED;
;       PG8_STAGE(PG8_SB(0, 1), b2 + hstep, voffB);
;       PG8_WAIT_V(6); PG8_BAR; PG8_MMA(1, 1, At, B1); PG8_BAR;
.LBB0_1052:
	ds_read_b128 v[128:131], v203
	ds_read_b128 v[132:135], v203 offset:1024
	ds_read_b128 v[136:139], v203 offset:2048
	ds_read_b128 v[140:143], v203 offset:3072
	s_add_u32 s12, s10, 0xfff80080
	s_addc_u32 s13, s11, -1
	s_cmp_eq_u32 s52, 28
	s_cselect_b32 s65, s41, s13
	s_cselect_b32 s64, s42, s12
	s_cselect_b32 s13, s43, s49
	s_cselect_b32 s12, s44, s45
	s_add_i32 m0, s61, 0xc000
	ds_read_b128 v[144:147], v204
	ds_read_b128 v[148:151], v204 offset:1024
	ds_read_b128 v[152:155], v204 offset:2048
	ds_read_b128 v[156:159], v204 offset:3072
	ds_read_b128 v[178:181], v204 offset:4096
	ds_read_b128 v[182:185], v204 offset:5120
	ds_read_b128 v[186:189], v204 offset:6144
	ds_read_b128 v[190:193], v204 offset:7168
	global_load_lds_dwordx4 v172, s[10:11]
	s_add_i32 m0, s61, 0xe000
	s_nop 0
	global_load_lds_dwordx4 v174, s[10:11]
	ds_read_b128 v[194:197], v205
	ds_read_b128 v[212:215], v205 offset:1024
	ds_read_b128 v[216:219], v205 offset:2048
	ds_read_b128 v[220:223], v205 offset:3072
	s_waitcnt vmcnt(8)
	s_waitcnt lgkmcnt(0)
	s_setprio 1
	s_barrier
	v_mfma_f32_16x16x32_bf16 v[124:127], v[128:131], v[144:147], v[124:127]
	v_mfma_f32_16x16x32_bf16 v[120:123], v[136:139], v[144:147], v[120:123]
	v_mfma_f32_16x16x32_bf16 v[116:119], v[128:131], v[152:155], v[116:119]
	v_mfma_f32_16x16x32_bf16 v[104:107], v[136:139], v[152:155], v[104:107]
	v_mfma_f32_16x16x32_bf16 v[92:95], v[128:131], v[178:181], v[92:95]
	v_mfma_f32_16x16x32_bf16 v[88:91], v[136:139], v[178:181], v[88:91]
	v_mfma_f32_16x16x32_bf16 v[84:87], v[128:131], v[186:189], v[84:87]
	v_mfma_f32_16x16x32_bf16 v[72:75], v[136:139], v[186:189], v[72:75]
	v_mfma_f32_16x16x32_bf16 v[124:127], v[132:135], v[148:151], v[124:127]
	v_mfma_f32_16x16x32_bf16 v[120:123], v[140:143], v[148:151], v[120:123]
	v_mfma_f32_16x16x32_bf16 v[116:119], v[132:135], v[156:159], v[116:119]
	v_mfma_f32_16x16x32_bf16 v[104:107], v[140:143], v[156:159], v[104:107]
	v_mfma_f32_16x16x32_bf16 v[92:95], v[132:135], v[182:185], v[92:95]
	v_mfma_f32_16x16x32_bf16 v[88:91], v[140:143], v[182:185], v[88:91]
	v_mfma_f32_16x16x32_bf16 v[84:87], v[132:135], v[190:193], v[84:87]
	v_mfma_f32_16x16x32_bf16 v[72:75], v[140:143], v[190:193], v[72:75]
	v_mfma_f32_16x16x32_bf16 v[112:115], v[194:197], v[144:147], v[112:115]
	v_mfma_f32_16x16x32_bf16 v[108:111], v[216:219], v[144:147], v[108:111]
	v_mfma_f32_16x16x32_bf16 v[100:103], v[194:197], v[152:155], v[100:103]
	v_mfma_f32_16x16x32_bf16 v[96:99], v[216:219], v[152:155], v[96:99]
	v_mfma_f32_16x16x32_bf16 v[80:83], v[194:197], v[178:181], v[80:83]
	v_mfma_f32_16x16x32_bf16 v[76:79], v[216:219], v[178:181], v[76:79]
	v_mfma_f32_16x16x32_bf16 v[68:71], v[194:197], v[186:189], v[68:71]
	v_mfma_f32_16x16x32_bf16 v[64:67], v[216:219], v[186:189], v[64:67]
	v_mfma_f32_16x16x32_bf16 v[112:115], v[212:215], v[148:151], v[112:115]
	v_mfma_f32_16x16x32_bf16 v[108:111], v[220:223], v[148:151], v[108:111]
	v_mfma_f32_16x16x32_bf16 v[100:103], v[212:215], v[156:159], v[100:103]
	v_mfma_f32_16x16x32_bf16 v[96:99], v[220:223], v[156:159], v[96:99]
	v_mfma_f32_16x16x32_bf16 v[80:83], v[212:215], v[182:185], v[80:83]
	v_mfma_f32_16x16x32_bf16 v[76:79], v[220:223], v[182:185], v[76:79]
	v_mfma_f32_16x16x32_bf16 v[68:71], v[212:215], v[190:193], v[68:71]
	v_mfma_f32_16x16x32_bf16 v[64:67], v[220:223], v[190:193], v[64:67]
	s_barrier
	s_setprio 0
	s_add_i32 s53, s80, s70
	s_add_u32 s98, s12, 0x80
	s_addc_u32 s99, s13, 0
	s_add_u32 s100, s64, 0x80
	s_addc_u32 s101, s65, 0
	s_mov_b32 m0, s53
	s_nop 0
	global_load_lds_dwordx4 v162, s[12:13]
	s_add_i32 m0, s53, 0x2000
	s_nop 0
	global_load_lds_dwordx4 v166, s[12:13]
	s_mov_b32 m0, s61
	ds_read_b128 v[144:147], v204 offset:16384
	ds_read_b128 v[148:151], v204 offset:17408
	ds_read_b128 v[152:155], v204 offset:18432
	ds_read_b128 v[156:159], v204 offset:19456
	ds_read_b128 v[178:181], v204 offset:20480
	ds_read_b128 v[182:185], v204 offset:21504
	ds_read_b128 v[186:189], v204 offset:22528
	ds_read_b128 v[190:193], v204 offset:23552
	global_load_lds_dwordx4 v160, s[64:65]
	s_mov_b32 m0, s63
	s_nop 0
	global_load_lds_dwordx4 v164, s[64:65]
	s_add_u32 s54, s12, 0x80000
	s_addc_u32 s55, s13, 0
	s_add_i32 s53, s81, s70
	s_mov_b32 m0, s53
	s_nop 0
	global_load_lds_dwordx4 v162, s[54:55]
	s_add_i32 m0, s53, 0x2000
	s_nop 0
	global_load_lds_dwordx4 v166, s[54:55]
	s_waitcnt vmcnt(8)
	s_waitcnt lgkmcnt(0)
	s_setprio 1
	s_barrier
	v_mfma_f32_16x16x32_bf16 v[60:63], v[128:131], v[144:147], v[60:63]
	v_mfma_f32_16x16x32_bf16 v[56:59], v[136:139], v[144:147], v[56:59]
	v_mfma_f32_16x16x32_bf16 v[48:51], v[128:131], v[152:155], v[48:51]
	v_mfma_f32_16x16x32_bf16 v[40:43], v[136:139], v[152:155], v[40:43]
	v_mfma_f32_16x16x32_bf16 v[28:31], v[128:131], v[178:181], v[28:31]
	v_mfma_f32_16x16x32_bf16 v[24:27], v[136:139], v[178:181], v[24:27]
	v_mfma_f32_16x16x32_bf16 v[12:15], v[128:131], v[186:189], v[12:15]
	v_mfma_f32_16x16x32_bf16 v[8:11], v[136:139], v[186:189], v[8:11]
	v_mfma_f32_16x16x32_bf16 v[60:63], v[132:135], v[148:151], v[60:63]
	v_mfma_f32_16x16x32_bf16 v[56:59], v[140:143], v[148:151], v[56:59]
	v_mfma_f32_16x16x32_bf16 v[48:51], v[132:135], v[156:159], v[48:51]
	v_mfma_f32_16x16x32_bf16 v[40:43], v[140:143], v[156:159], v[40:43]
	v_mfma_f32_16x16x32_bf16 v[28:31], v[132:135], v[182:185], v[28:31]
	v_mfma_f32_16x16x32_bf16 v[24:27], v[140:143], v[182:185], v[24:27]
	v_mfma_f32_16x16x32_bf16 v[12:15], v[132:135], v[190:193], v[12:15]
	v_mfma_f32_16x16x32_bf16 v[8:11], v[140:143], v[190:193], v[8:11]
	v_mfma_f32_16x16x32_bf16 v[52:55], v[194:197], v[144:147], v[52:55]
	v_mfma_f32_16x16x32_bf16 v[44:47], v[216:219], v[144:147], v[44:47]
	v_mfma_f32_16x16x32_bf16 v[36:39], v[194:197], v[152:155], v[36:39]
	v_mfma_f32_16x16x32_bf16 v[32:35], v[216:219], v[152:155], v[32:35]
	v_mfma_f32_16x16x32_bf16 v[20:23], v[194:197], v[178:181], v[20:23]
	v_mfma_f32_16x16x32_bf16 v[16:19], v[216:219], v[178:181], v[16:19]
	v_mfma_f32_16x16x32_bf16 v[4:7], v[194:197], v[186:189], v[4:7]
	v_mfma_f32_16x16x32_bf16 v[0:3], v[216:219], v[186:189], v[0:3]
	v_mfma_f32_16x16x32_bf16 v[52:55], v[212:215], v[148:151], v[52:55]
	v_mfma_f32_16x16x32_bf16 v[44:47], v[220:223], v[148:151], v[44:47]
	v_mfma_f32_16x16x32_bf16 v[36:39], v[212:215], v[156:159], v[36:39]
	v_mfma_f32_16x16x32_bf16 v[32:35], v[220:223], v[156:159], v[32:35]
	v_mfma_f32_16x16x32_bf16 v[20:23], v[212:215], v[182:185], v[20:23]
	v_mfma_f32_16x16x32_bf16 v[16:19], v[220:223], v[182:185], v[16:19]
	v_mfma_f32_16x16x32_bf16 v[4:7], v[212:215], v[190:193], v[4:7]
	v_mfma_f32_16x16x32_bf16 v[0:3], v[220:223], v[190:193], v[0:3]
	s_barrier
; #define PG8_STAGE(bufoff, gbase, voff) do { _Pragma("unroll") for (int _i = 0; _i < 2; ++_i) \
;     __builtin_amdgcn_global_load_lds((const unsigned*)((const char*)(gbase) + (voff)[_i]), (LAS unsigned*)(lds + (bufoff) + ldsw + _i * 8192), 16, 0, 0); } while (0)
; #define PG8_LDA(dst, b, h) do { _Pragma("unroll") for (int m = 0; m < 4; ++m) _Pragma("unroll") for (int k = 0; k < 2; ++k) dst[m][k] = *(const LAS bf16x8*)(lds + PG8_SA(b, h) + aoff + m * 2048 + k * 1024); } while (0)
; #define PG8_LDB(dst, b, h) do { _Pragma("unroll") for (int n = 0; n < 2; ++n) _Pragma("unroll") for (int k = 0; k < 2; ++k) dst[n][k] = *(const LAS bf16x8*)(lds + PG8_SB(b, h) + boff + n * 2048 + k * 1024); } while (0)
; #define PG8_MMA(ai, bj, At, Bt) do { __builtin_amdgcn_s_setprio(1); _Pragma("unroll") for (int m = 0; m < 4; ++m) _Pragma("unroll") for (int n = 0; n < 2; ++n) _Pragma("unroll") for (int k = 0; k < 2; ++k) \
;     acc[ai][bj][m][n] = __builtin_amdgcn_mfma_f32_16x16x32_bf16(Bt[n][k], At[m][k], acc[ai][bj][m][n], 0, 0, 0); __builtin_amdgcn_s_setprio(0); } while (0)
; #define PG8_WAIT_V(n) asm volatile("s_waitcnt vmcnt(" #n ")" ::: "memory")
; #define PG8_WAIT_L(n) asm volatile("s_waitcnt lgkmcnt(" #n ")" ::: "memory")
; #define PG8_BAR __builtin_amdgcn_s_barrier()
; #define PG8_SCHED __builtin_amdgcn_sched_barrier(0)
; template <class Epi, class Sched = StaticOrder>
; DI void gemm_phase(LAS unsigned char* lds, const Gemm g, const Sched& S, const Epi& E) {
;     ...
;       PG8_LDB(B0, 1, 0); PG8_SCHED; PG8_LDA(At, 1, 0); PG8_STAGE(PG8_SA(0, 1), a2 + hstep, voffA);
;       PG8_WAIT_L(8); PG8_BAR; PG8_WAIT_L(0); PG8_MMA(0, 0, At, B0); PG8_BAR; PG8_SCHED;
;       PG8_LDB(B1, 1, 1); PG8_STAGE(PG8_SB(1, 0), b3, voffB);
;       PG8_BAR; PG8_WAIT_L(0); PG8_MMA(0, 1, At, B1); PG8_BAR;
;       PG8_LDA(At, 1, 1); PG8_STAGE(PG8_SA(1, 0), a3, voffA);
;       PG8_BAR; PG8_WAIT_L(0); PG8_MMA(1, 0, At, B0); PG8_BAR; PG8_SCHED;
;       PG8_STAGE(PG8_SB(1, 1), b3 + hstep, voffB);
;       PG8_WAIT_V(6); PG8_BAR; PG8_MMA(1, 1, At, B1); PG8_BAR;
	s_setprio 0
	s_add_i32 s53, 0, 0x18000
	v_add_u32_e32 v140, s53, v199
	ds_read_b128 v[128:131], v140
	ds_read_b128 v[132:135], v140 offset:1024
	ds_read_b128 v[136:139], v140 offset:2048
	ds_read_b128 v[140:143], v140 offset:3072
	s_add_u32 s54, s64, 0x80000
	s_addc_u32 s55, s65, 0
	s_mov_b32 m0, s71
	ds_read_b128 v[144:147], v204 offset:32768
	ds_read_b128 v[148:151], v204 offset:33792
	ds_read_b128 v[152:155], v204 offset:34816
	ds_read_b128 v[156:159], v204 offset:35840
	ds_read_b128 v[178:181], v204 offset:36864
	ds_read_b128 v[182:185], v204 offset:37888
	ds_read_b128 v[186:189], v204 offset:38912
	ds_read_b128 v[190:193], v204 offset:39936
	global_load_lds_dwordx4 v160, s[54:55]
	s_mov_b32 m0, s72
	s_nop 0
	global_load_lds_dwordx4 v164, s[54:55]
	s_add_i32 s54, 0, 0x1c000
	v_add_u32_e32 v168, s54, v199
	ds_read_b128 v[194:197], v168
	ds_read_b128 v[212:215], v168 offset:1024
	ds_read_b128 v[216:219], v168 offset:2048
	ds_read_b128 v[220:223], v168 offset:3072
	s_waitcnt vmcnt(8)
	s_waitcnt lgkmcnt(0)
	s_setprio 1
	s_barrier
	v_mfma_f32_16x16x32_bf16 v[124:127], v[128:131], v[144:147], v[124:127]
	v_mfma_f32_16x16x32_bf16 v[120:123], v[136:139], v[144:147], v[120:123]
	v_mfma_f32_16x16x32_bf16 v[116:119], v[128:131], v[152:155], v[116:119]
	v_mfma_f32_16x16x32_bf16 v[104:107], v[136:139], v[152:155], v[104:107]
	v_mfma_f32_16x16x32_bf16 v[92:95], v[128:131], v[178:181], v[92:95]
	v_mfma_f32_16x16x32_bf16 v[88:91], v[136:139], v[178:181], v[88:91]
	v_mfma_f32_16x16x32_bf16 v[84:87], v[128:131], v[186:189], v[84:87]
	v_mfma_f32_16x16x32_bf16 v[72:75], v[136:139], v[186:189], v[72:75]
	v_mfma_f32_16x16x32_bf16 v[124:127], v[132:135], v[148:151], v[124:127]
	v_mfma_f32_16x16x32_bf16 v[120:123], v[140:143], v[148:151], v[120:123]
	v_mfma_f32_16x16x32_bf16 v[116:119], v[132:135], v[156:159], v[116:119]
	v_mfma_f32_16x16x32_bf16 v[104:107], v[140:143], v[156:159], v[104:107]
	v_mfma_f32_16x16x32_bf16 v[92:95], v[132:135], v[182:185], v[92:95]
	v_mfma_f32_16x16x32_bf16 v[88:91], v[140:143], v[182:185], v[88:91]
	v_mfma_f32_16x16x32_bf16 v[84:87], v[132:135], v[190:193], v[84:87]
	v_mfma_f32_16x16x32_bf16 v[72:75], v[140:143], v[190:193], v[72:75]
	v_mfma_f32_16x16x32_bf16 v[112:115], v[194:197], v[144:147], v[112:115]
	v_mfma_f32_16x16x32_bf16 v[108:111], v[216:219], v[144:147], v[108:111]
	v_mfma_f32_16x16x32_bf16 v[100:103], v[194:197], v[152:155], v[100:103]
	v_mfma_f32_16x16x32_bf16 v[96:99], v[216:219], v[152:155], v[96:99]
	v_mfma_f32_16x16x32_bf16 v[80:83], v[194:197], v[178:181], v[80:83]
	v_mfma_f32_16x16x32_bf16 v[76:79], v[216:219], v[178:181], v[76:79]
	v_mfma_f32_16x16x32_bf16 v[68:71], v[194:197], v[186:189], v[68:71]
	v_mfma_f32_16x16x32_bf16 v[64:67], v[216:219], v[186:189], v[64:67]
	v_mfma_f32_16x16x32_bf16 v[112:115], v[212:215], v[148:151], v[112:115]
	v_mfma_f32_16x16x32_bf16 v[108:111], v[220:223], v[148:151], v[108:111]
	v_mfma_f32_16x16x32_bf16 v[100:103], v[212:215], v[156:159], v[100:103]
	v_mfma_f32_16x16x32_bf16 v[96:99], v[220:223], v[156:159], v[96:99]
	v_mfma_f32_16x16x32_bf16 v[80:83], v[212:215], v[182:185], v[80:83]
	v_mfma_f32_16x16x32_bf16 v[76:79], v[220:223], v[182:185], v[76:79]
	v_mfma_f32_16x16x32_bf16 v[68:71], v[212:215], v[190:193], v[68:71]
	v_mfma_f32_16x16x32_bf16 v[64:67], v[220:223], v[190:193], v[64:67]
	s_barrier
	s_setprio 0
	s_add_i32 s53, s53, s70
	s_mov_b32 m0, s53
	s_nop 0
	global_load_lds_dwordx4 v162, s[98:99]
	s_add_i32 m0, s53, 0x2000
	s_nop 0
	global_load_lds_dwordx4 v166, s[98:99]
	s_mov_b32 m0, s76
	ds_read_b128 v[144:147], v204 offset:49152
	ds_read_b128 v[148:151], v204 offset:50176
	ds_read_b128 v[152:155], v204 offset:51200
	ds_read_b128 v[156:159], v204 offset:52224
	ds_read_b128 v[178:181], v204 offset:53248
	ds_read_b128 v[182:185], v204 offset:54272
	ds_read_b128 v[186:189], v204 offset:55296
	ds_read_b128 v[190:193], v204 offset:56320
	global_load_lds_dwordx4 v160, s[100:101]
	s_mov_b32 m0, s77
	s_nop 0
	global_load_lds_dwordx4 v164, s[100:101]
	s_add_u32 s12, s12, 0x80080
	s_addc_u32 s13, s13, 0
	s_add_i32 s53, s54, s70
	s_mov_b32 m0, s53
	s_nop 0
	global_load_lds_dwordx4 v162, s[12:13]
	s_add_i32 m0, s53, 0x2000
	s_nop 0
	global_load_lds_dwordx4 v166, s[12:13]
	s_add_i32 s52, s52, 2
	s_add_u32 s10, s10, 0x100
	s_addc_u32 s11, s11, 0
	s_add_u32 s45, s45, 0x100
	s_addc_u32 s49, s49, 0
	s_cmp_gt_u32 s52, 29
	s_waitcnt vmcnt(8)
	s_waitcnt lgkmcnt(0)
	s_setprio 1
	s_barrier
	v_mfma_f32_16x16x32_bf16 v[60:63], v[128:131], v[144:147], v[60:63]
	v_mfma_f32_16x16x32_bf16 v[56:59], v[136:139], v[144:147], v[56:59]
	v_mfma_f32_16x16x32_bf16 v[48:51], v[128:131], v[152:155], v[48:51]
	v_mfma_f32_16x16x32_bf16 v[40:43], v[136:139], v[152:155], v[40:43]
	v_mfma_f32_16x16x32_bf16 v[28:31], v[128:131], v[178:181], v[28:31]
	v_mfma_f32_16x16x32_bf16 v[24:27], v[136:139], v[178:181], v[24:27]
	v_mfma_f32_16x16x32_bf16 v[12:15], v[128:131], v[186:189], v[12:15]
	v_mfma_f32_16x16x32_bf16 v[8:11], v[136:139], v[186:189], v[8:11]
	v_mfma_f32_16x16x32_bf16 v[60:63], v[132:135], v[148:151], v[60:63]
	v_mfma_f32_16x16x32_bf16 v[56:59], v[140:143], v[148:151], v[56:59]
	v_mfma_f32_16x16x32_bf16 v[48:51], v[132:135], v[156:159], v[48:51]
	v_mfma_f32_16x16x32_bf16 v[40:43], v[140:143], v[156:159], v[40:43]
	v_mfma_f32_16x16x32_bf16 v[28:31], v[132:135], v[182:185], v[28:31]
	v_mfma_f32_16x16x32_bf16 v[24:27], v[140:143], v[182:185], v[24:27]
	v_mfma_f32_16x16x32_bf16 v[12:15], v[132:135], v[190:193], v[12:15]
	v_mfma_f32_16x16x32_bf16 v[8:11], v[140:143], v[190:193], v[8:11]
	v_mfma_f32_16x16x32_bf16 v[52:55], v[194:197], v[144:147], v[52:55]
	v_mfma_f32_16x16x32_bf16 v[44:47], v[216:219], v[144:147], v[44:47]
	v_mfma_f32_16x16x32_bf16 v[36:39], v[194:197], v[152:155], v[36:39]
	v_mfma_f32_16x16x32_bf16 v[32:35], v[216:219], v[152:155], v[32:35]
	v_mfma_f32_16x16x32_bf16 v[20:23], v[194:197], v[178:181], v[20:23]
	v_mfma_f32_16x16x32_bf16 v[16:19], v[216:219], v[178:181], v[16:19]
	v_mfma_f32_16x16x32_bf16 v[4:7], v[194:197], v[186:189], v[4:7]
	v_mfma_f32_16x16x32_bf16 v[0:3], v[216:219], v[186:189], v[0:3]
	v_mfma_f32_16x16x32_bf16 v[52:55], v[212:215], v[148:151], v[52:55]
	v_mfma_f32_16x16x32_bf16 v[44:47], v[220:223], v[148:151], v[44:47]
	v_mfma_f32_16x16x32_bf16 v[36:39], v[212:215], v[156:159], v[36:39]
	v_mfma_f32_16x16x32_bf16 v[32:35], v[220:223], v[156:159], v[32:35]
	v_mfma_f32_16x16x32_bf16 v[20:23], v[212:215], v[182:185], v[20:23]
	v_mfma_f32_16x16x32_bf16 v[16:19], v[220:223], v[182:185], v[16:19]
	v_mfma_f32_16x16x32_bf16 v[4:7], v[212:215], v[190:193], v[4:7]
	v_mfma_f32_16x16x32_bf16 v[0:3], v[220:223], v[190:193], v[0:3]
	s_barrier
; DI float row_rstd(const float* ssq, int row, int fq) {
;   const f32x4 a = *(const f32x4*)(ssq + (size_t)row * 32 + fq * 8), b = *(const f32x4*)(ssq + (size_t)row * 32 + fq * 8 + 4);
;   float sm = ((a[0] + a[1]) + (a[2] + a[3])) + ((b[0] + b[1]) + (b[2] + b[3]));
;   sm += __shfl_xor(sm, 16); sm += __shfl_xor(sm, 32);
;   return rsqrtf(sm * (1.0f / 2048.f) + 1e-6f);
; }
;   DI void operator()(const f32x4 (&acc)[2][2][4][2], const Unit& u, int wr, int wc, int fr, int fq) const {
;     ...
;     const int col = u.pn * 128 + wc * 32 + 8 * fq;
;     float w0[8], w1[8], w2[8];
; #pragma unroll
;     for (int e = 0; e < 8; ++e) { w0[e] = cw[col + e]; w1[e] = cw[2048 + col + e]; w2[e] = cw[4096 + col + e]; }
; #pragma unroll
;     for (int ai = 0; ai < 2; ++ai) {
;       const int row0 = u.pm * BM + ai * HALF + wr * 64, span = row0 >> 6;
;       float rsv[4];
; #pragma unroll
;       for (int m = 0; m < 4; ++m) rsv[m] = row_rstd(ssq, row0 + 16 * m + fr, fq);
;       float p1[8], p2[8];
; #pragma unroll
;       for (int e = 0; e < 8; ++e) { p1[e] = 0.f; p2[e] = 0.f; }
; #pragma unroll
;       for (int m = 0; m < 4; ++m) {
;         float g[8], a[8];
;         const float rs1 = rsv[m], rs2 = rs1 * rs1;
	s_setprio 0
	s_cbranch_scc0 .LBB0_1052
	s_cmp_lt_i32 s62, 16
	s_mov_b64 s[10:11], -1
	s_cbranch_scc0 .LBB0_1067
	s_lshl_b32 s41, s60, 8
	s_add_i32 s41, s41, s75
	v_or_b32_e32 v186, s41, v177
	v_ashrrev_i32_e32 v187, 31, v186
	v_lshlrev_b64 v[128:129], 7, v[186:187]
	v_or_b32_e32 v180, 16, v186
	v_lshl_add_u64 v[128:129], v[170:171], 0, v[128:129]
	v_ashrrev_i32_e32 v181, 31, v180
	global_load_dwordx4 v[152:155], v[128:129], off
	global_load_dwordx4 v[156:159], v[128:129], off offset:16
	v_lshlrev_b64 v[128:129], 7, v[180:181]
	v_lshl_add_u64 v[128:129], v[170:171], 0, v[128:129]
	global_load_dwordx4 v[188:191], v[128:129], off
	global_load_dwordx4 v[192:195], v[128:129], off offset:16
	v_or_b32_e32 v184, 32, v186
	v_ashrrev_i32_e32 v185, 31, v184
	v_lshlrev_b64 v[128:129], 7, v[184:185]
	v_or_b32_e32 v182, 48, v186
	v_lshl_add_u64 v[128:129], v[170:171], 0, v[128:129]
	v_ashrrev_i32_e32 v183, 31, v182
	global_load_dwordx4 v[212:215], v[128:129], off
	global_load_dwordx4 v[216:219], v[128:129], off offset:16
	v_lshlrev_b64 v[128:129], 7, v[182:183]
	v_lshl_add_u64 v[128:129], v[170:171], 0, v[128:129]
	global_load_dwordx4 v[220:223], v[128:129], off
	global_load_dwordx4 v[224:227], v[128:129], off offset:16
	v_and_b32_e32 v129, 64, v206
	v_lshl_or_b32 v178, s62, 7, v200
	v_xor_b32_e32 v128, 16, v206
	v_add_u32_e32 v129, 64, v129
	v_readlane_b32 s44, v243, 3
	v_xor_b32_e32 v130, 32, v206
	v_ashrrev_i32_e32 v179, 31, v178
	v_readlane_b32 s45, v243, 4
	v_cmp_lt_i32_e32 vcc, v128, v129
	s_movk_i32 s10, 0x2000
	v_lshl_add_u64 v[144:145], v[178:179], 2, s[44:45]
	v_cndmask_b32_e32 v134, v206, v128, vcc
	v_cmp_lt_i32_e32 vcc, v130, v129
	v_lshl_add_u64 v[132:133], v[144:145], 0, s[26:27]
	v_lshl_add_u64 v[136:137], v[144:145], 0, s[28:29]
	v_cndmask_b32_e32 v135, v206, v130, vcc
	v_add_co_u32_e32 v146, vcc, s10, v144
	global_load_dwordx4 v[128:131], v[144:145], off offset:16
	global_load_dwordx4 v[140:143], v[144:145], off
	v_addc_co_u32_e32 v147, vcc, 0, v145, vcc
	v_add_co_u32_e32 v148, vcc, s74, v144
	v_lshlrev_b32_e32 v196, 2, v134
	s_nop 0
	v_addc_co_u32_e32 v149, vcc, 0, v145, vcc
	v_lshlrev_b32_e32 v207, 2, v135
	global_load_dwordx4 v[132:135], v[132:133], off offset:16
	s_nop 0
	global_load_dwordx4 v[136:139], v[136:137], off offset:16
	s_nop 0
	global_load_dwordx4 v[144:147], v[146:147], off
	s_nop 0
	global_load_dwordx4 v[148:151], v[148:149], off
	v_mov_b32_e32 v197, 0
	v_mov_b32_e32 v211, 0
	v_readlane_b32 s46, v243, 5
	v_readlane_b32 s47, v243, 6
	v_readlane_b32 s48, v243, 7
	v_readlane_b32 s49, v243, 8
	v_readlane_b32 s50, v243, 9
	v_readlane_b32 s51, v243, 10
	v_readlane_b32 s52, v243, 11
	v_readlane_b32 s53, v243, 12
	v_readlane_b32 s54, v243, 13
	v_readlane_b32 s55, v243, 14
	v_readlane_b32 s56, v243, 15
	v_readlane_b32 s57, v243, 16
	v_readlane_b32 s58, v243, 17
	v_readlane_b32 s59, v243, 18
	s_waitcnt vmcnt(0)
	v_mov_b32_e32 v208, v152
	v_mov_b32_e32 v209, v156
	v_mov_b32_e32 v156, v153
	v_mov_b32_e32 v152, v154
	v_mov_b32_e32 v153, v158
	v_mov_b32_e32 v158, v155
	v_pk_add_f32 v[154:155], v[208:209], v[156:157]
	v_pk_add_f32 v[152:153], v[152:153], v[158:159]
	v_mov_b32_e32 v156, v188
	v_mov_b32_e32 v157, v192
	v_mov_b32_e32 v192, v189
	v_mov_b32_e32 v158, v190
	v_mov_b32_e32 v159, v194
	v_mov_b32_e32 v194, v191
	v_pk_add_f32 v[152:153], v[154:155], v[152:153]
	v_pk_add_f32 v[154:155], v[156:157], v[192:193]
	v_pk_add_f32 v[156:157], v[158:159], v[194:195]
	v_mov_b32_e32 v188, v212
	v_pk_add_f32 v[154:155], v[154:155], v[156:157]
	v_mov_b32_e32 v157, v152
	v_mov_b32_e32 v156, v154
	v_mov_b32_e32 v152, v155
	v_pk_add_f32 v[152:153], v[156:157], v[152:153]
	ds_bpermute_b32 v155, v196, v153
	ds_bpermute_b32 v154, v196, v152
	v_mov_b32_e32 v189, v216
	v_mov_b32_e32 v216, v213
	v_mov_b32_e32 v190, v214
	v_mov_b32_e32 v191, v218
	s_waitcnt lgkmcnt(0)
	v_pk_add_f32 v[152:153], v[152:153], v[154:155]
	ds_bpermute_b32 v155, v207, v153
	ds_bpermute_b32 v154, v207, v152
	v_mov_b32_e32 v218, v215
	v_mov_b32_e32 v208, v220
	v_mov_b32_e32 v209, v224
	v_mov_b32_e32 v224, v221
	v_mov_b32_e32 v212, v222
	v_mov_b32_e32 v213, v226
	v_mov_b32_e32 v226, v223
	v_pk_add_f32 v[156:157], v[188:189], v[216:217]
	v_pk_add_f32 v[158:159], v[190:191], v[218:219]
	v_pk_add_f32 v[188:189], v[208:209], v[224:225]
	v_pk_add_f32 v[190:191], v[212:213], v[226:227]
	s_waitcnt lgkmcnt(0)
; DI unsigned pack2(float lo, float hi) { f32x2 v = {lo, hi}; bf16v2 r = __builtin_convertvector(v, bf16v2); return __builtin_bit_cast(unsigned, r); }
; DI float dpp_ror1(float v) { return __int_as_float(__builtin_amdgcn_update_dpp(0, __float_as_int(v), 0x121, 0xf, 0xf, false)); }
; DI float dpp_ror2(float v) { return __int_as_float(__builtin_amdgcn_update_dpp(0, __float_as_int(v), 0x122, 0xf, 0xf, false)); }
;   DI void operator()(const f32x4 (&acc)[2][2][4][2], const Unit& u, int wr, int wc, int fr, int fq) const {
;     ...
;       for (int m = 0; m < 4; ++m) {
;         float g[8], a[8];
;         const float rs1 = rsv[m], rs2 = rs1 * rs1;
; #pragma unroll
;         for (int e = 0; e < 4; ++e) { g[e] = acc[ai][0][m][0][e] * acc[ai][1][m][0][e] * rs2; g[4 + e] = acc[ai][0][m][1][e] * acc[ai][1][m][1][e] * rs2; }
; #pragma unroll
;         for (int e = 0; e < 8; ++e) {
;           const float x1 = dpp_ror1(g[e]), x2 = dpp_ror2(g[e]);
;           const float pr1 = (fr == 0) ? p1[e] : x1, pr2 = (fr < 2) ? p2[e] : x2;
;           a[e] = w2[e] * g[e] + w1[e] * pr1 + w0[e] * pr2;
;           p1[e] = x1; p2[e] = x2;
;         }
;         if (m == 0 && fr < 2) {
;           float* hc = headC + (size_t)(span * 2 + fr) * 2048 + col;
;           *(f32x4*)hc = (f32x4){a[0], a[1], a[2], a[3]}; *(f32x4*)(hc + 4) = (f32x4){a[4], a[5], a[6], a[7]};
;         } else {
;           u32x4 w; w.x = pack2(a[0] * rs1, a[1] * rs1); w.y = pack2(a[2] * rs1, a[3] * rs1); w.z = pack2(a[4] * rs1, a[5] * rs1); w.w = pack2(a[6] * rs1, a[7] * rs1);
;           *(u32x4*)(C + (size_t)(row0 + 16 * m + fr) * 2048 + col) = w;
;         }
	v_pk_add_f32 v[152:153], v[152:153], v[154:155]
	v_pk_add_f32 v[156:157], v[156:157], v[158:159]
	v_pk_add_f32 v[158:159], v[188:189], v[190:191]
	v_pk_fma_f32 v[188:189], v[152:153], s[30:31], v[176:177] op_sel_hi:[1,0,0]
	v_mov_b32_e32 v153, v156
	v_mul_f32_e32 v152, 0x4b800000, v189
	v_cmp_gt_f32_e64 s[10:11], s84, v189
	v_mov_b32_e32 v156, v159
	v_mov_b32_e32 v194, v123
	v_cndmask_b32_e64 v152, v189, v152, s[10:11]
	v_rsq_f32_e32 v168, v152
	v_mov_b32_e32 v152, v158
	v_pk_add_f32 v[152:153], v[152:153], v[156:157]
	ds_bpermute_b32 v155, v196, v153
	ds_bpermute_b32 v154, v196, v152
	v_mul_f32_e32 v156, 0x45800000, v168
	v_cndmask_b32_e64 v195, v168, v156, s[10:11]
	v_mov_b32_e32 v217, 0
	v_mul_f32_e32 v156, v125, v113
	s_waitcnt lgkmcnt(0)
	v_pk_add_f32 v[190:191], v[152:153], v[154:155]
	v_mov_b32_e32 v152, v111
	v_mov_b32_e32 v153, v195
	v_mul_f32_e32 v154, v124, v112
	v_pk_mul_f32 v[152:153], v[194:195], v[152:153]
	v_mul_f32_e32 v155, v120, v108
	v_mul_f32_e32 v154, v154, v153
	v_pk_mul_f32 v[222:223], v[152:153], v[152:153] op_sel:[0,1] op_sel_hi:[1,0]
	v_mov_b32_e32 v213, 0
	v_mov_b32_dpp v217, v154 row_ror:1 row_mask:0xf bank_mask:0xf
	v_cndmask_b32_e64 v152, v217, 0, s[0:1]
	v_mul_f32_e32 v157, v121, v109
	v_mul_f32_e32 v158, v126, v114
	v_mul_f32_e32 v159, v122, v110
	v_mul_f32_e32 v168, v127, v115
	v_mul_f32_e32 v194, v155, v153
	v_mul_f32_e32 v155, v156, v153
	v_mov_b32_dpp v213, v154 row_ror:2 row_mask:0xf bank_mask:0xf
	v_mov_b32_e32 v221, 0
	v_mul_f32_e32 v152, v144, v152
	v_mul_f32_e32 v208, v157, v153
	v_mul_f32_e32 v156, v158, v153
	v_mul_f32_e32 v159, v159, v153
	v_mul_f32_e32 v157, v168, v153
	v_mov_b32_dpp v221, v155 row_ror:1 row_mask:0xf bank_mask:0xf
	v_cndmask_b32_e64 v153, v213, 0, s[8:9]
	v_fmac_f32_e32 v152, v148, v154
	v_mov_b32_e32 v219, 0
	v_fmac_f32_e32 v152, v140, v153
	v_cndmask_b32_e64 v153, v221, 0, s[0:1]
	v_mov_b32_dpp v219, v155 row_ror:2 row_mask:0xf bank_mask:0xf
	v_mul_f32_e32 v153, v145, v153
	v_mov_b32_e32 v216, 0
	v_cndmask_b32_e64 v154, v219, 0, s[8:9]
	v_fmac_f32_e32 v153, v149, v155
	v_mov_b32_dpp v216, v156 row_ror:1 row_mask:0xf bank_mask:0xf
	v_fmac_f32_e32 v153, v141, v154
	v_mov_b32_e32 v212, 0
	v_cndmask_b32_e64 v154, v216, 0, s[0:1]
	v_mov_b32_e32 v220, 0
	v_mov_b32_dpp v212, v156 row_ror:2 row_mask:0xf bank_mask:0xf
	v_mul_f32_e32 v154, v146, v154
	v_mov_b32_dpp v220, v157 row_ror:1 row_mask:0xf bank_mask:0xf
	v_cndmask_b32_e64 v155, v212, 0, s[8:9]
	v_fmac_f32_e32 v154, v150, v156
	v_mov_b32_e32 v218, 0
	v_fmac_f32_e32 v154, v142, v155
	v_cndmask_b32_e64 v155, v220, 0, s[0:1]
	v_mov_b32_dpp v218, v157 row_ror:2 row_mask:0xf bank_mask:0xf
	v_mul_f32_e32 v155, v147, v155
	v_cndmask_b32_e64 v156, v218, 0, s[8:9]
	v_fmac_f32_e32 v155, v151, v157
	v_mov_b32_dpp v197, v194 row_ror:1 row_mask:0xf bank_mask:0xf
	v_fmac_f32_e32 v155, v143, v156
	v_mov_b32_e32 v189, 0
	v_cndmask_b32_e64 v156, v197, 0, s[0:1]
	v_mov_b32_e32 v214, 0
	v_mov_b32_dpp v189, v194 row_ror:2 row_mask:0xf bank_mask:0xf
	v_mul_f32_e32 v156, v132, v156
	v_mov_b32_dpp v214, v208 row_ror:1 row_mask:0xf bank_mask:0xf
	v_cndmask_b32_e64 v157, v189, 0, s[8:9]
	v_fmac_f32_e32 v156, v136, v194
	v_fmac_f32_e32 v156, v128, v157
	v_cndmask_b32_e64 v157, v214, 0, s[0:1]
	v_mov_b32_e32 v209, 0
	v_mul_f32_e32 v157, v133, v157
	v_fmac_f32_e32 v157, v137, v208
	v_mov_b32_dpp v209, v208 row_ror:2 row_mask:0xf bank_mask:0xf
	v_mov_b32_e32 v208, 0
	v_cndmask_b32_e64 v158, v209, 0, s[8:9]
	v_fmac_f32_e32 v157, v129, v158
	v_mov_b32_dpp v208, v159 row_ror:1 row_mask:0xf bank_mask:0xf
	v_mov_b32_e32 v194, 0
	v_cndmask_b32_e64 v158, v208, 0, s[0:1]
	ds_bpermute_b32 v193, v207, v191
	ds_bpermute_b32 v192, v207, v190
	v_mov_b32_dpp v194, v159 row_ror:2 row_mask:0xf bank_mask:0xf
	v_mov_b32_e32 v215, 0
	v_mul_f32_e32 v158, v134, v158
	v_cndmask_b32_e64 v168, v194, 0, s[8:9]
	v_mov_b32_dpp v215, v222 row_ror:1 row_mask:0xf bank_mask:0xf
	v_fmac_f32_e32 v158, v138, v159
	v_mov_b32_dpp v211, v222 row_ror:2 row_mask:0xf bank_mask:0xf
	v_fmac_f32_e32 v158, v130, v168
	v_cndmask_b32_e64 v168, v215, 0, s[0:1]
	v_mul_f32_e32 v159, v139, v222
	v_cndmask_b32_e64 v223, v211, 0, s[8:9]
	v_fmac_f32_e32 v159, v135, v168
	v_cmp_gt_f32_e32 vcc, s84, v188
	v_fmac_f32_e32 v159, v131, v223
	s_and_saveexec_b64 s[10:11], s[4:5]
	s_xor_b64 s[10:11], exec, s[10:11]
	s_cbranch_execz .LBB0_1056
	v_mul_f32_e32 v152, v195, v152
	v_mul_f32_e32 v153, v195, v153
	v_cvt_pk_bf16_f32 v152, v152, v153
	v_mul_f32_e32 v153, v195, v154
	v_mul_f32_e32 v154, v195, v155
	v_cvt_pk_bf16_f32 v153, v153, v154
	v_mul_f32_e32 v154, v195, v156
	v_mul_f32_e32 v155, v195, v157
	v_cvt_pk_bf16_f32 v154, v154, v155
	v_mul_f32_e32 v155, v195, v158
	v_mul_f32_e32 v156, v195, v159
	v_cvt_pk_bf16_f32 v155, v155, v156
	v_lshlrev_b64 v[156:157], 12, v[186:187]
	v_lshl_add_u64 v[156:157], s[18:19], 0, v[156:157]
	v_lshl_add_u64 v[156:157], v[178:179], 1, v[156:157]
	global_store_dwordx4 v[156:157], v[152:155], off

; #define PG8_STAGE(bufoff, gbase, voff) do { _Pragma("unroll") for (int _i = 0; _i < 2; ++_i) \
;     __builtin_amdgcn_global_load_lds((const unsigned*)((const char*)(gbase) + (voff)[_i]), (LAS unsigned*)(lds + (bufoff) + ldsw + _i * 8192), 16, 0, 0); } while (0)
; #define PG8_WAIT_V(n) asm volatile("s_waitcnt vmcnt(" #n ")" ::: "memory")
; #define PG8_BAR __builtin_amdgcn_s_barrier()
; template <class Epi, class Sched = StaticOrder>
; DI void gemm_phase(LAS unsigned char* lds, const Gemm g, const Sched& S, const Epi& E) {
;     ...
;   for (int i = 0; i < 2; ++i) { int R, C; stage_rc(tid * 16 + i * 8192, R, C); const int Rb = Epi::PERM ? ((R & ~31) + perm32(R & 31)) : R;
;     voffA[i] = (unsigned)(R * K + C) * 2u; voffB[i] = (unsigned)(Rb * K + C) * 2u; }
;   const size_t kstep = (size_t)(BK * 2);
;   const size_t hstep = (size_t)HALF * K * 2;
;   const size_t tstep = 2 * hstep;
;   const unsigned ldsw = (unsigned)wid * 1024u;
;   const int aoff = lds_byte(wr * 64 + fr, fq * 8), boff = lds_byte(wc * 32 + fr, fq * 8);
;     ...
;   Unit cur, nxt; int ui = 0;
;   if (!S.next(0, cur)) return;
;   f32x4 acc[2][2][4][2];
; #pragma unroll
;   for (int a = 0; a < 2; ++a)
; #pragma unroll
;     for (int b = 0; b < 2; ++b)
; #pragma unroll
;       for (int m = 0; m < 4; ++m)
; #pragma unroll
;         for (int n = 0; n < 2; ++n) acc[a][b][m][n] = (f32x4){0.f, 0.f, 0.f, 0.f};
;   bf16x8 At[4][2], B0[2][2], B1[2][2];
;   const char* cA = (const char*)g.A + (size_t)cur.pm * tstep; const char* cB = (const char*)g.Bt + (size_t)cur.pn * tstep;
;   PG8_STAGE(PG8_SB(0, 0), cB, voffB); PG8_STAGE(PG8_SA(0, 0), cA, voffA); PG8_STAGE(PG8_SB(0, 1), cB + hstep, voffB); PG8_STAGE(PG8_SA(0, 1), cA + hstep, voffA);
;   if (wr == 1) PG8_BAR;
;   PG8_WAIT_V(4); PG8_BAR;
;   PG8_STAGE(PG8_SB(1, 0), cB + kstep, voffB); PG8_STAGE(PG8_SA(1, 0), cA + kstep, voffA); PG8_STAGE(PG8_SB(1, 1), cB + hstep + kstep, voffB);
;   PG8_WAIT_V(6); PG8_BAR;
.LBB0_1189:
	s_add_u32 s2, s84, 0xc103600
	s_addc_u32 s3, s85, 0
	s_add_u32 s8, s84, 0x10703600
	s_mov_b64 s[10:11], 0x80
	s_addc_u32 s9, s85, 0
	s_and_b32 s41, s4, 3
	s_add_i32 m0, s37, 0x18000
	v_lshl_add_u64 v[6:7], v[6:7], 0, s[10:11]
	s_lshl_b32 s13, s1, 13
	s_lshl_b32 s14, s41, 12
	s_waitcnt vmcnt(2)
	s_barrier
	global_load_lds_dwordx4 v[6:7], off
	v_lshl_add_u64 v[4:5], v[4:5], 0, s[10:11]
	s_add_i32 m0, s37, 0x1a000
	s_add_i32 s44, s37, 0x8000
	s_add_i32 s45, s37, 0xa000
	global_load_lds_dwordx4 v[4:5], off
	v_lshl_add_u64 v[2:3], v[2:3], 0, s[10:11]
	s_mov_b32 m0, s44
	s_add_u32 s4, s24, 0x80080
	global_load_lds_dwordx4 v[2:3], off
	v_lshl_add_u64 v[0:1], v[0:1], 0, s[10:11]
	s_mov_b32 m0, s45
	s_addc_u32 s5, s25, 0
	global_load_lds_dwordx4 v[0:1], off
	s_add_i32 m0, s37, 0x1c000
	v_lshl_add_u64 v[0:1], s[4:5], 0, v[180:181]
	global_load_lds_dwordx4 v[0:1], off
	v_lshl_add_u64 v[0:1], s[4:5], 0, v[176:177]
	s_add_i32 m0, s37, 0x1e000
	s_sext_i32_i8 s42, s0
	global_load_lds_dwordx4 v[0:1], off
	v_bfe_u32 v0, v210, 4, 2
	v_and_b32_e32 v1, 15, v210
	v_lshlrev_b32_e32 v3, 4, v0
	v_lshlrev_b32_e32 v5, 6, v210
	s_movk_i32 s0, 0x3c0
	v_lshl_or_b32 v211, s1, 6, v1
	v_lshlrev_b32_e32 v2, 3, v0
	v_lshl_or_b32 v1, v1, 6, v3
	v_and_or_b32 v3, v5, s0, v3
	v_cmp_eq_u32_e64 s[0:1], 0, v0
	v_lshlrev_b32_e32 v0, 9, v210
	v_lshl_or_b32 v213, s41, 5, v2
	v_and_b32_e32 v0, 0x70000, v0
	v_lshlrev_b32_e32 v2, 12, v11
	v_or3_b32 v0, v9, v0, v2
	v_add_u32_e32 v184, v0, v10
	v_lshlrev_b32_e32 v0, 5, v8
	v_lshlrev_b32_e32 v4, 2, v210
	v_and_b32_e32 v0, 0xf0000, v0
	v_and_b32_e32 v4, 32, v4
	s_waitcnt vmcnt(6)
	v_or3_b32 v0, v9, v0, v2
	v_bitop3_b32 v1, v1, s13, v4 bitop3:0xde
	v_bitop3_b32 v212, s14, v3, v4 bitop3:0xf6
	v_add_u32_e32 v186, v0, v10
	s_add_i32 s48, 0, 0x10000
	s_add_i32 s49, 0, 0x14000
	v_mbcnt_lo_u32_b32 v0, -1, 0
	s_mov_b32 s13, 0
	s_ashr_i32 s46, s96, 31
	s_mov_b32 s47, s96
	v_mov_b32_e32 v185, v181
	v_mov_b32_e32 v187, v181
	v_mov_b64_e32 v[188:189], 0x200
	v_mov_b64_e32 v[190:191], 0x1ff
	v_add_u32_e32 v214, s48, v212
	v_add_u32_e32 v215, 0, v1
	v_add_u32_e32 v216, s49, v212
	v_mbcnt_hi_u32_b32 v217, -1, v0
	s_mov_b32 s50, 0
	s_barrier
	s_branch .LBB0_1191

; #define PG8_STAGE(bufoff, gbase, voff) do { _Pragma("unroll") for (int _i = 0; _i < 2; ++_i) \
;     __builtin_amdgcn_global_load_lds((const unsigned*)((const char*)(gbase) + (voff)[_i]), (LAS unsigned*)(lds + (bufoff) + ldsw + _i * 8192), 16, 0, 0); } while (0)
; #define PG8_LDA(dst, b, h) do { _Pragma("unroll") for (int m = 0; m < 4; ++m) _Pragma("unroll") for (int k = 0; k < 2; ++k) dst[m][k] = *(const LAS bf16x8*)(lds + PG8_SA(b, h) + aoff + m * 2048 + k * 1024); } while (0)
; #define PG8_LDB(dst, b, h) do { _Pragma("unroll") for (int n = 0; n < 2; ++n) _Pragma("unroll") for (int k = 0; k < 2; ++k) dst[n][k] = *(const LAS bf16x8*)(lds + PG8_SB(b, h) + boff + n * 2048 + k * 1024); } while (0)
; #define PG8_MMA(ai, bj, At, Bt) do { __builtin_amdgcn_s_setprio(1); _Pragma("unroll") for (int m = 0; m < 4; ++m) _Pragma("unroll") for (int n = 0; n < 2; ++n) _Pragma("unroll") for (int k = 0; k < 2; ++k) \
;     acc[ai][bj][m][n] = __builtin_amdgcn_mfma_f32_16x16x32_bf16(Bt[n][k], At[m][k], acc[ai][bj][m][n], 0, 0, 0); __builtin_amdgcn_s_setprio(0); } while (0)
; #define PG8_WAIT_V(n) asm volatile("s_waitcnt vmcnt(" #n ")" ::: "memory")
; #define PG8_WAIT_L(n) asm volatile("s_waitcnt lgkmcnt(" #n ")" ::: "memory")
; #define PG8_BAR __builtin_amdgcn_s_barrier()
; #define PG8_SCHED __builtin_amdgcn_sched_barrier(0)
; template <class Epi, class Sched = StaticOrder>
; DI void gemm_phase(LAS unsigned char* lds, const Gemm g, const Sched& S, const Epi& E) {
;     ...
;     for (int t = 0; t < nt; t += 2) {
;       const bool last = (t == nt - 2);
;       const char* a1 = cA + (size_t)(t + 1) * kstep;
;       const char* a2 = last ? nA : cA + (size_t)(t + 2) * kstep; const char* b2 = last ? nB : cB + (size_t)(t + 2) * kstep;
;       const char* a3 = a2 + kstep; const char* b3 = b2 + kstep;
;       PG8_LDB(B0, 0, 0); PG8_SCHED; PG8_LDA(At, 0, 0); PG8_STAGE(PG8_SA(1, 1), a1 + hstep, voffA);
;       PG8_WAIT_L(8); PG8_BAR; PG8_WAIT_L(0); PG8_MMA(0, 0, At, B0); PG8_BAR; PG8_SCHED;
;       PG8_LDB(B1, 0, 1); PG8_STAGE(PG8_SB(0, 0), b2, voffB);
;       PG8_BAR; PG8_WAIT_L(0); PG8_MMA(0, 1, At, B1); PG8_BAR;
;       PG8_LDA(At, 0, 1); PG8_STAGE(PG8_SA(0, 0), a2, voffA);
;       PG8_BAR; PG8_WAIT_L(0); PG8_MMA(1, 0, At, B0); PG8_BAR; PG8_SCHED;
;       PG8_STAGE(PG8_SB(0, 1), b2 + hstep, voffB);
;       PG8_WAIT_V(6); PG8_BAR; PG8_MMA(1, 1, At, B1); PG8_BAR;
.LBB0_1194:
	ds_read_b128 v[128:131], v214
	ds_read_b128 v[132:135], v214 offset:1024
	ds_read_b128 v[136:139], v214 offset:2048
	ds_read_b128 v[140:143], v214 offset:3072
	s_add_u32 s24, s22, 0xfff80080
	s_addc_u32 s25, s23, -1
	s_cmp_eq_u32 s54, 28
	s_cselect_b32 s27, s17, s25
	s_cselect_b32 s26, s43, s24
	s_cselect_b32 s25, s15, s53
	s_cselect_b32 s24, s51, s52
	s_add_i32 m0, s37, 0xc000
	ds_read_b128 v[144:147], v215
	ds_read_b128 v[148:151], v215 offset:1024
	ds_read_b128 v[152:155], v215 offset:2048
	ds_read_b128 v[156:159], v215 offset:3072
	ds_read_b128 v[160:163], v215 offset:4096
	ds_read_b128 v[164:167], v215 offset:5120
	ds_read_b128 v[168:171], v215 offset:6144
	ds_read_b128 v[172:175], v215 offset:7168
	global_load_lds_dwordx4 v184, s[22:23]
	s_add_i32 m0, s37, 0xe000
	s_nop 0
	global_load_lds_dwordx4 v186, s[22:23]
	ds_read_b128 v[192:195], v216
	ds_read_b128 v[196:199], v216 offset:1024
	ds_read_b128 v[200:203], v216 offset:2048
	ds_read_b128 v[204:207], v216 offset:3072
	s_waitcnt vmcnt(8)
	s_waitcnt lgkmcnt(0)
	s_setprio 1
	s_barrier
	v_mfma_f32_16x16x32_bf16 v[124:127], v[128:131], v[144:147], v[124:127]
	v_mfma_f32_16x16x32_bf16 v[120:123], v[136:139], v[144:147], v[120:123]
	v_mfma_f32_16x16x32_bf16 v[108:111], v[128:131], v[152:155], v[108:111]
	v_mfma_f32_16x16x32_bf16 v[104:107], v[136:139], v[152:155], v[104:107]
	v_mfma_f32_16x16x32_bf16 v[92:95], v[128:131], v[160:163], v[92:95]
	v_mfma_f32_16x16x32_bf16 v[88:91], v[136:139], v[160:163], v[88:91]
	v_mfma_f32_16x16x32_bf16 v[76:79], v[128:131], v[168:171], v[76:79]
	v_mfma_f32_16x16x32_bf16 v[72:75], v[136:139], v[168:171], v[72:75]
	v_mfma_f32_16x16x32_bf16 v[124:127], v[132:135], v[148:151], v[124:127]
	v_mfma_f32_16x16x32_bf16 v[120:123], v[140:143], v[148:151], v[120:123]
	v_mfma_f32_16x16x32_bf16 v[108:111], v[132:135], v[156:159], v[108:111]
	v_mfma_f32_16x16x32_bf16 v[104:107], v[140:143], v[156:159], v[104:107]
	v_mfma_f32_16x16x32_bf16 v[92:95], v[132:135], v[164:167], v[92:95]
	v_mfma_f32_16x16x32_bf16 v[88:91], v[140:143], v[164:167], v[88:91]
	v_mfma_f32_16x16x32_bf16 v[76:79], v[132:135], v[172:175], v[76:79]
	v_mfma_f32_16x16x32_bf16 v[72:75], v[140:143], v[172:175], v[72:75]
	v_mfma_f32_16x16x32_bf16 v[116:119], v[192:195], v[144:147], v[116:119]
	v_mfma_f32_16x16x32_bf16 v[112:115], v[200:203], v[144:147], v[112:115]
	v_mfma_f32_16x16x32_bf16 v[100:103], v[192:195], v[152:155], v[100:103]
	v_mfma_f32_16x16x32_bf16 v[96:99], v[200:203], v[152:155], v[96:99]
	v_mfma_f32_16x16x32_bf16 v[84:87], v[192:195], v[160:163], v[84:87]
	v_mfma_f32_16x16x32_bf16 v[80:83], v[200:203], v[160:163], v[80:83]
	v_mfma_f32_16x16x32_bf16 v[68:71], v[192:195], v[168:171], v[68:71]
	v_mfma_f32_16x16x32_bf16 v[64:67], v[200:203], v[168:171], v[64:67]
	v_mfma_f32_16x16x32_bf16 v[116:119], v[196:199], v[148:151], v[116:119]
	v_mfma_f32_16x16x32_bf16 v[112:115], v[204:207], v[148:151], v[112:115]
	v_mfma_f32_16x16x32_bf16 v[100:103], v[196:199], v[156:159], v[100:103]
	v_mfma_f32_16x16x32_bf16 v[96:99], v[204:207], v[156:159], v[96:99]
	v_mfma_f32_16x16x32_bf16 v[84:87], v[196:199], v[164:167], v[84:87]
	v_mfma_f32_16x16x32_bf16 v[80:83], v[204:207], v[164:167], v[80:83]
	v_mfma_f32_16x16x32_bf16 v[68:71], v[196:199], v[172:175], v[68:71]
	v_mfma_f32_16x16x32_bf16 v[64:67], v[204:207], v[172:175], v[64:67]
	s_barrier
	s_setprio 0
	s_add_i32 s55, s48, s35
	s_add_u32 s98, s24, 0x80
	s_addc_u32 s99, s25, 0
	s_add_u32 s100, s26, 0x80
	s_addc_u32 s101, s27, 0
	s_mov_b32 m0, s55
	s_nop 0
	global_load_lds_dwordx4 v180, s[24:25]
	s_add_i32 m0, s55, 0x2000
	s_nop 0
	global_load_lds_dwordx4 v176, s[24:25]
	s_mov_b32 m0, s37
	ds_read_b128 v[144:147], v215 offset:16384
	ds_read_b128 v[148:151], v215 offset:17408
	ds_read_b128 v[152:155], v215 offset:18432
	ds_read_b128 v[156:159], v215 offset:19456
	ds_read_b128 v[160:163], v215 offset:20480
	ds_read_b128 v[164:167], v215 offset:21504
	ds_read_b128 v[168:171], v215 offset:22528
	ds_read_b128 v[172:175], v215 offset:23552
	global_load_lds_dwordx4 v182, s[26:27]
	s_mov_b32 m0, s38
	s_nop 0
	global_load_lds_dwordx4 v178, s[26:27]
	s_add_u32 s56, s24, 0x80000
	s_addc_u32 s57, s25, 0
	s_add_i32 s55, s49, s35
	s_mov_b32 m0, s55
	s_nop 0
	global_load_lds_dwordx4 v180, s[56:57]
	s_add_i32 m0, s55, 0x2000
	s_nop 0
	global_load_lds_dwordx4 v176, s[56:57]
	s_waitcnt vmcnt(8)
	s_waitcnt lgkmcnt(0)
	s_setprio 1
	s_barrier
	v_mfma_f32_16x16x32_bf16 v[60:63], v[128:131], v[144:147], v[60:63]
	v_mfma_f32_16x16x32_bf16 v[56:59], v[136:139], v[144:147], v[56:59]
	v_mfma_f32_16x16x32_bf16 v[44:47], v[128:131], v[152:155], v[44:47]
	v_mfma_f32_16x16x32_bf16 v[40:43], v[136:139], v[152:155], v[40:43]
	v_mfma_f32_16x16x32_bf16 v[28:31], v[128:131], v[160:163], v[28:31]
	v_mfma_f32_16x16x32_bf16 v[24:27], v[136:139], v[160:163], v[24:27]
	v_mfma_f32_16x16x32_bf16 v[12:15], v[128:131], v[168:171], v[12:15]
	v_mfma_f32_16x16x32_bf16 v[8:11], v[136:139], v[168:171], v[8:11]
	v_mfma_f32_16x16x32_bf16 v[60:63], v[132:135], v[148:151], v[60:63]
	v_mfma_f32_16x16x32_bf16 v[56:59], v[140:143], v[148:151], v[56:59]
	v_mfma_f32_16x16x32_bf16 v[44:47], v[132:135], v[156:159], v[44:47]
	v_mfma_f32_16x16x32_bf16 v[40:43], v[140:143], v[156:159], v[40:43]
	v_mfma_f32_16x16x32_bf16 v[28:31], v[132:135], v[164:167], v[28:31]
	v_mfma_f32_16x16x32_bf16 v[24:27], v[140:143], v[164:167], v[24:27]
	v_mfma_f32_16x16x32_bf16 v[12:15], v[132:135], v[172:175], v[12:15]
	v_mfma_f32_16x16x32_bf16 v[8:11], v[140:143], v[172:175], v[8:11]
	v_mfma_f32_16x16x32_bf16 v[52:55], v[192:195], v[144:147], v[52:55]
	v_mfma_f32_16x16x32_bf16 v[48:51], v[200:203], v[144:147], v[48:51]
	v_mfma_f32_16x16x32_bf16 v[36:39], v[192:195], v[152:155], v[36:39]
	v_mfma_f32_16x16x32_bf16 v[32:35], v[200:203], v[152:155], v[32:35]
	v_mfma_f32_16x16x32_bf16 v[20:23], v[192:195], v[160:163], v[20:23]
	v_mfma_f32_16x16x32_bf16 v[16:19], v[200:203], v[160:163], v[16:19]
	v_mfma_f32_16x16x32_bf16 v[4:7], v[192:195], v[168:171], v[4:7]
	v_mfma_f32_16x16x32_bf16 v[0:3], v[200:203], v[168:171], v[0:3]
	v_mfma_f32_16x16x32_bf16 v[52:55], v[196:199], v[148:151], v[52:55]
	v_mfma_f32_16x16x32_bf16 v[48:51], v[204:207], v[148:151], v[48:51]
	v_mfma_f32_16x16x32_bf16 v[36:39], v[196:199], v[156:159], v[36:39]
	v_mfma_f32_16x16x32_bf16 v[32:35], v[204:207], v[156:159], v[32:35]
	v_mfma_f32_16x16x32_bf16 v[20:23], v[196:199], v[164:167], v[20:23]
	v_mfma_f32_16x16x32_bf16 v[16:19], v[204:207], v[164:167], v[16:19]
	v_mfma_f32_16x16x32_bf16 v[4:7], v[196:199], v[172:175], v[4:7]
	v_mfma_f32_16x16x32_bf16 v[0:3], v[204:207], v[172:175], v[0:3]
	s_barrier
; #define PG8_STAGE(bufoff, gbase, voff) do { _Pragma("unroll") for (int _i = 0; _i < 2; ++_i) \
;     __builtin_amdgcn_global_load_lds((const unsigned*)((const char*)(gbase) + (voff)[_i]), (LAS unsigned*)(lds + (bufoff) + ldsw + _i * 8192), 16, 0, 0); } while (0)
; #define PG8_LDA(dst, b, h) do { _Pragma("unroll") for (int m = 0; m < 4; ++m) _Pragma("unroll") for (int k = 0; k < 2; ++k) dst[m][k] = *(const LAS bf16x8*)(lds + PG8_SA(b, h) + aoff + m * 2048 + k * 1024); } while (0)
; #define PG8_LDB(dst, b, h) do { _Pragma("unroll") for (int n = 0; n < 2; ++n) _Pragma("unroll") for (int k = 0; k < 2; ++k) dst[n][k] = *(const LAS bf16x8*)(lds + PG8_SB(b, h) + boff + n * 2048 + k * 1024); } while (0)
; #define PG8_MMA(ai, bj, At, Bt) do { __builtin_amdgcn_s_setprio(1); _Pragma("unroll") for (int m = 0; m < 4; ++m) _Pragma("unroll") for (int n = 0; n < 2; ++n) _Pragma("unroll") for (int k = 0; k < 2; ++k) \
;     acc[ai][bj][m][n] = __builtin_amdgcn_mfma_f32_16x16x32_bf16(Bt[n][k], At[m][k], acc[ai][bj][m][n], 0, 0, 0); __builtin_amdgcn_s_setprio(0); } while (0)
; #define PG8_WAIT_V(n) asm volatile("s_waitcnt vmcnt(" #n ")" ::: "memory")
; #define PG8_WAIT_L(n) asm volatile("s_waitcnt lgkmcnt(" #n ")" ::: "memory")
; #define PG8_BAR __builtin_amdgcn_s_barrier()
; #define PG8_SCHED __builtin_amdgcn_sched_barrier(0)
; template <class Epi, class Sched = StaticOrder>
; DI void gemm_phase(LAS unsigned char* lds, const Gemm g, const Sched& S, const Epi& E) {
;     ...
;       PG8_LDB(B0, 1, 0); PG8_SCHED; PG8_LDA(At, 1, 0); PG8_STAGE(PG8_SA(0, 1), a2 + hstep, voffA);
;       PG8_WAIT_L(8); PG8_BAR; PG8_WAIT_L(0); PG8_MMA(0, 0, At, B0); PG8_BAR; PG8_SCHED;
;       PG8_LDB(B1, 1, 1); PG8_STAGE(PG8_SB(1, 0), b3, voffB);
;       PG8_BAR; PG8_WAIT_L(0); PG8_MMA(0, 1, At, B1); PG8_BAR;
;       PG8_LDA(At, 1, 1); PG8_STAGE(PG8_SA(1, 0), a3, voffA);
;       PG8_BAR; PG8_WAIT_L(0); PG8_MMA(1, 0, At, B0); PG8_BAR; PG8_SCHED;
;       PG8_STAGE(PG8_SB(1, 1), b3 + hstep, voffB);
;       PG8_WAIT_V(6); PG8_BAR; PG8_MMA(1, 1, At, B1); PG8_BAR;
	s_setprio 0
	s_add_i32 s55, 0, 0x18000
	v_add_u32_e32 v140, s55, v212
	ds_read_b128 v[128:131], v140
	ds_read_b128 v[132:135], v140 offset:1024
	ds_read_b128 v[136:139], v140 offset:2048
	ds_read_b128 v[140:143], v140 offset:3072
	s_add_u32 s26, s26, 0x80000
	s_addc_u32 s27, s27, 0
	s_mov_b32 m0, s39
	ds_read_b128 v[144:147], v215 offset:32768
	ds_read_b128 v[148:151], v215 offset:33792
	ds_read_b128 v[152:155], v215 offset:34816
	ds_read_b128 v[156:159], v215 offset:35840
	ds_read_b128 v[160:163], v215 offset:36864
	ds_read_b128 v[164:167], v215 offset:37888
	ds_read_b128 v[168:171], v215 offset:38912
	ds_read_b128 v[172:175], v215 offset:39936
	global_load_lds_dwordx4 v182, s[26:27]
	s_mov_b32 m0, s40
	s_nop 0
	global_load_lds_dwordx4 v178, s[26:27]
	s_add_i32 s26, 0, 0x1c000
	v_add_u32_e32 v204, s26, v212
	ds_read_b128 v[192:195], v204
	ds_read_b128 v[196:199], v204 offset:1024
	ds_read_b128 v[200:203], v204 offset:2048
	ds_read_b128 v[204:207], v204 offset:3072
	s_waitcnt vmcnt(8)
	s_waitcnt lgkmcnt(0)
	s_setprio 1
	s_barrier
	v_mfma_f32_16x16x32_bf16 v[124:127], v[128:131], v[144:147], v[124:127]
	v_mfma_f32_16x16x32_bf16 v[120:123], v[136:139], v[144:147], v[120:123]
	v_mfma_f32_16x16x32_bf16 v[108:111], v[128:131], v[152:155], v[108:111]
	v_mfma_f32_16x16x32_bf16 v[104:107], v[136:139], v[152:155], v[104:107]
	v_mfma_f32_16x16x32_bf16 v[92:95], v[128:131], v[160:163], v[92:95]
	v_mfma_f32_16x16x32_bf16 v[88:91], v[136:139], v[160:163], v[88:91]
	v_mfma_f32_16x16x32_bf16 v[76:79], v[128:131], v[168:171], v[76:79]
	v_mfma_f32_16x16x32_bf16 v[72:75], v[136:139], v[168:171], v[72:75]
	v_mfma_f32_16x16x32_bf16 v[124:127], v[132:135], v[148:151], v[124:127]
	v_mfma_f32_16x16x32_bf16 v[120:123], v[140:143], v[148:151], v[120:123]
	v_mfma_f32_16x16x32_bf16 v[108:111], v[132:135], v[156:159], v[108:111]
	v_mfma_f32_16x16x32_bf16 v[104:107], v[140:143], v[156:159], v[104:107]
	v_mfma_f32_16x16x32_bf16 v[92:95], v[132:135], v[164:167], v[92:95]
	v_mfma_f32_16x16x32_bf16 v[88:91], v[140:143], v[164:167], v[88:91]
	v_mfma_f32_16x16x32_bf16 v[76:79], v[132:135], v[172:175], v[76:79]
	v_mfma_f32_16x16x32_bf16 v[72:75], v[140:143], v[172:175], v[72:75]
	v_mfma_f32_16x16x32_bf16 v[116:119], v[192:195], v[144:147], v[116:119]
	v_mfma_f32_16x16x32_bf16 v[112:115], v[200:203], v[144:147], v[112:115]
	v_mfma_f32_16x16x32_bf16 v[100:103], v[192:195], v[152:155], v[100:103]
	v_mfma_f32_16x16x32_bf16 v[96:99], v[200:203], v[152:155], v[96:99]
	v_mfma_f32_16x16x32_bf16 v[84:87], v[192:195], v[160:163], v[84:87]
	v_mfma_f32_16x16x32_bf16 v[80:83], v[200:203], v[160:163], v[80:83]
	v_mfma_f32_16x16x32_bf16 v[68:71], v[192:195], v[168:171], v[68:71]
	v_mfma_f32_16x16x32_bf16 v[64:67], v[200:203], v[168:171], v[64:67]
	v_mfma_f32_16x16x32_bf16 v[116:119], v[196:199], v[148:151], v[116:119]
	v_mfma_f32_16x16x32_bf16 v[112:115], v[204:207], v[148:151], v[112:115]
	v_mfma_f32_16x16x32_bf16 v[100:103], v[196:199], v[156:159], v[100:103]
	v_mfma_f32_16x16x32_bf16 v[96:99], v[204:207], v[156:159], v[96:99]
	v_mfma_f32_16x16x32_bf16 v[84:87], v[196:199], v[164:167], v[84:87]
	v_mfma_f32_16x16x32_bf16 v[80:83], v[204:207], v[164:167], v[80:83]
	v_mfma_f32_16x16x32_bf16 v[68:71], v[196:199], v[172:175], v[68:71]
	v_mfma_f32_16x16x32_bf16 v[64:67], v[204:207], v[172:175], v[64:67]
	s_barrier
	s_setprio 0
	s_add_i32 s27, s55, s35
	s_mov_b32 m0, s27
	s_nop 0
	global_load_lds_dwordx4 v180, s[98:99]
	s_add_i32 m0, s27, 0x2000
	s_nop 0
	global_load_lds_dwordx4 v176, s[98:99]
	s_mov_b32 m0, s44
	ds_read_b128 v[144:147], v215 offset:49152
	ds_read_b128 v[148:151], v215 offset:50176
	ds_read_b128 v[152:155], v215 offset:51200
	ds_read_b128 v[156:159], v215 offset:52224
	ds_read_b128 v[160:163], v215 offset:53248
	ds_read_b128 v[164:167], v215 offset:54272
	ds_read_b128 v[168:171], v215 offset:55296
	ds_read_b128 v[172:175], v215 offset:56320
	global_load_lds_dwordx4 v182, s[100:101]
	s_mov_b32 m0, s45
	s_nop 0
	global_load_lds_dwordx4 v178, s[100:101]
	s_add_u32 s24, s24, 0x80080
	s_addc_u32 s25, s25, 0
	s_add_i32 s26, s26, s35
	s_mov_b32 m0, s26
	s_nop 0
	global_load_lds_dwordx4 v180, s[24:25]
	s_add_i32 m0, s26, 0x2000
	s_nop 0
	global_load_lds_dwordx4 v176, s[24:25]
	s_add_i32 s54, s54, 2
	s_add_u32 s22, s22, 0x100
	s_addc_u32 s23, s23, 0
	s_add_u32 s52, s52, 0x100
	s_addc_u32 s53, s53, 0
	s_cmp_gt_u32 s54, 29
	s_waitcnt vmcnt(8)
	s_waitcnt lgkmcnt(0)
	s_setprio 1
	s_barrier
	v_mfma_f32_16x16x32_bf16 v[60:63], v[128:131], v[144:147], v[60:63]
	v_mfma_f32_16x16x32_bf16 v[56:59], v[136:139], v[144:147], v[56:59]
	v_mfma_f32_16x16x32_bf16 v[44:47], v[128:131], v[152:155], v[44:47]
	v_mfma_f32_16x16x32_bf16 v[40:43], v[136:139], v[152:155], v[40:43]
	v_mfma_f32_16x16x32_bf16 v[28:31], v[128:131], v[160:163], v[28:31]
	v_mfma_f32_16x16x32_bf16 v[24:27], v[136:139], v[160:163], v[24:27]
	v_mfma_f32_16x16x32_bf16 v[12:15], v[128:131], v[168:171], v[12:15]
	v_mfma_f32_16x16x32_bf16 v[8:11], v[136:139], v[168:171], v[8:11]
	v_mfma_f32_16x16x32_bf16 v[60:63], v[132:135], v[148:151], v[60:63]
	v_mfma_f32_16x16x32_bf16 v[56:59], v[140:143], v[148:151], v[56:59]
	v_mfma_f32_16x16x32_bf16 v[44:47], v[132:135], v[156:159], v[44:47]
	v_mfma_f32_16x16x32_bf16 v[40:43], v[140:143], v[156:159], v[40:43]
	v_mfma_f32_16x16x32_bf16 v[28:31], v[132:135], v[164:167], v[28:31]
	v_mfma_f32_16x16x32_bf16 v[24:27], v[140:143], v[164:167], v[24:27]
	v_mfma_f32_16x16x32_bf16 v[12:15], v[132:135], v[172:175], v[12:15]
	v_mfma_f32_16x16x32_bf16 v[8:11], v[140:143], v[172:175], v[8:11]
	v_mfma_f32_16x16x32_bf16 v[52:55], v[192:195], v[144:147], v[52:55]
	v_mfma_f32_16x16x32_bf16 v[48:51], v[200:203], v[144:147], v[48:51]
	v_mfma_f32_16x16x32_bf16 v[36:39], v[192:195], v[152:155], v[36:39]
	v_mfma_f32_16x16x32_bf16 v[32:35], v[200:203], v[152:155], v[32:35]
	v_mfma_f32_16x16x32_bf16 v[20:23], v[192:195], v[160:163], v[20:23]
	v_mfma_f32_16x16x32_bf16 v[16:19], v[200:203], v[160:163], v[16:19]
	v_mfma_f32_16x16x32_bf16 v[4:7], v[192:195], v[168:171], v[4:7]
	v_mfma_f32_16x16x32_bf16 v[0:3], v[200:203], v[168:171], v[0:3]
	v_mfma_f32_16x16x32_bf16 v[52:55], v[196:199], v[148:151], v[52:55]
	v_mfma_f32_16x16x32_bf16 v[48:51], v[204:207], v[148:151], v[48:51]
	v_mfma_f32_16x16x32_bf16 v[36:39], v[196:199], v[156:159], v[36:39]
	v_mfma_f32_16x16x32_bf16 v[32:35], v[204:207], v[156:159], v[32:35]
	v_mfma_f32_16x16x32_bf16 v[20:23], v[196:199], v[164:167], v[20:23]
	v_mfma_f32_16x16x32_bf16 v[16:19], v[204:207], v[164:167], v[16:19]
	v_mfma_f32_16x16x32_bf16 v[4:7], v[196:199], v[172:175], v[4:7]
	v_mfma_f32_16x16x32_bf16 v[0:3], v[204:207], v[172:175], v[0:3]
	s_barrier
; DI unsigned pack2(float lo, float hi) { f32x2 v = {lo, hi}; bf16v2 r = __builtin_convertvector(v, bf16v2); return __builtin_bit_cast(unsigned, r); }
;   DI void operator()(const f32x4 (&acc)[2][2][4][2], const Unit& u, int wr, int wc, int fr, int fq) const {
;     const int row0 = u.pm * BM + wr * 64 + fr, col0 = u.pn * BM + wc * 32 + 8 * fq;
; #pragma unroll
;     for (int ai = 0; ai < 2; ++ai) {
;       f32x4 bv[4][2][2];
; #pragma unroll
;       for (int m = 0; m < 4; ++m)
; #pragma unroll
;         for (int bj = 0; bj < 2; ++bj) {
;           const float* bp = base + (size_t)(row0 + ai * HALF + m * 16) * 2048 + col0 + bj * HALF;
;           bv[m][bj][0] = *(const f32x4*)bp; bv[m][bj][1] = *(const f32x4*)(bp + 4);
;         }
; #pragma unroll
;       for (int m = 0; m < 4; ++m) {
;         const int row = row0 + ai * HALF + m * 16;
;         const size_t off = (size_t)row * 2048 + col0;
;         float ss = 0.f;
; #pragma unroll
;         for (int bj = 0; bj < 2; ++bj) {
;           const f32x4 v0 = acc[ai][bj][m][0] + bv[m][bj][0], v1 = acc[ai][bj][m][1] + bv[m][bj][1];
;           *(f32x4*)(C + off + bj * HALF) = v0; *(f32x4*)(C + off + bj * HALF + 4) = v1;
;           if (xb) {
;             u32x4 w; w.x = pack2(v0[0], v0[1]); w.y = pack2(v0[2], v0[3]); w.z = pack2(v1[0], v1[1]); w.w = pack2(v1[2], v1[3]);
;             *(u32x4*)(xb + off + bj * HALF) = w;
;             ss += v0[0] * v0[0] + v0[1] * v0[1] + v0[2] * v0[2] + v0[3] * v0[3] + v1[0] * v1[0] + v1[1] * v1[1] + v1[2] * v1[2] + v1[3] * v1[3];
;           }
;         }
;         if (xb) {
;           ss += __shfl_xor(ss, 16); ss += __shfl_xor(ss, 32);
;           if (fq == 0) ssq[(size_t)row * 32 + u.pn * 4 + wc] = ss;
;         }
;       }
; template <class Epi, class Sched = StaticOrder>
; DI void gemm_phase(LAS unsigned char* lds, const Gemm g, const Sched& S, const Epi& E) {
;     ...
;     E(acc, cur, wr, wc, fr, fq);
	s_setprio 0
	s_cbranch_scc0 .LBB0_1194
	v_lshl_add_u32 v194, s12, 8, v211
	v_lshl_or_b32 v192, s42, 8, v213
	v_readlane_b32 s52, v243, 3
	v_ashrrev_i32_e32 v193, 31, v192
	v_readlane_b32 s66, v243, 17
	v_readlane_b32 s67, v243, 18
	v_ashrrev_i32_e32 v195, 31, v194
	v_lshlrev_b64 v[128:129], 13, v[194:195]
	v_lshl_add_u64 v[196:197], v[192:193], 2, s[66:67]
	v_lshl_add_u64 v[236:237], v[196:197], 0, v[128:129]
	global_load_dwordx4 v[220:223], v[236:237], off
	global_load_dwordx4 v[224:227], v[236:237], off offset:16
	global_load_dwordx4 v[228:231], v[236:237], off offset:512
	global_load_dwordx4 v[232:235], v[236:237], off offset:528
	v_or_b32_e32 v206, 16, v194
	v_or_b32_e32 v202, 32, v194
	v_or_b32_e32 v198, 48, v194
	v_ashrrev_i32_e32 v207, 31, v206
	v_ashrrev_i32_e32 v203, 31, v202
	v_ashrrev_i32_e32 v199, 31, v198
	v_lshlrev_b64 v[128:129], 13, v[206:207]
	v_lshlrev_b64 v[130:131], 13, v[202:203]
	v_lshlrev_b64 v[132:133], 13, v[198:199]
	v_lshl_add_u64 v[208:209], v[196:197], 0, v[128:129]
	v_lshl_add_u64 v[204:205], v[196:197], 0, v[130:131]
	v_lshl_add_u64 v[200:201], v[196:197], 0, v[132:133]
	global_load_dwordx4 v[168:171], v[208:209], off offset:16
	global_load_dwordx4 v[172:175], v[208:209], off
	global_load_dwordx4 v[160:163], v[208:209], off offset:528
	global_load_dwordx4 v[164:167], v[208:209], off offset:512
	global_load_dwordx4 v[152:155], v[204:205], off offset:16
	global_load_dwordx4 v[156:159], v[204:205], off
	global_load_dwordx4 v[144:147], v[204:205], off offset:528
	global_load_dwordx4 v[148:151], v[204:205], off offset:512
	global_load_dwordx4 v[136:139], v[200:201], off offset:16
	global_load_dwordx4 v[140:143], v[200:201], off
	global_load_dwordx4 v[128:131], v[200:201], off offset:528
	global_load_dwordx4 v[132:135], v[200:201], off offset:512
	v_and_b32_e32 v218, 64, v217
	v_xor_b32_e32 v238, 16, v217
	v_add_u32_e32 v240, 64, v218
	v_xor_b32_e32 v239, 32, v217
	v_cmp_lt_i32_e32 vcc, v238, v240
	v_lshlrev_b64 v[218:219], 11, v[194:195]
	s_lshl_b32 s22, s42, 2
	v_cndmask_b32_e32 v241, v217, v238, vcc
	v_cmp_lt_i32_e32 vcc, v239, v240
	s_ashr_i32 s23, s22, 31
	v_readlane_b32 s53, v243, 4
	v_cndmask_b32_e32 v240, v217, v239, vcc
	v_lshl_add_u64 v[238:239], v[218:219], 0, v[192:193]
	v_lshlrev_b32_e32 v218, 2, v241
	v_lshl_add_u64 v[238:239], v[238:239], 1, s[2:3]
	v_readlane_b32 s54, v243, 5
	v_readlane_b32 s55, v243, 6
	v_readlane_b32 s56, v243, 7
	v_readlane_b32 s57, v243, 8
	v_readlane_b32 s58, v243, 9
	v_readlane_b32 s59, v243, 10
	v_readlane_b32 s60, v243, 11
	v_readlane_b32 s61, v243, 12
	v_readlane_b32 s62, v243, 13
	v_readlane_b32 s63, v243, 14
	v_readlane_b32 s64, v243, 15
	v_readlane_b32 s65, v243, 16
	s_waitcnt vmcnt(0)
	v_pk_add_f32 v[126:127], v[126:127], v[222:223]
	v_pk_add_f32 v[124:125], v[124:125], v[220:221]
	v_pk_add_f32 v[116:117], v[116:117], v[228:229]
	v_pk_add_f32 v[122:123], v[122:123], v[226:227]
	v_pk_add_f32 v[120:121], v[120:121], v[224:225]
	v_pk_add_f32 v[220:221], v[112:113], v[232:233]
	global_store_dwordx4 v[236:237], v[124:127], off
	global_store_dwordx4 v[236:237], v[120:123], off offset:16
	v_cvt_pk_bf16_f32 v112, v124, v125
	v_mul_f32_e32 v125, v125, v125
	v_mul_f32_e32 v219, v117, v117
	v_pk_add_f32 v[118:119], v[118:119], v[230:231]
	v_fmac_f32_e32 v125, v124, v124
	v_fmac_f32_e32 v219, v116, v116
	v_fmac_f32_e32 v125, v126, v126
	v_fmac_f32_e32 v219, v118, v118
	v_fmac_f32_e32 v125, v127, v127
	v_fmac_f32_e32 v219, v119, v119
	v_fmac_f32_e32 v125, v120, v120
	v_fmac_f32_e32 v219, v220, v220
	v_pk_add_f32 v[222:223], v[114:115], v[234:235]
	v_fmac_f32_e32 v125, v121, v121
	v_fmac_f32_e32 v219, v221, v221
	v_fmac_f32_e32 v125, v122, v122
	v_fmac_f32_e32 v219, v222, v222
	v_fmac_f32_e32 v125, v123, v123
	v_fmac_f32_e32 v219, v223, v223
	v_cvt_pk_bf16_f32 v114, v120, v121
	v_add_f32_e32 v121, v125, v219
	v_cvt_pk_bf16_f32 v115, v122, v123
	ds_bpermute_b32 v122, v218, v121
	v_cvt_pk_bf16_f32 v113, v126, v127
	global_store_dwordx4 v[238:239], v[112:115], off
	global_store_dwordx4 v[236:237], v[116:119], off offset:512
	global_store_dwordx4 v[236:237], v[220:223], off offset:528
	v_lshlrev_b32_e32 v126, 2, v240
	v_cvt_pk_bf16_f32 v120, v116, v117
	s_waitcnt lgkmcnt(0)
	v_add_f32_e32 v112, v121, v122
	ds_bpermute_b32 v113, v126, v112
	v_cvt_pk_bf16_f32 v121, v118, v119
	v_cvt_pk_bf16_f32 v122, v220, v221
	v_cvt_pk_bf16_f32 v123, v222, v223
	global_store_dwordx4 v[238:239], v[120:123], off offset:256
	s_and_saveexec_b64 s[24:25], s[0:1]
	s_cbranch_execz .LBB0_1197
	s_waitcnt lgkmcnt(0)
	v_add_f32_e32 v114, v112, v113
	v_lshlrev_b64 v[112:113], 7, v[194:195]
	v_lshl_add_u64 v[112:113], s[8:9], 0, v[112:113]
	v_lshl_add_u64 v[112:113], s[22:23], 2, v[112:113]
	s_lshl_b32 s12, s41, 2
	v_lshl_add_u64 v[112:113], v[112:113], 0, s[12:13]
	global_store_dword v[112:113], v114, off

; #define PG8_STAGE(bufoff, gbase, voff) do { _Pragma("unroll") for (int _i = 0; _i < 2; ++_i) \
;     __builtin_amdgcn_global_load_lds((const unsigned*)((const char*)(gbase) + (voff)[_i]), (LAS unsigned*)(lds + (bufoff) + ldsw + _i * 8192), 16, 0, 0); } while (0)
; #define PG8_WAIT_V(n) asm volatile("s_waitcnt vmcnt(" #n ")" ::: "memory")
; #define PG8_BAR __builtin_amdgcn_s_barrier()
; template <class Epi, class Sched = StaticOrder>
; DI void gemm_phase(LAS unsigned char* lds, const Gemm g, const Sched& S, const Epi& E) {
;     ...
;   for (int i = 0; i < 2; ++i) { int R, C; stage_rc(tid * 16 + i * 8192, R, C); const int Rb = Epi::PERM ? ((R & ~31) + perm32(R & 31)) : R;
;     voffA[i] = (unsigned)(R * K + C) * 2u; voffB[i] = (unsigned)(Rb * K + C) * 2u; }
;   const size_t kstep = (size_t)(BK * 2);
;   const size_t hstep = (size_t)HALF * K * 2;
;   const size_t tstep = 2 * hstep;
;   const unsigned ldsw = (unsigned)wid * 1024u;
;   const int aoff = lds_byte(wr * 64 + fr, fq * 8), boff = lds_byte(wc * 32 + fr, fq * 8);
;     ...
;   Unit cur, nxt; int ui = 0;
;   if (!S.next(0, cur)) return;
;   f32x4 acc[2][2][4][2];
; #pragma unroll
;   for (int a = 0; a < 2; ++a)
; #pragma unroll
;     for (int b = 0; b < 2; ++b)
; #pragma unroll
;       for (int m = 0; m < 4; ++m)
; #pragma unroll
;         for (int n = 0; n < 2; ++n) acc[a][b][m][n] = (f32x4){0.f, 0.f, 0.f, 0.f};
;   bf16x8 At[4][2], B0[2][2], B1[2][2];
;   const char* cA = (const char*)g.A + (size_t)cur.pm * tstep; const char* cB = (const char*)g.Bt + (size_t)cur.pn * tstep;
;   PG8_STAGE(PG8_SB(0, 0), cB, voffB); PG8_STAGE(PG8_SA(0, 0), cA, voffA); PG8_STAGE(PG8_SB(0, 1), cB + hstep, voffB); PG8_STAGE(PG8_SA(0, 1), cA + hstep, voffA);
;   if (wr == 1) PG8_BAR;
;   PG8_WAIT_V(4); PG8_BAR;
;   PG8_STAGE(PG8_SB(1, 0), cB + kstep, voffB); PG8_STAGE(PG8_SA(1, 0), cA + kstep, voffA); PG8_STAGE(PG8_SB(1, 1), cB + hstep + kstep, voffB);
;   PG8_WAIT_V(6); PG8_BAR;
.LBB0_1272:
	v_readlane_b32 s16, v243, 3
	v_readlane_b32 s17, v243, 4
	v_readlane_b32 s18, v243, 5
	v_readlane_b32 s19, v243, 6
	v_readlane_b32 s24, v243, 11
	v_readlane_b32 s25, v243, 12
	v_readlane_b32 s26, v243, 13
	v_readlane_b32 s27, v243, 14
	s_mov_b64 s[16:17], s[24:25]
	s_add_u32 s16, s16, 0x10800
	s_mov_b64 s[18:19], s[26:27]
	s_addc_u32 s17, s17, 0
	s_add_u32 s18, s18, 0x5800
	v_readlane_b32 s20, v243, 7
	s_addc_u32 s19, s19, 0
	v_readlane_b32 s21, v243, 8
	s_add_u32 s20, s84, 0x10903600
	v_readlane_b32 s22, v243, 9
	s_addc_u32 s21, s85, 0
	v_readlane_b32 s23, v243, 10
	s_add_u32 s22, s84, 0x1b903600
	s_addc_u32 s23, s85, 0
	s_add_u32 s24, s84, 0x1c403600
	s_addc_u32 s25, s85, 0
	v_readlane_b32 s28, v243, 15
	v_readlane_b32 s29, v243, 16
	s_add_u32 s26, s84, 0x1cf03600
	s_addc_u32 s27, s85, 0
	s_lshl_b32 s1, s1, 5
	s_mov_b64 s[28:29], 0x80
	s_and_b32 s34, s1, 0x60
	s_add_i32 m0, s64, 0x18000
	v_lshl_add_u64 v[6:7], v[6:7], 0, s[28:29]
	s_lshl_b32 s54, s4, 6
	s_lshl_b32 s6, s4, 13
	s_lshl_b32 s1, s34, 7
	s_waitcnt vmcnt(2)
	s_barrier
	global_load_lds_dwordx4 v[6:7], off
	v_lshl_add_u64 v[4:5], v[4:5], 0, s[28:29]
	s_add_i32 m0, s64, 0x1a000
	s_add_i32 s55, s64, 0x8000
	s_add_i32 s68, s64, 0xa000
	global_load_lds_dwordx4 v[4:5], off
	v_lshl_add_u64 v[2:3], v[2:3], 0, s[28:29]
	s_mov_b32 m0, s55
	s_add_u32 s4, s48, 0x80080
	global_load_lds_dwordx4 v[2:3], off
	v_lshl_add_u64 v[0:1], v[0:1], 0, s[28:29]
	s_mov_b32 m0, s68
	s_addc_u32 s5, s49, 0
	global_load_lds_dwordx4 v[0:1], off
	s_add_i32 m0, s64, 0x1c000
	v_lshl_add_u64 v[0:1], s[4:5], 0, v[164:165]
	global_load_lds_dwordx4 v[0:1], off
	v_lshl_add_u64 v[0:1], s[4:5], 0, v[160:161]
	s_add_i32 m0, s64, 0x1e000
	v_and_b32_e32 v179, 15, v210
	global_load_lds_dwordx4 v[0:1], off
	v_lshlrev_b32_e32 v0, 1, v11
	v_lshlrev_b32_e32 v2, 2, v210
	v_lshl_or_b32 v1, v179, 6, v0
	v_and_b32_e32 v2, 32, v2
	s_sext_i32_i16 s13, s0
	v_bitop3_b32 v3, v1, s6, v2 bitop3:0xde
	v_lshlrev_b32_e32 v1, 6, v210
	s_movk_i32 s0, 0x3c0
	v_and_or_b32 v0, v1, s0, v0
	v_bitop3_b32 v198, s1, v0, v2 bitop3:0xf6
	v_lshlrev_b32_e32 v0, 2, v11
	v_mov_b32_e32 v1, v165
	v_lshl_add_u64 v[0:1], s[84:85], 0, v[0:1]
	s_mov_b64 s[8:9], 0x10703600
	v_lshl_add_u64 v[168:169], v[0:1], 0, s[8:9]
	v_lshlrev_b32_e32 v0, 9, v210
	v_and_b32_e32 v0, 0x70000, v0
	v_lshlrev_b32_e32 v1, 12, v12
	v_or3_b32 v0, v9, v0, v1
	v_add_u32_e32 v170, v0, v10
	v_lshlrev_b32_e32 v0, 5, v8
	v_and_b32_e32 v0, 0xf0000, v0
	s_waitcnt vmcnt(6)
	v_or3_b32 v0, v9, v0, v1
	v_readlane_b32 s30, v243, 17
	v_readlane_b32 s31, v243, 18
	v_add_u32_e32 v172, v0, v10
	s_add_i32 s72, 0, 0x10000
	s_add_i32 s73, 0, 0x14000
	v_mbcnt_lo_u32_b32 v0, -1, 0
	s_mov_b64 s[30:31], 0x5800
	s_mov_b32 s69, 0
	v_cmp_eq_u32_e64 s[0:1], 0, v179
	v_cmp_lt_u32_e64 s[10:11], 1, v179
	v_cmp_gt_u32_e64 s[4:5], 2, v179
	v_cmp_lt_u32_e64 s[6:7], 13, v179
	v_add_u32_e32 v199, -14, v179
	s_ashr_i32 s70, s96, 31
	s_mov_b32 s71, s96
	v_or_b32_e32 v200, s34, v11
	v_mov_b32_e32 v171, v165
	v_mov_b32_e32 v173, v165
	v_mov_b64_e32 v[174:175], 0xb00
	v_mov_b64_e32 v[176:177], 0xaff
	v_add_u32_e32 v201, s72, v198
	v_add_u32_e32 v202, 0, v3
	v_add_u32_e32 v203, s73, v198
	s_mov_b64 s[34:35], 0xb000
	s_mov_b32 s36, 0x3a000000
	s_mov_b32 s74, 0x800000
	s_movk_i32 s75, 0x2c00
	s_movk_i32 s76, 0x5800
	v_mbcnt_hi_u32_b32 v204, -1, v0
	v_mov_b32_e32 v178, 0x358637bd
	s_barrier
	s_branch .LBB0_1274

; #define PG8_STAGE(bufoff, gbase, voff) do { _Pragma("unroll") for (int _i = 0; _i < 2; ++_i) \
;     __builtin_amdgcn_global_load_lds((const unsigned*)((const char*)(gbase) + (voff)[_i]), (LAS unsigned*)(lds + (bufoff) + ldsw + _i * 8192), 16, 0, 0); } while (0)
; #define PG8_LDA(dst, b, h) do { _Pragma("unroll") for (int m = 0; m < 4; ++m) _Pragma("unroll") for (int k = 0; k < 2; ++k) dst[m][k] = *(const LAS bf16x8*)(lds + PG8_SA(b, h) + aoff + m * 2048 + k * 1024); } while (0)
; #define PG8_LDB(dst, b, h) do { _Pragma("unroll") for (int n = 0; n < 2; ++n) _Pragma("unroll") for (int k = 0; k < 2; ++k) dst[n][k] = *(const LAS bf16x8*)(lds + PG8_SB(b, h) + boff + n * 2048 + k * 1024); } while (0)
; #define PG8_MMA(ai, bj, At, Bt) do { __builtin_amdgcn_s_setprio(1); _Pragma("unroll") for (int m = 0; m < 4; ++m) _Pragma("unroll") for (int n = 0; n < 2; ++n) _Pragma("unroll") for (int k = 0; k < 2; ++k) \
;     acc[ai][bj][m][n] = __builtin_amdgcn_mfma_f32_16x16x32_bf16(Bt[n][k], At[m][k], acc[ai][bj][m][n], 0, 0, 0); __builtin_amdgcn_s_setprio(0); } while (0)
; #define PG8_WAIT_V(n) asm volatile("s_waitcnt vmcnt(" #n ")" ::: "memory")
; #define PG8_WAIT_L(n) asm volatile("s_waitcnt lgkmcnt(" #n ")" ::: "memory")
; #define PG8_BAR __builtin_amdgcn_s_barrier()
; #define PG8_SCHED __builtin_amdgcn_sched_barrier(0)
; template <class Epi, class Sched = StaticOrder>
; DI void gemm_phase(LAS unsigned char* lds, const Gemm g, const Sched& S, const Epi& E) {
;     ...
;     for (int t = 0; t < nt; t += 2) {
;       const bool last = (t == nt - 2);
;       const char* a1 = cA + (size_t)(t + 1) * kstep;
;       const char* a2 = last ? nA : cA + (size_t)(t + 2) * kstep; const char* b2 = last ? nB : cB + (size_t)(t + 2) * kstep;
;       const char* a3 = a2 + kstep; const char* b3 = b2 + kstep;
;       PG8_LDB(B0, 0, 0); PG8_SCHED; PG8_LDA(At, 0, 0); PG8_STAGE(PG8_SA(1, 1), a1 + hstep, voffA);
;       PG8_WAIT_L(8); PG8_BAR; PG8_WAIT_L(0); PG8_MMA(0, 0, At, B0); PG8_BAR; PG8_SCHED;
;       PG8_LDB(B1, 0, 1); PG8_STAGE(PG8_SB(0, 0), b2, voffB);
;       PG8_BAR; PG8_WAIT_L(0); PG8_MMA(0, 1, At, B1); PG8_BAR;
;       PG8_LDA(At, 0, 1); PG8_STAGE(PG8_SA(0, 0), a2, voffA);
;       PG8_BAR; PG8_WAIT_L(0); PG8_MMA(1, 0, At, B0); PG8_BAR; PG8_SCHED;
;       PG8_STAGE(PG8_SB(0, 1), b2 + hstep, voffB);
;       PG8_WAIT_V(6); PG8_BAR; PG8_MMA(1, 1, At, B1); PG8_BAR;
.LBB0_1277:
	ds_read_b128 v[64:67], v201
	ds_read_b128 v[68:71], v201 offset:1024
	ds_read_b128 v[72:75], v201 offset:2048
	ds_read_b128 v[76:79], v201 offset:3072
	s_add_u32 s48, s14, 0xfff80080
	s_addc_u32 s49, s15, -1
	s_cmp_eq_u32 s58, 28
	s_cselect_b32 s51, s41, s49
	s_cselect_b32 s50, s42, s48
	s_cselect_b32 s49, s39, s53
	s_cselect_b32 s48, s43, s52
	s_add_i32 m0, s64, 0xc000
	ds_read_b128 v[80:83], v202
	ds_read_b128 v[84:87], v202 offset:1024
	ds_read_b128 v[88:91], v202 offset:2048
	ds_read_b128 v[92:95], v202 offset:3072
	ds_read_b128 v[180:183], v202 offset:4096
	ds_read_b128 v[184:187], v202 offset:5120
	ds_read_b128 v[188:191], v202 offset:6144
	ds_read_b128 v[192:195], v202 offset:7168
	global_load_lds_dwordx4 v170, s[14:15]
	s_add_i32 m0, s64, 0xe000
	s_nop 0
	global_load_lds_dwordx4 v172, s[14:15]
	ds_read_b128 v[206:209], v203
	ds_read_b128 v[212:215], v203 offset:1024
	ds_read_b128 v[216:219], v203 offset:2048
	ds_read_b128 v[220:223], v203 offset:3072
	s_waitcnt vmcnt(8)
	s_waitcnt lgkmcnt(0)
	s_setprio 1
	s_barrier
	v_mfma_f32_16x16x32_bf16 v[156:159], v[64:67], v[80:83], v[156:159]
	v_mfma_f32_16x16x32_bf16 v[144:147], v[72:75], v[80:83], v[144:147]
	v_mfma_f32_16x16x32_bf16 v[140:143], v[64:67], v[88:91], v[140:143]
	v_mfma_f32_16x16x32_bf16 v[132:135], v[72:75], v[88:91], v[132:135]
	v_mfma_f32_16x16x32_bf16 v[124:127], v[64:67], v[180:183], v[124:127]
	v_mfma_f32_16x16x32_bf16 v[116:119], v[72:75], v[180:183], v[116:119]
	v_mfma_f32_16x16x32_bf16 v[112:115], v[64:67], v[188:191], v[112:115]
	v_mfma_f32_16x16x32_bf16 v[108:111], v[72:75], v[188:191], v[108:111]
	v_mfma_f32_16x16x32_bf16 v[156:159], v[68:71], v[84:87], v[156:159]
	v_mfma_f32_16x16x32_bf16 v[144:147], v[76:79], v[84:87], v[144:147]
	v_mfma_f32_16x16x32_bf16 v[140:143], v[68:71], v[92:95], v[140:143]
	v_mfma_f32_16x16x32_bf16 v[132:135], v[76:79], v[92:95], v[132:135]
	v_mfma_f32_16x16x32_bf16 v[124:127], v[68:71], v[184:187], v[124:127]
	v_mfma_f32_16x16x32_bf16 v[116:119], v[76:79], v[184:187], v[116:119]
	v_mfma_f32_16x16x32_bf16 v[112:115], v[68:71], v[192:195], v[112:115]
	v_mfma_f32_16x16x32_bf16 v[108:111], v[76:79], v[192:195], v[108:111]
	v_mfma_f32_16x16x32_bf16 v[152:155], v[206:209], v[80:83], v[152:155]
	v_mfma_f32_16x16x32_bf16 v[80:83], v[216:219], v[80:83], v[148:151]
	v_mfma_f32_16x16x32_bf16 v[152:155], v[212:215], v[84:87], v[152:155]
	v_mfma_f32_16x16x32_bf16 v[80:83], v[220:223], v[84:87], v[80:83]
	v_mfma_f32_16x16x32_bf16 v[84:87], v[206:209], v[88:91], v[136:139]
	v_mfma_f32_16x16x32_bf16 v[88:91], v[216:219], v[88:91], v[128:131]
	v_mfma_f32_16x16x32_bf16 v[104:107], v[216:219], v[180:183], v[104:107]
	v_mfma_f32_16x16x32_bf16 v[100:103], v[206:209], v[188:191], v[100:103]
	v_mfma_f32_16x16x32_bf16 v[96:99], v[216:219], v[188:191], v[96:99]
	v_mfma_f32_16x16x32_bf16 v[84:87], v[212:215], v[92:95], v[84:87]
	v_mfma_f32_16x16x32_bf16 v[88:91], v[220:223], v[92:95], v[88:91]
	v_mfma_f32_16x16x32_bf16 v[92:95], v[206:209], v[180:183], v[120:123]
	v_mfma_f32_16x16x32_bf16 v[104:107], v[220:223], v[184:187], v[104:107]
	v_mfma_f32_16x16x32_bf16 v[100:103], v[212:215], v[192:195], v[100:103]
	v_mfma_f32_16x16x32_bf16 v[96:99], v[220:223], v[192:195], v[96:99]
	v_mfma_f32_16x16x32_bf16 v[92:95], v[212:215], v[184:187], v[92:95]
	s_barrier
	s_setprio 0
	s_add_i32 s59, s72, s62
	s_add_u32 s98, s48, 0x80
	s_addc_u32 s99, s49, 0
	s_add_u32 s100, s50, 0x80
	s_addc_u32 s101, s51, 0
	s_mov_b32 m0, s59
	s_nop 0
	global_load_lds_dwordx4 v164, s[48:49]
	s_add_i32 m0, s59, 0x2000
	s_nop 0
	global_load_lds_dwordx4 v160, s[48:49]
	s_mov_b32 m0, s64
	ds_read_b128 v[120:123], v202 offset:16384
	ds_read_b128 v[128:131], v202 offset:17408
	ds_read_b128 v[136:139], v202 offset:18432
	ds_read_b128 v[148:151], v202 offset:19456
	ds_read_b128 v[180:183], v202 offset:20480
	ds_read_b128 v[184:187], v202 offset:21504
	ds_read_b128 v[188:191], v202 offset:22528
	ds_read_b128 v[192:195], v202 offset:23552
	global_load_lds_dwordx4 v166, s[50:51]
	s_mov_b32 m0, s65
	s_nop 0
	global_load_lds_dwordx4 v162, s[50:51]
	s_add_u32 s78, s48, 0x80000
	s_addc_u32 s79, s49, 0
	s_add_i32 s59, s73, s62
	s_mov_b32 m0, s59
	s_nop 0
	global_load_lds_dwordx4 v164, s[78:79]
	s_add_i32 m0, s59, 0x2000
	s_nop 0
	global_load_lds_dwordx4 v160, s[78:79]
	s_waitcnt vmcnt(8)
	s_waitcnt lgkmcnt(0)
	s_setprio 1
	s_barrier
	v_mfma_f32_16x16x32_bf16 v[60:63], v[64:67], v[120:123], v[60:63]
	v_mfma_f32_16x16x32_bf16 v[48:51], v[72:75], v[120:123], v[48:51]
	v_mfma_f32_16x16x32_bf16 v[44:47], v[64:67], v[136:139], v[44:47]
	v_mfma_f32_16x16x32_bf16 v[36:39], v[72:75], v[136:139], v[36:39]
	v_mfma_f32_16x16x32_bf16 v[28:31], v[64:67], v[180:183], v[28:31]
	v_mfma_f32_16x16x32_bf16 v[20:23], v[72:75], v[180:183], v[20:23]
	v_mfma_f32_16x16x32_bf16 v[16:19], v[64:67], v[188:191], v[16:19]
	v_mfma_f32_16x16x32_bf16 v[12:15], v[72:75], v[188:191], v[12:15]
	v_mfma_f32_16x16x32_bf16 v[60:63], v[68:71], v[128:131], v[60:63]
	v_mfma_f32_16x16x32_bf16 v[48:51], v[76:79], v[128:131], v[48:51]
	v_mfma_f32_16x16x32_bf16 v[44:47], v[68:71], v[148:151], v[44:47]
	v_mfma_f32_16x16x32_bf16 v[36:39], v[76:79], v[148:151], v[36:39]
	v_mfma_f32_16x16x32_bf16 v[28:31], v[68:71], v[184:187], v[28:31]
	v_mfma_f32_16x16x32_bf16 v[20:23], v[76:79], v[184:187], v[20:23]
	v_mfma_f32_16x16x32_bf16 v[16:19], v[68:71], v[192:195], v[16:19]
	v_mfma_f32_16x16x32_bf16 v[12:15], v[76:79], v[192:195], v[12:15]
	v_mfma_f32_16x16x32_bf16 v[56:59], v[206:209], v[120:123], v[56:59]
	v_mfma_f32_16x16x32_bf16 v[52:55], v[216:219], v[120:123], v[52:55]
	v_mfma_f32_16x16x32_bf16 v[40:43], v[206:209], v[136:139], v[40:43]
	v_mfma_f32_16x16x32_bf16 v[32:35], v[216:219], v[136:139], v[32:35]
	v_mfma_f32_16x16x32_bf16 v[24:27], v[206:209], v[180:183], v[24:27]
	v_mfma_f32_16x16x32_bf16 v[8:11], v[216:219], v[180:183], v[8:11]
	v_mfma_f32_16x16x32_bf16 v[4:7], v[206:209], v[188:191], v[4:7]
	v_mfma_f32_16x16x32_bf16 v[0:3], v[216:219], v[188:191], v[0:3]
	v_mfma_f32_16x16x32_bf16 v[56:59], v[212:215], v[128:131], v[56:59]
	v_mfma_f32_16x16x32_bf16 v[52:55], v[220:223], v[128:131], v[52:55]
	v_mfma_f32_16x16x32_bf16 v[40:43], v[212:215], v[148:151], v[40:43]
	v_mfma_f32_16x16x32_bf16 v[32:35], v[220:223], v[148:151], v[32:35]
	v_mfma_f32_16x16x32_bf16 v[24:27], v[212:215], v[184:187], v[24:27]
	v_mfma_f32_16x16x32_bf16 v[8:11], v[220:223], v[184:187], v[8:11]
	v_mfma_f32_16x16x32_bf16 v[4:7], v[212:215], v[192:195], v[4:7]
	v_mfma_f32_16x16x32_bf16 v[0:3], v[220:223], v[192:195], v[0:3]
	s_barrier
; #define PG8_STAGE(bufoff, gbase, voff) do { _Pragma("unroll") for (int _i = 0; _i < 2; ++_i) \
;     __builtin_amdgcn_global_load_lds((const unsigned*)((const char*)(gbase) + (voff)[_i]), (LAS unsigned*)(lds + (bufoff) + ldsw + _i * 8192), 16, 0, 0); } while (0)
; #define PG8_LDA(dst, b, h) do { _Pragma("unroll") for (int m = 0; m < 4; ++m) _Pragma("unroll") for (int k = 0; k < 2; ++k) dst[m][k] = *(const LAS bf16x8*)(lds + PG8_SA(b, h) + aoff + m * 2048 + k * 1024); } while (0)
; #define PG8_LDB(dst, b, h) do { _Pragma("unroll") for (int n = 0; n < 2; ++n) _Pragma("unroll") for (int k = 0; k < 2; ++k) dst[n][k] = *(const LAS bf16x8*)(lds + PG8_SB(b, h) + boff + n * 2048 + k * 1024); } while (0)
; #define PG8_MMA(ai, bj, At, Bt) do { __builtin_amdgcn_s_setprio(1); _Pragma("unroll") for (int m = 0; m < 4; ++m) _Pragma("unroll") for (int n = 0; n < 2; ++n) _Pragma("unroll") for (int k = 0; k < 2; ++k) \
;     acc[ai][bj][m][n] = __builtin_amdgcn_mfma_f32_16x16x32_bf16(Bt[n][k], At[m][k], acc[ai][bj][m][n], 0, 0, 0); __builtin_amdgcn_s_setprio(0); } while (0)
; #define PG8_WAIT_V(n) asm volatile("s_waitcnt vmcnt(" #n ")" ::: "memory")
; #define PG8_WAIT_L(n) asm volatile("s_waitcnt lgkmcnt(" #n ")" ::: "memory")
; #define PG8_BAR __builtin_amdgcn_s_barrier()
; #define PG8_SCHED __builtin_amdgcn_sched_barrier(0)
; template <class Epi, class Sched = StaticOrder>
; DI void gemm_phase(LAS unsigned char* lds, const Gemm g, const Sched& S, const Epi& E) {
;     ...
;       PG8_LDB(B0, 1, 0); PG8_SCHED; PG8_LDA(At, 1, 0); PG8_STAGE(PG8_SA(0, 1), a2 + hstep, voffA);
;       PG8_WAIT_L(8); PG8_BAR; PG8_WAIT_L(0); PG8_MMA(0, 0, At, B0); PG8_BAR; PG8_SCHED;
;       PG8_LDB(B1, 1, 1); PG8_STAGE(PG8_SB(1, 0), b3, voffB);
;       PG8_BAR; PG8_WAIT_L(0); PG8_MMA(0, 1, At, B1); PG8_BAR;
;       PG8_LDA(At, 1, 1); PG8_STAGE(PG8_SA(1, 0), a3, voffA);
;       PG8_BAR; PG8_WAIT_L(0); PG8_MMA(1, 0, At, B0); PG8_BAR; PG8_SCHED;
;       PG8_STAGE(PG8_SB(1, 1), b3 + hstep, voffB);
;       PG8_WAIT_V(6); PG8_BAR; PG8_MMA(1, 1, At, B1); PG8_BAR;
	s_setprio 0
	s_add_i32 s59, 0, 0x18000
	v_add_u32_e32 v76, s59, v198
	ds_read_b128 v[64:67], v76
	ds_read_b128 v[68:71], v76 offset:1024
	ds_read_b128 v[72:75], v76 offset:2048
	ds_read_b128 v[76:79], v76 offset:3072
	s_add_u32 s50, s50, 0x80000
	s_addc_u32 s51, s51, 0
	s_mov_b32 m0, s66
	ds_read_b128 v[120:123], v202 offset:32768
	ds_read_b128 v[128:131], v202 offset:33792
	ds_read_b128 v[180:183], v202 offset:34816
	ds_read_b128 v[184:187], v202 offset:35840
	ds_read_b128 v[188:191], v202 offset:36864
	ds_read_b128 v[192:195], v202 offset:37888
	ds_read_b128 v[206:209], v202 offset:38912
	ds_read_b128 v[212:215], v202 offset:39936
	global_load_lds_dwordx4 v166, s[50:51]
	s_mov_b32 m0, s67
	s_nop 0
	global_load_lds_dwordx4 v162, s[50:51]
	s_add_i32 s50, 0, 0x1c000
	v_add_u32_e32 v244, s50, v198
	ds_read_b128 v[216:219], v244
	ds_read_b128 v[220:223], v244 offset:1024
	ds_read_b128 v[224:227], v244 offset:2048
	ds_read_b128 v[228:231], v244 offset:3072
	s_waitcnt vmcnt(8)
	s_waitcnt lgkmcnt(0)
	s_setprio 1
	s_barrier
	v_mfma_f32_16x16x32_bf16 v[136:139], v[64:67], v[120:123], v[156:159]
	v_mfma_f32_16x16x32_bf16 v[156:159], v[68:71], v[128:131], v[136:139]
	v_mfma_f32_16x16x32_bf16 v[136:139], v[72:75], v[120:123], v[144:147]
	v_mfma_f32_16x16x32_bf16 v[144:147], v[76:79], v[128:131], v[136:139]
	v_mfma_f32_16x16x32_bf16 v[136:139], v[64:67], v[180:183], v[140:143]
	v_mfma_f32_16x16x32_bf16 v[132:135], v[72:75], v[180:183], v[132:135]
	v_mfma_f32_16x16x32_bf16 v[124:127], v[64:67], v[188:191], v[124:127]
	v_mfma_f32_16x16x32_bf16 v[116:119], v[72:75], v[188:191], v[116:119]
	v_mfma_f32_16x16x32_bf16 v[112:115], v[64:67], v[206:209], v[112:115]
	v_mfma_f32_16x16x32_bf16 v[108:111], v[72:75], v[206:209], v[108:111]
	v_mfma_f32_16x16x32_bf16 v[140:143], v[68:71], v[184:187], v[136:139]
	v_mfma_f32_16x16x32_bf16 v[132:135], v[76:79], v[184:187], v[132:135]
	v_mfma_f32_16x16x32_bf16 v[124:127], v[68:71], v[192:195], v[124:127]
	v_mfma_f32_16x16x32_bf16 v[116:119], v[76:79], v[192:195], v[116:119]
	v_mfma_f32_16x16x32_bf16 v[112:115], v[68:71], v[212:215], v[112:115]
	v_mfma_f32_16x16x32_bf16 v[108:111], v[76:79], v[212:215], v[108:111]
	v_mfma_f32_16x16x32_bf16 v[80:83], v[224:227], v[120:123], v[80:83]
	v_mfma_f32_16x16x32_bf16 v[136:139], v[216:219], v[120:123], v[152:155]
	v_mfma_f32_16x16x32_bf16 v[148:151], v[228:231], v[128:131], v[80:83]
	v_mfma_f32_16x16x32_bf16 v[80:83], v[216:219], v[180:183], v[84:87]
	v_mfma_f32_16x16x32_bf16 v[152:155], v[220:223], v[128:131], v[136:139]
	v_mfma_f32_16x16x32_bf16 v[136:139], v[220:223], v[184:187], v[80:83]
	v_mfma_f32_16x16x32_bf16 v[80:83], v[224:227], v[180:183], v[88:91]
	v_mfma_f32_16x16x32_bf16 v[128:131], v[228:231], v[184:187], v[80:83]
	v_mfma_f32_16x16x32_bf16 v[80:83], v[216:219], v[188:191], v[92:95]
	v_mfma_f32_16x16x32_bf16 v[120:123], v[220:223], v[192:195], v[80:83]
	v_mfma_f32_16x16x32_bf16 v[80:83], v[224:227], v[188:191], v[104:107]
	v_mfma_f32_16x16x32_bf16 v[104:107], v[228:231], v[192:195], v[80:83]
	v_mfma_f32_16x16x32_bf16 v[80:83], v[216:219], v[206:209], v[100:103]
	v_mfma_f32_16x16x32_bf16 v[100:103], v[220:223], v[212:215], v[80:83]
	v_mfma_f32_16x16x32_bf16 v[80:83], v[224:227], v[206:209], v[96:99]
	v_mfma_f32_16x16x32_bf16 v[96:99], v[228:231], v[212:215], v[80:83]
	s_barrier
	s_setprio 0
	s_add_i32 s51, s59, s62
	s_mov_b32 m0, s51
	s_nop 0
	global_load_lds_dwordx4 v164, s[98:99]
	s_add_i32 m0, s51, 0x2000
	s_nop 0
	global_load_lds_dwordx4 v160, s[98:99]
	s_mov_b32 m0, s55
	s_nop 2
	ds_read_b128 v[80:83], v202 offset:49152
	ds_read_b128 v[84:87], v202 offset:50176
	ds_read_b128 v[88:91], v202 offset:51200
	ds_read_b128 v[92:95], v202 offset:52224
	ds_read_b128 v[180:183], v202 offset:53248
	ds_read_b128 v[184:187], v202 offset:54272
	ds_read_b128 v[188:191], v202 offset:55296
	ds_read_b128 v[192:195], v202 offset:56320
	global_load_lds_dwordx4 v166, s[100:101]
	s_mov_b32 m0, s68
	s_nop 0
	global_load_lds_dwordx4 v162, s[100:101]
	s_add_u32 s48, s48, 0x80080
	s_addc_u32 s49, s49, 0
	s_add_i32 s50, s50, s62
	s_mov_b32 m0, s50
	s_nop 0
	global_load_lds_dwordx4 v164, s[48:49]
	s_add_i32 m0, s50, 0x2000
	s_nop 0
	global_load_lds_dwordx4 v160, s[48:49]
	s_add_i32 s58, s58, 2
	s_add_u32 s14, s14, 0x100
	s_addc_u32 s15, s15, 0
	s_add_u32 s52, s52, 0x100
	s_addc_u32 s53, s53, 0
	s_cmp_gt_u32 s58, 29
	s_waitcnt vmcnt(8)
	s_waitcnt lgkmcnt(0)
	s_setprio 1
	s_barrier
	v_mfma_f32_16x16x32_bf16 v[60:63], v[64:67], v[80:83], v[60:63]
	v_mfma_f32_16x16x32_bf16 v[48:51], v[72:75], v[80:83], v[48:51]
	v_mfma_f32_16x16x32_bf16 v[44:47], v[64:67], v[88:91], v[44:47]
	v_mfma_f32_16x16x32_bf16 v[36:39], v[72:75], v[88:91], v[36:39]
	v_mfma_f32_16x16x32_bf16 v[28:31], v[64:67], v[180:183], v[28:31]
	v_mfma_f32_16x16x32_bf16 v[20:23], v[72:75], v[180:183], v[20:23]
	v_mfma_f32_16x16x32_bf16 v[16:19], v[64:67], v[188:191], v[16:19]
	v_mfma_f32_16x16x32_bf16 v[12:15], v[72:75], v[188:191], v[12:15]
	v_mfma_f32_16x16x32_bf16 v[60:63], v[68:71], v[84:87], v[60:63]
	v_mfma_f32_16x16x32_bf16 v[48:51], v[76:79], v[84:87], v[48:51]
	v_mfma_f32_16x16x32_bf16 v[44:47], v[68:71], v[92:95], v[44:47]
	v_mfma_f32_16x16x32_bf16 v[36:39], v[76:79], v[92:95], v[36:39]
	v_mfma_f32_16x16x32_bf16 v[28:31], v[68:71], v[184:187], v[28:31]
	v_mfma_f32_16x16x32_bf16 v[20:23], v[76:79], v[184:187], v[20:23]
	v_mfma_f32_16x16x32_bf16 v[16:19], v[68:71], v[192:195], v[16:19]
	v_mfma_f32_16x16x32_bf16 v[12:15], v[76:79], v[192:195], v[12:15]
	v_mfma_f32_16x16x32_bf16 v[56:59], v[216:219], v[80:83], v[56:59]
	v_mfma_f32_16x16x32_bf16 v[52:55], v[224:227], v[80:83], v[52:55]
	v_mfma_f32_16x16x32_bf16 v[40:43], v[216:219], v[88:91], v[40:43]
	v_mfma_f32_16x16x32_bf16 v[32:35], v[224:227], v[88:91], v[32:35]
	v_mfma_f32_16x16x32_bf16 v[24:27], v[216:219], v[180:183], v[24:27]
	v_mfma_f32_16x16x32_bf16 v[8:11], v[224:227], v[180:183], v[8:11]
	v_mfma_f32_16x16x32_bf16 v[4:7], v[216:219], v[188:191], v[4:7]
	v_mfma_f32_16x16x32_bf16 v[0:3], v[224:227], v[188:191], v[0:3]
	v_mfma_f32_16x16x32_bf16 v[56:59], v[220:223], v[84:87], v[56:59]
	v_mfma_f32_16x16x32_bf16 v[52:55], v[228:231], v[84:87], v[52:55]
	v_mfma_f32_16x16x32_bf16 v[40:43], v[220:223], v[92:95], v[40:43]
	v_mfma_f32_16x16x32_bf16 v[32:35], v[228:231], v[92:95], v[32:35]
	v_mfma_f32_16x16x32_bf16 v[24:27], v[220:223], v[184:187], v[24:27]
	v_mfma_f32_16x16x32_bf16 v[8:11], v[228:231], v[184:187], v[8:11]
	v_mfma_f32_16x16x32_bf16 v[4:7], v[220:223], v[192:195], v[4:7]
	v_mfma_f32_16x16x32_bf16 v[0:3], v[228:231], v[192:195], v[0:3]
	s_barrier
; DI float dpp_ror1(float v) { return __int_as_float(__builtin_amdgcn_update_dpp(0, __float_as_int(v), 0x121, 0xf, 0xf, false)); }
; DI float dpp_ror2(float v) { return __int_as_float(__builtin_amdgcn_update_dpp(0, __float_as_int(v), 0x122, 0xf, 0xf, false)); }
; DI float row_rstd(const float* ssq, int row, int fq) {
;   const f32x4 a = *(const f32x4*)(ssq + (size_t)row * 32 + fq * 8), b = *(const f32x4*)(ssq + (size_t)row * 32 + fq * 8 + 4);
;   float sm = ((a[0] + a[1]) + (a[2] + a[3])) + ((b[0] + b[1]) + (b[2] + b[3]));
;   sm += __shfl_xor(sm, 16); sm += __shfl_xor(sm, 32);
;   return rsqrtf(sm * (1.0f / 2048.f) + 1e-6f);
; }
;   DI void operator()(const f32x4 (&acc)[2][2][4][2], const Unit& u, int wr, int wc, int fr, int fq) const {
;     const int col = u.pn * 128 + wc * 32 + 8 * fq;
;     float w0[8], w1[8], w2[8], bb[8];
; #pragma unroll
;     for (int e = 0; e < 8; ++e) { w0[e] = cw[col + e]; w1[e] = cw[5632 + col + e]; w2[e] = cw[2 * 5632 + col + e]; bb[e] = cb[col + e]; }
; #pragma unroll
;     for (int ai = 0; ai < 2; ++ai) {
;       const int row0 = u.pm * BM + ai * HALF + wr * 64, span = row0 >> 6;
;       float rsv[4];
; #pragma unroll
;       for (int m = 0; m < 4; ++m) rsv[m] = row_rstd(ssq, row0 + 16 * m + fr, fq);
;       float p1[8], p2[8];
; #pragma unroll
;       for (int e = 0; e < 8; ++e) { p1[e] = 0.f; p2[e] = 0.f; }
; #pragma unroll
;       for (int m = 0; m < 4; ++m) {
;         float g[8], uu[8], a[8];
;         const float rs = rsv[m];
; #pragma unroll
;         for (int e = 0; e < 4; ++e) { g[e] = acc[ai][0][m][0][e] * rs; g[4 + e] = acc[ai][0][m][1][e] * rs; uu[e] = acc[ai][1][m][0][e] * rs; uu[4 + e] = acc[ai][1][m][1][e] * rs; }
; #pragma unroll
;         for (int e = 0; e < 8; ++e) {
;           const float x1 = dpp_ror1(g[e]), x2 = dpp_ror2(g[e]);
;           const float pr1 = (fr == 0) ? p1[e] : x1, pr2 = (fr < 2) ? p2[e] : x2;
;           a[e] = w2[e] * g[e] + w1[e] * pr1 + w0[e] * pr2 + bb[e];
;           p1[e] = x1; p2[e] = x2;
;         }
	s_setprio 0
	s_cbranch_scc0 .LBB0_1277
	s_lshl_b32 s39, s12, 8
	s_add_i32 s39, s39, s54
	v_or_b32_e32 v190, s39, v179
	v_ashrrev_i32_e32 v191, 31, v190
	v_lshlrev_b64 v[64:65], 7, v[190:191]
	v_or_b32_e32 v188, 16, v190
	v_lshl_add_u64 v[64:65], v[168:169], 0, v[64:65]
	v_ashrrev_i32_e32 v189, 31, v188
	global_load_dwordx4 v[192:195], v[64:65], off
	global_load_dwordx4 v[206:209], v[64:65], off offset:16
	v_lshlrev_b64 v[64:65], 7, v[188:189]
	v_lshl_add_u64 v[64:65], v[168:169], 0, v[64:65]
	global_load_dwordx4 v[212:215], v[64:65], off
	global_load_dwordx4 v[216:219], v[64:65], off offset:16
	v_or_b32_e32 v186, 32, v190
	v_ashrrev_i32_e32 v187, 31, v186
	v_lshlrev_b64 v[64:65], 7, v[186:187]
	v_or_b32_e32 v184, 48, v190
	v_lshl_add_u64 v[64:65], v[168:169], 0, v[64:65]
	v_ashrrev_i32_e32 v185, 31, v184
	global_load_dwordx4 v[220:223], v[64:65], off
	global_load_dwordx4 v[224:227], v[64:65], off offset:16
	v_lshlrev_b64 v[64:65], 7, v[184:185]
	v_lshl_add_u64 v[64:65], v[168:169], 0, v[64:65]
	global_load_dwordx4 v[228:231], v[64:65], off
	global_load_dwordx4 v[232:235], v[64:65], off offset:16
	v_lshl_or_b32 v180, s13, 7, v200
	v_and_b32_e32 v65, 64, v204
	v_xor_b32_e32 v64, 16, v204
	v_ashrrev_i32_e32 v181, 31, v180
	v_add_u32_e32 v65, 64, v65
	v_xor_b32_e32 v66, 32, v204
	v_lshlrev_b64 v[182:183], 2, v[180:181]
	v_cmp_lt_i32_e32 vcc, v64, v65
	v_lshl_add_u64 v[88:89], s[16:17], 0, v[182:183]
	v_lshl_add_u64 v[72:73], s[18:19], 0, v[182:183]
	v_cndmask_b32_e32 v64, v204, v64, vcc
	v_cmp_lt_i32_e32 vcc, v66, v65
	v_lshl_add_u64 v[74:75], v[88:89], 0, s[30:31]
	v_lshl_add_u64 v[76:77], v[88:89], 0, s[34:35]
	v_cndmask_b32_e32 v65, v204, v66, vcc
	v_add_co_u32_e32 v90, vcc, 0x5000, v88
	v_lshlrev_b32_e32 v187, 2, v64
	s_nop 0
	v_addc_co_u32_e32 v91, vcc, 0, v89, vcc
	v_add_co_u32_e32 v92, vcc, 0xb000, v88
	v_lshlrev_b32_e32 v185, 2, v65
	s_nop 0
	v_addc_co_u32_e32 v93, vcc, 0, v89, vcc
	global_load_dwordx4 v[64:67], v[88:89], off offset:16
	global_load_dwordx4 v[80:83], v[88:89], off
	global_load_dwordx4 v[68:71], v[72:73], off offset:16
	global_load_dwordx4 v[84:87], v[72:73], off
	s_nop 0
	global_load_dwordx4 v[72:75], v[74:75], off offset:16
	s_nop 0
	global_load_dwordx4 v[76:79], v[76:77], off offset:16
	s_nop 0
	global_load_dwordx4 v[88:91], v[90:91], off offset:2048
	s_nop 0
	global_load_dwordx4 v[92:95], v[92:93], off
	v_mov_b32_e32 v211, 0
	v_mov_b32_e32 v205, 0
	s_waitcnt vmcnt(0)
	v_mov_b32_e32 v196, v192
	v_mov_b32_e32 v197, v206
	v_mov_b32_e32 v206, v193
	v_mov_b32_e32 v192, v194
	v_mov_b32_e32 v193, v208
	v_mov_b32_e32 v208, v195
	v_pk_add_f32 v[194:195], v[196:197], v[206:207]
	v_pk_add_f32 v[192:193], v[192:193], v[208:209]
	v_mov_b32_e32 v196, v212
	v_mov_b32_e32 v197, v216
	v_mov_b32_e32 v216, v213
	v_mov_b32_e32 v206, v214
	v_mov_b32_e32 v207, v218
	v_mov_b32_e32 v218, v215
	v_pk_add_f32 v[192:193], v[194:195], v[192:193]
	v_pk_add_f32 v[194:195], v[196:197], v[216:217]
	v_pk_add_f32 v[196:197], v[206:207], v[218:219]
	v_mov_b32_e32 v208, v220
	v_pk_add_f32 v[194:195], v[194:195], v[196:197]
	v_mov_b32_e32 v197, v192
	v_mov_b32_e32 v196, v194
	v_mov_b32_e32 v192, v195
	v_pk_add_f32 v[192:193], v[196:197], v[192:193]
	ds_bpermute_b32 v195, v187, v193
	ds_bpermute_b32 v194, v187, v192
	v_mov_b32_e32 v209, v224
	v_mov_b32_e32 v224, v221
	v_mov_b32_e32 v212, v222
	v_mov_b32_e32 v213, v226
	s_waitcnt lgkmcnt(0)
	v_pk_add_f32 v[192:193], v[192:193], v[194:195]
	ds_bpermute_b32 v195, v185, v193
	ds_bpermute_b32 v194, v185, v192
	v_mov_b32_e32 v226, v223
	v_mov_b32_e32 v196, v228
	v_mov_b32_e32 v197, v232
	v_mov_b32_e32 v232, v229
	s_waitcnt lgkmcnt(0)
	v_pk_add_f32 v[192:193], v[192:193], v[194:195]
	v_mov_b32_e32 v206, v230
	v_pk_fma_f32 v[192:193], v[192:193], s[36:37], v[178:179] op_sel_hi:[1,0,0]
	v_mov_b32_e32 v207, v234
	v_mul_f32_e32 v189, 0x4b800000, v193
	v_cmp_gt_f32_e64 s[12:13], s74, v193
	v_mov_b32_e32 v234, v231
	v_pk_add_f32 v[208:209], v[208:209], v[224:225]
	v_cndmask_b32_e64 v189, v193, v189, s[12:13]
	v_rsq_f32_e32 v189, v189
	v_pk_add_f32 v[212:213], v[212:213], v[226:227]
	v_pk_add_f32 v[196:197], v[196:197], v[232:233]
	v_pk_add_f32 v[194:195], v[206:207], v[234:235]
	v_mul_f32_e32 v191, 0x45800000, v189
	v_cndmask_b32_e64 v220, v189, v191, s[12:13]
	v_pk_add_f32 v[208:209], v[208:209], v[212:213]
	v_pk_add_f32 v[194:195], v[196:197], v[194:195]
	v_pk_mul_f32 v[156:157], v[156:157], v[220:221] op_sel_hi:[1,0]
	v_mov_b32_e32 v216, 0
	v_mov_b32_e32 v218, 0
	v_mov_b32_e32 v196, v194
	v_mov_b32_e32 v197, v208
	v_mov_b32_e32 v208, v195
	v_mov_b32_dpp v216, v156 row_ror:1 row_mask:0xf bank_mask:0xf
	v_mov_b32_dpp v218, v157 row_ror:1 row_mask:0xf bank_mask:0xf
	v_pk_add_f32 v[194:195], v[196:197], v[208:209]
	v_cndmask_b32_e64 v207, v218, 0, s[0:1]
	v_cndmask_b32_e64 v206, v216, 0, s[0:1]
	v_pk_mul_f32 v[158:159], v[158:159], v[220:221] op_sel_hi:[1,0]
	v_mov_b32_e32 v212, 0
	v_mov_b32_e32 v214, 0
	ds_bpermute_b32 v197, v187, v195
	ds_bpermute_b32 v196, v187, v194
	v_mov_b32_e32 v215, 0
	v_mov_b32_e32 v217, 0
	v_pk_mul_f32 v[206:207], v[88:89], v[206:207]
	v_mov_b32_dpp v212, v158 row_ror:1 row_mask:0xf bank_mask:0xf
	v_mov_b32_dpp v214, v159 row_ror:1 row_mask:0xf bank_mask:0xf
	v_mov_b32_dpp v215, v156 row_ror:2 row_mask:0xf bank_mask:0xf
	v_mov_b32_dpp v217, v157 row_ror:2 row_mask:0xf bank_mask:0xf
	v_pk_fma_f32 v[156:157], v[92:93], v[156:157], v[206:207]
	v_mov_b32_e32 v213, 0
	v_cndmask_b32_e64 v207, v214, 0, s[0:1]
	v_cndmask_b32_e64 v206, v212, 0, s[0:1]
	v_cndmask_b32_e64 v209, v217, 0, s[4:5]
	v_cndmask_b32_e64 v208, v215, 0, s[4:5]
	v_mov_b32_dpp v211, v158 row_ror:2 row_mask:0xf bank_mask:0xf
	v_mov_b32_dpp v213, v159 row_ror:2 row_mask:0xf bank_mask:0xf
	v_pk_mul_f32 v[206:207], v[90:91], v[206:207]
	v_pk_fma_f32 v[156:157], v[80:81], v[208:209], v[156:157]
	v_cndmask_b32_e64 v209, v213, 0, s[4:5]
	v_cndmask_b32_e64 v208, v211, 0, s[4:5]
	v_pk_fma_f32 v[158:159], v[94:95], v[158:159], v[206:207]
	v_pk_mul_f32 v[144:145], v[144:145], v[220:221] op_sel_hi:[1,0]
	v_pk_fma_f32 v[158:159], v[82:83], v[208:209], v[158:159]
	v_mov_b32_e32 v207, 0
	v_mov_b32_e32 v209, 0
	v_pk_mul_f32 v[146:147], v[146:147], v[220:221] op_sel_hi:[1,0]
	v_mov_b32_e32 v191, 0
	s_waitcnt lgkmcnt(0)
; DI unsigned pack2(float lo, float hi) { f32x2 v = {lo, hi}; bf16v2 r = __builtin_convertvector(v, bf16v2); return __builtin_bit_cast(unsigned, r); }
; DI float silu_f(float x) { return x * sigmoid_f(x); }
; DI float dpp_ror1(float v) { return __int_as_float(__builtin_amdgcn_update_dpp(0, __float_as_int(v), 0x121, 0xf, 0xf, false)); }
; DI float dpp_ror2(float v) { return __int_as_float(__builtin_amdgcn_update_dpp(0, __float_as_int(v), 0x122, 0xf, 0xf, false)); }
;   DI void operator()(const f32x4 (&acc)[2][2][4][2], const Unit& u, int wr, int wc, int fr, int fq) const {
;     ...
;       for (int m = 0; m < 4; ++m) {
;         float g[8], uu[8], a[8];
;         const float rs = rsv[m];
; #pragma unroll
;         for (int e = 0; e < 4; ++e) { g[e] = acc[ai][0][m][0][e] * rs; g[4 + e] = acc[ai][0][m][1][e] * rs; uu[e] = acc[ai][1][m][0][e] * rs; uu[4 + e] = acc[ai][1][m][1][e] * rs; }
; #pragma unroll
;         for (int e = 0; e < 8; ++e) {
;           const float x1 = dpp_ror1(g[e]), x2 = dpp_ror2(g[e]);
;           const float pr1 = (fr == 0) ? p1[e] : x1, pr2 = (fr < 2) ? p2[e] : x2;
;           a[e] = w2[e] * g[e] + w1[e] * pr1 + w0[e] * pr2 + bb[e];
;           p1[e] = x1; p2[e] = x2;
;         }
;         if (m == 0 && fr < 2) {
;           float* ha = headA + (size_t)(span * 2 + fr) * 5632 + col; float* hu = headU + (size_t)(span * 2 + fr) * 5632 + col;
;           *(f32x4*)ha = (f32x4){a[0], a[1], a[2], a[3]}; *(f32x4*)(ha + 4) = (f32x4){a[4], a[5], a[6], a[7]};
;           *(f32x4*)hu = (f32x4){uu[0], uu[1], uu[2], uu[3]}; *(f32x4*)(hu + 4) = (f32x4){uu[4], uu[5], uu[6], uu[7]};
;         } else {
;           u32x4 w;
;           w.x = pack2(silu_f(a[0]) * uu[0], silu_f(a[1]) * uu[1]);
;           w.y = pack2(silu_f(a[2]) * uu[2], silu_f(a[3]) * uu[3]);
;           w.z = pack2(silu_f(a[4]) * uu[4], silu_f(a[5]) * uu[5]);
;           w.w = pack2(silu_f(a[6]) * uu[6], silu_f(a[7]) * uu[7]);
;           *(u32x4*)(H + (size_t)(row0 + 16 * m + fr) * 5632 + col) = w;
;         }
	v_pk_add_f32 v[194:195], v[194:195], v[196:197]
	v_mov_b32_dpp v207, v144 row_ror:1 row_mask:0xf bank_mask:0xf
	v_mov_b32_dpp v209, v145 row_ror:1 row_mask:0xf bank_mask:0xf
	v_mov_b32_dpp v191, v146 row_ror:1 row_mask:0xf bank_mask:0xf
	v_mov_b32_dpp v205, v147 row_ror:1 row_mask:0xf bank_mask:0xf
	ds_bpermute_b32 v197, v185, v195
	ds_bpermute_b32 v196, v185, v194
	v_pk_mul_f32 v[152:153], v[152:153], v[220:221] op_sel_hi:[1,0]
	v_pk_mul_f32 v[148:149], v[148:149], v[220:221] op_sel_hi:[1,0]
	v_pk_mul_f32 v[154:155], v[154:155], v[220:221] op_sel_hi:[1,0]
	v_pk_mul_f32 v[150:151], v[150:151], v[220:221] op_sel_hi:[1,0]
	v_mov_b32_e32 v206, 0
	v_mov_b32_e32 v208, 0
	v_cndmask_b32_e64 v223, v209, 0, s[0:1]
	v_cndmask_b32_e64 v222, v207, 0, s[0:1]
	v_mov_b32_e32 v189, 0
	v_mov_b32_e32 v193, 0
	v_cndmask_b32_e64 v221, v205, 0, s[0:1]
	v_cndmask_b32_e64 v220, v191, 0, s[0:1]
	v_mov_b32_dpp v206, v144 row_ror:2 row_mask:0xf bank_mask:0xf
	v_mov_b32_dpp v208, v145 row_ror:2 row_mask:0xf bank_mask:0xf
	v_pk_mul_f32 v[222:223], v[72:73], v[222:223]
	v_mov_b32_dpp v189, v146 row_ror:2 row_mask:0xf bank_mask:0xf
	v_mov_b32_dpp v193, v147 row_ror:2 row_mask:0xf bank_mask:0xf
	v_pk_mul_f32 v[220:221], v[74:75], v[220:221]
	v_cndmask_b32_e64 v225, v208, 0, s[4:5]
	v_cndmask_b32_e64 v224, v206, 0, s[4:5]
	v_pk_fma_f32 v[144:145], v[76:77], v[144:145], v[222:223]
	v_cndmask_b32_e64 v223, v193, 0, s[4:5]
	v_cndmask_b32_e64 v222, v189, 0, s[4:5]
	v_pk_fma_f32 v[146:147], v[78:79], v[146:147], v[220:221]
	v_pk_fma_f32 v[144:145], v[64:65], v[224:225], v[144:145]
	v_pk_fma_f32 v[146:147], v[66:67], v[222:223], v[146:147]
	v_cmp_gt_f32_e32 vcc, s74, v192
	v_pk_add_f32 v[156:157], v[84:85], v[156:157]
	v_pk_add_f32 v[158:159], v[86:87], v[158:159]
	v_pk_add_f32 v[144:145], v[68:69], v[144:145]
	v_pk_add_f32 v[146:147], v[70:71], v[146:147]
	s_and_saveexec_b64 s[12:13], s[10:11]
	s_xor_b64 s[12:13], exec, s[12:13]
	s_cbranch_execz .LBB0_1280
	v_mul_f32_e32 v219, 0xbfb8aa3b, v156
	v_exp_f32_e32 v219, v219
	v_mul_f32_e32 v220, 0xbfb8aa3b, v157
	v_exp_f32_e32 v220, v220
	v_mul_f32_e32 v222, 0xbfb8aa3b, v159
	v_add_f32_e32 v219, 1.0, v219
	v_exp_f32_e32 v223, v222
	v_add_f32_e32 v221, 1.0, v220
	v_rcp_f32_e32 v220, v219
	v_mul_f32_e32 v219, 0xbfb8aa3b, v158
	v_exp_f32_e32 v219, v219
	v_rcp_f32_e32 v221, v221
	v_add_f32_e32 v219, 1.0, v219
	v_rcp_f32_e32 v222, v219
	v_add_f32_e32 v219, 1.0, v223
	v_rcp_f32_e32 v223, v219
	v_pk_mul_f32 v[156:157], v[156:157], v[220:221]
	s_nop 0
	v_pk_mul_f32 v[152:153], v[152:153], v[156:157]
	v_pk_mul_f32 v[156:157], v[158:159], v[222:223]
	v_cvt_pk_bf16_f32 v152, v152, v153
	v_mul_f32_e32 v153, 0xbfb8aa3b, v144
	v_pk_mul_f32 v[154:155], v[154:155], v[156:157]
	v_exp_f32_e32 v156, v153
	v_mul_f32_e32 v153, 0xbfb8aa3b, v145
	v_exp_f32_e32 v157, v153
	v_cvt_pk_bf16_f32 v153, v154, v155
	v_add_f32_e32 v154, 1.0, v156
	v_mul_f32_e32 v156, 0xbfb8aa3b, v146
	v_add_f32_e32 v155, 1.0, v157
	v_mul_f32_e32 v157, 0xbfb8aa3b, v147
	v_exp_f32_e32 v156, v156
	v_exp_f32_e32 v157, v157
	v_rcp_f32_e32 v154, v154
	v_rcp_f32_e32 v155, v155
	v_add_f32_e32 v156, 1.0, v156
	v_add_f32_e32 v157, 1.0, v157
	v_rcp_f32_e32 v156, v156
	v_rcp_f32_e32 v157, v157
	v_pk_mul_f32 v[144:145], v[144:145], v[154:155]
	s_nop 0
	v_pk_mul_f32 v[144:145], v[148:149], v[144:145]
	s_nop 0
	v_cvt_pk_bf16_f32 v154, v144, v145
	v_pk_mul_f32 v[144:145], v[146:147], v[156:157]
	s_nop 0
	v_pk_mul_f32 v[144:145], v[150:151], v[144:145]
	s_nop 0
	v_cvt_pk_bf16_f32 v155, v144, v145
	v_mov_b64_e32 v[144:145], s[20:21]
	v_mad_i64_i32 v[144:145], s[14:15], v190, s75, v[144:145]
	v_lshl_add_u64 v[144:145], v[180:181], 1, v[144:145]
	global_store_dwordx4 v[144:145], v[152:155], off

; #define PG8_STAGE(bufoff, gbase, voff) do { _Pragma("unroll") for (int _i = 0; _i < 2; ++_i) \
;     __builtin_amdgcn_global_load_lds((const unsigned*)((const char*)(gbase) + (voff)[_i]), (LAS unsigned*)(lds + (bufoff) + ldsw + _i * 8192), 16, 0, 0); } while (0)
; #define PG8_WAIT_V(n) asm volatile("s_waitcnt vmcnt(" #n ")" ::: "memory")
; #define PG8_BAR __builtin_amdgcn_s_barrier()
; template <class Epi, class Sched = StaticOrder>
; DI void gemm_phase(LAS unsigned char* lds, const Gemm g, const Sched& S, const Epi& E) {
;     ...
;   for (int i = 0; i < 2; ++i) { int R, C; stage_rc(tid * 16 + i * 8192, R, C); const int Rb = Epi::PERM ? ((R & ~31) + perm32(R & 31)) : R;
;     voffA[i] = (unsigned)(R * K + C) * 2u; voffB[i] = (unsigned)(Rb * K + C) * 2u; }
;   const size_t kstep = (size_t)(BK * 2);
;   const size_t hstep = (size_t)HALF * K * 2;
;   const size_t tstep = 2 * hstep;
;   const unsigned ldsw = (unsigned)wid * 1024u;
;   const int aoff = lds_byte(wr * 64 + fr, fq * 8), boff = lds_byte(wc * 32 + fr, fq * 8);
;     ...
;   Unit cur, nxt; int ui = 0;
;   if (!S.next(0, cur)) return;
;   f32x4 acc[2][2][4][2];
; #pragma unroll
;   for (int a = 0; a < 2; ++a)
; #pragma unroll
;     for (int b = 0; b < 2; ++b)
; #pragma unroll
;       for (int m = 0; m < 4; ++m)
; #pragma unroll
;         for (int n = 0; n < 2; ++n) acc[a][b][m][n] = (f32x4){0.f, 0.f, 0.f, 0.f};
;   bf16x8 At[4][2], B0[2][2], B1[2][2];
;   const char* cA = (const char*)g.A + (size_t)cur.pm * tstep; const char* cB = (const char*)g.Bt + (size_t)cur.pn * tstep;
;   PG8_STAGE(PG8_SB(0, 0), cB, voffB); PG8_STAGE(PG8_SA(0, 0), cA, voffA); PG8_STAGE(PG8_SB(0, 1), cB + hstep, voffB); PG8_STAGE(PG8_SA(0, 1), cA + hstep, voffA);
;   if (wr == 1) PG8_BAR;
;   PG8_WAIT_V(4); PG8_BAR;
;   PG8_STAGE(PG8_SB(1, 0), cB + kstep, voffB); PG8_STAGE(PG8_SA(1, 0), cA + kstep, voffA); PG8_STAGE(PG8_SB(1, 1), cB + hstep + kstep, voffB);
;   PG8_WAIT_V(6); PG8_BAR;
.LBB0_1416:
	s_mov_b64 s[8:9], 0x80
	s_and_b32 s4, s2, 3
	s_add_i32 m0, s30, 0x18000
	v_lshl_add_u64 v[6:7], v[6:7], 0, s[8:9]
	s_lshl_b32 s5, s1, 13
	s_lshl_b32 s10, s4, 12
	s_waitcnt vmcnt(2)
	s_barrier
	global_load_lds_dwordx4 v[6:7], off
	v_lshl_add_u64 v[4:5], v[4:5], 0, s[8:9]
	s_add_i32 m0, s30, 0x1a000
	s_add_i32 s35, s30, 0x8000
	s_add_i32 s36, s30, 0xa000
	global_load_lds_dwordx4 v[4:5], off
	v_lshl_add_u64 v[2:3], v[2:3], 0, s[8:9]
	s_mov_b32 m0, s35
	s_add_u32 s2, s18, 0x160080
	global_load_lds_dwordx4 v[2:3], off
	v_lshl_add_u64 v[0:1], v[0:1], 0, s[8:9]
	s_mov_b32 m0, s36
	s_addc_u32 s3, s19, 0
	global_load_lds_dwordx4 v[0:1], off
	s_add_i32 m0, s30, 0x1c000
	v_lshl_add_u64 v[0:1], s[2:3], 0, v[132:133]
	global_load_lds_dwordx4 v[0:1], off
	v_lshl_add_u64 v[0:1], s[2:3], 0, v[128:129]
	s_add_i32 m0, s30, 0x1e000
	s_sext_i32_i8 s44, s0
	global_load_lds_dwordx4 v[0:1], off
	v_bfe_u32 v0, v210, 4, 2
	v_and_b32_e32 v1, 15, v210
	v_lshlrev_b32_e32 v2, 3, v0
	v_lshlrev_b32_e32 v0, 4, v0
	v_lshlrev_b32_e32 v3, 2, v210
	v_lshlrev_b32_e32 v4, 6, v210
	s_movk_i32 s0, 0x3c0
	v_lshl_or_b32 v156, s1, 6, v1
	v_lshl_or_b32 v1, v1, 6, v0
	v_and_b32_e32 v3, 32, v3
	v_and_or_b32 v0, v4, s0, v0
	v_bitop3_b32 v157, s10, v0, v3 bitop3:0xf6
	s_waitcnt vmcnt(6)
	v_add_u16_e32 v0, v8, v9
	v_readlane_b32 s48, v243, 3
	v_bitop3_b32 v1, v1, s5, v3 bitop3:0xde
	v_lshrrev_b16_e32 v0, 1, v0
	s_add_i32 s39, 0, 0x10000
	s_add_i32 s40, 0, 0x14000
	v_readlane_b32 s54, v243, 9
	v_readlane_b32 s55, v243, 10
	v_readlane_b32 s62, v243, 17
	v_readlane_b32 s63, v243, 18
	s_mov_b32 s37, 0
	v_lshl_or_b32 v158, s4, 5, v2
	s_ashr_i32 s38, s96, 31
	v_add_lshl_u32 v136, v11, v0, 1
	v_mov_b32_e32 v137, v133
	v_add_lshl_u32 v138, v10, v0, 1
	v_mov_b32_e32 v139, v133
	v_mov_b64_e32 v[140:141], 0x200
	v_mov_b64_e32 v[142:143], 0x1ff
	v_add_u32_e32 v159, s39, v157
	v_add_u32_e32 v160, 0, v1
	v_add_u32_e32 v161, s40, v157
	s_mov_b64 s[10:11], 0x100000
	s_mov_b64 s[12:13], 0x120000
	s_mov_b64 s[14:15], 0x140000
	s_mov_b64 s[54:55], s[62:63]
	s_barrier
	v_readlane_b32 s49, v243, 4
	v_readlane_b32 s50, v243, 5
	v_readlane_b32 s51, v243, 6
	v_readlane_b32 s52, v243, 7
	v_readlane_b32 s53, v243, 8
	v_readlane_b32 s56, v243, 11
	v_readlane_b32 s57, v243, 12
	v_readlane_b32 s58, v243, 13
	v_readlane_b32 s59, v243, 14
	v_readlane_b32 s60, v243, 15
	v_readlane_b32 s61, v243, 16

; #define PG8_STAGE(bufoff, gbase, voff) do { _Pragma("unroll") for (int _i = 0; _i < 2; ++_i) \
;     __builtin_amdgcn_global_load_lds((const unsigned*)((const char*)(gbase) + (voff)[_i]), (LAS unsigned*)(lds + (bufoff) + ldsw + _i * 8192), 16, 0, 0); } while (0)
; #define PG8_LDA(dst, b, h) do { _Pragma("unroll") for (int m = 0; m < 4; ++m) _Pragma("unroll") for (int k = 0; k < 2; ++k) dst[m][k] = *(const LAS bf16x8*)(lds + PG8_SA(b, h) + aoff + m * 2048 + k * 1024); } while (0)
; #define PG8_LDB(dst, b, h) do { _Pragma("unroll") for (int n = 0; n < 2; ++n) _Pragma("unroll") for (int k = 0; k < 2; ++k) dst[n][k] = *(const LAS bf16x8*)(lds + PG8_SB(b, h) + boff + n * 2048 + k * 1024); } while (0)
; #define PG8_MMA(ai, bj, At, Bt) do { __builtin_amdgcn_s_setprio(1); _Pragma("unroll") for (int m = 0; m < 4; ++m) _Pragma("unroll") for (int n = 0; n < 2; ++n) _Pragma("unroll") for (int k = 0; k < 2; ++k) \
;     acc[ai][bj][m][n] = __builtin_amdgcn_mfma_f32_16x16x32_bf16(Bt[n][k], At[m][k], acc[ai][bj][m][n], 0, 0, 0); __builtin_amdgcn_s_setprio(0); } while (0)
; #define PG8_WAIT_V(n) asm volatile("s_waitcnt vmcnt(" #n ")" ::: "memory")
; #define PG8_WAIT_L(n) asm volatile("s_waitcnt lgkmcnt(" #n ")" ::: "memory")
; #define PG8_BAR __builtin_amdgcn_s_barrier()
; #define PG8_SCHED __builtin_amdgcn_sched_barrier(0)
; template <class Epi, class Sched = StaticOrder>
; DI void gemm_phase(LAS unsigned char* lds, const Gemm g, const Sched& S, const Epi& E) {
;     ...
;     for (int t = 0; t < nt; t += 2) {
;       const bool last = (t == nt - 2);
;       const char* a1 = cA + (size_t)(t + 1) * kstep;
;       const char* a2 = last ? nA : cA + (size_t)(t + 2) * kstep; const char* b2 = last ? nB : cB + (size_t)(t + 2) * kstep;
;       const char* a3 = a2 + kstep; const char* b3 = b2 + kstep;
;       PG8_LDB(B0, 0, 0); PG8_SCHED; PG8_LDA(At, 0, 0); PG8_STAGE(PG8_SA(1, 1), a1 + hstep, voffA);
;       PG8_WAIT_L(8); PG8_BAR; PG8_WAIT_L(0); PG8_MMA(0, 0, At, B0); PG8_BAR; PG8_SCHED;
;       PG8_LDB(B1, 0, 1); PG8_STAGE(PG8_SB(0, 0), b2, voffB);
;       PG8_BAR; PG8_WAIT_L(0); PG8_MMA(0, 1, At, B1); PG8_BAR;
;       PG8_LDA(At, 0, 1); PG8_STAGE(PG8_SA(0, 0), a2, voffA);
;       PG8_BAR; PG8_WAIT_L(0); PG8_MMA(1, 0, At, B0); PG8_BAR; PG8_SCHED;
;       PG8_STAGE(PG8_SB(0, 1), b2 + hstep, voffB);
;       PG8_WAIT_V(6); PG8_BAR; PG8_MMA(1, 1, At, B1); PG8_BAR;
.LBB0_1424:
	ds_read_b128 v[144:147], v159
	ds_read_b128 v[148:151], v159 offset:1024
	ds_read_b128 v[152:155], v159 offset:2048
	ds_read_b128 v[162:165], v159 offset:3072
	s_add_u32 s18, s16, 0xffea0080
	s_addc_u32 s19, s17, -1
	s_cmpk_eq_i32 s47, 0x54
	s_cselect_b32 s21, s3, s19
	s_cselect_b32 s20, s2, s18
	s_cselect_b32 s19, s5, s46
	s_cselect_b32 s18, s4, s45
	s_add_i32 m0, s30, 0xc000
	ds_read_b128 v[166:169], v160
	ds_read_b128 v[170:173], v160 offset:1024
	ds_read_b128 v[174:177], v160 offset:2048
	ds_read_b128 v[178:181], v160 offset:3072
	ds_read_b128 v[182:185], v160 offset:4096
	ds_read_b128 v[186:189], v160 offset:5120
	ds_read_b128 v[190:193], v160 offset:6144
	ds_read_b128 v[194:197], v160 offset:7168
	global_load_lds_dwordx4 v136, s[16:17]
	s_add_i32 m0, s30, 0xe000
	s_nop 0
	global_load_lds_dwordx4 v138, s[16:17]
	ds_read_b128 v[198:201], v161
	ds_read_b128 v[202:205], v161 offset:1024
	ds_read_b128 v[206:209], v161 offset:2048
	ds_read_b128 v[210:213], v161 offset:3072
	s_waitcnt vmcnt(8)
	s_waitcnt lgkmcnt(0)
	s_setprio 1
	s_barrier
	v_mfma_f32_16x16x32_bf16 v[124:127], v[144:147], v[166:169], v[124:127]
	v_mfma_f32_16x16x32_bf16 v[120:123], v[152:155], v[166:169], v[120:123]
	v_mfma_f32_16x16x32_bf16 v[116:119], v[144:147], v[174:177], v[116:119]
	v_mfma_f32_16x16x32_bf16 v[112:115], v[152:155], v[174:177], v[112:115]
	v_mfma_f32_16x16x32_bf16 v[104:107], v[144:147], v[182:185], v[104:107]
	v_mfma_f32_16x16x32_bf16 v[96:99], v[152:155], v[182:185], v[96:99]
	v_mfma_f32_16x16x32_bf16 v[88:91], v[144:147], v[190:193], v[88:91]
	v_mfma_f32_16x16x32_bf16 v[80:83], v[152:155], v[190:193], v[80:83]
	v_mfma_f32_16x16x32_bf16 v[124:127], v[148:151], v[170:173], v[124:127]
	v_mfma_f32_16x16x32_bf16 v[120:123], v[162:165], v[170:173], v[120:123]
	v_mfma_f32_16x16x32_bf16 v[116:119], v[148:151], v[178:181], v[116:119]
	v_mfma_f32_16x16x32_bf16 v[112:115], v[162:165], v[178:181], v[112:115]
	v_mfma_f32_16x16x32_bf16 v[104:107], v[148:151], v[186:189], v[104:107]
	v_mfma_f32_16x16x32_bf16 v[96:99], v[162:165], v[186:189], v[96:99]
	v_mfma_f32_16x16x32_bf16 v[88:91], v[148:151], v[194:197], v[88:91]
	v_mfma_f32_16x16x32_bf16 v[80:83], v[162:165], v[194:197], v[80:83]
	v_mfma_f32_16x16x32_bf16 v[108:111], v[198:201], v[166:169], v[108:111]
	v_mfma_f32_16x16x32_bf16 v[100:103], v[206:209], v[166:169], v[100:103]
	v_mfma_f32_16x16x32_bf16 v[92:95], v[198:201], v[174:177], v[92:95]
	v_mfma_f32_16x16x32_bf16 v[84:87], v[206:209], v[174:177], v[84:87]
	v_mfma_f32_16x16x32_bf16 v[76:79], v[198:201], v[182:185], v[76:79]
	v_mfma_f32_16x16x32_bf16 v[72:75], v[206:209], v[182:185], v[72:75]
	v_mfma_f32_16x16x32_bf16 v[68:71], v[198:201], v[190:193], v[68:71]
	v_mfma_f32_16x16x32_bf16 v[64:67], v[206:209], v[190:193], v[64:67]
	v_mfma_f32_16x16x32_bf16 v[108:111], v[202:205], v[170:173], v[108:111]
	v_mfma_f32_16x16x32_bf16 v[100:103], v[210:213], v[170:173], v[100:103]
	v_mfma_f32_16x16x32_bf16 v[92:95], v[202:205], v[178:181], v[92:95]
	v_mfma_f32_16x16x32_bf16 v[84:87], v[210:213], v[178:181], v[84:87]
	v_mfma_f32_16x16x32_bf16 v[76:79], v[202:205], v[186:189], v[76:79]
	v_mfma_f32_16x16x32_bf16 v[72:75], v[210:213], v[186:189], v[72:75]
	v_mfma_f32_16x16x32_bf16 v[68:71], v[202:205], v[194:197], v[68:71]
	v_mfma_f32_16x16x32_bf16 v[64:67], v[210:213], v[194:197], v[64:67]
	s_barrier
	s_setprio 0
	s_add_i32 s48, s39, s28
	s_add_u32 s98, s18, 0x80
	s_addc_u32 s99, s19, 0
	s_add_u32 s100, s20, 0x80
	s_addc_u32 s101, s21, 0
	s_mov_b32 m0, s48
	s_nop 0
	global_load_lds_dwordx4 v132, s[18:19]
	s_add_i32 m0, s48, 0x2000
	s_nop 0
	global_load_lds_dwordx4 v128, s[18:19]
	s_mov_b32 m0, s30
	ds_read_b128 v[166:169], v160 offset:16384
	ds_read_b128 v[170:173], v160 offset:17408
	ds_read_b128 v[174:177], v160 offset:18432
	ds_read_b128 v[178:181], v160 offset:19456
	ds_read_b128 v[182:185], v160 offset:20480
	ds_read_b128 v[186:189], v160 offset:21504
	ds_read_b128 v[190:193], v160 offset:22528
	ds_read_b128 v[194:197], v160 offset:23552
	global_load_lds_dwordx4 v134, s[20:21]
	s_mov_b32 m0, s31
	s_nop 0
	global_load_lds_dwordx4 v130, s[20:21]
	s_add_u32 s48, s18, 0x160000
	s_addc_u32 s49, s19, 0
	s_add_i32 s50, s40, s28
	s_mov_b32 m0, s50
	s_nop 0
	global_load_lds_dwordx4 v132, s[48:49]
	s_add_i32 m0, s50, 0x2000
	s_nop 0
	global_load_lds_dwordx4 v128, s[48:49]
	s_waitcnt vmcnt(8)
	s_waitcnt lgkmcnt(0)
	s_setprio 1
	s_barrier
	v_mfma_f32_16x16x32_bf16 v[60:63], v[144:147], v[166:169], v[60:63]
	v_mfma_f32_16x16x32_bf16 v[56:59], v[152:155], v[166:169], v[56:59]
	v_mfma_f32_16x16x32_bf16 v[52:55], v[144:147], v[174:177], v[52:55]
	v_mfma_f32_16x16x32_bf16 v[44:47], v[152:155], v[174:177], v[44:47]
	v_mfma_f32_16x16x32_bf16 v[36:39], v[144:147], v[182:185], v[36:39]
	v_mfma_f32_16x16x32_bf16 v[28:31], v[152:155], v[182:185], v[28:31]
	v_mfma_f32_16x16x32_bf16 v[20:23], v[144:147], v[190:193], v[20:23]
	v_mfma_f32_16x16x32_bf16 v[12:15], v[152:155], v[190:193], v[12:15]
	v_mfma_f32_16x16x32_bf16 v[60:63], v[148:151], v[170:173], v[60:63]
	v_mfma_f32_16x16x32_bf16 v[56:59], v[162:165], v[170:173], v[56:59]
	v_mfma_f32_16x16x32_bf16 v[52:55], v[148:151], v[178:181], v[52:55]
	v_mfma_f32_16x16x32_bf16 v[44:47], v[162:165], v[178:181], v[44:47]
	v_mfma_f32_16x16x32_bf16 v[36:39], v[148:151], v[186:189], v[36:39]
	v_mfma_f32_16x16x32_bf16 v[28:31], v[162:165], v[186:189], v[28:31]
	v_mfma_f32_16x16x32_bf16 v[20:23], v[148:151], v[194:197], v[20:23]
	v_mfma_f32_16x16x32_bf16 v[12:15], v[162:165], v[194:197], v[12:15]
	v_mfma_f32_16x16x32_bf16 v[48:51], v[198:201], v[166:169], v[48:51]
	v_mfma_f32_16x16x32_bf16 v[40:43], v[206:209], v[166:169], v[40:43]
	v_mfma_f32_16x16x32_bf16 v[32:35], v[198:201], v[174:177], v[32:35]
	v_mfma_f32_16x16x32_bf16 v[24:27], v[206:209], v[174:177], v[24:27]
	v_mfma_f32_16x16x32_bf16 v[16:19], v[198:201], v[182:185], v[16:19]
	v_mfma_f32_16x16x32_bf16 v[8:11], v[206:209], v[182:185], v[8:11]
	v_mfma_f32_16x16x32_bf16 v[4:7], v[198:201], v[190:193], v[4:7]
	v_mfma_f32_16x16x32_bf16 v[0:3], v[206:209], v[190:193], v[0:3]
	v_mfma_f32_16x16x32_bf16 v[48:51], v[202:205], v[170:173], v[48:51]
	v_mfma_f32_16x16x32_bf16 v[40:43], v[210:213], v[170:173], v[40:43]
	v_mfma_f32_16x16x32_bf16 v[32:35], v[202:205], v[178:181], v[32:35]
	v_mfma_f32_16x16x32_bf16 v[24:27], v[210:213], v[178:181], v[24:27]
	v_mfma_f32_16x16x32_bf16 v[16:19], v[202:205], v[186:189], v[16:19]
	v_mfma_f32_16x16x32_bf16 v[8:11], v[210:213], v[186:189], v[8:11]
	v_mfma_f32_16x16x32_bf16 v[4:7], v[202:205], v[194:197], v[4:7]
	v_mfma_f32_16x16x32_bf16 v[0:3], v[210:213], v[194:197], v[0:3]
	s_barrier
; #define PG8_STAGE(bufoff, gbase, voff) do { _Pragma("unroll") for (int _i = 0; _i < 2; ++_i) \
;     __builtin_amdgcn_global_load_lds((const unsigned*)((const char*)(gbase) + (voff)[_i]), (LAS unsigned*)(lds + (bufoff) + ldsw + _i * 8192), 16, 0, 0); } while (0)
; #define PG8_LDA(dst, b, h) do { _Pragma("unroll") for (int m = 0; m < 4; ++m) _Pragma("unroll") for (int k = 0; k < 2; ++k) dst[m][k] = *(const LAS bf16x8*)(lds + PG8_SA(b, h) + aoff + m * 2048 + k * 1024); } while (0)
; #define PG8_LDB(dst, b, h) do { _Pragma("unroll") for (int n = 0; n < 2; ++n) _Pragma("unroll") for (int k = 0; k < 2; ++k) dst[n][k] = *(const LAS bf16x8*)(lds + PG8_SB(b, h) + boff + n * 2048 + k * 1024); } while (0)
; #define PG8_MMA(ai, bj, At, Bt) do { __builtin_amdgcn_s_setprio(1); _Pragma("unroll") for (int m = 0; m < 4; ++m) _Pragma("unroll") for (int n = 0; n < 2; ++n) _Pragma("unroll") for (int k = 0; k < 2; ++k) \
;     acc[ai][bj][m][n] = __builtin_amdgcn_mfma_f32_16x16x32_bf16(Bt[n][k], At[m][k], acc[ai][bj][m][n], 0, 0, 0); __builtin_amdgcn_s_setprio(0); } while (0)
; #define PG8_WAIT_V(n) asm volatile("s_waitcnt vmcnt(" #n ")" ::: "memory")
; #define PG8_WAIT_L(n) asm volatile("s_waitcnt lgkmcnt(" #n ")" ::: "memory")
; #define PG8_BAR __builtin_amdgcn_s_barrier()
; #define PG8_SCHED __builtin_amdgcn_sched_barrier(0)
; template <class Epi, class Sched = StaticOrder>
; DI void gemm_phase(LAS unsigned char* lds, const Gemm g, const Sched& S, const Epi& E) {
;     ...
;       PG8_LDB(B0, 1, 0); PG8_SCHED; PG8_LDA(At, 1, 0); PG8_STAGE(PG8_SA(0, 1), a2 + hstep, voffA);
;       PG8_WAIT_L(8); PG8_BAR; PG8_WAIT_L(0); PG8_MMA(0, 0, At, B0); PG8_BAR; PG8_SCHED;
;       PG8_LDB(B1, 1, 1); PG8_STAGE(PG8_SB(1, 0), b3, voffB);
;       PG8_BAR; PG8_WAIT_L(0); PG8_MMA(0, 1, At, B1); PG8_BAR;
;       PG8_LDA(At, 1, 1); PG8_STAGE(PG8_SA(1, 0), a3, voffA);
;       PG8_BAR; PG8_WAIT_L(0); PG8_MMA(1, 0, At, B0); PG8_BAR; PG8_SCHED;
;       PG8_STAGE(PG8_SB(1, 1), b3 + hstep, voffB);
;       PG8_WAIT_V(6); PG8_BAR; PG8_MMA(1, 1, At, B1); PG8_BAR;
	s_setprio 0
	s_add_i32 s48, 0, 0x18000
	v_add_u32_e32 v162, s48, v157
	ds_read_b128 v[144:147], v162
	ds_read_b128 v[148:151], v162 offset:1024
	ds_read_b128 v[152:155], v162 offset:2048
	ds_read_b128 v[162:165], v162 offset:3072
	s_add_u32 s20, s20, 0x160000
	s_addc_u32 s21, s21, 0
	s_mov_b32 m0, s33
	ds_read_b128 v[166:169], v160 offset:32768
	ds_read_b128 v[170:173], v160 offset:33792
	ds_read_b128 v[174:177], v160 offset:34816
	ds_read_b128 v[178:181], v160 offset:35840
	ds_read_b128 v[182:185], v160 offset:36864
	ds_read_b128 v[186:189], v160 offset:37888
	ds_read_b128 v[190:193], v160 offset:38912
	ds_read_b128 v[194:197], v160 offset:39936
	global_load_lds_dwordx4 v134, s[20:21]
	s_mov_b32 m0, s34
	s_nop 0
	global_load_lds_dwordx4 v130, s[20:21]
	s_add_i32 s20, 0, 0x1c000
	v_add_u32_e32 v210, s20, v157
	ds_read_b128 v[198:201], v210
	ds_read_b128 v[202:205], v210 offset:1024
	ds_read_b128 v[206:209], v210 offset:2048
	ds_read_b128 v[210:213], v210 offset:3072
	s_waitcnt vmcnt(8)
	s_waitcnt lgkmcnt(0)
	s_setprio 1
	s_barrier
	v_mfma_f32_16x16x32_bf16 v[124:127], v[144:147], v[166:169], v[124:127]
	v_mfma_f32_16x16x32_bf16 v[120:123], v[152:155], v[166:169], v[120:123]
	v_mfma_f32_16x16x32_bf16 v[116:119], v[144:147], v[174:177], v[116:119]
	v_mfma_f32_16x16x32_bf16 v[112:115], v[152:155], v[174:177], v[112:115]
	v_mfma_f32_16x16x32_bf16 v[104:107], v[144:147], v[182:185], v[104:107]
	v_mfma_f32_16x16x32_bf16 v[96:99], v[152:155], v[182:185], v[96:99]
	v_mfma_f32_16x16x32_bf16 v[88:91], v[144:147], v[190:193], v[88:91]
	v_mfma_f32_16x16x32_bf16 v[80:83], v[152:155], v[190:193], v[80:83]
	v_mfma_f32_16x16x32_bf16 v[124:127], v[148:151], v[170:173], v[124:127]
	v_mfma_f32_16x16x32_bf16 v[120:123], v[162:165], v[170:173], v[120:123]
	v_mfma_f32_16x16x32_bf16 v[116:119], v[148:151], v[178:181], v[116:119]
	v_mfma_f32_16x16x32_bf16 v[112:115], v[162:165], v[178:181], v[112:115]
	v_mfma_f32_16x16x32_bf16 v[104:107], v[148:151], v[186:189], v[104:107]
	v_mfma_f32_16x16x32_bf16 v[96:99], v[162:165], v[186:189], v[96:99]
	v_mfma_f32_16x16x32_bf16 v[88:91], v[148:151], v[194:197], v[88:91]
	v_mfma_f32_16x16x32_bf16 v[80:83], v[162:165], v[194:197], v[80:83]
	v_mfma_f32_16x16x32_bf16 v[108:111], v[198:201], v[166:169], v[108:111]
	v_mfma_f32_16x16x32_bf16 v[100:103], v[206:209], v[166:169], v[100:103]
	v_mfma_f32_16x16x32_bf16 v[92:95], v[198:201], v[174:177], v[92:95]
	v_mfma_f32_16x16x32_bf16 v[84:87], v[206:209], v[174:177], v[84:87]
	v_mfma_f32_16x16x32_bf16 v[76:79], v[198:201], v[182:185], v[76:79]
	v_mfma_f32_16x16x32_bf16 v[72:75], v[206:209], v[182:185], v[72:75]
	v_mfma_f32_16x16x32_bf16 v[68:71], v[198:201], v[190:193], v[68:71]
	v_mfma_f32_16x16x32_bf16 v[64:67], v[206:209], v[190:193], v[64:67]
	v_mfma_f32_16x16x32_bf16 v[108:111], v[202:205], v[170:173], v[108:111]
	v_mfma_f32_16x16x32_bf16 v[100:103], v[210:213], v[170:173], v[100:103]
	v_mfma_f32_16x16x32_bf16 v[92:95], v[202:205], v[178:181], v[92:95]
	v_mfma_f32_16x16x32_bf16 v[84:87], v[210:213], v[178:181], v[84:87]
	v_mfma_f32_16x16x32_bf16 v[76:79], v[202:205], v[186:189], v[76:79]
	v_mfma_f32_16x16x32_bf16 v[72:75], v[210:213], v[186:189], v[72:75]
	v_mfma_f32_16x16x32_bf16 v[68:71], v[202:205], v[194:197], v[68:71]
	v_mfma_f32_16x16x32_bf16 v[64:67], v[210:213], v[194:197], v[64:67]
	s_barrier
	s_setprio 0
	s_add_i32 s21, s48, s28
	s_mov_b32 m0, s21
	s_nop 0
	global_load_lds_dwordx4 v132, s[98:99]
	s_add_i32 m0, s21, 0x2000
	s_nop 0
	global_load_lds_dwordx4 v128, s[98:99]
	s_mov_b32 m0, s35
	ds_read_b128 v[166:169], v160 offset:49152
	ds_read_b128 v[170:173], v160 offset:50176
	ds_read_b128 v[174:177], v160 offset:51200
	ds_read_b128 v[178:181], v160 offset:52224
	ds_read_b128 v[182:185], v160 offset:53248
	ds_read_b128 v[186:189], v160 offset:54272
	ds_read_b128 v[190:193], v160 offset:55296
	ds_read_b128 v[194:197], v160 offset:56320
	global_load_lds_dwordx4 v134, s[100:101]
	s_mov_b32 m0, s36
	s_nop 0
	global_load_lds_dwordx4 v130, s[100:101]
	s_add_u32 s18, s18, 0x160080
	s_addc_u32 s19, s19, 0
	s_add_i32 s20, s20, s28
	s_mov_b32 m0, s20
	s_nop 0
	global_load_lds_dwordx4 v132, s[18:19]
	s_add_i32 m0, s20, 0x2000
	s_nop 0
	global_load_lds_dwordx4 v128, s[18:19]
	s_add_i32 s47, s47, 2
	s_add_u32 s16, s16, 0x100
	s_addc_u32 s17, s17, 0
	s_add_u32 s45, s45, 0x100
	s_addc_u32 s46, s46, 0
	s_cmpk_gt_u32 s47, 0x55
	s_waitcnt vmcnt(8)
	s_waitcnt lgkmcnt(0)
	s_setprio 1
	s_barrier
	v_mfma_f32_16x16x32_bf16 v[60:63], v[144:147], v[166:169], v[60:63]
	v_mfma_f32_16x16x32_bf16 v[56:59], v[152:155], v[166:169], v[56:59]
	v_mfma_f32_16x16x32_bf16 v[52:55], v[144:147], v[174:177], v[52:55]
	v_mfma_f32_16x16x32_bf16 v[44:47], v[152:155], v[174:177], v[44:47]
	v_mfma_f32_16x16x32_bf16 v[36:39], v[144:147], v[182:185], v[36:39]
	v_mfma_f32_16x16x32_bf16 v[28:31], v[152:155], v[182:185], v[28:31]
	v_mfma_f32_16x16x32_bf16 v[20:23], v[144:147], v[190:193], v[20:23]
	v_mfma_f32_16x16x32_bf16 v[12:15], v[152:155], v[190:193], v[12:15]
	v_mfma_f32_16x16x32_bf16 v[60:63], v[148:151], v[170:173], v[60:63]
	v_mfma_f32_16x16x32_bf16 v[56:59], v[162:165], v[170:173], v[56:59]
	v_mfma_f32_16x16x32_bf16 v[52:55], v[148:151], v[178:181], v[52:55]
	v_mfma_f32_16x16x32_bf16 v[44:47], v[162:165], v[178:181], v[44:47]
	v_mfma_f32_16x16x32_bf16 v[36:39], v[148:151], v[186:189], v[36:39]
	v_mfma_f32_16x16x32_bf16 v[28:31], v[162:165], v[186:189], v[28:31]
	v_mfma_f32_16x16x32_bf16 v[20:23], v[148:151], v[194:197], v[20:23]
	v_mfma_f32_16x16x32_bf16 v[12:15], v[162:165], v[194:197], v[12:15]
	v_mfma_f32_16x16x32_bf16 v[48:51], v[198:201], v[166:169], v[48:51]
	v_mfma_f32_16x16x32_bf16 v[40:43], v[206:209], v[166:169], v[40:43]
	v_mfma_f32_16x16x32_bf16 v[32:35], v[198:201], v[174:177], v[32:35]
	v_mfma_f32_16x16x32_bf16 v[24:27], v[206:209], v[174:177], v[24:27]
	v_mfma_f32_16x16x32_bf16 v[16:19], v[198:201], v[182:185], v[16:19]
	v_mfma_f32_16x16x32_bf16 v[8:11], v[206:209], v[182:185], v[8:11]
	v_mfma_f32_16x16x32_bf16 v[4:7], v[198:201], v[190:193], v[4:7]
	v_mfma_f32_16x16x32_bf16 v[0:3], v[206:209], v[190:193], v[0:3]
	v_mfma_f32_16x16x32_bf16 v[48:51], v[202:205], v[170:173], v[48:51]
	v_mfma_f32_16x16x32_bf16 v[40:43], v[210:213], v[170:173], v[40:43]
	v_mfma_f32_16x16x32_bf16 v[32:35], v[202:205], v[178:181], v[32:35]
	v_mfma_f32_16x16x32_bf16 v[24:27], v[210:213], v[178:181], v[24:27]
	v_mfma_f32_16x16x32_bf16 v[16:19], v[202:205], v[186:189], v[16:19]
	v_mfma_f32_16x16x32_bf16 v[8:11], v[210:213], v[186:189], v[8:11]
	v_mfma_f32_16x16x32_bf16 v[4:7], v[202:205], v[194:197], v[4:7]
	v_mfma_f32_16x16x32_bf16 v[0:3], v[210:213], v[194:197], v[0:3]
	s_barrier
;   DI void operator()(const f32x4 (&acc)[2][2][4][2], const Unit& u, int wr, int wc, int fr, int fq) const {
;     const int row0 = u.pm * BM + wr * 64 + fr, col0 = u.pn * BM + wc * 32 + 8 * fq;
; #pragma unroll
;     for (int ai = 0; ai < 2; ++ai) {
;       f32x4 bv[4][2][2];
; #pragma unroll
;       for (int m = 0; m < 4; ++m)
; #pragma unroll
;         for (int bj = 0; bj < 2; ++bj) {
;           const float* bp = base + (size_t)(row0 + ai * HALF + m * 16) * 2048 + col0 + bj * HALF;
;           bv[m][bj][0] = *(const f32x4*)bp; bv[m][bj][1] = *(const f32x4*)(bp + 4);
;         }
; #pragma unroll
;       for (int m = 0; m < 4; ++m) {
;         const int row = row0 + ai * HALF + m * 16;
;         const size_t off = (size_t)row * 2048 + col0;
;         float ss = 0.f;
; #pragma unroll
;         for (int bj = 0; bj < 2; ++bj) {
;           const f32x4 v0 = acc[ai][bj][m][0] + bv[m][bj][0], v1 = acc[ai][bj][m][1] + bv[m][bj][1];
;           *(f32x4*)(C + off + bj * HALF) = v0; *(f32x4*)(C + off + bj * HALF + 4) = v1;
	s_setprio 0
	s_cbranch_scc0 .LBB0_1424
	v_lshl_or_b32 v144, s44, 8, v158
	v_lshl_add_u32 v154, s43, 8, v156
	v_ashrrev_i32_e32 v145, 31, v144
	v_lshlrev_b64 v[144:145], 2, v[144:145]
	v_ashrrev_i32_e32 v155, 31, v154
	v_lshl_add_u64 v[146:147], s[54:55], 0, v[144:145]
	v_lshlrev_b64 v[148:149], 13, v[154:155]
	v_or_b32_e32 v174, 16, v154
	v_lshl_add_u64 v[170:171], v[146:147], 0, v[148:149]
	v_ashrrev_i32_e32 v175, 31, v174
	global_load_dwordx4 v[150:153], v[170:171], off offset:16
	global_load_dwordx4 v[162:165], v[170:171], off
	global_load_dwordx4 v[166:169], v[170:171], off offset:528
	s_nop 0
	global_load_dwordx4 v[170:173], v[170:171], off offset:512
	v_lshlrev_b64 v[222:223], 13, v[174:175]
	v_or_b32_e32 v190, 32, v154
	v_lshl_add_u64 v[186:187], v[146:147], 0, v[222:223]
	v_ashrrev_i32_e32 v191, 31, v190
	global_load_dwordx4 v[174:177], v[186:187], off offset:16
	global_load_dwordx4 v[178:181], v[186:187], off
	global_load_dwordx4 v[182:185], v[186:187], off offset:528
	s_nop 0
	global_load_dwordx4 v[186:189], v[186:187], off offset:512
	v_lshlrev_b64 v[224:225], 13, v[190:191]
	v_or_b32_e32 v154, 48, v154
	v_lshl_add_u64 v[202:203], v[146:147], 0, v[224:225]
	v_ashrrev_i32_e32 v155, 31, v154
	global_load_dwordx4 v[190:193], v[202:203], off offset:16
	global_load_dwordx4 v[194:197], v[202:203], off
	global_load_dwordx4 v[198:201], v[202:203], off offset:528
	s_nop 0
	global_load_dwordx4 v[202:205], v[202:203], off offset:512
	v_lshlrev_b64 v[154:155], 13, v[154:155]
	v_lshl_add_u64 v[218:219], v[146:147], 0, v[154:155]
	global_load_dwordx4 v[206:209], v[218:219], off offset:16
	global_load_dwordx4 v[210:213], v[218:219], off
	global_load_dwordx4 v[214:217], v[218:219], off offset:528
	s_nop 0
	global_load_dwordx4 v[218:221], v[218:219], off offset:512
	s_and_b64 vcc, exec, s[0:1]
	s_mov_b32 s44, s41
	s_mov_b32 s43, s42
	s_mov_b64 s[18:19], s[4:5]
	s_mov_b64 s[16:17], s[2:3]
	s_waitcnt vmcnt(0)
	v_pk_add_f32 v[120:121], v[120:121], v[150:151]
	v_lshl_add_u64 v[150:151], s[54:55], 0, v[148:149]
	v_pk_add_f32 v[126:127], v[126:127], v[164:165]
	v_pk_add_f32 v[124:125], v[124:125], v[162:163]
	v_lshl_add_u64 v[150:151], v[150:151], 0, v[144:145]
	v_pk_add_f32 v[110:111], v[110:111], v[172:173]
	v_pk_add_f32 v[108:109], v[108:109], v[170:171]
	v_pk_add_f32 v[122:123], v[122:123], v[152:153]
	global_store_dwordx4 v[150:151], v[124:127], off
	global_store_dwordx4 v[150:151], v[120:123], off offset:16
	v_pk_add_f32 v[102:103], v[102:103], v[168:169]
	v_pk_add_f32 v[100:101], v[100:101], v[166:167]
	global_store_dwordx4 v[150:151], v[108:111], off offset:512
	global_store_dwordx4 v[150:151], v[100:103], off offset:528
	v_pk_add_f32 v[94:95], v[94:95], v[188:189]
	v_pk_add_f32 v[108:109], v[112:113], v[174:175]
	v_lshl_add_u64 v[112:113], s[54:55], 0, v[222:223]
	v_pk_add_f32 v[102:103], v[118:119], v[180:181]
	v_pk_add_f32 v[100:101], v[116:117], v[178:179]
	v_lshl_add_u64 v[112:113], v[112:113], 0, v[144:145]
	v_pk_add_f32 v[92:93], v[92:93], v[186:187]
	v_pk_add_f32 v[110:111], v[114:115], v[176:177]
	global_store_dwordx4 v[112:113], v[100:103], off
	global_store_dwordx4 v[112:113], v[108:111], off offset:16
	v_pk_add_f32 v[86:87], v[86:87], v[184:185]
	v_pk_add_f32 v[84:85], v[84:85], v[182:183]
	global_store_dwordx4 v[112:113], v[92:95], off offset:512
	global_store_dwordx4 v[112:113], v[84:87], off offset:528
	v_pk_add_f32 v[78:79], v[78:79], v[204:205]
	v_pk_add_f32 v[92:93], v[96:97], v[190:191]
	v_lshl_add_u64 v[96:97], s[54:55], 0, v[224:225]
	v_pk_add_f32 v[86:87], v[106:107], v[196:197]
	v_pk_add_f32 v[84:85], v[104:105], v[194:195]
	v_lshl_add_u64 v[96:97], v[96:97], 0, v[144:145]
	v_pk_add_f32 v[76:77], v[76:77], v[202:203]
	v_pk_add_f32 v[94:95], v[98:99], v[192:193]
	global_store_dwordx4 v[96:97], v[84:87], off
	global_store_dwordx4 v[96:97], v[92:95], off offset:16
	v_pk_add_f32 v[74:75], v[74:75], v[200:201]
	v_pk_add_f32 v[72:73], v[72:73], v[198:199]
	global_store_dwordx4 v[96:97], v[76:79], off offset:512
	global_store_dwordx4 v[96:97], v[72:75], off offset:528
	v_pk_add_f32 v[70:71], v[70:71], v[220:221]
	v_pk_add_f32 v[76:77], v[80:81], v[206:207]
	v_lshl_add_u64 v[80:81], s[54:55], 0, v[154:155]
	v_pk_add_f32 v[74:75], v[90:91], v[212:213]
	v_pk_add_f32 v[72:73], v[88:89], v[210:211]
	v_lshl_add_u64 v[80:81], v[80:81], 0, v[144:145]
	v_pk_add_f32 v[68:69], v[68:69], v[218:219]
	v_pk_add_f32 v[64:65], v[64:65], v[214:215]
	v_lshl_add_u64 v[154:155], v[148:149], 0, s[10:11]
	v_pk_add_f32 v[78:79], v[82:83], v[208:209]
	global_store_dwordx4 v[80:81], v[72:75], off
	global_store_dwordx4 v[80:81], v[76:79], off offset:16
	v_pk_add_f32 v[66:67], v[66:67], v[216:217]
	global_store_dwordx4 v[80:81], v[68:71], off offset:512
	global_store_dwordx4 v[80:81], v[64:67], off offset:528
	v_lshl_add_u64 v[152:153], v[148:149], 0, s[12:13]
	v_lshl_add_u64 v[150:151], v[148:149], 0, s[14:15]
	v_lshl_add_u64 v[64:65], v[146:147], 0, v[154:155]
	global_load_dwordx4 v[108:111], v[64:65], off offset:16
	global_load_dwordx4 v[120:123], v[64:65], off
	global_load_dwordx4 v[92:95], v[64:65], off offset:528
	global_load_dwordx4 v[100:103], v[64:65], off offset:512
	v_lshl_add_u64 v[64:65], v[146:147], 0, v[152:153]
	global_load_dwordx4 v[88:91], v[64:65], off offset:16
	global_load_dwordx4 v[96:99], v[64:65], off
	global_load_dwordx4 v[76:79], v[64:65], off offset:528
	global_load_dwordx4 v[84:87], v[64:65], off offset:512
	v_lshl_add_u64 v[68:69], v[146:147], 0, v[150:151]
	global_load_dwordx4 v[72:75], v[68:69], off offset:16
	global_load_dwordx4 v[80:83], v[68:69], off
	global_load_dwordx4 v[64:67], v[68:69], off offset:528
	s_nop 0
	global_load_dwordx4 v[68:71], v[68:69], off offset:512
	v_lshl_add_u64 v[148:149], v[148:149], 0, s[6:7]
	v_lshl_add_u64 v[112:113], v[146:147], 0, v[148:149]
	global_load_dwordx4 v[116:119], v[112:113], off offset:16
	global_load_dwordx4 v[124:127], v[112:113], off
	global_load_dwordx4 v[104:107], v[112:113], off offset:528
	s_nop 0
	global_load_dwordx4 v[112:115], v[112:113], off offset:512
	s_waitcnt vmcnt(0)
; #define PG8_WAIT_V(n) asm volatile("s_waitcnt vmcnt(" #n ")" ::: "memory")
; #define PG8_BAR __builtin_amdgcn_s_barrier()
;   DI void operator()(const f32x4 (&acc)[2][2][4][2], const Unit& u, int wr, int wc, int fr, int fq) const {
;     ...
;     for (int ai = 0; ai < 2; ++ai) {
;       f32x4 bv[4][2][2];
; #pragma unroll
;       for (int m = 0; m < 4; ++m)
; #pragma unroll
;         for (int bj = 0; bj < 2; ++bj) {
;           const float* bp = base + (size_t)(row0 + ai * HALF + m * 16) * 2048 + col0 + bj * HALF;
;           bv[m][bj][0] = *(const f32x4*)bp; bv[m][bj][1] = *(const f32x4*)(bp + 4);
;         }
; #pragma unroll
;       for (int m = 0; m < 4; ++m) {
;         const int row = row0 + ai * HALF + m * 16;
;         const size_t off = (size_t)row * 2048 + col0;
;         float ss = 0.f;
; #pragma unroll
;         for (int bj = 0; bj < 2; ++bj) {
;           const f32x4 v0 = acc[ai][bj][m][0] + bv[m][bj][0], v1 = acc[ai][bj][m][1] + bv[m][bj][1];
;           *(f32x4*)(C + off + bj * HALF) = v0; *(f32x4*)(C + off + bj * HALF + 4) = v1;
; template <class Epi, class Sched = StaticOrder>
; DI void gemm_phase(LAS unsigned char* lds, const Gemm g, const Sched& S, const Epi& E) {
;     ...
;     E(acc, cur, wr, wc, fr, fq);
;     if (!has_next) break;
; #pragma unroll
;     for (int a = 0; a < 2; ++a)
; #pragma unroll
;       for (int b = 0; b < 2; ++b)
; #pragma unroll
;         for (int m = 0; m < 4; ++m)
; #pragma unroll
;           for (int n = 0; n < 2; ++n) acc[a][b][m][n] = (f32x4){0.f, 0.f, 0.f, 0.f};
;     cur = nxt; cA = nA; cB = nB; ++ui;
;   }
;   PG8_WAIT_V(0);
;   if (wr == 0) PG8_BAR;
;   PG8_BAR;
	v_pk_add_f32 v[56:57], v[56:57], v[108:109]
	v_lshl_add_u64 v[108:109], s[54:55], 0, v[154:155]
	v_pk_add_f32 v[62:63], v[62:63], v[122:123]
	v_pk_add_f32 v[60:61], v[60:61], v[120:121]
	v_lshl_add_u64 v[108:109], v[108:109], 0, v[144:145]
	v_pk_add_f32 v[50:51], v[50:51], v[102:103]
	v_pk_add_f32 v[48:49], v[48:49], v[100:101]
	v_pk_add_f32 v[58:59], v[58:59], v[110:111]
	global_store_dwordx4 v[108:109], v[60:63], off
	global_store_dwordx4 v[108:109], v[56:59], off offset:16
	v_pk_add_f32 v[42:43], v[42:43], v[94:95]
	v_pk_add_f32 v[40:41], v[40:41], v[92:93]
	global_store_dwordx4 v[108:109], v[48:51], off offset:512
	global_store_dwordx4 v[108:109], v[40:43], off offset:528
	v_pk_add_f32 v[34:35], v[34:35], v[86:87]
	v_lshl_add_u64 v[48:49], s[54:55], 0, v[152:153]
	v_pk_add_f32 v[42:43], v[54:55], v[98:99]
	v_pk_add_f32 v[40:41], v[52:53], v[96:97]
	v_lshl_add_u64 v[48:49], v[48:49], 0, v[144:145]
	v_pk_add_f32 v[32:33], v[32:33], v[84:85]
	v_pk_add_f32 v[46:47], v[46:47], v[90:91]
	v_pk_add_f32 v[44:45], v[44:45], v[88:89]
	global_store_dwordx4 v[48:49], v[40:43], off
	global_store_dwordx4 v[48:49], v[44:47], off offset:16
	v_pk_add_f32 v[26:27], v[26:27], v[78:79]
	v_pk_add_f32 v[24:25], v[24:25], v[76:77]
	global_store_dwordx4 v[48:49], v[32:35], off offset:512
	global_store_dwordx4 v[48:49], v[24:27], off offset:528
	v_pk_add_f32 v[18:19], v[18:19], v[70:71]
	v_lshl_add_u64 v[32:33], s[54:55], 0, v[150:151]
	v_pk_add_f32 v[26:27], v[38:39], v[82:83]
	v_pk_add_f32 v[24:25], v[36:37], v[80:81]
	v_lshl_add_u64 v[32:33], v[32:33], 0, v[144:145]
	v_pk_add_f32 v[16:17], v[16:17], v[68:69]
	v_pk_add_f32 v[30:31], v[30:31], v[74:75]
	v_pk_add_f32 v[28:29], v[28:29], v[72:73]
	global_store_dwordx4 v[32:33], v[24:27], off
	global_store_dwordx4 v[32:33], v[28:31], off offset:16
	v_pk_add_f32 v[10:11], v[10:11], v[66:67]
	v_pk_add_f32 v[8:9], v[8:9], v[64:65]
	global_store_dwordx4 v[32:33], v[16:19], off offset:512
	global_store_dwordx4 v[32:33], v[8:11], off offset:528
	v_pk_add_f32 v[6:7], v[6:7], v[114:115]
	v_lshl_add_u64 v[16:17], s[54:55], 0, v[148:149]
	v_pk_add_f32 v[10:11], v[22:23], v[126:127]
	v_pk_add_f32 v[8:9], v[20:21], v[124:125]
	v_lshl_add_u64 v[16:17], v[16:17], 0, v[144:145]
	v_pk_add_f32 v[4:5], v[4:5], v[112:113]
	v_pk_add_f32 v[14:15], v[14:15], v[118:119]
	v_pk_add_f32 v[12:13], v[12:13], v[116:117]
	global_store_dwordx4 v[16:17], v[8:11], off
	global_store_dwordx4 v[16:17], v[12:15], off offset:16
	v_pk_add_f32 v[2:3], v[2:3], v[106:107]
	v_pk_add_f32 v[0:1], v[0:1], v[104:105]
	global_store_dwordx4 v[16:17], v[4:7], off offset:512
	global_store_dwordx4 v[16:17], v[0:3], off offset:528
	s_cbranch_vccz .LBB0_1417
	s_waitcnt vmcnt(0)
	s_cmpk_gt_u32 s23, 0xff
	s_cbranch_scc1 .LBB0_1428
	s_barrier
